# peeled first K-iteration after each epilogue with relaxed vmcnt(24) on its first two waits (epilogue stores may stay in flight); stacks on v7
# baseline (speedup 1.0000x reference)
; #define PG8_STAGE(bufoff, gbase, voff) do { _Pragma("unroll") for (int _i = 0; _i < 2; ++_i) \
;         __builtin_amdgcn_global_load_lds((const unsigned*)((const char*)(gbase) + (voff)[_i]), (PG8_LAS unsigned*)(lds + (bufoff) + ldsw + _i * 8192), 16, 0, 0); } while (0)
; #define PG8_WAIT_V(n) asm volatile("s_waitcnt vmcnt(" #n ")" ::: "memory")
; #define PG8_BAR __builtin_amdgcn_s_barrier()
; template <class Epi, class Sched, bool ALIGN_EPI = false, bool SP2 = false>
; __device__ __forceinline__ void gemm_phase(PG8_LAS unsigned char* lds, const Gemm g, const Sched& S, const Epi& E) {
;     ...
;     for (int i = 0; i < 2; ++i) { int R, C; stage_rc(tid * 16 + i * 8192, R, C); const int Rb = Epi::PERM ? ((R & ~31) + perm32(R & 31)) : R;
;         voffA[i] = (unsigned)(R * K + C) * 2u; voffB[i] = (unsigned)(Rb * K + C) * 2u; }
;     const size_t kstep = (size_t)(BK * 2);
;     const size_t hstep = (size_t)HALF * K * 2;
;     const size_t tstep = 2 * hstep;
;     const unsigned ldsw = (unsigned)wid * 1024u;
;     const int aoff = lds_byte(wr * 64 + fr, fq * 8), boff = lds_byte(wc * 32 + fr, fq * 8);
;     ...
;     if constexpr (SP2) {
;         PG8_STAGE(PG8_SB(0, 0), cB, voffB); PG8_STAGE(PG8_SB(0, 1), cB + hstep, voffB); PG8_STAGE(PG8_SA(0, 0), cA, voffA); PG8_STAGE(PG8_SA(0, 1), cA + hstep, voffA);
;         if (wr == 1) PG8_BAR;
;         PG8_WAIT_V(2); PG8_BAR;
;         PG8_STAGE(PG8_SB(1, 0), cB + kstep, voffB); PG8_STAGE(PG8_SA(1, 0), cA + kstep, voffA); PG8_STAGE(PG8_SB(1, 1), cB + hstep + kstep, voffB);
;         PG8_WAIT_V(6); PG8_BAR;
.LBB0_196:
	s_mov_b32 s99, 0
	s_lshl_b32 s3, s16, 5
	s_mov_b64 s[16:17], 0x80
	s_and_b32 s3, s3, 0x60
	s_add_i32 m0, s31, 0x18000
	v_lshl_add_u64 v[6:7], v[6:7], 0, s[16:17]
	s_lshl_b32 s1, s9, 13
	s_lshl_b32 s20, s3, 7
	s_waitcnt vmcnt(2)
	s_barrier
	global_load_lds_dwordx4 v[6:7], off
	v_lshl_add_u64 v[2:3], v[2:3], 0, s[16:17]
	s_add_i32 m0, s31, 0x1a000
	s_add_i32 s38, s31, 0x8000
	s_add_i32 s39, s31, 0xa000
	global_load_lds_dwordx4 v[2:3], off
	v_lshl_add_u64 v[0:1], v[0:1], 0, s[16:17]
	s_mov_b32 m0, s38
	s_add_u32 s18, s6, 0x80080
	global_load_lds_dwordx4 v[0:1], off
	v_lshl_add_u64 v[0:1], v[4:5], 0, s[16:17]
	s_mov_b32 m0, s39
	s_addc_u32 s19, s7, 0
	global_load_lds_dwordx4 v[0:1], off
	s_add_i32 m0, s31, 0x1c000
	v_lshl_add_u64 v[0:1], s[18:19], 0, v[164:165]
	global_load_lds_dwordx4 v[0:1], off
	v_lshl_add_u64 v[0:1], s[18:19], 0, v[168:169]
	s_add_i32 m0, s31, 0x1e000
	s_cmpk_lt_u32 s8, 0x100
	global_load_lds_dwordx4 v[0:1], off
	v_lshrrev_b32_e32 v1, 1, v8
	v_and_b32_e32 v1, 24, v1
	v_and_b32_e32 v0, 15, v8
	v_lshlrev_b32_e32 v2, 1, v1
	v_lshl_or_b32 v161, s9, 6, v0
	v_lshl_or_b32 v0, v0, 6, v2
	v_lshlrev_b32_e32 v2, 2, v8
	v_and_b32_e32 v2, 32, v2
	v_bitop3_b32 v3, v0, s1, v2 bitop3:0xde
	v_bitop3_b32 v188, v0, s20, v2 bitop3:0xde
	v_lshlrev_b32_e32 v0, 15, v9
	v_and_b32_e32 v0, 0xffff0000, v0
	v_or_b32_e32 v189, s3, v1
	v_lshl_add_u32 v0, v10, 12, v0
	v_and_b32_e32 v1, 1, v9
	v_lshl_or_b32 v0, v1, 6, v0
	v_lshl_add_u32 v172, v11, 1, v0
	v_lshlrev_b32_e32 v0, 15, v12
	v_and_b32_e32 v0, 0xffff0000, v0
	s_waitcnt vmcnt(6)
	v_lshl_add_u32 v0, v13, 12, v0
	v_and_b32_e32 v1, 1, v12
	s_cselect_b64 s[18:19], -1, 0
	v_lshl_or_b32 v0, v1, 6, v0
	s_add_i32 s43, 0, 0x10000
	s_add_i32 s44, 0, 0x14000
	s_ashr_i32 s40, s62, 31
	s_mov_b32 s41, s62
	s_ashr_i32 s42, s55, 31
	v_mov_b32_e32 v173, v171
	v_lshl_add_u32 v174, v14, 1, v0
	v_mov_b32_e32 v175, v171
	v_mov_b64_e32 v[176:177], 0x980
	v_mov_b64_e32 v[178:179], 0x97f
	v_add_u32_e32 v190, s43, v188
	v_add_u32_e32 v191, s44, v188
	v_add_u32_e32 v192, 0, v3
	s_movk_i32 s45, 0x4400
	s_mov_b32 s46, 0x800000
	s_mov_b32 s47, 0x3f317217
	s_mov_b32 s49, 0x7f800000
	v_mov_b32_e32 v193, 0x41b17218
	s_barrier
	s_branch .LBB0_199

;     __device__ __forceinline__ bool next(int i, Unit& u) const { if (!base.next(i >> 1, u)) return false; if (i & 1) { u.pm += 64; u.pn += 8; } return true; }
; #define PG8_STAGE(bufoff, gbase, voff) do { _Pragma("unroll") for (int _i = 0; _i < 2; ++_i) \
;         __builtin_amdgcn_global_load_lds((const unsigned*)((const char*)(gbase) + (voff)[_i]), (PG8_LAS unsigned*)(lds + (bufoff) + ldsw + _i * 8192), 16, 0, 0); } while (0)
; #define PG8_LDA(dst, b, h) do { _Pragma("unroll") for (int m = 0; m < 4; ++m) _Pragma("unroll") for (int k = 0; k < 2; ++k) dst[m][k] = *(const PG8_LAS bf16x8*)(lds + PG8_SA(b, h) + aoff + m * 2048 + k * 1024); } while (0)
; #define PG8_LDB(dst, b, h) do { _Pragma("unroll") for (int n = 0; n < 2; ++n) _Pragma("unroll") for (int k = 0; k < 2; ++k) dst[n][k] = *(const PG8_LAS bf16x8*)(lds + PG8_SB(b, h) + boff + n * 2048 + k * 1024); } while (0)
; #define PG8_WAIT_V(n) asm volatile("s_waitcnt vmcnt(" #n ")" ::: "memory")
; #define PG8_BAR __builtin_amdgcn_s_barrier()
; template <class Epi, class Sched, bool ALIGN_EPI = false, bool SP2 = false>
; __device__ __forceinline__ void gemm_phase(PG8_LAS unsigned char* lds, const Gemm g, const Sched& S, const Epi& E) {
;     ...
;         const bool has_next = S.next(ui + 1, nxt);
;         const char* nA = has_next ? (const char*)g.A + (size_t)nxt.pm * tstep : cA; const char* nB = has_next ? (const char*)g.Bt + (size_t)nxt.pn * tstep : cB;
;         for (int t = 0; t < nt; t += 2) {
;             const bool last = (t == nt - 2);
;             const char* a1 = cA + (size_t)(t + 1) * kstep;
;             const char* a2 = last ? nA : cA + (size_t)(t + 2) * kstep; const char* b2 = last ? nB : cB + (size_t)(t + 2) * kstep;
;             const char* a3 = a2 + kstep; const char* b3 = b2 + kstep;
;             if (last && has_next) S.a_ready(nxt);
;             if constexpr (SP2) {
;             PG8_LDB(B0, 0, 0); PG8_LDB(B1, 0, 1); PG8_SCHED; PG8_LDA(At, 0, 0); PG8_STAGE(PG8_SA(1, 1), a1 + hstep, voffA);
;             PG8_WAIT_V(8); PG8_WAIT_L(0); PG8_BAR; PG8_MMA(0, 0, At, B0); PG8_MMA(0, 1, At, B1); PG8_BAR; PG8_SCHED;
;     ...
; #pragma unroll
;         for (int a = 0; a < 2; ++a)
; #pragma unroll
;             for (int b = 0; b < 2; ++b)
; #pragma unroll
;                 for (int m = 0; m < 4; ++m)
; #pragma unroll
;                     for (int n = 0; n < 2; ++n) acc[a][b][m][n] = (f32x4){0.f, 0.f, 0.f, 0.f};
.LBB0_204:
	s_ashr_i32 s21, s20, 31
	s_lshl_b64 s[24:25], s[20:21], 20
	v_readlane_b32 s26, v236, 50
	v_readlane_b32 s27, v236, 51
	s_add_u32 s24, s26, s24
	s_addc_u32 s25, s27, s25
	s_and_b64 s[26:27], s[8:9], exec
	s_cselect_b32 s1, s25, s5
	s_cselect_b32 s3, s24, s4
	s_ashr_i32 s23, s22, 31
	s_lshl_b64 s[26:27], s[22:23], 20
	s_add_u32 s26, s10, s26
	s_addc_u32 s27, s11, s27
	s_and_b64 s[28:29], s[8:9], exec
	s_cselect_b32 s21, s27, s7
	s_cselect_b32 s23, s26, s6
	s_add_u32 s4, s4, 0x80080
	s_addc_u32 s5, s5, 0
	s_add_u32 s33, s6, 0x100
	v_mov_b32_e32 v0, 0
	s_addc_u32 s50, s7, 0
	s_mov_b32 s51, -2
	v_mov_b32_e32 v1, v0
	v_mov_b32_e32 v2, v0
	v_mov_b32_e32 v3, v0
	v_mov_b32_e32 v4, v0
	v_mov_b32_e32 v5, v0
	v_mov_b32_e32 v6, v0
	v_mov_b32_e32 v7, v0
	s_waitcnt vmcnt(0)
	v_mov_b32_e32 v16, v0
	v_mov_b32_e32 v17, v0
	v_mov_b32_e32 v18, v0
	v_mov_b32_e32 v19, v0
	v_mov_b32_e32 v20, v0
	v_mov_b32_e32 v21, v0
	v_mov_b32_e32 v22, v0
	v_mov_b32_e32 v23, v0
	v_mov_b32_e32 v32, v0
	v_mov_b32_e32 v33, v0
	v_mov_b32_e32 v34, v0
	v_mov_b32_e32 v35, v0
	v_mov_b32_e32 v36, v0
	v_mov_b32_e32 v37, v0
	v_mov_b32_e32 v38, v0
	v_mov_b32_e32 v39, v0
	v_mov_b32_e32 v48, v0
	v_mov_b32_e32 v49, v0
	v_mov_b32_e32 v50, v0
	v_mov_b32_e32 v51, v0
	v_mov_b32_e32 v52, v0
	v_mov_b32_e32 v53, v0
	v_mov_b32_e32 v54, v0
	v_mov_b32_e32 v55, v0
	v_mov_b32_e32 v8, v0
	v_mov_b32_e32 v9, v0
	v_mov_b32_e32 v10, v0
	v_mov_b32_e32 v11, v0
	v_mov_b32_e32 v12, v0
	v_mov_b32_e32 v13, v0
	v_mov_b32_e32 v14, v0
	v_mov_b32_e32 v15, v0
	v_mov_b32_e32 v24, v0
	v_mov_b32_e32 v25, v0
	v_mov_b32_e32 v26, v0
	v_mov_b32_e32 v27, v0
	v_mov_b32_e32 v28, v0
	v_mov_b32_e32 v29, v0
	v_mov_b32_e32 v30, v0
	v_mov_b32_e32 v31, v0
	v_mov_b32_e32 v40, v0
	v_mov_b32_e32 v41, v0
	v_mov_b32_e32 v42, v0
	v_mov_b32_e32 v43, v0
	v_mov_b32_e32 v44, v0
	v_mov_b32_e32 v45, v0
	v_mov_b32_e32 v46, v0
	v_mov_b32_e32 v47, v0
	v_mov_b32_e32 v56, v0
	v_mov_b32_e32 v57, v0
	v_mov_b32_e32 v58, v0
	v_mov_b32_e32 v59, v0
	v_mov_b32_e32 v60, v0
	v_mov_b32_e32 v61, v0
	v_mov_b32_e32 v62, v0
	v_mov_b32_e32 v63, v0
	v_mov_b32_e32 v64, v0
	v_mov_b32_e32 v65, v0
	v_mov_b32_e32 v66, v0
	v_mov_b32_e32 v67, v0
	v_mov_b32_e32 v68, v0
	v_mov_b32_e32 v69, v0
	v_mov_b32_e32 v70, v0
	v_mov_b32_e32 v71, v0
	v_mov_b32_e32 v80, v0
	v_mov_b32_e32 v81, v0
	v_mov_b32_e32 v82, v0
	v_mov_b32_e32 v83, v0
	v_mov_b32_e32 v84, v0
	v_mov_b32_e32 v85, v0
	v_mov_b32_e32 v86, v0
	v_mov_b32_e32 v87, v0
	v_mov_b32_e32 v96, v0
	v_mov_b32_e32 v97, v0
	v_mov_b32_e32 v98, v0
	v_mov_b32_e32 v99, v0
	v_mov_b32_e32 v100, v0
	v_mov_b32_e32 v101, v0
	v_mov_b32_e32 v102, v0
	v_mov_b32_e32 v103, v0
	v_mov_b32_e32 v112, v0
	v_mov_b32_e32 v113, v0
	v_mov_b32_e32 v114, v0
	v_mov_b32_e32 v115, v0
	v_mov_b32_e32 v116, v0
	v_mov_b32_e32 v117, v0
	v_mov_b32_e32 v118, v0
	v_mov_b32_e32 v119, v0
	v_mov_b32_e32 v72, v0
	v_mov_b32_e32 v73, v0
	v_mov_b32_e32 v74, v0
	v_mov_b32_e32 v75, v0
	v_mov_b32_e32 v76, v0
	v_mov_b32_e32 v77, v0
	v_mov_b32_e32 v78, v0
	v_mov_b32_e32 v79, v0
	v_mov_b32_e32 v88, v0
	v_mov_b32_e32 v89, v0
	v_mov_b32_e32 v90, v0
	v_mov_b32_e32 v91, v0
	v_mov_b32_e32 v92, v0
	v_mov_b32_e32 v93, v0
	v_mov_b32_e32 v94, v0
	v_mov_b32_e32 v95, v0
	v_mov_b32_e32 v104, v0
	v_mov_b32_e32 v105, v0
	v_mov_b32_e32 v106, v0
	v_mov_b32_e32 v107, v0
	v_mov_b32_e32 v108, v0
	v_mov_b32_e32 v109, v0
	v_mov_b32_e32 v110, v0
	v_mov_b32_e32 v111, v0
	v_mov_b32_e32 v120, v0
	v_mov_b32_e32 v121, v0
	v_mov_b32_e32 v122, v0
	v_mov_b32_e32 v123, v0
	v_mov_b32_e32 v124, v0
	v_mov_b32_e32 v125, v0
	v_mov_b32_e32 v126, v0
	v_mov_b32_e32 v127, v0
	s_cmp_eq_u32 s99, 0
	s_cbranch_scc1 .LBB0_205
	ds_read_b128 v[128:131], v190
	ds_read_b128 v[132:135], v190 offset:1024
	ds_read_b128 v[136:139], v190 offset:2048
	ds_read_b128 v[140:143], v190 offset:3072
	ds_read_b128 v[144:147], v191
	ds_read_b128 v[148:151], v191 offset:1024
	ds_read_b128 v[152:155], v191 offset:2048
	ds_read_b128 v[156:159], v191 offset:3072
	s_add_u32 s6, s4, 0xfff80080
	s_addc_u32 s7, s5, -1
	s_cmp_eq_u32 s51, 28
	s_cselect_b32 s29, s1, s7
	s_cselect_b32 s28, s3, s6
	s_cselect_b32 s7, s21, s50
	s_cselect_b32 s6, s23, s33
	v_lshl_add_u64 v[184:185], s[4:5], 0, v[172:173]
	s_add_i32 m0, s31, 0xc000
	ds_read_b128 v[180:183], v192
	ds_read_b128 v[194:197], v192 offset:1024
	ds_read_b128 v[198:201], v192 offset:2048
	ds_read_b128 v[202:205], v192 offset:3072
	ds_read_b128 v[206:209], v192 offset:4096
	ds_read_b128 v[210:213], v192 offset:5120
	ds_read_b128 v[214:217], v192 offset:6144
	ds_read_b128 v[218:221], v192 offset:7168
	global_load_lds_dwordx4 v[184:185], off
	v_lshl_add_u64 v[184:185], s[4:5], 0, v[174:175]
	s_add_i32 m0, s31, 0xe000
	s_nop 0
	global_load_lds_dwordx4 v[184:185], off
	s_waitcnt vmcnt(24)
	s_waitcnt lgkmcnt(0)
	s_barrier
; #define PG8_STAGE(bufoff, gbase, voff) do { _Pragma("unroll") for (int _i = 0; _i < 2; ++_i) \
;         __builtin_amdgcn_global_load_lds((const unsigned*)((const char*)(gbase) + (voff)[_i]), (PG8_LAS unsigned*)(lds + (bufoff) + ldsw + _i * 8192), 16, 0, 0); } while (0)
; #define PG8_LDA(dst, b, h) do { _Pragma("unroll") for (int m = 0; m < 4; ++m) _Pragma("unroll") for (int k = 0; k < 2; ++k) dst[m][k] = *(const PG8_LAS bf16x8*)(lds + PG8_SA(b, h) + aoff + m * 2048 + k * 1024); } while (0)
; #define PG8_MMA(ai, bj, At, Bt) do { __builtin_amdgcn_s_setprio(1); _Pragma("unroll") for (int m = 0; m < 4; ++m) _Pragma("unroll") for (int n = 0; n < 2; ++n) _Pragma("unroll") for (int k = 0; k < 2; ++k) \
;         acc[ai][bj][m][n] = __builtin_amdgcn_mfma_f32_16x16x32_bf16(Bt[n][k], At[m][k], acc[ai][bj][m][n], 0, 0, 0); __builtin_amdgcn_s_setprio(0); } while (0)
; #define PG8_WAIT_V(n) asm volatile("s_waitcnt vmcnt(" #n ")" ::: "memory")
; #define PG8_WAIT_L(n) asm volatile("s_waitcnt lgkmcnt(" #n ")" ::: "memory")
; #define PG8_BAR __builtin_amdgcn_s_barrier()
; #define PG8_SCHED __builtin_amdgcn_sched_barrier(0)
; template <class Epi, class Sched, bool ALIGN_EPI = false, bool SP2 = false>
; __device__ __forceinline__ void gemm_phase(PG8_LAS unsigned char* lds, const Gemm g, const Sched& S, const Epi& E) {
;     ...
;             PG8_WAIT_V(8); PG8_WAIT_L(0); PG8_BAR; PG8_MMA(0, 0, At, B0); PG8_MMA(0, 1, At, B1); PG8_BAR; PG8_SCHED;
;             PG8_LDA(At, 0, 1); PG8_STAGE(PG8_SB(0, 0), b2, voffB); PG8_STAGE(PG8_SB(0, 1), b2 + hstep, voffB); PG8_STAGE(PG8_SA(0, 0), a2, voffA);
;             PG8_WAIT_V(8); PG8_WAIT_L(0); PG8_BAR; PG8_MMA(1, 0, At, B0); PG8_MMA(1, 1, At, B1); PG8_BAR; PG8_SCHED;
	s_setprio 1
	s_waitcnt lgkmcnt(0)
	v_mfma_f32_16x16x32_bf16 v[124:127], v[128:131], v[180:183], v[124:127]
	v_mfma_f32_16x16x32_bf16 v[120:123], v[136:139], v[180:183], v[120:123]
	v_mfma_f32_16x16x32_bf16 v[108:111], v[128:131], v[198:201], v[108:111]
	v_mfma_f32_16x16x32_bf16 v[104:107], v[136:139], v[198:201], v[104:107]
	v_mfma_f32_16x16x32_bf16 v[92:95], v[128:131], v[206:209], v[92:95]
	v_mfma_f32_16x16x32_bf16 v[88:91], v[136:139], v[206:209], v[88:91]
	v_mfma_f32_16x16x32_bf16 v[76:79], v[128:131], v[214:217], v[76:79]
	v_mfma_f32_16x16x32_bf16 v[72:75], v[136:139], v[214:217], v[72:75]
	v_mfma_f32_16x16x32_bf16 v[124:127], v[132:135], v[194:197], v[124:127]
	v_mfma_f32_16x16x32_bf16 v[120:123], v[140:143], v[194:197], v[120:123]
	v_mfma_f32_16x16x32_bf16 v[108:111], v[132:135], v[202:205], v[108:111]
	v_mfma_f32_16x16x32_bf16 v[104:107], v[140:143], v[202:205], v[104:107]
	v_mfma_f32_16x16x32_bf16 v[92:95], v[132:135], v[210:213], v[92:95]
	v_mfma_f32_16x16x32_bf16 v[88:91], v[140:143], v[210:213], v[88:91]
	v_mfma_f32_16x16x32_bf16 v[76:79], v[132:135], v[218:221], v[76:79]
	v_mfma_f32_16x16x32_bf16 v[72:75], v[140:143], v[218:221], v[72:75]
	s_setprio 0
	s_setprio 1
	v_mfma_f32_16x16x32_bf16 v[116:119], v[144:147], v[180:183], v[116:119]
	v_mfma_f32_16x16x32_bf16 v[112:115], v[152:155], v[180:183], v[112:115]
	v_mfma_f32_16x16x32_bf16 v[100:103], v[144:147], v[198:201], v[100:103]
	v_mfma_f32_16x16x32_bf16 v[96:99], v[152:155], v[198:201], v[96:99]
	v_mfma_f32_16x16x32_bf16 v[84:87], v[144:147], v[206:209], v[84:87]
	v_mfma_f32_16x16x32_bf16 v[80:83], v[152:155], v[206:209], v[80:83]
	v_mfma_f32_16x16x32_bf16 v[68:71], v[144:147], v[214:217], v[68:71]
	v_mfma_f32_16x16x32_bf16 v[64:67], v[152:155], v[214:217], v[64:67]
	v_mfma_f32_16x16x32_bf16 v[116:119], v[148:151], v[194:197], v[116:119]
	v_mfma_f32_16x16x32_bf16 v[112:115], v[156:159], v[194:197], v[112:115]
	v_mfma_f32_16x16x32_bf16 v[100:103], v[148:151], v[202:205], v[100:103]
	v_mfma_f32_16x16x32_bf16 v[96:99], v[156:159], v[202:205], v[96:99]
	v_mfma_f32_16x16x32_bf16 v[84:87], v[148:151], v[210:213], v[84:87]
	v_mfma_f32_16x16x32_bf16 v[80:83], v[156:159], v[210:213], v[80:83]
	v_mfma_f32_16x16x32_bf16 v[68:71], v[148:151], v[218:221], v[68:71]
	v_mfma_f32_16x16x32_bf16 v[64:67], v[156:159], v[218:221], v[64:67]
	s_setprio 0
	s_barrier
	s_add_i32 s52, s43, s30
	v_lshl_add_u64 v[184:185], s[6:7], 0, v[164:165]
	s_mov_b32 m0, s52
	ds_read_b128 v[180:183], v192 offset:16384
	ds_read_b128 v[194:197], v192 offset:17408
	ds_read_b128 v[198:201], v192 offset:18432
	ds_read_b128 v[202:205], v192 offset:19456
	ds_read_b128 v[206:209], v192 offset:20480
	ds_read_b128 v[210:213], v192 offset:21504
	ds_read_b128 v[214:217], v192 offset:22528
	ds_read_b128 v[218:221], v192 offset:23552
	global_load_lds_dwordx4 v[184:185], off
	s_add_i32 m0, s52, 0x2000
	s_add_u32 s52, s6, 0x80000
	v_lshl_add_u64 v[222:223], s[6:7], 0, v[168:169]
	s_addc_u32 s53, s7, 0
	s_add_i32 s54, s44, s30
	global_load_lds_dwordx4 v[222:223], off
	v_lshl_add_u64 v[224:225], s[52:53], 0, v[164:165]
	s_mov_b32 m0, s54
	v_lshl_add_u64 v[226:227], s[28:29], 0, v[166:167]
	global_load_lds_dwordx4 v[224:225], off
	v_lshl_add_u64 v[224:225], s[52:53], 0, v[168:169]
	s_add_i32 m0, s54, 0x2000
	s_nop 0
	global_load_lds_dwordx4 v[224:225], off
	v_lshl_add_u64 v[224:225], s[28:29], 0, v[162:163]
	s_mov_b32 m0, s31
	s_nop 0
	global_load_lds_dwordx4 v[224:225], off
	s_mov_b32 m0, s34
	s_nop 0
	global_load_lds_dwordx4 v[226:227], off
	s_waitcnt vmcnt(24)
	s_waitcnt lgkmcnt(0)
	s_barrier
	s_setprio 1
	s_waitcnt lgkmcnt(0)
	v_mfma_f32_16x16x32_bf16 v[60:63], v[128:131], v[180:183], v[60:63]
	v_mfma_f32_16x16x32_bf16 v[56:59], v[136:139], v[180:183], v[56:59]
	v_mfma_f32_16x16x32_bf16 v[44:47], v[128:131], v[198:201], v[44:47]
	v_mfma_f32_16x16x32_bf16 v[40:43], v[136:139], v[198:201], v[40:43]
	v_mfma_f32_16x16x32_bf16 v[28:31], v[128:131], v[206:209], v[28:31]
	v_mfma_f32_16x16x32_bf16 v[24:27], v[136:139], v[206:209], v[24:27]
	v_mfma_f32_16x16x32_bf16 v[12:15], v[128:131], v[214:217], v[12:15]
	v_mfma_f32_16x16x32_bf16 v[8:11], v[136:139], v[214:217], v[8:11]
	v_mfma_f32_16x16x32_bf16 v[60:63], v[132:135], v[194:197], v[60:63]
	v_mfma_f32_16x16x32_bf16 v[56:59], v[140:143], v[194:197], v[56:59]
	v_mfma_f32_16x16x32_bf16 v[44:47], v[132:135], v[202:205], v[44:47]
	v_mfma_f32_16x16x32_bf16 v[40:43], v[140:143], v[202:205], v[40:43]
	v_mfma_f32_16x16x32_bf16 v[28:31], v[132:135], v[210:213], v[28:31]
	v_mfma_f32_16x16x32_bf16 v[24:27], v[140:143], v[210:213], v[24:27]
	v_mfma_f32_16x16x32_bf16 v[12:15], v[132:135], v[218:221], v[12:15]
	v_mfma_f32_16x16x32_bf16 v[8:11], v[140:143], v[218:221], v[8:11]
	s_setprio 0
	s_setprio 1
	v_mfma_f32_16x16x32_bf16 v[52:55], v[144:147], v[180:183], v[52:55]
	v_mfma_f32_16x16x32_bf16 v[48:51], v[152:155], v[180:183], v[48:51]
	v_mfma_f32_16x16x32_bf16 v[36:39], v[144:147], v[198:201], v[36:39]
	v_mfma_f32_16x16x32_bf16 v[32:35], v[152:155], v[198:201], v[32:35]
	v_mfma_f32_16x16x32_bf16 v[20:23], v[144:147], v[206:209], v[20:23]
	v_mfma_f32_16x16x32_bf16 v[16:19], v[152:155], v[206:209], v[16:19]
	v_mfma_f32_16x16x32_bf16 v[4:7], v[144:147], v[214:217], v[4:7]
	v_mfma_f32_16x16x32_bf16 v[0:3], v[152:155], v[214:217], v[0:3]
	v_mfma_f32_16x16x32_bf16 v[52:55], v[148:151], v[194:197], v[52:55]
	v_mfma_f32_16x16x32_bf16 v[48:51], v[156:159], v[194:197], v[48:51]
	v_mfma_f32_16x16x32_bf16 v[36:39], v[148:151], v[202:205], v[36:39]
	v_mfma_f32_16x16x32_bf16 v[32:35], v[156:159], v[202:205], v[32:35]
	v_mfma_f32_16x16x32_bf16 v[20:23], v[148:151], v[210:213], v[20:23]
	v_mfma_f32_16x16x32_bf16 v[16:19], v[156:159], v[210:213], v[16:19]
	v_mfma_f32_16x16x32_bf16 v[4:7], v[148:151], v[218:221], v[4:7]
	v_mfma_f32_16x16x32_bf16 v[0:3], v[156:159], v[218:221], v[0:3]
	s_setprio 0
	s_barrier
; #define PG8_STAGE(bufoff, gbase, voff) do { _Pragma("unroll") for (int _i = 0; _i < 2; ++_i) \
;         __builtin_amdgcn_global_load_lds((const unsigned*)((const char*)(gbase) + (voff)[_i]), (PG8_LAS unsigned*)(lds + (bufoff) + ldsw + _i * 8192), 16, 0, 0); } while (0)
; #define PG8_LDA(dst, b, h) do { _Pragma("unroll") for (int m = 0; m < 4; ++m) _Pragma("unroll") for (int k = 0; k < 2; ++k) dst[m][k] = *(const PG8_LAS bf16x8*)(lds + PG8_SA(b, h) + aoff + m * 2048 + k * 1024); } while (0)
; #define PG8_LDB(dst, b, h) do { _Pragma("unroll") for (int n = 0; n < 2; ++n) _Pragma("unroll") for (int k = 0; k < 2; ++k) dst[n][k] = *(const PG8_LAS bf16x8*)(lds + PG8_SB(b, h) + boff + n * 2048 + k * 1024); } while (0)
; #define PG8_MMA(ai, bj, At, Bt) do { __builtin_amdgcn_s_setprio(1); _Pragma("unroll") for (int m = 0; m < 4; ++m) _Pragma("unroll") for (int n = 0; n < 2; ++n) _Pragma("unroll") for (int k = 0; k < 2; ++k) \
;         acc[ai][bj][m][n] = __builtin_amdgcn_mfma_f32_16x16x32_bf16(Bt[n][k], At[m][k], acc[ai][bj][m][n], 0, 0, 0); __builtin_amdgcn_s_setprio(0); } while (0)
; #define PG8_WAIT_V(n) asm volatile("s_waitcnt vmcnt(" #n ")" ::: "memory")
; #define PG8_WAIT_L(n) asm volatile("s_waitcnt lgkmcnt(" #n ")" ::: "memory")
; #define PG8_BAR __builtin_amdgcn_s_barrier()
; #define PG8_SCHED __builtin_amdgcn_sched_barrier(0)
; template <class Epi, class Sched, bool ALIGN_EPI = false, bool SP2 = false>
; __device__ __forceinline__ void gemm_phase(PG8_LAS unsigned char* lds, const Gemm g, const Sched& S, const Epi& E) {
;     ...
;             PG8_LDB(B0, 1, 0); PG8_LDB(B1, 1, 1); PG8_SCHED; PG8_LDA(At, 1, 0); PG8_STAGE(PG8_SA(0, 1), a2 + hstep, voffA);
;             PG8_WAIT_V(8); PG8_WAIT_L(0); PG8_BAR; PG8_MMA(0, 0, At, B0); PG8_MMA(0, 1, At, B1); PG8_BAR; PG8_SCHED;
	s_add_i32 s52, 0, 0x18000
	s_add_i32 s53, 0, 0x1c000
	v_add_u32_e32 v140, s52, v188
	v_add_u32_e32 v156, s53, v188
	ds_read_b128 v[128:131], v140
	ds_read_b128 v[132:135], v140 offset:1024
	ds_read_b128 v[136:139], v140 offset:2048
	ds_read_b128 v[140:143], v140 offset:3072
	ds_read_b128 v[144:147], v156
	ds_read_b128 v[148:151], v156 offset:1024
	ds_read_b128 v[152:155], v156 offset:2048
	ds_read_b128 v[156:159], v156 offset:3072
	s_add_u32 s28, s28, 0x80000
	s_addc_u32 s29, s29, 0
	s_mov_b32 m0, s35
	v_lshl_add_u64 v[228:229], s[28:29], 0, v[162:163]
	ds_read_b128 v[180:183], v192 offset:32768
	ds_read_b128 v[194:197], v192 offset:33792
	ds_read_b128 v[198:201], v192 offset:34816
	ds_read_b128 v[202:205], v192 offset:35840
	ds_read_b128 v[206:209], v192 offset:36864
	ds_read_b128 v[210:213], v192 offset:37888
	ds_read_b128 v[214:217], v192 offset:38912
	ds_read_b128 v[218:221], v192 offset:39936
	global_load_lds_dwordx4 v[228:229], off
	v_lshl_add_u64 v[228:229], s[28:29], 0, v[166:167]
	s_mov_b32 m0, s36
	s_nop 0
	global_load_lds_dwordx4 v[228:229], off
	s_waitcnt vmcnt(8)
	s_waitcnt lgkmcnt(0)
	s_barrier
	s_setprio 1
	s_waitcnt lgkmcnt(0)
	v_mfma_f32_16x16x32_bf16 v[124:127], v[128:131], v[180:183], v[124:127]
	v_mfma_f32_16x16x32_bf16 v[120:123], v[136:139], v[180:183], v[120:123]
	v_mfma_f32_16x16x32_bf16 v[108:111], v[128:131], v[198:201], v[108:111]
	v_mfma_f32_16x16x32_bf16 v[104:107], v[136:139], v[198:201], v[104:107]
	v_mfma_f32_16x16x32_bf16 v[92:95], v[128:131], v[206:209], v[92:95]
	v_mfma_f32_16x16x32_bf16 v[88:91], v[136:139], v[206:209], v[88:91]
	v_mfma_f32_16x16x32_bf16 v[76:79], v[128:131], v[214:217], v[76:79]
	v_mfma_f32_16x16x32_bf16 v[72:75], v[136:139], v[214:217], v[72:75]
	v_mfma_f32_16x16x32_bf16 v[124:127], v[132:135], v[194:197], v[124:127]
	v_mfma_f32_16x16x32_bf16 v[120:123], v[140:143], v[194:197], v[120:123]
	v_mfma_f32_16x16x32_bf16 v[108:111], v[132:135], v[202:205], v[108:111]
	v_mfma_f32_16x16x32_bf16 v[104:107], v[140:143], v[202:205], v[104:107]
	v_mfma_f32_16x16x32_bf16 v[92:95], v[132:135], v[210:213], v[92:95]
	v_mfma_f32_16x16x32_bf16 v[88:91], v[140:143], v[210:213], v[88:91]
	v_mfma_f32_16x16x32_bf16 v[76:79], v[132:135], v[218:221], v[76:79]
	v_mfma_f32_16x16x32_bf16 v[72:75], v[140:143], v[218:221], v[72:75]
	s_setprio 0
	s_setprio 1
	v_mfma_f32_16x16x32_bf16 v[116:119], v[144:147], v[180:183], v[116:119]
	v_mfma_f32_16x16x32_bf16 v[112:115], v[152:155], v[180:183], v[112:115]
	v_mfma_f32_16x16x32_bf16 v[100:103], v[144:147], v[198:201], v[100:103]
	v_mfma_f32_16x16x32_bf16 v[96:99], v[152:155], v[198:201], v[96:99]
	v_mfma_f32_16x16x32_bf16 v[84:87], v[144:147], v[206:209], v[84:87]
	v_mfma_f32_16x16x32_bf16 v[80:83], v[152:155], v[206:209], v[80:83]
	v_mfma_f32_16x16x32_bf16 v[68:71], v[144:147], v[214:217], v[68:71]
	v_mfma_f32_16x16x32_bf16 v[64:67], v[152:155], v[214:217], v[64:67]
	v_mfma_f32_16x16x32_bf16 v[116:119], v[148:151], v[194:197], v[116:119]
	v_mfma_f32_16x16x32_bf16 v[112:115], v[156:159], v[194:197], v[112:115]
	v_mfma_f32_16x16x32_bf16 v[100:103], v[148:151], v[202:205], v[100:103]
	v_mfma_f32_16x16x32_bf16 v[96:99], v[156:159], v[202:205], v[96:99]
	v_mfma_f32_16x16x32_bf16 v[84:87], v[148:151], v[210:213], v[84:87]
	v_mfma_f32_16x16x32_bf16 v[80:83], v[156:159], v[210:213], v[80:83]
	v_mfma_f32_16x16x32_bf16 v[68:71], v[148:151], v[218:221], v[68:71]
	v_mfma_f32_16x16x32_bf16 v[64:67], v[156:159], v[218:221], v[64:67]
	s_setprio 0
	s_barrier
; #define PG8_STAGE(bufoff, gbase, voff) do { _Pragma("unroll") for (int _i = 0; _i < 2; ++_i) \
;         __builtin_amdgcn_global_load_lds((const unsigned*)((const char*)(gbase) + (voff)[_i]), (PG8_LAS unsigned*)(lds + (bufoff) + ldsw + _i * 8192), 16, 0, 0); } while (0)
; #define PG8_LDA(dst, b, h) do { _Pragma("unroll") for (int m = 0; m < 4; ++m) _Pragma("unroll") for (int k = 0; k < 2; ++k) dst[m][k] = *(const PG8_LAS bf16x8*)(lds + PG8_SA(b, h) + aoff + m * 2048 + k * 1024); } while (0)
; #define PG8_MMA(ai, bj, At, Bt) do { __builtin_amdgcn_s_setprio(1); _Pragma("unroll") for (int m = 0; m < 4; ++m) _Pragma("unroll") for (int n = 0; n < 2; ++n) _Pragma("unroll") for (int k = 0; k < 2; ++k) \
;         acc[ai][bj][m][n] = __builtin_amdgcn_mfma_f32_16x16x32_bf16(Bt[n][k], At[m][k], acc[ai][bj][m][n], 0, 0, 0); __builtin_amdgcn_s_setprio(0); } while (0)
; #define PG8_WAIT_V(n) asm volatile("s_waitcnt vmcnt(" #n ")" ::: "memory")
; #define PG8_WAIT_L(n) asm volatile("s_waitcnt lgkmcnt(" #n ")" ::: "memory")
; #define PG8_BAR __builtin_amdgcn_s_barrier()
; #define PG8_SCHED __builtin_amdgcn_sched_barrier(0)
; template <class Epi, class Sched, bool ALIGN_EPI = false, bool SP2 = false>
; __device__ __forceinline__ void gemm_phase(PG8_LAS unsigned char* lds, const Gemm g, const Sched& S, const Epi& E) {
;     ...
;         for (int t = 0; t < nt; t += 2) {
;     ...
;             PG8_LDA(At, 1, 1); PG8_STAGE(PG8_SB(1, 0), b3, voffB); PG8_STAGE(PG8_SB(1, 1), b3 + hstep, voffB); PG8_STAGE(PG8_SA(1, 0), a3, voffA);
;             PG8_WAIT_V(8); PG8_WAIT_L(0); PG8_BAR; PG8_MMA(1, 0, At, B0); PG8_MMA(1, 1, At, B1); PG8_BAR; PG8_SCHED;
	s_add_i32 s28, s52, s30
	v_lshl_add_u64 v[184:185], v[184:185], 0, s[16:17]
	s_mov_b32 m0, s28
	ds_read_b128 v[180:183], v192 offset:49152
	ds_read_b128 v[194:197], v192 offset:50176
	ds_read_b128 v[198:201], v192 offset:51200
	ds_read_b128 v[202:205], v192 offset:52224
	ds_read_b128 v[206:209], v192 offset:53248
	ds_read_b128 v[210:213], v192 offset:54272
	ds_read_b128 v[214:217], v192 offset:55296
	ds_read_b128 v[218:221], v192 offset:56320
	global_load_lds_dwordx4 v[184:185], off
	s_add_i32 m0, s28, 0x2000
	s_add_u32 s6, s6, 0x80080
	v_lshl_add_u64 v[184:185], v[222:223], 0, s[16:17]
	s_addc_u32 s7, s7, 0
	s_add_i32 s28, s53, s30
	global_load_lds_dwordx4 v[184:185], off
	v_lshl_add_u64 v[184:185], s[6:7], 0, v[164:165]
	s_mov_b32 m0, s28
	s_nop 0
	global_load_lds_dwordx4 v[184:185], off
	v_lshl_add_u64 v[184:185], s[6:7], 0, v[168:169]
	s_add_i32 m0, s28, 0x2000
	s_nop 0
	global_load_lds_dwordx4 v[184:185], off
	v_lshl_add_u64 v[184:185], v[224:225], 0, s[16:17]
	s_mov_b32 m0, s38
	s_nop 0
	global_load_lds_dwordx4 v[184:185], off
	v_lshl_add_u64 v[184:185], v[226:227], 0, s[16:17]
	s_mov_b32 m0, s39
	s_nop 0
	global_load_lds_dwordx4 v[184:185], off
	s_waitcnt vmcnt(8)
	s_waitcnt lgkmcnt(0)
	s_barrier
	s_setprio 1
	s_waitcnt lgkmcnt(0)
	v_mfma_f32_16x16x32_bf16 v[60:63], v[128:131], v[180:183], v[60:63]
	v_mfma_f32_16x16x32_bf16 v[56:59], v[136:139], v[180:183], v[56:59]
	v_mfma_f32_16x16x32_bf16 v[44:47], v[128:131], v[198:201], v[44:47]
	v_mfma_f32_16x16x32_bf16 v[40:43], v[136:139], v[198:201], v[40:43]
	v_mfma_f32_16x16x32_bf16 v[28:31], v[128:131], v[206:209], v[28:31]
	v_mfma_f32_16x16x32_bf16 v[24:27], v[136:139], v[206:209], v[24:27]
	v_mfma_f32_16x16x32_bf16 v[12:15], v[128:131], v[214:217], v[12:15]
	v_mfma_f32_16x16x32_bf16 v[8:11], v[136:139], v[214:217], v[8:11]
	v_mfma_f32_16x16x32_bf16 v[60:63], v[132:135], v[194:197], v[60:63]
	v_mfma_f32_16x16x32_bf16 v[56:59], v[140:143], v[194:197], v[56:59]
	v_mfma_f32_16x16x32_bf16 v[44:47], v[132:135], v[202:205], v[44:47]
	v_mfma_f32_16x16x32_bf16 v[40:43], v[140:143], v[202:205], v[40:43]
	v_mfma_f32_16x16x32_bf16 v[28:31], v[132:135], v[210:213], v[28:31]
	v_mfma_f32_16x16x32_bf16 v[24:27], v[140:143], v[210:213], v[24:27]
	v_mfma_f32_16x16x32_bf16 v[12:15], v[132:135], v[218:221], v[12:15]
	v_mfma_f32_16x16x32_bf16 v[8:11], v[140:143], v[218:221], v[8:11]
	s_setprio 0
	s_setprio 1
	v_mfma_f32_16x16x32_bf16 v[52:55], v[144:147], v[180:183], v[52:55]
	v_mfma_f32_16x16x32_bf16 v[48:51], v[152:155], v[180:183], v[48:51]
	v_mfma_f32_16x16x32_bf16 v[36:39], v[144:147], v[198:201], v[36:39]
	v_mfma_f32_16x16x32_bf16 v[32:35], v[152:155], v[198:201], v[32:35]
	v_mfma_f32_16x16x32_bf16 v[20:23], v[144:147], v[206:209], v[20:23]
	v_mfma_f32_16x16x32_bf16 v[16:19], v[152:155], v[206:209], v[16:19]
	v_mfma_f32_16x16x32_bf16 v[4:7], v[144:147], v[214:217], v[4:7]
	v_mfma_f32_16x16x32_bf16 v[0:3], v[152:155], v[214:217], v[0:3]
	v_mfma_f32_16x16x32_bf16 v[52:55], v[148:151], v[194:197], v[52:55]
	v_mfma_f32_16x16x32_bf16 v[48:51], v[156:159], v[194:197], v[48:51]
	v_mfma_f32_16x16x32_bf16 v[36:39], v[148:151], v[202:205], v[36:39]
	v_mfma_f32_16x16x32_bf16 v[32:35], v[156:159], v[202:205], v[32:35]
	v_mfma_f32_16x16x32_bf16 v[20:23], v[148:151], v[210:213], v[20:23]
	v_mfma_f32_16x16x32_bf16 v[16:19], v[156:159], v[210:213], v[16:19]
	v_mfma_f32_16x16x32_bf16 v[4:7], v[148:151], v[218:221], v[4:7]
	v_mfma_f32_16x16x32_bf16 v[0:3], v[156:159], v[218:221], v[0:3]
	s_setprio 0
	s_barrier
	s_add_i32 s51, s51, 2
	s_add_u32 s4, s4, 0x100
	s_addc_u32 s5, s5, 0
	s_add_u32 s33, s33, 0x100
	s_addc_u32 s50, s50, 0
	s_cmp_gt_u32 s51, 29

; #define PG8_BAR __builtin_amdgcn_s_barrier()
; template <class Epi, class Sched, bool ALIGN_EPI = false, bool SP2 = false>
; __device__ __forceinline__ void gemm_phase(PG8_LAS unsigned char* lds, const Gemm g, const Sched& S, const Epi& E) {
;     ...
;         if (!has_next) break;
; #pragma unroll
;         for (int a = 0; a < 2; ++a)
; #pragma unroll
;             for (int b = 0; b < 2; ++b)
; #pragma unroll
;                 for (int m = 0; m < 4; ++m)
; #pragma unroll
;                     for (int n = 0; n < 2; ++n) acc[a][b][m][n] = (f32x4){0.f, 0.f, 0.f, 0.f};
;         cur = nxt; cA = nA; cB = nB; ++ui;
;         if constexpr (ALIGN_EPI) { if (wr == 1) PG8_BAR; }
;     }
.LBB0_210:
	s_andn2_b64 vcc, exec, s[8:9]
	s_mov_b64 s[0:1], -1
	s_mov_b32 s99, 1
	s_cbranch_vccnz .LBB0_198
	s_branch .LBB0_261

;     __device__ __forceinline__ void operator()(const f32x4 (&acc)[2][2][4][2], const Unit& u, int wr, int wc, int fr, int fq) const {
;     ...
;         if (pn >= 4 && pn < 8) {
;             float lbv[2][8];
; #pragma unroll
;             for (int bj = 0; bj < 2; ++bj)
; #pragma unroll
;                 for (int e = 0; e < 8; ++e) { const int c = colt - 1024 + bj * HALF + e; lbv[bj][e] = 1.0f / (1.0f + __expf(lbl[1024 + c] - lbl[c])); }
; #pragma unroll
;             for (int ai = 0; ai < 2; ++ai)
; #pragma unroll
;                 for (int m = 0; m < 4; ++m) { float* rowp = LOGF + (size_t)(row0 + ai * HALF + m * 16) * 1024 + (colt - 1024);
; #pragma unroll
;                     for (int bj = 0; bj < 2; ++bj)
; #pragma unroll
;                         for (int n = 0; n < 2; ++n) { f32x4 z = acc[ai][bj][m][n], o;
; #pragma unroll
;                             for (int e = 0; e < 4; ++e) { const float lb = lbv[bj][4 * n + e]; const float sg = 1.0f / (1.0f + __expf(-z[e])); o[e] = __logf(lb + (1.0f - lb) * sg); }
.LBB0_260:
	v_readlane_b32 s76, v236, 7
	v_lshlrev_b64 v[184:185], 2, v[170:171]
	v_readlane_b32 s88, v236, 19
	v_readlane_b32 s89, v236, 20
	v_ashrrev_i32_e32 v183, 31, v182
	v_mul_f32_e32 v170, 0xbfb8aa3b, v124
	v_lshl_add_u64 v[148:149], s[88:89], 0, v[184:185]
	global_load_dwordx4 v[136:139], v[148:149], off offset:-4096
	global_load_dwordx4 v[140:143], v[148:149], off
	global_load_dwordx4 v[128:131], v[148:149], off offset:16
	global_load_dwordx4 v[132:135], v[148:149], off offset:-4080
	global_load_dwordx4 v[152:155], v[148:149], off offset:-3584
	global_load_dwordx4 v[156:159], v[148:149], off offset:512
	global_load_dwordx4 v[144:147], v[148:149], off offset:528
	s_nop 0
	global_load_dwordx4 v[148:151], v[148:149], off offset:-3568
	v_mul_f32_e32 v180, 0xbfb8aa3b, v125
	v_lshlrev_b64 v[124:125], 12, v[182:183]
	v_lshl_add_u64 v[124:125], s[58:59], 0, v[124:125]
	v_exp_f32_e32 v197, v180
	v_lshl_add_u64 v[180:181], v[124:125], 0, v[184:185]
	v_exp_f32_e32 v195, v170
	v_mul_f32_e32 v126, 0xbfb8aa3b, v126
	v_mul_f32_e32 v127, 0xbfb8aa3b, v127
	v_mul_f32_e32 v120, 0xbfb8aa3b, v120
	v_mul_f32_e32 v121, 0xbfb8aa3b, v121
	v_mul_f32_e32 v122, 0xbfb8aa3b, v122
	v_mul_f32_e32 v116, 0xbfb8aa3b, v116
	v_mul_f32_e32 v119, 0xbfb8aa3b, v119
	v_mul_f32_e32 v112, 0xbfb8aa3b, v112
	v_mul_f32_e32 v113, 0xbfb8aa3b, v113
	v_mul_f32_e32 v114, 0xbfb8aa3b, v114
	v_mul_f32_e32 v108, 0xbfb8aa3b, v108
	v_exp_f32_e32 v108, v108
	v_mul_f32_e32 v109, 0xbfb8aa3b, v109
	v_exp_f32_e32 v109, v109
	v_mul_f32_e32 v110, 0xbfb8aa3b, v110
	v_add_f32_e32 v108, 1.0, v108
	v_exp_f32_e32 v110, v110
	v_add_f32_e32 v109, 1.0, v109
	v_mul_f32_e32 v111, 0xbfb8aa3b, v111
	v_exp_f32_e32 v111, v111
	v_add_f32_e32 v110, 1.0, v110
	v_mul_f32_e32 v104, 0xbfb8aa3b, v104
	v_exp_f32_e32 v104, v104
	v_add_f32_e32 v111, 1.0, v111
	v_mul_f32_e32 v105, 0xbfb8aa3b, v105
	v_exp_f32_e32 v105, v105
	v_add_f32_e32 v104, 1.0, v104
	v_mul_f32_e32 v106, 0xbfb8aa3b, v106
	v_exp_f32_e32 v106, v106
	v_add_f32_e32 v105, 1.0, v105
	v_mul_f32_e32 v107, 0xbfb8aa3b, v107
	v_exp_f32_e32 v107, v107
	v_add_f32_e32 v106, 1.0, v106
	v_mul_f32_e32 v100, 0xbfb8aa3b, v100
	v_exp_f32_e32 v100, v100
	v_add_f32_e32 v107, 1.0, v107
	v_mul_f32_e32 v101, 0xbfb8aa3b, v101
	v_exp_f32_e32 v101, v101
	v_add_f32_e32 v100, 1.0, v100
	v_mul_f32_e32 v102, 0xbfb8aa3b, v102
	v_exp_f32_e32 v102, v102
	v_add_f32_e32 v101, 1.0, v101
	v_mul_f32_e32 v103, 0xbfb8aa3b, v103
	v_exp_f32_e32 v103, v103
	v_add_f32_e32 v102, 1.0, v102
	v_mul_f32_e32 v96, 0xbfb8aa3b, v96
	v_exp_f32_e32 v96, v96
	v_add_f32_e32 v103, 1.0, v103
	v_mul_f32_e32 v97, 0xbfb8aa3b, v97
	v_exp_f32_e32 v97, v97
	v_add_f32_e32 v96, 1.0, v96
	v_mul_f32_e32 v98, 0xbfb8aa3b, v98
	v_exp_f32_e32 v98, v98
	v_add_f32_e32 v97, 1.0, v97
	v_mul_f32_e32 v99, 0xbfb8aa3b, v99
	v_exp_f32_e32 v99, v99
	v_add_f32_e32 v98, 1.0, v98
	v_mul_f32_e32 v92, 0xbfb8aa3b, v92
	v_exp_f32_e32 v92, v92
	v_add_f32_e32 v99, 1.0, v99
	v_mul_f32_e32 v93, 0xbfb8aa3b, v93
	v_exp_f32_e32 v93, v93
	v_add_f32_e32 v92, 1.0, v92
	v_mul_f32_e32 v94, 0xbfb8aa3b, v94
	v_exp_f32_e32 v94, v94
	v_add_f32_e32 v93, 1.0, v93
	v_mul_f32_e32 v95, 0xbfb8aa3b, v95
	s_waitcnt vmcnt(0)
	v_sub_f32_e32 v124, v140, v136
	v_mul_f32_e32 v124, 0x3fb8aa3b, v124
	v_exp_f32_e32 v194, v124
	v_sub_f32_e32 v125, v141, v137
	v_sub_f32_e32 v129, v129, v133
	v_mul_f32_e32 v125, 0x3fb8aa3b, v125
	v_sub_f32_e32 v137, v143, v139
	v_sub_f32_e32 v128, v128, v132
	v_sub_f32_e32 v132, v156, v152
	v_sub_f32_e32 v133, v157, v153
	v_sub_f32_e32 v139, v145, v149
	v_mul_f32_e32 v129, 0x3fb8aa3b, v129
	v_exp_f32_e32 v196, v125
	v_pk_add_f32 v[124:125], v[194:195], 1.0 op_sel_hi:[1,0]
	v_sub_f32_e32 v136, v142, v138
	v_sub_f32_e32 v138, v144, v148
	v_sub_f32_e32 v140, v146, v150
	v_sub_f32_e32 v141, v147, v151
	v_mul_f32_e32 v132, 0x3fb8aa3b, v132
	v_mul_f32_e32 v133, 0x3fb8aa3b, v133
	v_mul_f32_e32 v139, 0x3fb8aa3b, v139
	v_exp_f32_e32 v148, v129
	v_div_scale_f32 v129, s[0:1], v125, v125, 1.0
	v_mul_f32_e32 v128, 0x3fb8aa3b, v128
	v_mul_f32_e32 v145, 0x3fb8aa3b, v140
	v_mul_f32_e32 v141, 0x3fb8aa3b, v141
	v_exp_f32_e32 v142, v132
	v_exp_f32_e32 v140, v133
	v_exp_f32_e32 v132, v139
	v_div_scale_f32 v133, s[0:1], v124, v124, 1.0
	v_rcp_f32_e32 v139, v129
	v_exp_f32_e32 v150, v128
	v_exp_f32_e32 v128, v141
	v_rcp_f32_e32 v141, v133
	v_sub_f32_e32 v131, v131, v135
	v_sub_f32_e32 v135, v159, v155
	v_mul_f32_e32 v131, 0x3fb8aa3b, v131
	v_fma_f32 v147, -v129, v139, 1.0
	v_mul_f32_e32 v136, 0x3fb8aa3b, v136
	v_mul_f32_e32 v135, 0x3fb8aa3b, v135
	v_exp_f32_e32 v144, v131
	v_div_scale_f32 v131, vcc, 1.0, v125, 1.0
	v_fma_f32 v149, -v133, v141, 1.0
	v_fmac_f32_e32 v139, v147, v139
	v_sub_f32_e32 v130, v130, v134
	v_sub_f32_e32 v134, v158, v154
	v_exp_f32_e32 v154, v136
	v_exp_f32_e32 v136, v135
	v_div_scale_f32 v135, s[4:5], 1.0, v124, 1.0
	v_fmac_f32_e32 v141, v149, v141
	v_mul_f32_e32 v147, v131, v139
	v_mul_f32_e32 v149, v135, v141
	v_fma_f32 v151, -v129, v147, v131
	v_fma_f32 v153, -v133, v149, v135
	v_fmac_f32_e32 v147, v151, v139
	v_fmac_f32_e32 v149, v153, v141
	v_fma_f32 v129, -v129, v147, v131
	v_fma_f32 v131, -v133, v149, v135
	v_div_fmas_f32 v129, v129, v139, v147
	s_mov_b64 vcc, s[4:5]
	v_div_fixup_f32 v125, v129, v125, 1.0
	v_div_fmas_f32 v129, v131, v141, v149
	v_div_fixup_f32 v156, v129, v124, 1.0
	v_sub_f32_e32 v157, 1.0, v156
	v_fma_f32 v124, v125, v157, v156
	v_cmp_gt_f32_e64 s[4:5], s46, v124
	v_mul_f32_e32 v137, 0x3fb8aa3b, v137
	v_pk_add_f32 v[158:159], v[196:197], 1.0 op_sel_hi:[1,0]
	v_cndmask_b32_e64 v125, 0, 32, s[4:5]
	v_ldexp_f32 v124, v124, v125
	v_mul_f32_e32 v130, 0x3fb8aa3b, v130
	v_exp_f32_e32 v152, v137
;     __device__ __forceinline__ void operator()(const f32x4 (&acc)[2][2][4][2], const Unit& u, int wr, int wc, int fr, int fq) const {
;     ...
;                         for (int n = 0; n < 2; ++n) { f32x4 z = acc[ai][bj][m][n], o;
; #pragma unroll
;                             for (int e = 0; e < 4; ++e) { const float lb = lbv[bj][4 * n + e]; const float sg = 1.0f / (1.0f + __expf(-z[e])); o[e] = __logf(lb + (1.0f - lb) * sg); }
;                             *(f32x4*)(rowp + bj * HALF + 4 * n) = o; } }
	v_div_scale_f32 v137, s[0:1], v159, v159, 1.0
	v_log_f32_e32 v124, v124
	v_exp_f32_e32 v146, v130
	v_exp_f32_e32 v130, v145
	v_rcp_f32_e32 v145, v137
	v_mul_f32_e32 v129, 0x3f317217, v124
	v_mul_f32_e32 v134, 0x3fb8aa3b, v134
	v_mul_f32_e32 v143, 0x3fb8aa3b, v138
	v_fma_f32 v125, -v137, v145, 1.0
	v_fma_f32 v129, v124, s47, -v129
	v_exp_f32_e32 v138, v134
	v_exp_f32_e32 v134, v143
	v_div_scale_f32 v143, s[0:1], 1.0, v159, 1.0
	v_fmac_f32_e32 v145, v125, v145
	v_fmac_f32_e32 v129, 0x3377d1cf, v124
	v_div_scale_f32 v131, s[2:3], v158, v158, 1.0
	v_mul_f32_e32 v125, v143, v145
	v_fmac_f32_e32 v129, 0x3f317217, v124
	v_cmp_lt_f32_e64 vcc, |v124|, s49
	v_rcp_f32_e32 v133, v131
	v_exp_f32_e32 v155, v126
	v_cndmask_b32_e32 v124, v124, v129, vcc
	v_fma_f32 v129, -v137, v125, v143
	v_fmac_f32_e32 v125, v129, v145
	v_fma_f32 v129, -v137, v125, v143
	s_mov_b64 vcc, s[0:1]
	v_div_fmas_f32 v125, v129, v145, v125
	v_fma_f32 v129, -v131, v133, 1.0
	v_fmac_f32_e32 v133, v129, v133
	v_div_scale_f32 v129, vcc, 1.0, v158, 1.0
	v_mul_f32_e32 v135, v129, v133
	v_fma_f32 v137, -v131, v135, v129
	v_fmac_f32_e32 v135, v137, v133
	v_fma_f32 v129, -v131, v135, v129
	v_div_fmas_f32 v129, v129, v133, v135
	v_div_fixup_f32 v158, v129, v158, 1.0
	v_div_fixup_f32 v125, v125, v159, 1.0
	v_sub_f32_e32 v159, 1.0, v158
	v_fma_f32 v125, v125, v159, v158
	v_cmp_gt_f32_e64 s[0:1], s46, v125
	v_pk_add_f32 v[154:155], v[154:155], 1.0 op_sel_hi:[1,0]
	v_cndmask_b32_e64 v126, 0, v193, s[4:5]
	v_cndmask_b32_e64 v129, 0, 32, s[0:1]
	v_ldexp_f32 v125, v125, v129
	v_div_scale_f32 v129, s[2:3], v155, v155, 1.0
	v_rcp_f32_e32 v131, v129
	v_log_f32_e32 v125, v125
	v_sub_f32_e32 v124, v124, v126
	v_exp_f32_e32 v153, v127
	v_fma_f32 v133, -v129, v131, 1.0
	v_fmac_f32_e32 v131, v133, v131
	v_div_scale_f32 v133, vcc, 1.0, v155, 1.0
	v_mul_f32_e32 v135, v133, v131
	v_fma_f32 v137, -v129, v135, v133
	v_fmac_f32_e32 v135, v137, v131
	v_fma_f32 v129, -v129, v135, v133
	v_div_scale_f32 v133, s[2:3], v154, v154, 1.0
	v_rcp_f32_e32 v137, v133
	v_div_fmas_f32 v129, v129, v131, v135
	v_div_fixup_f32 v129, v129, v155, 1.0
	v_mul_f32_e32 v126, 0x3f317217, v125
	v_fma_f32 v131, -v133, v137, 1.0
	v_fmac_f32_e32 v137, v131, v137
	v_div_scale_f32 v131, vcc, 1.0, v154, 1.0
	v_mul_f32_e32 v135, v131, v137
	v_fma_f32 v139, -v133, v135, v131
	v_fmac_f32_e32 v135, v139, v137
	v_fma_f32 v131, -v133, v135, v131
	v_div_fmas_f32 v131, v131, v137, v135
	v_div_fixup_f32 v154, v131, v154, 1.0
	v_sub_f32_e32 v155, 1.0, v154
	v_fma_f32 v129, v129, v155, v154
	v_cmp_gt_f32_e32 vcc, s46, v129
	v_fma_f32 v126, v125, s47, -v126
	v_fmac_f32_e32 v126, 0x3377d1cf, v125
	v_cndmask_b32_e64 v131, 0, 32, vcc
	v_ldexp_f32 v129, v129, v131
	v_log_f32_e32 v129, v129
	v_fmac_f32_e32 v126, 0x3f317217, v125
	v_cmp_lt_f32_e64 s[4:5], |v125|, s49
	v_exp_f32_e32 v151, v120
	v_exp_f32_e32 v149, v121
	v_cndmask_b32_e64 v125, v125, v126, s[4:5]
	v_cndmask_b32_e64 v126, 0, v193, s[0:1]
	v_sub_f32_e32 v125, v125, v126
	v_mul_f32_e32 v126, 0x3f317217, v129
	v_fma_f32 v131, v129, s47, -v126
	v_pk_add_f32 v[126:127], v[152:153], 1.0 op_sel_hi:[1,0]
	v_fmac_f32_e32 v131, 0x3377d1cf, v129
	v_div_scale_f32 v133, s[0:1], v127, v127, 1.0
	v_rcp_f32_e32 v135, v133
	v_fmac_f32_e32 v131, 0x3f317217, v129
	v_cmp_lt_f32_e64 s[0:1], |v129|, s49
	v_pk_add_f32 v[150:151], v[150:151], 1.0 op_sel_hi:[1,0]
	v_fma_f32 v137, -v133, v135, 1.0
	v_cndmask_b32_e64 v129, v129, v131, s[0:1]
	v_cndmask_b32_e32 v131, 0, v193, vcc
	v_fmac_f32_e32 v135, v137, v135
	v_div_scale_f32 v137, vcc, 1.0, v127, 1.0
	v_mul_f32_e32 v139, v137, v135
	v_fma_f32 v141, -v133, v139, v137
	v_fmac_f32_e32 v139, v141, v135
	v_fma_f32 v133, -v133, v139, v137
	v_div_scale_f32 v137, s[0:1], v126, v126, 1.0
	v_rcp_f32_e32 v141, v137
	v_div_fmas_f32 v133, v133, v135, v139
	v_div_fixup_f32 v127, v133, v127, 1.0
	v_exp_f32_e32 v147, v122
	v_fma_f32 v133, -v137, v141, 1.0
	v_fmac_f32_e32 v141, v133, v141
	v_div_scale_f32 v133, vcc, 1.0, v126, 1.0
	v_mul_f32_e32 v135, v133, v141
	v_fma_f32 v139, -v137, v135, v133
	v_fmac_f32_e32 v135, v139, v141
	v_fma_f32 v133, -v137, v135, v133
	v_div_fmas_f32 v133, v133, v141, v135
	v_div_fixup_f32 v152, v133, v126, 1.0
	v_sub_f32_e32 v153, 1.0, v152
	v_fma_f32 v126, v127, v153, v152
	v_cmp_gt_f32_e64 s[0:1], s46, v126
	v_exp_f32_e32 v143, v116
	v_add_f32_e32 v94, 1.0, v94
	v_cndmask_b32_e64 v127, 0, 32, s[0:1]
	v_ldexp_f32 v126, v126, v127
	v_log_f32_e32 v127, v126
	v_sub_f32_e32 v126, v129, v131
	v_div_scale_f32 v129, s[2:3], v151, v151, 1.0
	v_mul_f32_e32 v120, 0x3f317217, v127
	v_rcp_f32_e32 v131, v129
	v_fma_f32 v120, v127, s47, -v120
	v_fmac_f32_e32 v120, 0x3377d1cf, v127
	v_fmac_f32_e32 v120, 0x3f317217, v127
	v_cmp_lt_f32_e64 vcc, |v127|, s49
	v_pk_add_f32 v[142:143], v[142:143], 1.0 op_sel_hi:[1,0]
	v_exp_f32_e32 v95, v95
	v_cndmask_b32_e32 v120, v127, v120, vcc
	v_fma_f32 v127, -v129, v131, 1.0
	v_fmac_f32_e32 v131, v127, v131
	v_div_scale_f32 v127, vcc, 1.0, v151, 1.0
	v_mul_f32_e32 v133, v127, v131
	v_fma_f32 v135, -v129, v133, v127
	v_fmac_f32_e32 v133, v135, v131
	v_fma_f32 v127, -v129, v133, v127
	v_div_scale_f32 v129, s[2:3], v150, v150, 1.0
	v_rcp_f32_e32 v135, v129
	v_div_fmas_f32 v127, v127, v131, v133
	v_div_fixup_f32 v127, v127, v151, 1.0
	v_add_f32_e32 v95, 1.0, v95
	v_fma_f32 v131, -v129, v135, 1.0
	v_fmac_f32_e32 v135, v131, v135
	v_div_scale_f32 v131, vcc, 1.0, v150, 1.0
	v_mul_f32_e32 v133, v131, v135
	v_fma_f32 v137, -v129, v133, v131
	v_fmac_f32_e32 v133, v137, v135
	v_fma_f32 v129, -v129, v133, v131
	v_div_fmas_f32 v129, v129, v135, v133
	v_div_fixup_f32 v150, v129, v150, 1.0
	v_sub_f32_e32 v151, 1.0, v150
	v_fma_f32 v127, v127, v151, v150
;     __device__ __forceinline__ void operator()(const f32x4 (&acc)[2][2][4][2], const Unit& u, int wr, int wc, int fr, int fq) const {
;     ...
;                         for (int n = 0; n < 2; ++n) { f32x4 z = acc[ai][bj][m][n], o;
; #pragma unroll
;                             for (int e = 0; e < 4; ++e) { const float lb = lbv[bj][4 * n + e]; const float sg = 1.0f / (1.0f + __expf(-z[e])); o[e] = __logf(lb + (1.0f - lb) * sg); }
;                             *(f32x4*)(rowp + bj * HALF + 4 * n) = o; } }
	v_cmp_gt_f32_e32 vcc, s46, v127
	v_mul_f32_e32 v88, 0xbfb8aa3b, v88
	v_exp_f32_e32 v88, v88
	v_cndmask_b32_e64 v129, 0, 32, vcc
	v_ldexp_f32 v127, v127, v129
	v_log_f32_e32 v129, v127
	v_cndmask_b32_e64 v127, 0, v193, s[0:1]
	v_sub_f32_e32 v127, v120, v127
	global_store_dwordx4 v[180:181], v[124:127], off offset:-4096
	v_mul_f32_e32 v120, 0x3f317217, v129
	v_add_f32_e32 v88, 1.0, v88
	v_fma_f32 v124, v129, s47, -v120
	v_pk_add_f32 v[120:121], v[148:149], 1.0 op_sel_hi:[1,0]
	v_fmac_f32_e32 v124, 0x3377d1cf, v129
	v_div_scale_f32 v125, s[0:1], v121, v121, 1.0
	v_rcp_f32_e32 v126, v125
	v_fmac_f32_e32 v124, 0x3f317217, v129
	v_cmp_lt_f32_e64 s[0:1], |v129|, s49
	v_mul_f32_e32 v89, 0xbfb8aa3b, v89
	v_exp_f32_e32 v89, v89
	v_cndmask_b32_e64 v127, v129, v124, s[0:1]
	v_fma_f32 v124, -v125, v126, 1.0
	v_cndmask_b32_e32 v129, 0, v193, vcc
	v_fmac_f32_e32 v126, v124, v126
	v_div_scale_f32 v124, vcc, 1.0, v121, 1.0
	v_mul_f32_e32 v131, v124, v126
	v_fma_f32 v133, -v125, v131, v124
	v_fmac_f32_e32 v131, v133, v126
	v_fma_f32 v124, -v125, v131, v124
	v_div_scale_f32 v125, s[0:1], v120, v120, 1.0
	v_rcp_f32_e32 v133, v125
	v_div_fmas_f32 v124, v124, v126, v131
	v_div_fixup_f32 v121, v124, v121, 1.0
	v_add_f32_e32 v89, 1.0, v89
	v_fma_f32 v124, -v125, v133, 1.0
	v_fmac_f32_e32 v133, v124, v133
	v_div_scale_f32 v124, vcc, 1.0, v120, 1.0
	v_mul_f32_e32 v126, v124, v133
	v_fma_f32 v131, -v125, v126, v124
	v_fmac_f32_e32 v126, v131, v133
	v_fma_f32 v124, -v125, v126, v124
	v_div_fmas_f32 v124, v124, v133, v126
	v_div_fixup_f32 v124, v124, v120, 1.0
	v_sub_f32_e32 v125, 1.0, v124
	v_fma_f32 v120, v121, v125, v124
	v_cmp_gt_f32_e64 s[0:1], s46, v120
	v_mul_f32_e32 v90, 0xbfb8aa3b, v90
	v_exp_f32_e32 v90, v90
	v_cndmask_b32_e64 v121, 0, 32, s[0:1]
	v_ldexp_f32 v120, v120, v121
	v_log_f32_e32 v121, v120
	v_sub_f32_e32 v120, v127, v129
	v_pk_add_f32 v[126:127], v[146:147], 1.0 op_sel_hi:[1,0]
	v_add_f32_e32 v90, 1.0, v90
	v_div_scale_f32 v129, s[2:3], v127, v127, 1.0
	v_mul_f32_e32 v122, 0x3f317217, v121
	v_rcp_f32_e32 v131, v129
	v_fma_f32 v122, v121, s47, -v122
	v_fmac_f32_e32 v122, 0x3377d1cf, v121
	v_fmac_f32_e32 v122, 0x3f317217, v121
	v_cmp_lt_f32_e64 vcc, |v121|, s49
	v_mul_f32_e32 v91, 0xbfb8aa3b, v91
	v_exp_f32_e32 v91, v91
	v_cndmask_b32_e32 v121, v121, v122, vcc
	v_fma_f32 v122, -v129, v131, 1.0
	v_fmac_f32_e32 v131, v122, v131
	v_div_scale_f32 v122, vcc, 1.0, v127, 1.0
	v_mul_f32_e32 v133, v122, v131
	v_fma_f32 v135, -v129, v133, v122
	v_fmac_f32_e32 v133, v135, v131
	v_fma_f32 v122, -v129, v133, v122
	v_div_scale_f32 v129, s[2:3], v126, v126, 1.0
	v_rcp_f32_e32 v135, v129
	v_div_fmas_f32 v122, v122, v131, v133
	v_div_fixup_f32 v122, v122, v127, 1.0
	v_add_f32_e32 v91, 1.0, v91
	v_fma_f32 v127, -v129, v135, 1.0
	v_fmac_f32_e32 v135, v127, v135
	v_div_scale_f32 v127, vcc, 1.0, v126, 1.0
	v_mul_f32_e32 v131, v127, v135
	v_fma_f32 v133, -v129, v131, v127
	v_fmac_f32_e32 v131, v133, v135
	v_fma_f32 v127, -v129, v131, v127
	v_div_fmas_f32 v127, v127, v135, v131
	v_div_fixup_f32 v126, v127, v126, 1.0
	v_sub_f32_e32 v127, 1.0, v126
	v_fma_f32 v122, v122, v127, v126
	v_cmp_gt_f32_e64 s[4:5], s46, v122
	v_mul_f32_e32 v84, 0xbfb8aa3b, v84
	v_exp_f32_e32 v84, v84
	v_cndmask_b32_e64 v129, 0, 32, s[4:5]
	v_ldexp_f32 v122, v122, v129
	v_log_f32_e32 v129, v122
	v_mul_f32_e32 v122, 0xbfb8aa3b, v123
	v_exp_f32_e32 v145, v122
	v_cndmask_b32_e64 v122, 0, v193, s[0:1]
	v_sub_f32_e32 v121, v121, v122
	v_mul_f32_e32 v131, 0x3f317217, v129
	v_pk_add_f32 v[122:123], v[144:145], 1.0 op_sel_hi:[1,0]
	v_fma_f32 v131, v129, s47, -v131
	v_div_scale_f32 v133, s[0:1], v123, v123, 1.0
	v_rcp_f32_e32 v135, v133
	v_fmac_f32_e32 v131, 0x3377d1cf, v129
	v_fmac_f32_e32 v131, 0x3f317217, v129
	v_add_f32_e32 v84, 1.0, v84
	v_fma_f32 v137, -v133, v135, 1.0
	v_fmac_f32_e32 v135, v137, v135
	v_div_scale_f32 v137, vcc, 1.0, v123, 1.0
	v_mul_f32_e32 v139, v137, v135
	v_fma_f32 v141, -v133, v139, v137
	v_fmac_f32_e32 v139, v141, v135
	v_fma_f32 v133, -v133, v139, v137
	v_div_scale_f32 v137, s[0:1], v122, v122, 1.0
	v_rcp_f32_e32 v141, v137
	v_div_fmas_f32 v133, v133, v135, v139
	v_div_fixup_f32 v123, v133, v123, 1.0
	v_cmp_lt_f32_e64 s[0:1], |v129|, s49
	v_fma_f32 v133, -v137, v141, 1.0
	v_fmac_f32_e32 v141, v133, v141
	v_div_scale_f32 v133, vcc, 1.0, v122, 1.0
	v_mul_f32_e32 v135, v133, v141
	v_fma_f32 v139, -v137, v135, v133
	v_fmac_f32_e32 v135, v139, v141
	v_fma_f32 v133, -v137, v135, v133
	v_div_fmas_f32 v133, v133, v141, v135
	v_div_fixup_f32 v144, v133, v122, 1.0
	v_sub_f32_e32 v145, 1.0, v144
	v_fma_f32 v122, v123, v145, v144
	v_cmp_gt_f32_e32 vcc, s46, v122
	v_mul_f32_e32 v85, 0xbfb8aa3b, v85
	v_exp_f32_e32 v85, v85
	v_cndmask_b32_e64 v123, 0, 32, vcc
	v_ldexp_f32 v122, v122, v123
	v_log_f32_e32 v123, v122
	v_cndmask_b32_e64 v122, v129, v131, s[0:1]
	v_cndmask_b32_e64 v129, 0, v193, s[4:5]
	v_sub_f32_e32 v122, v122, v129
	v_mul_f32_e32 v129, 0x3f317217, v123
	v_fma_f32 v116, v123, s47, -v129
	v_div_scale_f32 v129, s[0:1], v143, v143, 1.0
	v_rcp_f32_e32 v131, v129
	v_fmac_f32_e32 v116, 0x3377d1cf, v123
	v_fmac_f32_e32 v116, 0x3f317217, v123
	v_cmp_lt_f32_e64 s[0:1], |v123|, s49
	v_add_f32_e32 v85, 1.0, v85
	v_mul_f32_e32 v86, 0xbfb8aa3b, v86
	v_cndmask_b32_e64 v116, v123, v116, s[0:1]
	v_cndmask_b32_e32 v123, 0, v193, vcc
	v_sub_f32_e32 v123, v116, v123
	v_fma_f32 v116, -v129, v131, 1.0
	v_fmac_f32_e32 v131, v116, v131
	v_div_scale_f32 v116, vcc, 1.0, v143, 1.0
	v_mul_f32_e32 v133, v116, v131
	v_fma_f32 v135, -v129, v133, v116
	v_fmac_f32_e32 v133, v135, v131
	v_fma_f32 v116, -v129, v133, v116
	v_div_scale_f32 v129, s[0:1], v142, v142, 1.0
	v_rcp_f32_e32 v135, v129
;     __device__ __forceinline__ void operator()(const f32x4 (&acc)[2][2][4][2], const Unit& u, int wr, int wc, int fr, int fq) const {
;     ...
;                         for (int n = 0; n < 2; ++n) { f32x4 z = acc[ai][bj][m][n], o;
; #pragma unroll
;                             for (int e = 0; e < 4; ++e) { const float lb = lbv[bj][4 * n + e]; const float sg = 1.0f / (1.0f + __expf(-z[e])); o[e] = __logf(lb + (1.0f - lb) * sg); }
;                             *(f32x4*)(rowp + bj * HALF + 4 * n) = o; } }
	v_div_fmas_f32 v116, v116, v131, v133
	v_div_fixup_f32 v116, v116, v143, 1.0
	global_store_dwordx4 v[180:181], v[120:123], off offset:-4080
	v_fma_f32 v131, -v129, v135, 1.0
	v_fmac_f32_e32 v135, v131, v135
	v_div_scale_f32 v131, vcc, 1.0, v142, 1.0
	v_mul_f32_e32 v133, v131, v135
	v_fma_f32 v137, -v129, v133, v131
	v_fmac_f32_e32 v133, v137, v135
	v_fma_f32 v129, -v129, v133, v131
	v_div_fmas_f32 v129, v129, v135, v133
	v_div_fixup_f32 v142, v129, v142, 1.0
	v_sub_f32_e32 v143, 1.0, v142
	v_fma_f32 v116, v116, v143, v142
	v_cmp_gt_f32_e64 s[0:1], s46, v116
	v_exp_f32_e32 v86, v86
	v_mul_f32_e32 v87, 0xbfb8aa3b, v87
	v_cndmask_b32_e64 v129, 0, 32, s[0:1]
	v_ldexp_f32 v116, v116, v129
	v_log_f32_e32 v129, v116
	v_mul_f32_e32 v116, 0xbfb8aa3b, v117
	v_exp_f32_e32 v141, v116
	v_add_f32_e32 v86, 1.0, v86
	v_mul_f32_e32 v116, 0x3f317217, v129
	v_fma_f32 v120, v129, s47, -v116
	v_pk_add_f32 v[116:117], v[140:141], 1.0 op_sel_hi:[1,0]
	v_fmac_f32_e32 v120, 0x3377d1cf, v129
	v_div_scale_f32 v121, s[2:3], v117, v117, 1.0
	v_rcp_f32_e32 v122, v121
	v_fmac_f32_e32 v120, 0x3f317217, v129
	v_cmp_lt_f32_e64 vcc, |v129|, s49
	v_exp_f32_e32 v87, v87
	v_mul_f32_e32 v80, 0xbfb8aa3b, v80
	v_cndmask_b32_e32 v123, v129, v120, vcc
	v_fma_f32 v120, -v121, v122, 1.0
	v_fmac_f32_e32 v122, v120, v122
	v_div_scale_f32 v120, vcc, 1.0, v117, 1.0
	v_mul_f32_e32 v129, v120, v122
	v_fma_f32 v131, -v121, v129, v120
	v_fmac_f32_e32 v129, v131, v122
	v_fma_f32 v120, -v121, v129, v120
	v_div_scale_f32 v121, s[2:3], v116, v116, 1.0
	v_rcp_f32_e32 v131, v121
	v_div_fmas_f32 v120, v120, v122, v129
	v_div_fixup_f32 v117, v120, v117, 1.0
	v_add_f32_e32 v87, 1.0, v87
	v_fma_f32 v120, -v121, v131, 1.0
	v_fmac_f32_e32 v131, v120, v131
	v_div_scale_f32 v120, vcc, 1.0, v116, 1.0
	v_mul_f32_e32 v122, v120, v131
	v_fma_f32 v129, -v121, v122, v120
	v_fmac_f32_e32 v122, v129, v131
	v_fma_f32 v120, -v121, v122, v120
	v_div_fmas_f32 v120, v120, v131, v122
	v_div_fixup_f32 v120, v120, v116, 1.0
	v_sub_f32_e32 v121, 1.0, v120
	v_fma_f32 v116, v117, v121, v120
	v_cmp_gt_f32_e64 s[4:5], s46, v116
	v_exp_f32_e32 v80, v80
	v_mul_f32_e32 v81, 0xbfb8aa3b, v81
	v_cndmask_b32_e64 v117, 0, 32, s[4:5]
	v_ldexp_f32 v116, v116, v117
	v_log_f32_e32 v117, v116
	v_mul_f32_e32 v116, 0xbfb8aa3b, v118
	v_exp_f32_e32 v139, v116
	v_cndmask_b32_e64 v116, 0, v193, s[0:1]
	v_sub_f32_e32 v116, v123, v116
	v_mul_f32_e32 v118, 0x3f317217, v117
	v_pk_add_f32 v[122:123], v[138:139], 1.0 op_sel_hi:[1,0]
	v_fma_f32 v118, v117, s47, -v118
	v_div_scale_f32 v129, s[0:1], v123, v123, 1.0
	v_rcp_f32_e32 v131, v129
	v_fmac_f32_e32 v118, 0x3377d1cf, v117
	v_fmac_f32_e32 v118, 0x3f317217, v117
	v_add_f32_e32 v80, 1.0, v80
	v_fma_f32 v133, -v129, v131, 1.0
	v_fmac_f32_e32 v131, v133, v131
	v_div_scale_f32 v133, vcc, 1.0, v123, 1.0
	v_mul_f32_e32 v135, v133, v131
	v_fma_f32 v137, -v129, v135, v133
	v_fmac_f32_e32 v135, v137, v131
	v_fma_f32 v129, -v129, v135, v133
	v_div_scale_f32 v133, s[0:1], v122, v122, 1.0
	v_rcp_f32_e32 v137, v133
	v_div_fmas_f32 v129, v129, v131, v135
	v_div_fixup_f32 v129, v129, v123, 1.0
	v_cmp_lt_f32_e64 s[0:1], |v117|, s49
	v_fma_f32 v123, -v133, v137, 1.0
	v_fmac_f32_e32 v137, v123, v137
	v_div_scale_f32 v123, vcc, 1.0, v122, 1.0
	v_mul_f32_e32 v131, v123, v137
	v_fma_f32 v135, -v133, v131, v123
	v_fmac_f32_e32 v131, v135, v137
	v_fma_f32 v123, -v133, v131, v123
	v_div_fmas_f32 v123, v123, v137, v131
	v_div_fixup_f32 v122, v123, v122, 1.0
	v_sub_f32_e32 v123, 1.0, v122
	v_fma_f32 v129, v129, v123, v122
	v_cmp_gt_f32_e32 vcc, s46, v129
	v_exp_f32_e32 v137, v119
	v_cndmask_b32_e64 v117, v117, v118, s[0:1]
	v_cndmask_b32_e64 v131, 0, 32, vcc
	v_ldexp_f32 v129, v129, v131
	v_log_f32_e32 v129, v129
	v_cndmask_b32_e64 v118, 0, v193, s[4:5]
	v_sub_f32_e32 v117, v117, v118
	v_exp_f32_e32 v81, v81
	v_mul_f32_e32 v118, 0x3f317217, v129
	v_fma_f32 v131, v129, s47, -v118
	v_pk_add_f32 v[118:119], v[136:137], 1.0 op_sel_hi:[1,0]
	v_fmac_f32_e32 v131, 0x3377d1cf, v129
	v_div_scale_f32 v133, s[0:1], v119, v119, 1.0
	v_rcp_f32_e32 v135, v133
	v_fmac_f32_e32 v131, 0x3f317217, v129
	v_cmp_lt_f32_e64 s[0:1], |v129|, s49
	v_add_f32_e32 v81, 1.0, v81
	v_fma_f32 v136, -v133, v135, 1.0
	v_cndmask_b32_e64 v129, v129, v131, s[0:1]
	v_cndmask_b32_e32 v131, 0, v193, vcc
	v_fmac_f32_e32 v135, v136, v135
	v_div_scale_f32 v136, vcc, 1.0, v119, 1.0
	v_mul_f32_e32 v137, v136, v135
	v_fma_f32 v138, -v133, v137, v136
	v_fmac_f32_e32 v137, v138, v135
	v_fma_f32 v133, -v133, v137, v136
	v_div_scale_f32 v136, s[0:1], v118, v118, 1.0
	v_rcp_f32_e32 v138, v136
	v_div_fmas_f32 v133, v133, v135, v137
	v_div_fixup_f32 v119, v133, v119, 1.0
	v_mul_f32_e32 v82, 0xbfb8aa3b, v82
	v_fma_f32 v133, -v136, v138, 1.0
	v_fmac_f32_e32 v138, v133, v138
	v_div_scale_f32 v133, vcc, 1.0, v118, 1.0
	v_mul_f32_e32 v135, v133, v138
	v_fma_f32 v137, -v136, v135, v133
	v_fmac_f32_e32 v135, v137, v138
	v_fma_f32 v133, -v136, v135, v133
	v_div_fmas_f32 v133, v133, v138, v135
	v_div_fixup_f32 v136, v133, v118, 1.0
	v_sub_f32_e32 v137, 1.0, v136
	v_fma_f32 v118, v119, v137, v136
	v_cmp_gt_f32_e64 s[0:1], s46, v118
	v_exp_f32_e32 v135, v112
	v_exp_f32_e32 v82, v82
	v_cndmask_b32_e64 v119, 0, 32, s[0:1]
	v_ldexp_f32 v118, v118, v119
	v_log_f32_e32 v119, v118
	v_pk_add_f32 v[134:135], v[134:135], 1.0 op_sel_hi:[1,0]
	v_sub_f32_e32 v118, v129, v131
	v_div_scale_f32 v129, s[2:3], v135, v135, 1.0
	v_mul_f32_e32 v112, 0x3f317217, v119
	v_rcp_f32_e32 v131, v129
	v_fma_f32 v112, v119, s47, -v112
	v_fmac_f32_e32 v112, 0x3377d1cf, v119
	v_fmac_f32_e32 v112, 0x3f317217, v119
	v_cmp_lt_f32_e64 vcc, |v119|, s49
	v_add_f32_e32 v82, 1.0, v82
	v_mul_f32_e32 v83, 0xbfb8aa3b, v83
;     __device__ __forceinline__ void operator()(const f32x4 (&acc)[2][2][4][2], const Unit& u, int wr, int wc, int fr, int fq) const {
;     ...
;                         for (int n = 0; n < 2; ++n) { f32x4 z = acc[ai][bj][m][n], o;
; #pragma unroll
;                             for (int e = 0; e < 4; ++e) { const float lb = lbv[bj][4 * n + e]; const float sg = 1.0f / (1.0f + __expf(-z[e])); o[e] = __logf(lb + (1.0f - lb) * sg); }
;                             *(f32x4*)(rowp + bj * HALF + 4 * n) = o; } }
	v_cndmask_b32_e32 v112, v119, v112, vcc
	v_fma_f32 v119, -v129, v131, 1.0
	v_fmac_f32_e32 v131, v119, v131
	v_div_scale_f32 v119, vcc, 1.0, v135, 1.0
	v_mul_f32_e32 v133, v119, v131
	v_fma_f32 v138, -v129, v133, v119
	v_fmac_f32_e32 v133, v138, v131
	v_fma_f32 v119, -v129, v133, v119
	v_div_scale_f32 v129, s[2:3], v134, v134, 1.0
	v_rcp_f32_e32 v138, v129
	v_div_fmas_f32 v119, v119, v131, v133
	v_div_fixup_f32 v119, v119, v135, 1.0
	v_exp_f32_e32 v83, v83
	v_fma_f32 v131, -v129, v138, 1.0
	v_fmac_f32_e32 v138, v131, v138
	v_div_scale_f32 v131, vcc, 1.0, v134, 1.0
	v_mul_f32_e32 v133, v131, v138
	v_fma_f32 v135, -v129, v133, v131
	v_fmac_f32_e32 v133, v135, v138
	v_fma_f32 v129, -v129, v133, v131
	v_div_fmas_f32 v129, v129, v138, v133
	v_div_fixup_f32 v134, v129, v134, 1.0
	v_sub_f32_e32 v135, 1.0, v134
	v_fma_f32 v119, v119, v135, v134
	v_cmp_gt_f32_e32 vcc, s46, v119
	v_exp_f32_e32 v133, v113
	v_add_f32_e32 v83, 1.0, v83
	v_cndmask_b32_e64 v129, 0, 32, vcc
	v_ldexp_f32 v119, v119, v129
	v_log_f32_e32 v129, v119
	v_cndmask_b32_e64 v119, 0, v193, s[0:1]
	v_sub_f32_e32 v119, v112, v119
	global_store_dwordx4 v[180:181], v[116:119], off offset:-3584
	v_mul_f32_e32 v112, 0x3f317217, v129
	v_mul_f32_e32 v76, 0xbfb8aa3b, v76
	v_fma_f32 v116, v129, s47, -v112
	v_pk_add_f32 v[112:113], v[132:133], 1.0 op_sel_hi:[1,0]
	v_fmac_f32_e32 v116, 0x3377d1cf, v129
	v_div_scale_f32 v117, s[0:1], v113, v113, 1.0
	v_rcp_f32_e32 v118, v117
	v_fmac_f32_e32 v116, 0x3f317217, v129
	v_cmp_lt_f32_e64 s[0:1], |v129|, s49
	v_exp_f32_e32 v76, v76
	v_mul_f32_e32 v77, 0xbfb8aa3b, v77
	v_cndmask_b32_e64 v119, v129, v116, s[0:1]
	v_fma_f32 v116, -v117, v118, 1.0
	v_cndmask_b32_e32 v129, 0, v193, vcc
	v_fmac_f32_e32 v118, v116, v118
	v_div_scale_f32 v116, vcc, 1.0, v113, 1.0
	v_mul_f32_e32 v131, v116, v118
	v_fma_f32 v132, -v117, v131, v116
	v_fmac_f32_e32 v131, v132, v118
	v_fma_f32 v116, -v117, v131, v116
	v_div_scale_f32 v117, s[0:1], v112, v112, 1.0
	v_rcp_f32_e32 v132, v117
	v_div_fmas_f32 v116, v116, v118, v131
	v_div_fixup_f32 v113, v116, v113, 1.0
	v_add_f32_e32 v76, 1.0, v76
	v_fma_f32 v116, -v117, v132, 1.0
	v_fmac_f32_e32 v132, v116, v132
	v_div_scale_f32 v116, vcc, 1.0, v112, 1.0
	v_mul_f32_e32 v118, v116, v132
	v_fma_f32 v131, -v117, v118, v116
	v_fmac_f32_e32 v118, v131, v132
	v_fma_f32 v116, -v117, v118, v116
	v_div_fmas_f32 v116, v116, v132, v118
	v_div_fixup_f32 v116, v116, v112, 1.0
	v_sub_f32_e32 v117, 1.0, v116
	v_fma_f32 v112, v113, v117, v116
	v_cmp_gt_f32_e64 s[0:1], s46, v112
	v_exp_f32_e32 v131, v114
	v_exp_f32_e32 v77, v77
	v_cndmask_b32_e64 v113, 0, 32, s[0:1]
	v_ldexp_f32 v112, v112, v113
	v_log_f32_e32 v113, v112
	v_sub_f32_e32 v112, v119, v129
	v_pk_add_f32 v[118:119], v[130:131], 1.0 op_sel_hi:[1,0]
	v_add_f32_e32 v77, 1.0, v77
	v_div_scale_f32 v129, s[2:3], v119, v119, 1.0
	v_mul_f32_e32 v114, 0x3f317217, v113
	v_rcp_f32_e32 v130, v129
	v_fma_f32 v114, v113, s47, -v114
	v_fmac_f32_e32 v114, 0x3377d1cf, v113
	v_fmac_f32_e32 v114, 0x3f317217, v113
	v_cmp_lt_f32_e64 vcc, |v113|, s49
	v_mul_f32_e32 v78, 0xbfb8aa3b, v78
	v_exp_f32_e32 v78, v78
	v_cndmask_b32_e32 v113, v113, v114, vcc
	v_fma_f32 v114, -v129, v130, 1.0
	v_fmac_f32_e32 v130, v114, v130
	v_div_scale_f32 v114, vcc, 1.0, v119, 1.0
	v_mul_f32_e32 v131, v114, v130
	v_fma_f32 v132, -v129, v131, v114
	v_fmac_f32_e32 v131, v132, v130
	v_fma_f32 v114, -v129, v131, v114
	v_div_scale_f32 v129, s[2:3], v118, v118, 1.0
	v_rcp_f32_e32 v132, v129
	v_div_fmas_f32 v114, v114, v130, v131
	v_div_fixup_f32 v114, v114, v119, 1.0
	v_add_f32_e32 v78, 1.0, v78
	v_fma_f32 v119, -v129, v132, 1.0
	v_fmac_f32_e32 v132, v119, v132
	v_div_scale_f32 v119, vcc, 1.0, v118, 1.0
	v_mul_f32_e32 v130, v119, v132
	v_fma_f32 v131, -v129, v130, v119
	v_fmac_f32_e32 v130, v131, v132
	v_fma_f32 v119, -v129, v130, v119
	v_div_fmas_f32 v119, v119, v132, v130
	v_div_fixup_f32 v118, v119, v118, 1.0
	v_sub_f32_e32 v119, 1.0, v118
	v_fma_f32 v114, v114, v119, v118
	v_cmp_gt_f32_e64 s[4:5], s46, v114
	v_mul_f32_e32 v79, 0xbfb8aa3b, v79
	v_exp_f32_e32 v79, v79
	v_cndmask_b32_e64 v129, 0, 32, s[4:5]
	v_ldexp_f32 v114, v114, v129
	v_log_f32_e32 v130, v114
	v_mul_f32_e32 v114, 0xbfb8aa3b, v115
	v_exp_f32_e32 v129, v114
	v_cndmask_b32_e64 v114, 0, v193, s[0:1]
	v_sub_f32_e32 v113, v113, v114
	v_mul_f32_e32 v131, 0x3f317217, v130
	v_pk_add_f32 v[114:115], v[128:129], 1.0 op_sel_hi:[1,0]
	v_fma_f32 v131, v130, s47, -v131
	v_div_scale_f32 v128, s[0:1], v115, v115, 1.0
	v_rcp_f32_e32 v129, v128
	v_fmac_f32_e32 v131, 0x3377d1cf, v130
	v_fmac_f32_e32 v131, 0x3f317217, v130
	v_add_f32_e32 v79, 1.0, v79
	v_fma_f32 v132, -v128, v129, 1.0
	v_fmac_f32_e32 v129, v132, v129
	v_div_scale_f32 v132, vcc, 1.0, v115, 1.0
	v_mul_f32_e32 v133, v132, v129
	v_fma_f32 v138, -v128, v133, v132
	v_fmac_f32_e32 v133, v138, v129
	v_fma_f32 v128, -v128, v133, v132
	v_div_scale_f32 v132, s[0:1], v114, v114, 1.0
	v_rcp_f32_e32 v138, v132
	v_div_fmas_f32 v128, v128, v129, v133
	v_div_fixup_f32 v115, v128, v115, 1.0
	v_cmp_lt_f32_e64 s[0:1], |v130|, s49
	v_fma_f32 v128, -v132, v138, 1.0
	v_fmac_f32_e32 v138, v128, v138
	v_div_scale_f32 v128, vcc, 1.0, v114, 1.0
	v_mul_f32_e32 v129, v128, v138
	v_fma_f32 v133, -v132, v129, v128
	v_fmac_f32_e32 v129, v133, v138
	v_fma_f32 v128, -v132, v129, v128
	v_div_fmas_f32 v128, v128, v138, v129
	v_div_fixup_f32 v128, v128, v114, 1.0
	v_sub_f32_e32 v129, 1.0, v128
	v_fma_f32 v114, v115, v129, v128
	v_cmp_gt_f32_e32 vcc, s46, v114
	v_mul_f32_e32 v72, 0xbfb8aa3b, v72
	v_exp_f32_e32 v72, v72
	v_cndmask_b32_e64 v115, 0, 32, vcc
	v_ldexp_f32 v114, v114, v115
	v_log_f32_e32 v115, v114
	v_cndmask_b32_e64 v114, v130, v131, s[0:1]
;     __device__ __forceinline__ void operator()(const f32x4 (&acc)[2][2][4][2], const Unit& u, int wr, int wc, int fr, int fq) const {
;     ...
;                 for (int m = 0; m < 4; ++m) { float* rowp = LOGF + (size_t)(row0 + ai * HALF + m * 16) * 1024 + (colt - 1024);
; #pragma unroll
;                     for (int bj = 0; bj < 2; ++bj)
; #pragma unroll
;                         for (int n = 0; n < 2; ++n) { f32x4 z = acc[ai][bj][m][n], o;
; #pragma unroll
;                             for (int e = 0; e < 4; ++e) { const float lb = lbv[bj][4 * n + e]; const float sg = 1.0f / (1.0f + __expf(-z[e])); o[e] = __logf(lb + (1.0f - lb) * sg); }
;                             *(f32x4*)(rowp + bj * HALF + 4 * n) = o; } }
	v_cndmask_b32_e64 v130, 0, v193, s[4:5]
	v_sub_f32_e32 v114, v114, v130
	v_mul_f32_e32 v130, 0x3f317217, v115
	v_fma_f32 v130, v115, s47, -v130
	v_fmac_f32_e32 v130, 0x3377d1cf, v115
	v_fmac_f32_e32 v130, 0x3f317217, v115
	v_cmp_lt_f32_e64 s[0:1], |v115|, s49
	v_add_f32_e32 v72, 1.0, v72
	v_mul_f32_e32 v73, 0xbfb8aa3b, v73
	v_cndmask_b32_e64 v115, v115, v130, s[0:1]
	v_cndmask_b32_e32 v130, 0, v193, vcc
	v_sub_f32_e32 v115, v115, v130
	global_store_dwordx4 v[180:181], v[112:115], off offset:-3568
	v_exp_f32_e32 v73, v73
	v_mul_f32_e32 v74, 0xbfb8aa3b, v74
	v_div_scale_f32 v114, s[0:1], v108, v108, 1.0
	v_rcp_f32_e32 v115, v114
	v_or_b32_e32 v112, 16, v182
	v_ashrrev_i32_e32 v113, 31, v112
	v_lshlrev_b64 v[112:113], 12, v[112:113]
	v_fma_f32 v130, -v114, v115, 1.0
	v_fmac_f32_e32 v115, v130, v115
	v_div_scale_f32 v130, vcc, 1.0, v108, 1.0
	v_mul_f32_e32 v131, v130, v115
	v_fma_f32 v132, -v114, v131, v130
	v_fmac_f32_e32 v131, v132, v115
	v_fma_f32 v114, -v114, v131, v130
	v_div_fmas_f32 v114, v114, v115, v131
	v_div_fixup_f32 v108, v114, v108, 1.0
	v_fma_f32 v108, v108, v157, v156
	v_cmp_gt_f32_e64 s[0:1], s46, v108
	v_div_scale_f32 v115, s[2:3], v109, v109, 1.0
	s_nop 0
	v_cndmask_b32_e64 v114, 0, 32, s[0:1]
	v_ldexp_f32 v108, v108, v114
	v_log_f32_e32 v108, v108
	v_rcp_f32_e32 v130, v115
	v_lshl_add_u64 v[112:113], s[58:59], 0, v[112:113]
	v_lshl_add_u64 v[112:113], v[112:113], 0, v[184:185]
	v_mul_f32_e32 v114, 0x3f317217, v108
	v_fma_f32 v114, v108, s47, -v114
	v_fmac_f32_e32 v114, 0x3377d1cf, v108
	v_fmac_f32_e32 v114, 0x3f317217, v108
	v_cmp_lt_f32_e64 vcc, |v108|, s49
	v_add_f32_e32 v73, 1.0, v73
	v_exp_f32_e32 v74, v74
	v_cndmask_b32_e32 v108, v108, v114, vcc
	v_fma_f32 v114, -v115, v130, 1.0
	v_fmac_f32_e32 v130, v114, v130
	v_div_scale_f32 v114, vcc, 1.0, v109, 1.0
	v_mul_f32_e32 v131, v114, v130
	v_fma_f32 v132, -v115, v131, v114
	v_fmac_f32_e32 v131, v132, v130
	v_fma_f32 v114, -v115, v131, v114
	v_div_fmas_f32 v114, v114, v130, v131
	v_div_fixup_f32 v109, v114, v109, 1.0
	v_fma_f32 v109, v109, v159, v158
	v_cmp_gt_f32_e64 s[4:5], s46, v109
	v_add_f32_e32 v74, 1.0, v74
	v_mul_f32_e32 v75, 0xbfb8aa3b, v75
	v_cndmask_b32_e64 v114, 0, 32, s[4:5]
	v_ldexp_f32 v109, v109, v114
	v_cndmask_b32_e64 v114, 0, v193, s[0:1]
	v_div_scale_f32 v115, s[0:1], v110, v110, 1.0
	v_rcp_f32_e32 v130, v115
	v_log_f32_e32 v109, v109
	v_sub_f32_e32 v108, v108, v114
	v_exp_f32_e32 v75, v75
	v_fma_f32 v131, -v115, v130, 1.0
	v_fmac_f32_e32 v130, v131, v130
	v_div_scale_f32 v131, vcc, 1.0, v110, 1.0
	v_mul_f32_e32 v132, v131, v130
	v_fma_f32 v133, -v115, v132, v131
	v_fmac_f32_e32 v132, v133, v130
	v_fma_f32 v115, -v115, v132, v131
	v_div_fmas_f32 v115, v115, v130, v132
	v_div_fixup_f32 v110, v115, v110, 1.0
	v_fma_f32 v110, v110, v155, v154
	v_cmp_gt_f32_e32 vcc, s46, v110
	v_mul_f32_e32 v114, 0x3f317217, v109
	v_fma_f32 v114, v109, s47, -v114
	v_cndmask_b32_e64 v115, 0, 32, vcc
	v_ldexp_f32 v110, v110, v115
	v_fmac_f32_e32 v114, 0x3377d1cf, v109
	v_log_f32_e32 v110, v110
	v_fmac_f32_e32 v114, 0x3f317217, v109
	v_cmp_lt_f32_e64 s[0:1], |v109|, s49
	v_add_f32_e32 v75, 1.0, v75
	v_mul_f32_e32 v68, 0xbfb8aa3b, v68
	v_cndmask_b32_e64 v109, v109, v114, s[0:1]
	v_div_scale_f32 v115, s[0:1], v111, v111, 1.0
	v_cndmask_b32_e64 v114, 0, v193, s[4:5]
	v_rcp_f32_e32 v130, v115
	v_sub_f32_e32 v109, v109, v114
	v_mul_f32_e32 v114, 0x3f317217, v110
	v_fma_f32 v114, v110, s47, -v114
	v_fmac_f32_e32 v114, 0x3377d1cf, v110
	v_fmac_f32_e32 v114, 0x3f317217, v110
	v_cmp_lt_f32_e64 s[0:1], |v110|, s49
	v_fma_f32 v131, -v115, v130, 1.0
	v_fmac_f32_e32 v130, v131, v130
	v_cndmask_b32_e64 v110, v110, v114, s[0:1]
	v_cndmask_b32_e32 v114, 0, v193, vcc
	v_div_scale_f32 v131, vcc, 1.0, v111, 1.0
	v_mul_f32_e32 v132, v131, v130
	v_fma_f32 v133, -v115, v132, v131
	v_fmac_f32_e32 v132, v133, v130
	v_fma_f32 v115, -v115, v132, v131
	v_div_fmas_f32 v115, v115, v130, v132
	v_div_fixup_f32 v111, v115, v111, 1.0
	v_fma_f32 v111, v111, v153, v152
	v_cmp_gt_f32_e64 s[0:1], s46, v111
	v_sub_f32_e32 v110, v110, v114
	v_exp_f32_e32 v68, v68
	v_cndmask_b32_e64 v115, 0, 32, s[0:1]
	v_ldexp_f32 v111, v111, v115
	v_log_f32_e32 v111, v111
	v_div_scale_f32 v115, s[2:3], v104, v104, 1.0
	v_rcp_f32_e32 v130, v115
	v_mul_f32_e32 v114, 0x3f317217, v111
	v_fma_f32 v114, v111, s47, -v114
	v_fmac_f32_e32 v114, 0x3377d1cf, v111
	v_fmac_f32_e32 v114, 0x3f317217, v111
	v_cmp_lt_f32_e64 vcc, |v111|, s49
	v_add_f32_e32 v68, 1.0, v68
	v_mul_f32_e32 v69, 0xbfb8aa3b, v69
	v_cndmask_b32_e32 v111, v111, v114, vcc
	v_fma_f32 v114, -v115, v130, 1.0
	v_fmac_f32_e32 v130, v114, v130
	v_div_scale_f32 v114, vcc, 1.0, v104, 1.0
	v_mul_f32_e32 v131, v114, v130
	v_fma_f32 v132, -v115, v131, v114
	v_fmac_f32_e32 v131, v132, v130
	v_fma_f32 v114, -v115, v131, v114
	v_div_fmas_f32 v114, v114, v130, v131
	v_div_fixup_f32 v104, v114, v104, 1.0
	v_fma_f32 v104, v104, v151, v150
	v_cmp_gt_f32_e32 vcc, s46, v104
	v_exp_f32_e32 v69, v69
	v_mul_f32_e32 v70, 0xbfb8aa3b, v70
	v_cndmask_b32_e64 v114, 0, 32, vcc
	v_ldexp_f32 v104, v104, v114
	v_log_f32_e32 v104, v104
	v_cndmask_b32_e64 v114, 0, v193, s[0:1]
	v_sub_f32_e32 v111, v111, v114
	global_store_dwordx4 v[112:113], v[108:111], off offset:-4096
	v_add_f32_e32 v69, 1.0, v69
	v_exp_f32_e32 v70, v70
	v_div_scale_f32 v109, s[0:1], v105, v105, 1.0
	v_rcp_f32_e32 v110, v109
	v_mul_f32_e32 v108, 0x3f317217, v104
	v_fma_f32 v108, v104, s47, -v108
	v_fmac_f32_e32 v108, 0x3377d1cf, v104
	v_fmac_f32_e32 v108, 0x3f317217, v104
	v_cmp_lt_f32_e64 s[0:1], |v104|, s49
	v_fma_f32 v111, -v109, v110, 1.0
	v_fmac_f32_e32 v110, v111, v110
	v_cndmask_b32_e64 v104, v104, v108, s[0:1]
;     __device__ __forceinline__ void operator()(const f32x4 (&acc)[2][2][4][2], const Unit& u, int wr, int wc, int fr, int fq) const {
;     ...
;                         for (int n = 0; n < 2; ++n) { f32x4 z = acc[ai][bj][m][n], o;
; #pragma unroll
;                             for (int e = 0; e < 4; ++e) { const float lb = lbv[bj][4 * n + e]; const float sg = 1.0f / (1.0f + __expf(-z[e])); o[e] = __logf(lb + (1.0f - lb) * sg); }
;                             *(f32x4*)(rowp + bj * HALF + 4 * n) = o; } }
	v_cndmask_b32_e32 v108, 0, v193, vcc
	v_div_scale_f32 v111, vcc, 1.0, v105, 1.0
	v_mul_f32_e32 v114, v111, v110
	v_fma_f32 v115, -v109, v114, v111
	v_fmac_f32_e32 v114, v115, v110
	v_fma_f32 v109, -v109, v114, v111
	v_div_fmas_f32 v109, v109, v110, v114
	v_div_fixup_f32 v105, v109, v105, 1.0
	v_fma_f32 v105, v105, v125, v124
	v_cmp_gt_f32_e64 s[0:1], s46, v105
	v_sub_f32_e32 v104, v104, v108
	v_add_f32_e32 v70, 1.0, v70
	v_cndmask_b32_e64 v109, 0, 32, s[0:1]
	v_ldexp_f32 v105, v105, v109
	v_log_f32_e32 v105, v105
	v_div_scale_f32 v109, s[2:3], v106, v106, 1.0
	v_rcp_f32_e32 v110, v109
	v_mul_f32_e32 v108, 0x3f317217, v105
	v_fma_f32 v108, v105, s47, -v108
	v_fmac_f32_e32 v108, 0x3377d1cf, v105
	v_fmac_f32_e32 v108, 0x3f317217, v105
	v_cmp_lt_f32_e64 vcc, |v105|, s49
	v_mul_f32_e32 v71, 0xbfb8aa3b, v71
	v_exp_f32_e32 v71, v71
	v_cndmask_b32_e32 v105, v105, v108, vcc
	v_fma_f32 v108, -v109, v110, 1.0
	v_fmac_f32_e32 v110, v108, v110
	v_div_scale_f32 v108, vcc, 1.0, v106, 1.0
	v_mul_f32_e32 v111, v108, v110
	v_fma_f32 v114, -v109, v111, v108
	v_fmac_f32_e32 v111, v114, v110
	v_fma_f32 v108, -v109, v111, v108
	v_div_fmas_f32 v108, v108, v110, v111
	v_div_fixup_f32 v106, v108, v106, 1.0
	v_fma_f32 v106, v106, v127, v126
	v_cmp_gt_f32_e64 s[4:5], s46, v106
	v_add_f32_e32 v71, 1.0, v71
	v_mul_f32_e32 v64, 0xbfb8aa3b, v64
	v_cndmask_b32_e64 v108, 0, 32, s[4:5]
	v_ldexp_f32 v106, v106, v108
	v_cndmask_b32_e64 v108, 0, v193, s[0:1]
	v_div_scale_f32 v109, s[0:1], v107, v107, 1.0
	v_rcp_f32_e32 v110, v109
	v_log_f32_e32 v106, v106
	v_sub_f32_e32 v105, v105, v108
	v_exp_f32_e32 v64, v64
	v_fma_f32 v111, -v109, v110, 1.0
	v_fmac_f32_e32 v110, v111, v110
	v_div_scale_f32 v111, vcc, 1.0, v107, 1.0
	v_mul_f32_e32 v114, v111, v110
	v_fma_f32 v115, -v109, v114, v111
	v_fmac_f32_e32 v114, v115, v110
	v_fma_f32 v109, -v109, v114, v111
	v_div_fmas_f32 v109, v109, v110, v114
	v_div_fixup_f32 v107, v109, v107, 1.0
	v_fma_f32 v107, v107, v145, v144
	v_cmp_gt_f32_e32 vcc, s46, v107
	v_mul_f32_e32 v108, 0x3f317217, v106
	v_fma_f32 v108, v106, s47, -v108
	v_cndmask_b32_e64 v109, 0, 32, vcc
	v_ldexp_f32 v107, v107, v109
	v_log_f32_e32 v107, v107
	v_fmac_f32_e32 v108, 0x3377d1cf, v106
	v_fmac_f32_e32 v108, 0x3f317217, v106
	v_cmp_lt_f32_e64 s[0:1], |v106|, s49
	v_add_f32_e32 v64, 1.0, v64
	v_mul_f32_e32 v65, 0xbfb8aa3b, v65
	v_cndmask_b32_e64 v106, v106, v108, s[0:1]
	v_cndmask_b32_e64 v108, 0, v193, s[4:5]
	v_sub_f32_e32 v106, v106, v108
	v_mul_f32_e32 v108, 0x3f317217, v107
	v_div_scale_f32 v109, s[0:1], v100, v100, 1.0
	v_fma_f32 v108, v107, s47, -v108
	v_rcp_f32_e32 v110, v109
	v_fmac_f32_e32 v108, 0x3377d1cf, v107
	v_fmac_f32_e32 v108, 0x3f317217, v107
	v_cmp_lt_f32_e64 s[0:1], |v107|, s49
	v_exp_f32_e32 v65, v65
	v_mul_f32_e32 v66, 0xbfb8aa3b, v66
	v_cndmask_b32_e64 v107, v107, v108, s[0:1]
	v_cndmask_b32_e32 v108, 0, v193, vcc
	v_sub_f32_e32 v107, v107, v108
	v_fma_f32 v108, -v109, v110, 1.0
	v_fmac_f32_e32 v110, v108, v110
	v_div_scale_f32 v108, vcc, 1.0, v100, 1.0
	v_mul_f32_e32 v111, v108, v110
	v_fma_f32 v114, -v109, v111, v108
	v_fmac_f32_e32 v111, v114, v110
	v_fma_f32 v108, -v109, v111, v108
	v_div_fmas_f32 v108, v108, v110, v111
	v_div_fixup_f32 v100, v108, v100, 1.0
	v_fma_f32 v100, v100, v143, v142
	v_cmp_gt_f32_e64 s[0:1], s46, v100
	global_store_dwordx4 v[112:113], v[104:107], off offset:-4080
	v_add_f32_e32 v65, 1.0, v65
	v_cndmask_b32_e64 v108, 0, 32, s[0:1]
	v_ldexp_f32 v100, v100, v108
	v_log_f32_e32 v100, v100
	v_div_scale_f32 v105, s[2:3], v101, v101, 1.0
	v_rcp_f32_e32 v106, v105
	v_mul_f32_e32 v104, 0x3f317217, v100
	v_fma_f32 v104, v100, s47, -v104
	v_fmac_f32_e32 v104, 0x3377d1cf, v100
	v_fmac_f32_e32 v104, 0x3f317217, v100
	v_cmp_lt_f32_e64 vcc, |v100|, s49
	v_exp_f32_e32 v66, v66
	v_mul_f32_e32 v67, 0xbfb8aa3b, v67
	v_cndmask_b32_e32 v100, v100, v104, vcc
	v_fma_f32 v104, -v105, v106, 1.0
	v_fmac_f32_e32 v106, v104, v106
	v_div_scale_f32 v104, vcc, 1.0, v101, 1.0
	v_mul_f32_e32 v107, v104, v106
	v_fma_f32 v108, -v105, v107, v104
	v_fmac_f32_e32 v107, v108, v106
	v_fma_f32 v104, -v105, v107, v104
	v_div_fmas_f32 v104, v104, v106, v107
	v_div_fixup_f32 v101, v104, v101, 1.0
	v_fma_f32 v101, v101, v121, v120
	v_cmp_gt_f32_e64 s[4:5], s46, v101
	v_add_f32_e32 v66, 1.0, v66
	v_exp_f32_e32 v67, v67
	v_cndmask_b32_e64 v104, 0, 32, s[4:5]
	v_ldexp_f32 v101, v101, v104
	v_cndmask_b32_e64 v104, 0, v193, s[0:1]
	v_div_scale_f32 v105, s[0:1], v102, v102, 1.0
	v_rcp_f32_e32 v106, v105
	v_log_f32_e32 v101, v101
	v_sub_f32_e32 v100, v100, v104
	v_add_f32_e32 v67, 1.0, v67
	v_fma_f32 v107, -v105, v106, 1.0
	v_fmac_f32_e32 v106, v107, v106
	v_div_scale_f32 v107, vcc, 1.0, v102, 1.0
	v_mul_f32_e32 v108, v107, v106
	v_fma_f32 v109, -v105, v108, v107
	v_fmac_f32_e32 v108, v109, v106
	v_fma_f32 v105, -v105, v108, v107
	v_div_fmas_f32 v105, v105, v106, v108
	v_div_fixup_f32 v102, v105, v102, 1.0
	v_fma_f32 v102, v102, v123, v122
	v_cmp_gt_f32_e32 vcc, s46, v102
	v_mul_f32_e32 v104, 0x3f317217, v101
	v_fma_f32 v104, v101, s47, -v104
	v_cndmask_b32_e64 v105, 0, 32, vcc
	v_ldexp_f32 v102, v102, v105
	v_fmac_f32_e32 v104, 0x3377d1cf, v101
	v_log_f32_e32 v102, v102
	v_fmac_f32_e32 v104, 0x3f317217, v101
	v_cmp_lt_f32_e64 s[0:1], |v101|, s49
	v_mul_f32_e32 v60, 0xbfb8aa3b, v60
	v_exp_f32_e32 v60, v60
	v_cndmask_b32_e64 v101, v101, v104, s[0:1]
	v_div_scale_f32 v105, s[0:1], v103, v103, 1.0
	v_cndmask_b32_e64 v104, 0, v193, s[4:5]
	v_rcp_f32_e32 v106, v105
	v_sub_f32_e32 v101, v101, v104
	v_mul_f32_e32 v104, 0x3f317217, v102
	v_fma_f32 v104, v102, s47, -v104
	v_fmac_f32_e32 v104, 0x3377d1cf, v102
	v_fmac_f32_e32 v104, 0x3f317217, v102
	v_cmp_lt_f32_e64 s[0:1], |v102|, s49
;     __device__ __forceinline__ void operator()(const f32x4 (&acc)[2][2][4][2], const Unit& u, int wr, int wc, int fr, int fq) const {
;     ...
;                 for (int m = 0; m < 4; ++m) { float* rowp = LOGF + (size_t)(row0 + ai * HALF + m * 16) * 1024 + (colt - 1024);
; #pragma unroll
;                     for (int bj = 0; bj < 2; ++bj)
; #pragma unroll
;                         for (int n = 0; n < 2; ++n) { f32x4 z = acc[ai][bj][m][n], o;
; #pragma unroll
;                             for (int e = 0; e < 4; ++e) { const float lb = lbv[bj][4 * n + e]; const float sg = 1.0f / (1.0f + __expf(-z[e])); o[e] = __logf(lb + (1.0f - lb) * sg); }
;                             *(f32x4*)(rowp + bj * HALF + 4 * n) = o; } }
	v_fma_f32 v107, -v105, v106, 1.0
	v_fmac_f32_e32 v106, v107, v106
	v_cndmask_b32_e64 v102, v102, v104, s[0:1]
	v_cndmask_b32_e32 v104, 0, v193, vcc
	v_div_scale_f32 v107, vcc, 1.0, v103, 1.0
	v_mul_f32_e32 v108, v107, v106
	v_fma_f32 v109, -v105, v108, v107
	v_fmac_f32_e32 v108, v109, v106
	v_fma_f32 v105, -v105, v108, v107
	v_div_fmas_f32 v105, v105, v106, v108
	v_div_fixup_f32 v103, v105, v103, 1.0
	v_fma_f32 v103, v103, v137, v136
	v_cmp_gt_f32_e64 s[0:1], s46, v103
	v_sub_f32_e32 v102, v102, v104
	v_add_f32_e32 v60, 1.0, v60
	v_cndmask_b32_e64 v105, 0, 32, s[0:1]
	v_ldexp_f32 v103, v103, v105
	v_log_f32_e32 v103, v103
	v_div_scale_f32 v105, s[2:3], v96, v96, 1.0
	v_rcp_f32_e32 v106, v105
	v_mul_f32_e32 v104, 0x3f317217, v103
	v_fma_f32 v104, v103, s47, -v104
	v_fmac_f32_e32 v104, 0x3377d1cf, v103
	v_fmac_f32_e32 v104, 0x3f317217, v103
	v_cmp_lt_f32_e64 vcc, |v103|, s49
	v_mul_f32_e32 v61, 0xbfb8aa3b, v61
	v_exp_f32_e32 v61, v61
	v_cndmask_b32_e32 v103, v103, v104, vcc
	v_fma_f32 v104, -v105, v106, 1.0
	v_fmac_f32_e32 v106, v104, v106
	v_div_scale_f32 v104, vcc, 1.0, v96, 1.0
	v_mul_f32_e32 v107, v104, v106
	v_fma_f32 v108, -v105, v107, v104
	v_fmac_f32_e32 v107, v108, v106
	v_fma_f32 v104, -v105, v107, v104
	v_div_fmas_f32 v104, v104, v106, v107
	v_div_fixup_f32 v96, v104, v96, 1.0
	v_fma_f32 v96, v96, v135, v134
	v_cmp_gt_f32_e32 vcc, s46, v96
	v_add_f32_e32 v61, 1.0, v61
	v_mul_f32_e32 v62, 0xbfb8aa3b, v62
	v_cndmask_b32_e64 v104, 0, 32, vcc
	v_ldexp_f32 v96, v96, v104
	v_log_f32_e32 v96, v96
	v_cndmask_b32_e64 v104, 0, v193, s[0:1]
	v_sub_f32_e32 v103, v103, v104
	global_store_dwordx4 v[112:113], v[100:103], off offset:-3584
	v_exp_f32_e32 v62, v62
	v_mul_f32_e32 v63, 0xbfb8aa3b, v63
	v_div_scale_f32 v101, s[0:1], v97, v97, 1.0
	v_rcp_f32_e32 v102, v101
	v_mul_f32_e32 v100, 0x3f317217, v96
	v_fma_f32 v100, v96, s47, -v100
	v_fmac_f32_e32 v100, 0x3377d1cf, v96
	v_fmac_f32_e32 v100, 0x3f317217, v96
	v_cmp_lt_f32_e64 s[0:1], |v96|, s49
	v_fma_f32 v103, -v101, v102, 1.0
	v_fmac_f32_e32 v102, v103, v102
	v_cndmask_b32_e64 v96, v96, v100, s[0:1]
	v_cndmask_b32_e32 v100, 0, v193, vcc
	v_div_scale_f32 v103, vcc, 1.0, v97, 1.0
	v_mul_f32_e32 v104, v103, v102
	v_fma_f32 v105, -v101, v104, v103
	v_fmac_f32_e32 v104, v105, v102
	v_fma_f32 v101, -v101, v104, v103
	v_div_fmas_f32 v101, v101, v102, v104
	v_div_fixup_f32 v97, v101, v97, 1.0
	v_fma_f32 v97, v97, v117, v116
	v_cmp_gt_f32_e64 s[0:1], s46, v97
	v_sub_f32_e32 v96, v96, v100
	v_add_f32_e32 v62, 1.0, v62
	v_cndmask_b32_e64 v101, 0, 32, s[0:1]
	v_ldexp_f32 v97, v97, v101
	v_log_f32_e32 v97, v97
	v_div_scale_f32 v101, s[2:3], v98, v98, 1.0
	v_rcp_f32_e32 v102, v101
	v_mul_f32_e32 v100, 0x3f317217, v97
	v_fma_f32 v100, v97, s47, -v100
	v_fmac_f32_e32 v100, 0x3377d1cf, v97
	v_fmac_f32_e32 v100, 0x3f317217, v97
	v_cmp_lt_f32_e64 vcc, |v97|, s49
	v_exp_f32_e32 v63, v63
	v_mul_f32_e32 v56, 0xbfb8aa3b, v56
	v_cndmask_b32_e32 v97, v97, v100, vcc
	v_fma_f32 v100, -v101, v102, 1.0
	v_fmac_f32_e32 v102, v100, v102
	v_div_scale_f32 v100, vcc, 1.0, v98, 1.0
	v_mul_f32_e32 v103, v100, v102
	v_fma_f32 v104, -v101, v103, v100
	v_fmac_f32_e32 v103, v104, v102
	v_fma_f32 v100, -v101, v103, v100
	v_div_fmas_f32 v100, v100, v102, v103
	v_div_fixup_f32 v98, v100, v98, 1.0
	v_fma_f32 v98, v98, v119, v118
	v_cmp_gt_f32_e64 s[4:5], s46, v98
	v_add_f32_e32 v63, 1.0, v63
	v_exp_f32_e32 v56, v56
	v_cndmask_b32_e64 v100, 0, 32, s[4:5]
	v_ldexp_f32 v98, v98, v100
	v_cndmask_b32_e64 v100, 0, v193, s[0:1]
	v_div_scale_f32 v101, s[0:1], v99, v99, 1.0
	v_rcp_f32_e32 v102, v101
	v_log_f32_e32 v98, v98
	v_sub_f32_e32 v97, v97, v100
	v_add_f32_e32 v56, 1.0, v56
	v_fma_f32 v103, -v101, v102, 1.0
	v_fmac_f32_e32 v102, v103, v102
	v_div_scale_f32 v103, vcc, 1.0, v99, 1.0
	v_mul_f32_e32 v104, v103, v102
	v_fma_f32 v105, -v101, v104, v103
	v_fmac_f32_e32 v104, v105, v102
	v_fma_f32 v101, -v101, v104, v103
	v_div_fmas_f32 v101, v101, v102, v104
	v_div_fixup_f32 v99, v101, v99, 1.0
	v_fma_f32 v99, v99, v129, v128
	v_cmp_gt_f32_e32 vcc, s46, v99
	v_mul_f32_e32 v100, 0x3f317217, v98
	v_fma_f32 v100, v98, s47, -v100
	v_cndmask_b32_e64 v101, 0, 32, vcc
	v_ldexp_f32 v99, v99, v101
	v_log_f32_e32 v99, v99
	v_fmac_f32_e32 v100, 0x3377d1cf, v98
	v_fmac_f32_e32 v100, 0x3f317217, v98
	v_cmp_lt_f32_e64 s[0:1], |v98|, s49
	v_mul_f32_e32 v57, 0xbfb8aa3b, v57
	v_exp_f32_e32 v57, v57
	v_cndmask_b32_e64 v98, v98, v100, s[0:1]
	v_cndmask_b32_e64 v100, 0, v193, s[4:5]
	v_sub_f32_e32 v98, v98, v100
	v_mul_f32_e32 v100, 0x3f317217, v99
	v_fma_f32 v100, v99, s47, -v100
	v_fmac_f32_e32 v100, 0x3377d1cf, v99
	v_fmac_f32_e32 v100, 0x3f317217, v99
	v_cmp_lt_f32_e64 s[0:1], |v99|, s49
	v_add_f32_e32 v57, 1.0, v57
	v_mul_f32_e32 v58, 0xbfb8aa3b, v58
	v_cndmask_b32_e64 v99, v99, v100, s[0:1]
	v_cndmask_b32_e32 v100, 0, v193, vcc
	v_sub_f32_e32 v99, v99, v100
	global_store_dwordx4 v[112:113], v[96:99], off offset:-3568
	v_exp_f32_e32 v58, v58
	v_mul_f32_e32 v59, 0xbfb8aa3b, v59
	v_div_scale_f32 v98, s[0:1], v92, v92, 1.0
	v_rcp_f32_e32 v99, v98
	v_or_b32_e32 v96, 32, v182
	v_ashrrev_i32_e32 v97, 31, v96
	v_lshlrev_b64 v[96:97], 12, v[96:97]
	v_fma_f32 v100, -v98, v99, 1.0
	v_fmac_f32_e32 v99, v100, v99
	v_div_scale_f32 v100, vcc, 1.0, v92, 1.0
	v_mul_f32_e32 v101, v100, v99
	v_fma_f32 v102, -v98, v101, v100
	v_fmac_f32_e32 v101, v102, v99
	v_fma_f32 v98, -v98, v101, v100
	v_div_fmas_f32 v98, v98, v99, v101
	v_div_fixup_f32 v92, v98, v92, 1.0
	v_fma_f32 v92, v92, v157, v156
	v_cmp_gt_f32_e64 s[0:1], s46, v92
	v_div_scale_f32 v99, s[2:3], v93, v93, 1.0
	s_nop 0
	v_cndmask_b32_e64 v98, 0, 32, s[0:1]
	v_ldexp_f32 v92, v92, v98
	v_log_f32_e32 v92, v92
;     __device__ __forceinline__ void operator()(const f32x4 (&acc)[2][2][4][2], const Unit& u, int wr, int wc, int fr, int fq) const {
;     ...
;                         for (int n = 0; n < 2; ++n) { f32x4 z = acc[ai][bj][m][n], o;
; #pragma unroll
;                             for (int e = 0; e < 4; ++e) { const float lb = lbv[bj][4 * n + e]; const float sg = 1.0f / (1.0f + __expf(-z[e])); o[e] = __logf(lb + (1.0f - lb) * sg); }
;                             *(f32x4*)(rowp + bj * HALF + 4 * n) = o; } }
	v_rcp_f32_e32 v100, v99
	v_lshl_add_u64 v[96:97], s[58:59], 0, v[96:97]
	v_lshl_add_u64 v[96:97], v[96:97], 0, v[184:185]
	v_mul_f32_e32 v98, 0x3f317217, v92
	v_fma_f32 v98, v92, s47, -v98
	v_fmac_f32_e32 v98, 0x3377d1cf, v92
	v_fmac_f32_e32 v98, 0x3f317217, v92
	v_cmp_lt_f32_e64 vcc, |v92|, s49
	v_add_f32_e32 v58, 1.0, v58
	v_exp_f32_e32 v59, v59
	v_cndmask_b32_e32 v92, v92, v98, vcc
	v_fma_f32 v98, -v99, v100, 1.0
	v_fmac_f32_e32 v100, v98, v100
	v_div_scale_f32 v98, vcc, 1.0, v93, 1.0
	v_mul_f32_e32 v101, v98, v100
	v_fma_f32 v102, -v99, v101, v98
	v_fmac_f32_e32 v101, v102, v100
	v_fma_f32 v98, -v99, v101, v98
	v_div_fmas_f32 v98, v98, v100, v101
	v_div_fixup_f32 v93, v98, v93, 1.0
	v_fma_f32 v93, v93, v159, v158
	v_cmp_gt_f32_e64 s[4:5], s46, v93
	v_add_f32_e32 v59, 1.0, v59
	v_mul_f32_e32 v52, 0xbfb8aa3b, v52
	v_cndmask_b32_e64 v98, 0, 32, s[4:5]
	v_ldexp_f32 v93, v93, v98
	v_cndmask_b32_e64 v98, 0, v193, s[0:1]
	v_div_scale_f32 v99, s[0:1], v94, v94, 1.0
	v_rcp_f32_e32 v100, v99
	v_log_f32_e32 v93, v93
	v_sub_f32_e32 v92, v92, v98
	v_exp_f32_e32 v52, v52
	v_fma_f32 v101, -v99, v100, 1.0
	v_fmac_f32_e32 v100, v101, v100
	v_div_scale_f32 v101, vcc, 1.0, v94, 1.0
	v_mul_f32_e32 v102, v101, v100
	v_fma_f32 v103, -v99, v102, v101
	v_fmac_f32_e32 v102, v103, v100
	v_fma_f32 v99, -v99, v102, v101
	v_div_fmas_f32 v99, v99, v100, v102
	v_div_fixup_f32 v94, v99, v94, 1.0
	v_fma_f32 v94, v94, v155, v154
	v_cmp_gt_f32_e32 vcc, s46, v94
	v_mul_f32_e32 v98, 0x3f317217, v93
	v_fma_f32 v98, v93, s47, -v98
	v_cndmask_b32_e64 v99, 0, 32, vcc
	v_ldexp_f32 v94, v94, v99
	v_fmac_f32_e32 v98, 0x3377d1cf, v93
	v_log_f32_e32 v94, v94
	v_fmac_f32_e32 v98, 0x3f317217, v93
	v_cmp_lt_f32_e64 s[0:1], |v93|, s49
	v_add_f32_e32 v52, 1.0, v52
	v_mul_f32_e32 v53, 0xbfb8aa3b, v53
	v_cndmask_b32_e64 v93, v93, v98, s[0:1]
	v_div_scale_f32 v99, s[0:1], v95, v95, 1.0
	v_cndmask_b32_e64 v98, 0, v193, s[4:5]
	v_rcp_f32_e32 v100, v99
	v_sub_f32_e32 v93, v93, v98
	v_mul_f32_e32 v98, 0x3f317217, v94
	v_fma_f32 v98, v94, s47, -v98
	v_fmac_f32_e32 v98, 0x3377d1cf, v94
	v_fmac_f32_e32 v98, 0x3f317217, v94
	v_cmp_lt_f32_e64 s[0:1], |v94|, s49
	v_fma_f32 v101, -v99, v100, 1.0
	v_fmac_f32_e32 v100, v101, v100
	v_cndmask_b32_e64 v94, v94, v98, s[0:1]
	v_cndmask_b32_e32 v98, 0, v193, vcc
	v_div_scale_f32 v101, vcc, 1.0, v95, 1.0
	v_mul_f32_e32 v102, v101, v100
	v_fma_f32 v103, -v99, v102, v101
	v_fmac_f32_e32 v102, v103, v100
	v_fma_f32 v99, -v99, v102, v101
	v_div_fmas_f32 v99, v99, v100, v102
	v_div_fixup_f32 v95, v99, v95, 1.0
	v_fma_f32 v95, v95, v153, v152
	v_cmp_gt_f32_e64 s[0:1], s46, v95
	v_sub_f32_e32 v94, v94, v98
	v_exp_f32_e32 v53, v53
	v_cndmask_b32_e64 v99, 0, 32, s[0:1]
	v_ldexp_f32 v95, v95, v99
	v_log_f32_e32 v95, v95
	v_div_scale_f32 v99, s[2:3], v88, v88, 1.0
	v_rcp_f32_e32 v100, v99
	v_mul_f32_e32 v98, 0x3f317217, v95
	v_fma_f32 v98, v95, s47, -v98
	v_fmac_f32_e32 v98, 0x3377d1cf, v95
	v_fmac_f32_e32 v98, 0x3f317217, v95
	v_cmp_lt_f32_e64 vcc, |v95|, s49
	v_add_f32_e32 v53, 1.0, v53
	v_mul_f32_e32 v54, 0xbfb8aa3b, v54
	v_cndmask_b32_e32 v95, v95, v98, vcc
	v_fma_f32 v98, -v99, v100, 1.0
	v_fmac_f32_e32 v100, v98, v100
	v_div_scale_f32 v98, vcc, 1.0, v88, 1.0
	v_mul_f32_e32 v101, v98, v100
	v_fma_f32 v102, -v99, v101, v98
	v_fmac_f32_e32 v101, v102, v100
	v_fma_f32 v98, -v99, v101, v98
	v_div_fmas_f32 v98, v98, v100, v101
	v_div_fixup_f32 v88, v98, v88, 1.0
	v_fma_f32 v88, v88, v151, v150
	v_cmp_gt_f32_e32 vcc, s46, v88
	v_exp_f32_e32 v54, v54
	v_mul_f32_e32 v55, 0xbfb8aa3b, v55
	v_cndmask_b32_e64 v98, 0, 32, vcc
	v_ldexp_f32 v88, v88, v98
	v_log_f32_e32 v88, v88
	v_cndmask_b32_e64 v98, 0, v193, s[0:1]
	v_sub_f32_e32 v95, v95, v98
	global_store_dwordx4 v[96:97], v[92:95], off offset:-4096
	v_add_f32_e32 v54, 1.0, v54
	v_exp_f32_e32 v55, v55
	v_div_scale_f32 v93, s[0:1], v89, v89, 1.0
	v_rcp_f32_e32 v94, v93
	v_mul_f32_e32 v92, 0x3f317217, v88
	v_fma_f32 v92, v88, s47, -v92
	v_fmac_f32_e32 v92, 0x3377d1cf, v88
	v_fmac_f32_e32 v92, 0x3f317217, v88
	v_cmp_lt_f32_e64 s[0:1], |v88|, s49
	v_fma_f32 v95, -v93, v94, 1.0
	v_fmac_f32_e32 v94, v95, v94
	v_cndmask_b32_e64 v88, v88, v92, s[0:1]
	v_cndmask_b32_e32 v92, 0, v193, vcc
	v_div_scale_f32 v95, vcc, 1.0, v89, 1.0
	v_mul_f32_e32 v98, v95, v94
	v_fma_f32 v99, -v93, v98, v95
	v_fmac_f32_e32 v98, v99, v94
	v_fma_f32 v93, -v93, v98, v95
	v_div_fmas_f32 v93, v93, v94, v98
	v_div_fixup_f32 v89, v93, v89, 1.0
	v_fma_f32 v89, v89, v125, v124
	v_cmp_gt_f32_e64 s[0:1], s46, v89
	v_sub_f32_e32 v88, v88, v92
	v_add_f32_e32 v55, 1.0, v55
	v_cndmask_b32_e64 v93, 0, 32, s[0:1]
	v_ldexp_f32 v89, v89, v93
	v_log_f32_e32 v89, v89
	v_div_scale_f32 v93, s[2:3], v90, v90, 1.0
	v_rcp_f32_e32 v94, v93
	v_mul_f32_e32 v92, 0x3f317217, v89
	v_fma_f32 v92, v89, s47, -v92
	v_fmac_f32_e32 v92, 0x3377d1cf, v89
	v_fmac_f32_e32 v92, 0x3f317217, v89
	v_cmp_lt_f32_e64 vcc, |v89|, s49
	v_mul_f32_e32 v48, 0xbfb8aa3b, v48
	v_exp_f32_e32 v48, v48
	v_cndmask_b32_e32 v89, v89, v92, vcc
	v_fma_f32 v92, -v93, v94, 1.0
	v_fmac_f32_e32 v94, v92, v94
	v_div_scale_f32 v92, vcc, 1.0, v90, 1.0
	v_mul_f32_e32 v95, v92, v94
	v_fma_f32 v98, -v93, v95, v92
	v_fmac_f32_e32 v95, v98, v94
	v_fma_f32 v92, -v93, v95, v92
	v_div_fmas_f32 v92, v92, v94, v95
	v_div_fixup_f32 v90, v92, v90, 1.0
	v_fma_f32 v90, v90, v127, v126
	v_cmp_gt_f32_e64 s[4:5], s46, v90
	v_add_f32_e32 v48, 1.0, v48
	v_mul_f32_e32 v49, 0xbfb8aa3b, v49
	v_cndmask_b32_e64 v92, 0, 32, s[4:5]
	v_ldexp_f32 v90, v90, v92
	v_cndmask_b32_e64 v92, 0, v193, s[0:1]
	v_div_scale_f32 v93, s[0:1], v91, v91, 1.0
	v_rcp_f32_e32 v94, v93
	v_log_f32_e32 v90, v90
	v_sub_f32_e32 v89, v89, v92
	v_exp_f32_e32 v49, v49
;     __device__ __forceinline__ void operator()(const f32x4 (&acc)[2][2][4][2], const Unit& u, int wr, int wc, int fr, int fq) const {
;     ...
;                         for (int n = 0; n < 2; ++n) { f32x4 z = acc[ai][bj][m][n], o;
; #pragma unroll
;                             for (int e = 0; e < 4; ++e) { const float lb = lbv[bj][4 * n + e]; const float sg = 1.0f / (1.0f + __expf(-z[e])); o[e] = __logf(lb + (1.0f - lb) * sg); }
;                             *(f32x4*)(rowp + bj * HALF + 4 * n) = o; } }
	v_fma_f32 v95, -v93, v94, 1.0
	v_fmac_f32_e32 v94, v95, v94
	v_div_scale_f32 v95, vcc, 1.0, v91, 1.0
	v_mul_f32_e32 v98, v95, v94
	v_fma_f32 v99, -v93, v98, v95
	v_fmac_f32_e32 v98, v99, v94
	v_fma_f32 v93, -v93, v98, v95
	v_div_fmas_f32 v93, v93, v94, v98
	v_div_fixup_f32 v91, v93, v91, 1.0
	v_fma_f32 v91, v91, v145, v144
	v_cmp_gt_f32_e32 vcc, s46, v91
	v_mul_f32_e32 v92, 0x3f317217, v90
	v_fma_f32 v92, v90, s47, -v92
	v_cndmask_b32_e64 v93, 0, 32, vcc
	v_ldexp_f32 v91, v91, v93
	v_log_f32_e32 v91, v91
	v_fmac_f32_e32 v92, 0x3377d1cf, v90
	v_fmac_f32_e32 v92, 0x3f317217, v90
	v_cmp_lt_f32_e64 s[0:1], |v90|, s49
	v_add_f32_e32 v49, 1.0, v49
	v_mul_f32_e32 v50, 0xbfb8aa3b, v50
	v_cndmask_b32_e64 v90, v90, v92, s[0:1]
	v_cndmask_b32_e64 v92, 0, v193, s[4:5]
	v_sub_f32_e32 v90, v90, v92
	v_mul_f32_e32 v92, 0x3f317217, v91
	v_div_scale_f32 v93, s[0:1], v84, v84, 1.0
	v_fma_f32 v92, v91, s47, -v92
	v_rcp_f32_e32 v94, v93
	v_fmac_f32_e32 v92, 0x3377d1cf, v91
	v_fmac_f32_e32 v92, 0x3f317217, v91
	v_cmp_lt_f32_e64 s[0:1], |v91|, s49
	v_exp_f32_e32 v50, v50
	v_mul_f32_e32 v51, 0xbfb8aa3b, v51
	v_cndmask_b32_e64 v91, v91, v92, s[0:1]
	v_cndmask_b32_e32 v92, 0, v193, vcc
	v_sub_f32_e32 v91, v91, v92
	v_fma_f32 v92, -v93, v94, 1.0
	v_fmac_f32_e32 v94, v92, v94
	v_div_scale_f32 v92, vcc, 1.0, v84, 1.0
	v_mul_f32_e32 v95, v92, v94
	v_fma_f32 v98, -v93, v95, v92
	v_fmac_f32_e32 v95, v98, v94
	v_fma_f32 v92, -v93, v95, v92
	v_div_fmas_f32 v92, v92, v94, v95
	v_div_fixup_f32 v84, v92, v84, 1.0
	v_fma_f32 v84, v84, v143, v142
	v_cmp_gt_f32_e64 s[0:1], s46, v84
	global_store_dwordx4 v[96:97], v[88:91], off offset:-4080
	v_add_f32_e32 v50, 1.0, v50
	v_cndmask_b32_e64 v92, 0, 32, s[0:1]
	v_ldexp_f32 v84, v84, v92
	v_log_f32_e32 v84, v84
	v_div_scale_f32 v89, s[2:3], v85, v85, 1.0
	v_rcp_f32_e32 v90, v89
	v_mul_f32_e32 v88, 0x3f317217, v84
	v_fma_f32 v88, v84, s47, -v88
	v_fmac_f32_e32 v88, 0x3377d1cf, v84
	v_fmac_f32_e32 v88, 0x3f317217, v84
	v_cmp_lt_f32_e64 vcc, |v84|, s49
	v_exp_f32_e32 v51, v51
	v_mul_f32_e32 v44, 0xbfb8aa3b, v44
	v_cndmask_b32_e32 v84, v84, v88, vcc
	v_fma_f32 v88, -v89, v90, 1.0
	v_fmac_f32_e32 v90, v88, v90
	v_div_scale_f32 v88, vcc, 1.0, v85, 1.0
	v_mul_f32_e32 v91, v88, v90
	v_fma_f32 v92, -v89, v91, v88
	v_fmac_f32_e32 v91, v92, v90
	v_fma_f32 v88, -v89, v91, v88
	v_div_fmas_f32 v88, v88, v90, v91
	v_div_fixup_f32 v85, v88, v85, 1.0
	v_fma_f32 v85, v85, v121, v120
	v_cmp_gt_f32_e64 s[4:5], s46, v85
	v_add_f32_e32 v51, 1.0, v51
	v_exp_f32_e32 v44, v44
	v_cndmask_b32_e64 v88, 0, 32, s[4:5]
	v_ldexp_f32 v85, v85, v88
	v_cndmask_b32_e64 v88, 0, v193, s[0:1]
	v_div_scale_f32 v89, s[0:1], v86, v86, 1.0
	v_rcp_f32_e32 v90, v89
	v_log_f32_e32 v85, v85
	v_sub_f32_e32 v84, v84, v88
	v_add_f32_e32 v44, 1.0, v44
	v_fma_f32 v91, -v89, v90, 1.0
	v_fmac_f32_e32 v90, v91, v90
	v_div_scale_f32 v91, vcc, 1.0, v86, 1.0
	v_mul_f32_e32 v92, v91, v90
	v_fma_f32 v93, -v89, v92, v91
	v_fmac_f32_e32 v92, v93, v90
	v_fma_f32 v89, -v89, v92, v91
	v_div_fmas_f32 v89, v89, v90, v92
	v_div_fixup_f32 v86, v89, v86, 1.0
	v_fma_f32 v86, v86, v123, v122
	v_cmp_gt_f32_e32 vcc, s46, v86
	v_mul_f32_e32 v88, 0x3f317217, v85
	v_fma_f32 v88, v85, s47, -v88
	v_cndmask_b32_e64 v89, 0, 32, vcc
	v_ldexp_f32 v86, v86, v89
	v_fmac_f32_e32 v88, 0x3377d1cf, v85
	v_log_f32_e32 v86, v86
	v_fmac_f32_e32 v88, 0x3f317217, v85
	v_cmp_lt_f32_e64 s[0:1], |v85|, s49
	v_mul_f32_e32 v45, 0xbfb8aa3b, v45
	v_exp_f32_e32 v45, v45
	v_cndmask_b32_e64 v85, v85, v88, s[0:1]
	v_div_scale_f32 v89, s[0:1], v87, v87, 1.0
	v_cndmask_b32_e64 v88, 0, v193, s[4:5]
	v_rcp_f32_e32 v90, v89
	v_sub_f32_e32 v85, v85, v88
	v_mul_f32_e32 v88, 0x3f317217, v86
	v_fma_f32 v88, v86, s47, -v88
	v_fmac_f32_e32 v88, 0x3377d1cf, v86
	v_fmac_f32_e32 v88, 0x3f317217, v86
	v_cmp_lt_f32_e64 s[0:1], |v86|, s49
	v_fma_f32 v91, -v89, v90, 1.0
	v_fmac_f32_e32 v90, v91, v90
	v_cndmask_b32_e64 v86, v86, v88, s[0:1]
	v_cndmask_b32_e32 v88, 0, v193, vcc
	v_div_scale_f32 v91, vcc, 1.0, v87, 1.0
	v_mul_f32_e32 v92, v91, v90
	v_fma_f32 v93, -v89, v92, v91
	v_fmac_f32_e32 v92, v93, v90
	v_fma_f32 v89, -v89, v92, v91
	v_div_fmas_f32 v89, v89, v90, v92
	v_div_fixup_f32 v87, v89, v87, 1.0
	v_fma_f32 v87, v87, v137, v136
	v_cmp_gt_f32_e64 s[0:1], s46, v87
	v_sub_f32_e32 v86, v86, v88
	v_add_f32_e32 v45, 1.0, v45
	v_cndmask_b32_e64 v89, 0, 32, s[0:1]
	v_ldexp_f32 v87, v87, v89
	v_log_f32_e32 v87, v87
	v_div_scale_f32 v89, s[2:3], v80, v80, 1.0
	v_rcp_f32_e32 v90, v89
	v_mul_f32_e32 v88, 0x3f317217, v87
	v_fma_f32 v88, v87, s47, -v88
	v_fmac_f32_e32 v88, 0x3377d1cf, v87
	v_fmac_f32_e32 v88, 0x3f317217, v87
	v_cmp_lt_f32_e64 vcc, |v87|, s49
	v_mul_f32_e32 v46, 0xbfb8aa3b, v46
	v_exp_f32_e32 v46, v46
	v_cndmask_b32_e32 v87, v87, v88, vcc
	v_fma_f32 v88, -v89, v90, 1.0
	v_fmac_f32_e32 v90, v88, v90
	v_div_scale_f32 v88, vcc, 1.0, v80, 1.0
	v_mul_f32_e32 v91, v88, v90
	v_fma_f32 v92, -v89, v91, v88
	v_fmac_f32_e32 v91, v92, v90
	v_fma_f32 v88, -v89, v91, v88
	v_div_fmas_f32 v88, v88, v90, v91
	v_div_fixup_f32 v80, v88, v80, 1.0
	v_fma_f32 v80, v80, v135, v134
	v_cmp_gt_f32_e32 vcc, s46, v80
	v_add_f32_e32 v46, 1.0, v46
	v_mul_f32_e32 v47, 0xbfb8aa3b, v47
	v_cndmask_b32_e64 v88, 0, 32, vcc
	v_ldexp_f32 v80, v80, v88
	v_log_f32_e32 v80, v80
	v_cndmask_b32_e64 v88, 0, v193, s[0:1]
	v_sub_f32_e32 v87, v87, v88
	global_store_dwordx4 v[96:97], v[84:87], off offset:-3584
	v_exp_f32_e32 v47, v47
	v_mul_f32_e32 v40, 0xbfb8aa3b, v40
	v_div_scale_f32 v85, s[0:1], v81, v81, 1.0
	v_rcp_f32_e32 v86, v85
	v_mul_f32_e32 v84, 0x3f317217, v80
	v_fma_f32 v84, v80, s47, -v84
	v_fmac_f32_e32 v84, 0x3377d1cf, v80
	v_fmac_f32_e32 v84, 0x3f317217, v80
;     __device__ __forceinline__ void operator()(const f32x4 (&acc)[2][2][4][2], const Unit& u, int wr, int wc, int fr, int fq) const {
;     ...
;                         for (int n = 0; n < 2; ++n) { f32x4 z = acc[ai][bj][m][n], o;
; #pragma unroll
;                             for (int e = 0; e < 4; ++e) { const float lb = lbv[bj][4 * n + e]; const float sg = 1.0f / (1.0f + __expf(-z[e])); o[e] = __logf(lb + (1.0f - lb) * sg); }
;                             *(f32x4*)(rowp + bj * HALF + 4 * n) = o; } }
	v_cmp_lt_f32_e64 s[0:1], |v80|, s49
	v_fma_f32 v87, -v85, v86, 1.0
	v_fmac_f32_e32 v86, v87, v86
	v_cndmask_b32_e64 v80, v80, v84, s[0:1]
	v_cndmask_b32_e32 v84, 0, v193, vcc
	v_div_scale_f32 v87, vcc, 1.0, v81, 1.0
	v_mul_f32_e32 v88, v87, v86
	v_fma_f32 v89, -v85, v88, v87
	v_fmac_f32_e32 v88, v89, v86
	v_fma_f32 v85, -v85, v88, v87
	v_div_fmas_f32 v85, v85, v86, v88
	v_div_fixup_f32 v81, v85, v81, 1.0
	v_fma_f32 v81, v81, v117, v116
	v_cmp_gt_f32_e64 s[0:1], s46, v81
	v_sub_f32_e32 v80, v80, v84
	v_add_f32_e32 v47, 1.0, v47
	v_cndmask_b32_e64 v85, 0, 32, s[0:1]
	v_ldexp_f32 v81, v81, v85
	v_log_f32_e32 v81, v81
	v_div_scale_f32 v85, s[2:3], v82, v82, 1.0
	v_rcp_f32_e32 v86, v85
	v_mul_f32_e32 v84, 0x3f317217, v81
	v_fma_f32 v84, v81, s47, -v84
	v_fmac_f32_e32 v84, 0x3377d1cf, v81
	v_fmac_f32_e32 v84, 0x3f317217, v81
	v_cmp_lt_f32_e64 vcc, |v81|, s49
	v_exp_f32_e32 v40, v40
	v_mul_f32_e32 v41, 0xbfb8aa3b, v41
	v_cndmask_b32_e32 v81, v81, v84, vcc
	v_fma_f32 v84, -v85, v86, 1.0
	v_fmac_f32_e32 v86, v84, v86
	v_div_scale_f32 v84, vcc, 1.0, v82, 1.0
	v_mul_f32_e32 v87, v84, v86
	v_fma_f32 v88, -v85, v87, v84
	v_fmac_f32_e32 v87, v88, v86
	v_fma_f32 v84, -v85, v87, v84
	v_div_fmas_f32 v84, v84, v86, v87
	v_div_fixup_f32 v82, v84, v82, 1.0
	v_fma_f32 v82, v82, v119, v118
	v_cmp_gt_f32_e64 s[4:5], s46, v82
	v_add_f32_e32 v40, 1.0, v40
	v_exp_f32_e32 v41, v41
	v_cndmask_b32_e64 v84, 0, 32, s[4:5]
	v_ldexp_f32 v82, v82, v84
	v_cndmask_b32_e64 v84, 0, v193, s[0:1]
	v_div_scale_f32 v85, s[0:1], v83, v83, 1.0
	v_rcp_f32_e32 v86, v85
	v_log_f32_e32 v82, v82
	v_sub_f32_e32 v81, v81, v84
	v_add_f32_e32 v41, 1.0, v41
	v_fma_f32 v87, -v85, v86, 1.0
	v_fmac_f32_e32 v86, v87, v86
	v_div_scale_f32 v87, vcc, 1.0, v83, 1.0
	v_mul_f32_e32 v88, v87, v86
	v_fma_f32 v89, -v85, v88, v87
	v_fmac_f32_e32 v88, v89, v86
	v_fma_f32 v85, -v85, v88, v87
	v_div_fmas_f32 v85, v85, v86, v88
	v_div_fixup_f32 v83, v85, v83, 1.0
	v_fma_f32 v83, v83, v129, v128
	v_cmp_gt_f32_e32 vcc, s46, v83
	v_mul_f32_e32 v84, 0x3f317217, v82
	v_fma_f32 v84, v82, s47, -v84
	v_cndmask_b32_e64 v85, 0, 32, vcc
	v_ldexp_f32 v83, v83, v85
	v_log_f32_e32 v83, v83
	v_fmac_f32_e32 v84, 0x3377d1cf, v82
	v_fmac_f32_e32 v84, 0x3f317217, v82
	v_cmp_lt_f32_e64 s[0:1], |v82|, s49
	v_mul_f32_e32 v42, 0xbfb8aa3b, v42
	v_exp_f32_e32 v42, v42
	v_cndmask_b32_e64 v82, v82, v84, s[0:1]
	v_cndmask_b32_e64 v84, 0, v193, s[4:5]
	v_sub_f32_e32 v82, v82, v84
	v_mul_f32_e32 v84, 0x3f317217, v83
	v_fma_f32 v84, v83, s47, -v84
	v_fmac_f32_e32 v84, 0x3377d1cf, v83
	v_fmac_f32_e32 v84, 0x3f317217, v83
	v_cmp_lt_f32_e64 s[0:1], |v83|, s49
	v_add_f32_e32 v42, 1.0, v42
	v_mul_f32_e32 v43, 0xbfb8aa3b, v43
	v_cndmask_b32_e64 v83, v83, v84, s[0:1]
	v_cndmask_b32_e32 v84, 0, v193, vcc
	v_sub_f32_e32 v83, v83, v84
	global_store_dwordx4 v[96:97], v[80:83], off offset:-3568
	v_exp_f32_e32 v43, v43
	v_mul_f32_e32 v36, 0xbfb8aa3b, v36
	v_div_scale_f32 v82, s[0:1], v76, v76, 1.0
	v_rcp_f32_e32 v83, v82
	v_or_b32_e32 v80, 48, v182
	v_ashrrev_i32_e32 v81, 31, v80
	v_lshlrev_b64 v[80:81], 12, v[80:81]
	v_fma_f32 v84, -v82, v83, 1.0
	v_fmac_f32_e32 v83, v84, v83
	v_div_scale_f32 v84, vcc, 1.0, v76, 1.0
	v_mul_f32_e32 v85, v84, v83
	v_fma_f32 v86, -v82, v85, v84
	v_fmac_f32_e32 v85, v86, v83
	v_fma_f32 v82, -v82, v85, v84
	v_div_fmas_f32 v82, v82, v83, v85
	v_div_fixup_f32 v76, v82, v76, 1.0
	v_fma_f32 v76, v76, v157, v156
	v_cmp_gt_f32_e64 s[0:1], s46, v76
	v_div_scale_f32 v83, s[2:3], v77, v77, 1.0
	s_nop 0
	v_cndmask_b32_e64 v82, 0, 32, s[0:1]
	v_ldexp_f32 v76, v76, v82
	v_log_f32_e32 v76, v76
	v_rcp_f32_e32 v84, v83
	v_lshl_add_u64 v[80:81], s[58:59], 0, v[80:81]
	v_lshl_add_u64 v[80:81], v[80:81], 0, v[184:185]
	v_mul_f32_e32 v82, 0x3f317217, v76
	v_fma_f32 v82, v76, s47, -v82
	v_fmac_f32_e32 v82, 0x3377d1cf, v76
	v_fmac_f32_e32 v82, 0x3f317217, v76
	v_cmp_lt_f32_e64 vcc, |v76|, s49
	v_add_f32_e32 v43, 1.0, v43
	v_exp_f32_e32 v36, v36
	v_cndmask_b32_e32 v76, v76, v82, vcc
	v_fma_f32 v82, -v83, v84, 1.0
	v_fmac_f32_e32 v84, v82, v84
	v_div_scale_f32 v82, vcc, 1.0, v77, 1.0
	v_mul_f32_e32 v85, v82, v84
	v_fma_f32 v86, -v83, v85, v82
	v_fmac_f32_e32 v85, v86, v84
	v_fma_f32 v82, -v83, v85, v82
	v_div_fmas_f32 v82, v82, v84, v85
	v_div_fixup_f32 v77, v82, v77, 1.0
	v_fma_f32 v77, v77, v159, v158
	v_cmp_gt_f32_e64 s[4:5], s46, v77
	v_add_f32_e32 v36, 1.0, v36
	v_mul_f32_e32 v37, 0xbfb8aa3b, v37
	v_cndmask_b32_e64 v82, 0, 32, s[4:5]
	v_ldexp_f32 v77, v77, v82
	v_cndmask_b32_e64 v82, 0, v193, s[0:1]
	v_div_scale_f32 v83, s[0:1], v78, v78, 1.0
	v_rcp_f32_e32 v84, v83
	v_log_f32_e32 v77, v77
	v_sub_f32_e32 v76, v76, v82
	v_exp_f32_e32 v37, v37
	v_fma_f32 v85, -v83, v84, 1.0
	v_fmac_f32_e32 v84, v85, v84
	v_div_scale_f32 v85, vcc, 1.0, v78, 1.0
	v_mul_f32_e32 v86, v85, v84
	v_fma_f32 v87, -v83, v86, v85
	v_fmac_f32_e32 v86, v87, v84
	v_fma_f32 v83, -v83, v86, v85
	v_div_fmas_f32 v83, v83, v84, v86
	v_div_fixup_f32 v78, v83, v78, 1.0
	v_fma_f32 v78, v78, v155, v154
	v_cmp_gt_f32_e32 vcc, s46, v78
	v_mul_f32_e32 v82, 0x3f317217, v77
	v_fma_f32 v82, v77, s47, -v82
	v_cndmask_b32_e64 v83, 0, 32, vcc
	v_ldexp_f32 v78, v78, v83
	v_fmac_f32_e32 v82, 0x3377d1cf, v77
	v_log_f32_e32 v78, v78
	v_fmac_f32_e32 v82, 0x3f317217, v77
	v_cmp_lt_f32_e64 s[0:1], |v77|, s49
	v_add_f32_e32 v37, 1.0, v37
	v_mul_f32_e32 v38, 0xbfb8aa3b, v38
	v_cndmask_b32_e64 v77, v77, v82, s[0:1]
	v_div_scale_f32 v83, s[0:1], v79, v79, 1.0
	v_cndmask_b32_e64 v82, 0, v193, s[4:5]
	v_rcp_f32_e32 v84, v83
	v_sub_f32_e32 v77, v77, v82
	v_mul_f32_e32 v82, 0x3f317217, v78
	v_fma_f32 v82, v78, s47, -v82
	v_fmac_f32_e32 v82, 0x3377d1cf, v78
	v_fmac_f32_e32 v82, 0x3f317217, v78
;     __device__ __forceinline__ void operator()(const f32x4 (&acc)[2][2][4][2], const Unit& u, int wr, int wc, int fr, int fq) const {
;     ...
;                         for (int n = 0; n < 2; ++n) { f32x4 z = acc[ai][bj][m][n], o;
; #pragma unroll
;                             for (int e = 0; e < 4; ++e) { const float lb = lbv[bj][4 * n + e]; const float sg = 1.0f / (1.0f + __expf(-z[e])); o[e] = __logf(lb + (1.0f - lb) * sg); }
;                             *(f32x4*)(rowp + bj * HALF + 4 * n) = o; } }
	v_cmp_lt_f32_e64 s[0:1], |v78|, s49
	v_fma_f32 v85, -v83, v84, 1.0
	v_fmac_f32_e32 v84, v85, v84
	v_cndmask_b32_e64 v78, v78, v82, s[0:1]
	v_cndmask_b32_e32 v82, 0, v193, vcc
	v_div_scale_f32 v85, vcc, 1.0, v79, 1.0
	v_mul_f32_e32 v86, v85, v84
	v_fma_f32 v87, -v83, v86, v85
	v_fmac_f32_e32 v86, v87, v84
	v_fma_f32 v83, -v83, v86, v85
	v_div_fmas_f32 v83, v83, v84, v86
	v_div_fixup_f32 v79, v83, v79, 1.0
	v_fma_f32 v79, v79, v153, v152
	v_cmp_gt_f32_e64 s[0:1], s46, v79
	v_sub_f32_e32 v78, v78, v82
	v_exp_f32_e32 v38, v38
	v_cndmask_b32_e64 v83, 0, 32, s[0:1]
	v_ldexp_f32 v79, v79, v83
	v_log_f32_e32 v79, v79
	v_div_scale_f32 v83, s[2:3], v72, v72, 1.0
	v_rcp_f32_e32 v84, v83
	v_mul_f32_e32 v82, 0x3f317217, v79
	v_fma_f32 v82, v79, s47, -v82
	v_fmac_f32_e32 v82, 0x3377d1cf, v79
	v_fmac_f32_e32 v82, 0x3f317217, v79
	v_cmp_lt_f32_e64 vcc, |v79|, s49
	v_add_f32_e32 v38, 1.0, v38
	v_mul_f32_e32 v39, 0xbfb8aa3b, v39
	v_cndmask_b32_e32 v79, v79, v82, vcc
	v_fma_f32 v82, -v83, v84, 1.0
	v_fmac_f32_e32 v84, v82, v84
	v_div_scale_f32 v82, vcc, 1.0, v72, 1.0
	v_mul_f32_e32 v85, v82, v84
	v_fma_f32 v86, -v83, v85, v82
	v_fmac_f32_e32 v85, v86, v84
	v_fma_f32 v82, -v83, v85, v82
	v_div_fmas_f32 v82, v82, v84, v85
	v_div_fixup_f32 v72, v82, v72, 1.0
	v_fma_f32 v72, v72, v151, v150
	v_cmp_gt_f32_e32 vcc, s46, v72
	v_exp_f32_e32 v39, v39
	v_mul_f32_e32 v32, 0xbfb8aa3b, v32
	v_cndmask_b32_e64 v82, 0, 32, vcc
	v_ldexp_f32 v72, v72, v82
	v_log_f32_e32 v72, v72
	v_cndmask_b32_e64 v82, 0, v193, s[0:1]
	v_sub_f32_e32 v79, v79, v82
	global_store_dwordx4 v[80:81], v[76:79], off offset:-4096
	v_add_f32_e32 v39, 1.0, v39
	v_exp_f32_e32 v32, v32
	v_div_scale_f32 v77, s[0:1], v73, v73, 1.0
	v_rcp_f32_e32 v78, v77
	v_mul_f32_e32 v76, 0x3f317217, v72
	v_fma_f32 v76, v72, s47, -v76
	v_fmac_f32_e32 v76, 0x3377d1cf, v72
	v_fmac_f32_e32 v76, 0x3f317217, v72
	v_cmp_lt_f32_e64 s[0:1], |v72|, s49
	v_fma_f32 v79, -v77, v78, 1.0
	v_fmac_f32_e32 v78, v79, v78
	v_cndmask_b32_e64 v72, v72, v76, s[0:1]
	v_cndmask_b32_e32 v76, 0, v193, vcc
	v_div_scale_f32 v79, vcc, 1.0, v73, 1.0
	v_mul_f32_e32 v82, v79, v78
	v_fma_f32 v83, -v77, v82, v79
	v_fmac_f32_e32 v82, v83, v78
	v_fma_f32 v77, -v77, v82, v79
	v_div_fmas_f32 v77, v77, v78, v82
	v_div_fixup_f32 v73, v77, v73, 1.0
	v_fma_f32 v73, v73, v125, v124
	v_cmp_gt_f32_e64 s[0:1], s46, v73
	v_sub_f32_e32 v72, v72, v76
	v_add_f32_e32 v32, 1.0, v32
	v_cndmask_b32_e64 v77, 0, 32, s[0:1]
	v_ldexp_f32 v73, v73, v77
	v_log_f32_e32 v73, v73
	v_div_scale_f32 v77, s[2:3], v74, v74, 1.0
	v_rcp_f32_e32 v78, v77
	v_mul_f32_e32 v76, 0x3f317217, v73
	v_fma_f32 v76, v73, s47, -v76
	v_fmac_f32_e32 v76, 0x3377d1cf, v73
	v_fmac_f32_e32 v76, 0x3f317217, v73
	v_cmp_lt_f32_e64 vcc, |v73|, s49
	v_mul_f32_e32 v33, 0xbfb8aa3b, v33
	v_exp_f32_e32 v33, v33
	v_cndmask_b32_e32 v73, v73, v76, vcc
	v_fma_f32 v76, -v77, v78, 1.0
	v_fmac_f32_e32 v78, v76, v78
	v_div_scale_f32 v76, vcc, 1.0, v74, 1.0
	v_mul_f32_e32 v79, v76, v78
	v_fma_f32 v82, -v77, v79, v76
	v_fmac_f32_e32 v79, v82, v78
	v_fma_f32 v76, -v77, v79, v76
	v_div_fmas_f32 v76, v76, v78, v79
	v_div_fixup_f32 v74, v76, v74, 1.0
	v_fma_f32 v74, v74, v127, v126
	v_cmp_gt_f32_e64 s[4:5], s46, v74
	v_add_f32_e32 v33, 1.0, v33
	v_mul_f32_e32 v34, 0xbfb8aa3b, v34
	v_cndmask_b32_e64 v76, 0, 32, s[4:5]
	v_ldexp_f32 v74, v74, v76
	v_cndmask_b32_e64 v76, 0, v193, s[0:1]
	v_div_scale_f32 v77, s[0:1], v75, v75, 1.0
	v_rcp_f32_e32 v78, v77
	v_log_f32_e32 v74, v74
	v_sub_f32_e32 v73, v73, v76
	v_exp_f32_e32 v34, v34
	v_fma_f32 v79, -v77, v78, 1.0
	v_fmac_f32_e32 v78, v79, v78
	v_div_scale_f32 v79, vcc, 1.0, v75, 1.0
	v_mul_f32_e32 v82, v79, v78
	v_fma_f32 v83, -v77, v82, v79
	v_fmac_f32_e32 v82, v83, v78
	v_fma_f32 v77, -v77, v82, v79
	v_div_fmas_f32 v77, v77, v78, v82
	v_div_fixup_f32 v75, v77, v75, 1.0
	v_fma_f32 v75, v75, v145, v144
	v_cmp_gt_f32_e32 vcc, s46, v75
	v_mul_f32_e32 v76, 0x3f317217, v74
	v_fma_f32 v76, v74, s47, -v76
	v_cndmask_b32_e64 v77, 0, 32, vcc
	v_ldexp_f32 v75, v75, v77
	v_log_f32_e32 v75, v75
	v_fmac_f32_e32 v76, 0x3377d1cf, v74
	v_fmac_f32_e32 v76, 0x3f317217, v74
	v_cmp_lt_f32_e64 s[0:1], |v74|, s49
	v_add_f32_e32 v34, 1.0, v34
	v_mul_f32_e32 v35, 0xbfb8aa3b, v35
	v_cndmask_b32_e64 v74, v74, v76, s[0:1]
	v_cndmask_b32_e64 v76, 0, v193, s[4:5]
	v_sub_f32_e32 v74, v74, v76
	v_mul_f32_e32 v76, 0x3f317217, v75
	v_div_scale_f32 v77, s[0:1], v68, v68, 1.0
	v_fma_f32 v76, v75, s47, -v76
	v_rcp_f32_e32 v78, v77
	v_fmac_f32_e32 v76, 0x3377d1cf, v75
	v_fmac_f32_e32 v76, 0x3f317217, v75
	v_cmp_lt_f32_e64 s[0:1], |v75|, s49
	v_exp_f32_e32 v35, v35
	v_mul_f32_e32 v28, 0xbfb8aa3b, v28
	v_cndmask_b32_e64 v75, v75, v76, s[0:1]
	v_cndmask_b32_e32 v76, 0, v193, vcc
	v_sub_f32_e32 v75, v75, v76
	v_fma_f32 v76, -v77, v78, 1.0
	v_fmac_f32_e32 v78, v76, v78
	v_div_scale_f32 v76, vcc, 1.0, v68, 1.0
	v_mul_f32_e32 v79, v76, v78
	v_fma_f32 v82, -v77, v79, v76
	v_fmac_f32_e32 v79, v82, v78
	v_fma_f32 v76, -v77, v79, v76
	v_div_fmas_f32 v76, v76, v78, v79
	v_div_fixup_f32 v68, v76, v68, 1.0
	v_fma_f32 v68, v68, v143, v142
	v_cmp_gt_f32_e64 s[0:1], s46, v68
	global_store_dwordx4 v[80:81], v[72:75], off offset:-4080
	v_add_f32_e32 v35, 1.0, v35
	v_cndmask_b32_e64 v76, 0, 32, s[0:1]
	v_ldexp_f32 v68, v68, v76
	v_log_f32_e32 v68, v68
	v_div_scale_f32 v73, s[2:3], v69, v69, 1.0
	v_rcp_f32_e32 v74, v73
	v_mul_f32_e32 v72, 0x3f317217, v68
	v_fma_f32 v72, v68, s47, -v72
	v_fmac_f32_e32 v72, 0x3377d1cf, v68
	v_fmac_f32_e32 v72, 0x3f317217, v68
	v_cmp_lt_f32_e64 vcc, |v68|, s49
	v_exp_f32_e32 v28, v28
	v_mul_f32_e32 v29, 0xbfb8aa3b, v29
	v_cndmask_b32_e32 v68, v68, v72, vcc
	v_fma_f32 v72, -v73, v74, 1.0
	v_fmac_f32_e32 v74, v72, v74
;     __device__ __forceinline__ void operator()(const f32x4 (&acc)[2][2][4][2], const Unit& u, int wr, int wc, int fr, int fq) const {
;     ...
;                         for (int n = 0; n < 2; ++n) { f32x4 z = acc[ai][bj][m][n], o;
; #pragma unroll
;                             for (int e = 0; e < 4; ++e) { const float lb = lbv[bj][4 * n + e]; const float sg = 1.0f / (1.0f + __expf(-z[e])); o[e] = __logf(lb + (1.0f - lb) * sg); }
;                             *(f32x4*)(rowp + bj * HALF + 4 * n) = o; } }
	v_div_scale_f32 v72, vcc, 1.0, v69, 1.0
	v_mul_f32_e32 v75, v72, v74
	v_fma_f32 v76, -v73, v75, v72
	v_fmac_f32_e32 v75, v76, v74
	v_fma_f32 v72, -v73, v75, v72
	v_div_fmas_f32 v72, v72, v74, v75
	v_div_fixup_f32 v69, v72, v69, 1.0
	v_fma_f32 v69, v69, v121, v120
	v_cmp_gt_f32_e64 s[4:5], s46, v69
	v_add_f32_e32 v28, 1.0, v28
	v_exp_f32_e32 v29, v29
	v_cndmask_b32_e64 v72, 0, 32, s[4:5]
	v_ldexp_f32 v69, v69, v72
	v_cndmask_b32_e64 v72, 0, v193, s[0:1]
	v_div_scale_f32 v73, s[0:1], v70, v70, 1.0
	v_rcp_f32_e32 v74, v73
	v_log_f32_e32 v69, v69
	v_sub_f32_e32 v68, v68, v72
	v_add_f32_e32 v29, 1.0, v29
	v_fma_f32 v75, -v73, v74, 1.0
	v_fmac_f32_e32 v74, v75, v74
	v_div_scale_f32 v75, vcc, 1.0, v70, 1.0
	v_mul_f32_e32 v76, v75, v74
	v_fma_f32 v77, -v73, v76, v75
	v_fmac_f32_e32 v76, v77, v74
	v_fma_f32 v73, -v73, v76, v75
	v_div_fmas_f32 v73, v73, v74, v76
	v_div_fixup_f32 v70, v73, v70, 1.0
	v_fma_f32 v70, v70, v123, v122
	v_cmp_gt_f32_e32 vcc, s46, v70
	v_mul_f32_e32 v72, 0x3f317217, v69
	v_fma_f32 v72, v69, s47, -v72
	v_cndmask_b32_e64 v73, 0, 32, vcc
	v_ldexp_f32 v70, v70, v73
	v_fmac_f32_e32 v72, 0x3377d1cf, v69
	v_log_f32_e32 v70, v70
	v_fmac_f32_e32 v72, 0x3f317217, v69
	v_cmp_lt_f32_e64 s[0:1], |v69|, s49
	v_mul_f32_e32 v30, 0xbfb8aa3b, v30
	v_exp_f32_e32 v30, v30
	v_cndmask_b32_e64 v69, v69, v72, s[0:1]
	v_div_scale_f32 v73, s[0:1], v71, v71, 1.0
	v_cndmask_b32_e64 v72, 0, v193, s[4:5]
	v_rcp_f32_e32 v74, v73
	v_sub_f32_e32 v69, v69, v72
	v_mul_f32_e32 v72, 0x3f317217, v70
	v_fma_f32 v72, v70, s47, -v72
	v_fmac_f32_e32 v72, 0x3377d1cf, v70
	v_fmac_f32_e32 v72, 0x3f317217, v70
	v_cmp_lt_f32_e64 s[0:1], |v70|, s49
	v_fma_f32 v75, -v73, v74, 1.0
	v_fmac_f32_e32 v74, v75, v74
	v_cndmask_b32_e64 v70, v70, v72, s[0:1]
	v_cndmask_b32_e32 v72, 0, v193, vcc
	v_div_scale_f32 v75, vcc, 1.0, v71, 1.0
	v_mul_f32_e32 v76, v75, v74
	v_fma_f32 v77, -v73, v76, v75
	v_fmac_f32_e32 v76, v77, v74
	v_fma_f32 v73, -v73, v76, v75
	v_div_fmas_f32 v73, v73, v74, v76
	v_div_fixup_f32 v71, v73, v71, 1.0
	v_fma_f32 v71, v71, v137, v136
	v_cmp_gt_f32_e64 s[0:1], s46, v71
	v_sub_f32_e32 v70, v70, v72
	v_add_f32_e32 v30, 1.0, v30
	v_cndmask_b32_e64 v73, 0, 32, s[0:1]
	v_ldexp_f32 v71, v71, v73
	v_log_f32_e32 v71, v71
	v_div_scale_f32 v73, s[2:3], v64, v64, 1.0
	v_rcp_f32_e32 v74, v73
	v_mul_f32_e32 v72, 0x3f317217, v71
	v_fma_f32 v72, v71, s47, -v72
	v_fmac_f32_e32 v72, 0x3377d1cf, v71
	v_fmac_f32_e32 v72, 0x3f317217, v71
	v_cmp_lt_f32_e64 vcc, |v71|, s49
	v_mul_f32_e32 v31, 0xbfb8aa3b, v31
	v_exp_f32_e32 v31, v31
	v_cndmask_b32_e32 v71, v71, v72, vcc
	v_fma_f32 v72, -v73, v74, 1.0
	v_fmac_f32_e32 v74, v72, v74
	v_div_scale_f32 v72, vcc, 1.0, v64, 1.0
	v_mul_f32_e32 v75, v72, v74
	v_fma_f32 v76, -v73, v75, v72
	v_fmac_f32_e32 v75, v76, v74
	v_fma_f32 v72, -v73, v75, v72
	v_div_fmas_f32 v72, v72, v74, v75
	v_div_fixup_f32 v64, v72, v64, 1.0
	v_fma_f32 v64, v64, v135, v134
	v_cmp_gt_f32_e32 vcc, s46, v64
	v_add_f32_e32 v31, 1.0, v31
	v_mul_f32_e32 v24, 0xbfb8aa3b, v24
	v_cndmask_b32_e64 v72, 0, 32, vcc
	v_ldexp_f32 v64, v64, v72
	v_log_f32_e32 v64, v64
	v_cndmask_b32_e64 v72, 0, v193, s[0:1]
	v_sub_f32_e32 v71, v71, v72
	global_store_dwordx4 v[80:81], v[68:71], off offset:-3584
	v_exp_f32_e32 v24, v24
	v_mul_f32_e32 v25, 0xbfb8aa3b, v25
	v_div_scale_f32 v69, s[0:1], v65, v65, 1.0
	v_rcp_f32_e32 v70, v69
	v_mul_f32_e32 v68, 0x3f317217, v64
	v_fma_f32 v68, v64, s47, -v68
	v_fmac_f32_e32 v68, 0x3377d1cf, v64
	v_fmac_f32_e32 v68, 0x3f317217, v64
	v_cmp_lt_f32_e64 s[0:1], |v64|, s49
	v_fma_f32 v71, -v69, v70, 1.0
	v_fmac_f32_e32 v70, v71, v70
	v_cndmask_b32_e64 v64, v64, v68, s[0:1]
	v_cndmask_b32_e32 v68, 0, v193, vcc
	v_div_scale_f32 v71, vcc, 1.0, v65, 1.0
	v_mul_f32_e32 v72, v71, v70
	v_fma_f32 v73, -v69, v72, v71
	v_fmac_f32_e32 v72, v73, v70
	v_fma_f32 v69, -v69, v72, v71
	v_div_fmas_f32 v69, v69, v70, v72
	v_div_fixup_f32 v65, v69, v65, 1.0
	v_fma_f32 v65, v65, v117, v116
	v_cmp_gt_f32_e64 s[0:1], s46, v65
	v_sub_f32_e32 v64, v64, v68
	v_add_f32_e32 v24, 1.0, v24
	v_cndmask_b32_e64 v69, 0, 32, s[0:1]
	v_ldexp_f32 v65, v65, v69
	v_log_f32_e32 v65, v65
	v_div_scale_f32 v69, s[2:3], v66, v66, 1.0
	v_rcp_f32_e32 v70, v69
	v_mul_f32_e32 v68, 0x3f317217, v65
	v_fma_f32 v68, v65, s47, -v68
	v_fmac_f32_e32 v68, 0x3377d1cf, v65
	v_fmac_f32_e32 v68, 0x3f317217, v65
	v_cmp_lt_f32_e64 vcc, |v65|, s49
	s_mov_b64 s[2:3], 0x80000
	v_exp_f32_e32 v25, v25
	v_cndmask_b32_e32 v65, v65, v68, vcc
	v_fma_f32 v68, -v69, v70, 1.0
	v_fmac_f32_e32 v70, v68, v70
	v_div_scale_f32 v68, vcc, 1.0, v66, 1.0
	v_mul_f32_e32 v71, v68, v70
	v_fma_f32 v72, -v69, v71, v68
	v_fmac_f32_e32 v71, v72, v70
	v_fma_f32 v68, -v69, v71, v68
	v_div_fmas_f32 v68, v68, v70, v71
	v_div_fixup_f32 v66, v68, v66, 1.0
	v_fma_f32 v66, v66, v119, v118
	v_cmp_gt_f32_e64 s[4:5], s46, v66
	v_add_f32_e32 v25, 1.0, v25
	v_mul_f32_e32 v26, 0xbfb8aa3b, v26
	v_cndmask_b32_e64 v68, 0, 32, s[4:5]
	v_ldexp_f32 v66, v66, v68
	v_cndmask_b32_e64 v68, 0, v193, s[0:1]
	v_div_scale_f32 v69, s[0:1], v67, v67, 1.0
	v_rcp_f32_e32 v70, v69
	v_log_f32_e32 v66, v66
	v_sub_f32_e32 v65, v65, v68
	v_exp_f32_e32 v26, v26
	v_fma_f32 v71, -v69, v70, 1.0
	v_fmac_f32_e32 v70, v71, v70
	v_div_scale_f32 v71, vcc, 1.0, v67, 1.0
	v_mul_f32_e32 v72, v71, v70
	v_fma_f32 v73, -v69, v72, v71
	v_fmac_f32_e32 v72, v73, v70
	v_fma_f32 v69, -v69, v72, v71
	v_div_fmas_f32 v69, v69, v70, v72
	v_div_fixup_f32 v67, v69, v67, 1.0
	v_fma_f32 v67, v67, v129, v128
	v_cmp_gt_f32_e32 vcc, s46, v67
	v_mul_f32_e32 v68, 0x3f317217, v66
	v_fma_f32 v68, v66, s47, -v68
	v_cndmask_b32_e64 v69, 0, 32, vcc
	v_ldexp_f32 v67, v67, v69
	v_log_f32_e32 v67, v67
	v_fmac_f32_e32 v68, 0x3377d1cf, v66
;     __device__ __forceinline__ void operator()(const f32x4 (&acc)[2][2][4][2], const Unit& u, int wr, int wc, int fr, int fq) const {
;     ...
;                         for (int n = 0; n < 2; ++n) { f32x4 z = acc[ai][bj][m][n], o;
; #pragma unroll
;                             for (int e = 0; e < 4; ++e) { const float lb = lbv[bj][4 * n + e]; const float sg = 1.0f / (1.0f + __expf(-z[e])); o[e] = __logf(lb + (1.0f - lb) * sg); }
;                             *(f32x4*)(rowp + bj * HALF + 4 * n) = o; } }
	v_fmac_f32_e32 v68, 0x3f317217, v66
	v_cmp_lt_f32_e64 s[0:1], |v66|, s49
	v_add_f32_e32 v26, 1.0, v26
	v_mul_f32_e32 v27, 0xbfb8aa3b, v27
	v_cndmask_b32_e64 v66, v66, v68, s[0:1]
	v_cndmask_b32_e64 v68, 0, v193, s[4:5]
	v_sub_f32_e32 v66, v66, v68
	v_mul_f32_e32 v68, 0x3f317217, v67
	v_fma_f32 v68, v67, s47, -v68
	v_fmac_f32_e32 v68, 0x3377d1cf, v67
	v_fmac_f32_e32 v68, 0x3f317217, v67
	v_cmp_lt_f32_e64 s[0:1], |v67|, s49
	v_exp_f32_e32 v27, v27
	v_mul_f32_e32 v20, 0xbfb8aa3b, v20
	v_cndmask_b32_e64 v67, v67, v68, s[0:1]
	v_cndmask_b32_e32 v68, 0, v193, vcc
	v_sub_f32_e32 v67, v67, v68
	v_div_scale_f32 v68, s[0:1], v60, v60, 1.0
	v_rcp_f32_e32 v69, v68
	global_store_dwordx4 v[80:81], v[64:67], off offset:-3568
	v_add_f32_e32 v27, 1.0, v27
	v_exp_f32_e32 v20, v20
	v_fma_f32 v64, -v68, v69, 1.0
	v_fmac_f32_e32 v69, v64, v69
	v_div_scale_f32 v64, vcc, 1.0, v60, 1.0
	v_mul_f32_e32 v65, v64, v69
	v_fma_f32 v66, -v68, v65, v64
	v_fmac_f32_e32 v65, v66, v69
	v_fma_f32 v64, -v68, v65, v64
	v_div_fmas_f32 v64, v64, v69, v65
	v_div_fixup_f32 v60, v64, v60, 1.0
	v_fma_f32 v60, v60, v157, v156
	v_cmp_gt_f32_e64 s[0:1], s46, v60
	v_add_f32_e32 v20, 1.0, v20
	v_mul_f32_e32 v21, 0xbfb8aa3b, v21
	v_cndmask_b32_e64 v64, 0, 32, s[0:1]
	v_ldexp_f32 v60, v60, v64
	v_log_f32_e32 v60, v60
	v_lshl_add_u64 v[64:65], v[180:181], 0, s[2:3]
	v_div_scale_f32 v67, s[2:3], v61, v61, 1.0
	v_mul_f32_e32 v66, 0x3f317217, v60
	v_rcp_f32_e32 v68, v67
	v_fma_f32 v66, v60, s47, -v66
	v_fmac_f32_e32 v66, 0x3377d1cf, v60
	v_fmac_f32_e32 v66, 0x3f317217, v60
	v_cmp_lt_f32_e64 vcc, |v60|, s49
	v_exp_f32_e32 v21, v21
	v_mul_f32_e32 v22, 0xbfb8aa3b, v22
	v_cndmask_b32_e32 v60, v60, v66, vcc
	v_fma_f32 v66, -v67, v68, 1.0
	v_fmac_f32_e32 v68, v66, v68
	v_div_scale_f32 v66, vcc, 1.0, v61, 1.0
	v_mul_f32_e32 v69, v66, v68
	v_fma_f32 v70, -v67, v69, v66
	v_fmac_f32_e32 v69, v70, v68
	v_fma_f32 v66, -v67, v69, v66
	v_div_fmas_f32 v66, v66, v68, v69
	v_div_fixup_f32 v61, v66, v61, 1.0
	v_fma_f32 v61, v61, v159, v158
	v_cmp_gt_f32_e64 s[4:5], s46, v61
	v_add_f32_e32 v21, 1.0, v21
	v_exp_f32_e32 v22, v22
	v_cndmask_b32_e64 v66, 0, 32, s[4:5]
	v_ldexp_f32 v61, v61, v66
	v_cndmask_b32_e64 v66, 0, v193, s[0:1]
	v_div_scale_f32 v67, s[0:1], v62, v62, 1.0
	v_rcp_f32_e32 v68, v67
	v_log_f32_e32 v61, v61
	v_sub_f32_e32 v60, v60, v66
	v_add_f32_e32 v22, 1.0, v22
	v_fma_f32 v69, -v67, v68, 1.0
	v_fmac_f32_e32 v68, v69, v68
	v_div_scale_f32 v69, vcc, 1.0, v62, 1.0
	v_mul_f32_e32 v70, v69, v68
	v_fma_f32 v71, -v67, v70, v69
	v_fmac_f32_e32 v70, v71, v68
	v_fma_f32 v67, -v67, v70, v69
	v_div_fmas_f32 v67, v67, v68, v70
	v_div_fixup_f32 v62, v67, v62, 1.0
	v_fma_f32 v62, v62, v155, v154
	v_cmp_gt_f32_e32 vcc, s46, v62
	v_mul_f32_e32 v66, 0x3f317217, v61
	v_fma_f32 v66, v61, s47, -v66
	v_cndmask_b32_e64 v67, 0, 32, vcc
	v_ldexp_f32 v62, v62, v67
	v_fmac_f32_e32 v66, 0x3377d1cf, v61
	v_log_f32_e32 v62, v62
	v_fmac_f32_e32 v66, 0x3f317217, v61
	v_cmp_lt_f32_e64 s[0:1], |v61|, s49
	v_mul_f32_e32 v23, 0xbfb8aa3b, v23
	v_exp_f32_e32 v23, v23
	v_cndmask_b32_e64 v61, v61, v66, s[0:1]
	v_div_scale_f32 v67, s[0:1], v63, v63, 1.0
	v_cndmask_b32_e64 v66, 0, v193, s[4:5]
	v_rcp_f32_e32 v68, v67
	v_sub_f32_e32 v61, v61, v66
	v_mul_f32_e32 v66, 0x3f317217, v62
	v_fma_f32 v66, v62, s47, -v66
	v_fmac_f32_e32 v66, 0x3377d1cf, v62
	v_fmac_f32_e32 v66, 0x3f317217, v62
	v_cmp_lt_f32_e64 s[0:1], |v62|, s49
	v_fma_f32 v69, -v67, v68, 1.0
	v_fmac_f32_e32 v68, v69, v68
	v_cndmask_b32_e64 v62, v62, v66, s[0:1]
	v_cndmask_b32_e32 v66, 0, v193, vcc
	v_div_scale_f32 v69, vcc, 1.0, v63, 1.0
	v_mul_f32_e32 v70, v69, v68
	v_fma_f32 v71, -v67, v70, v69
	v_fmac_f32_e32 v70, v71, v68
	v_fma_f32 v67, -v67, v70, v69
	v_div_fmas_f32 v67, v67, v68, v70
	v_div_fixup_f32 v63, v67, v63, 1.0
	v_fma_f32 v63, v63, v153, v152
	v_cmp_gt_f32_e64 s[0:1], s46, v63
	v_sub_f32_e32 v62, v62, v66
	v_add_f32_e32 v23, 1.0, v23
	v_cndmask_b32_e64 v67, 0, 32, s[0:1]
	v_ldexp_f32 v63, v63, v67
	v_log_f32_e32 v63, v63
	v_div_scale_f32 v67, s[2:3], v56, v56, 1.0
	v_rcp_f32_e32 v68, v67
	v_mul_f32_e32 v66, 0x3f317217, v63
	v_fma_f32 v66, v63, s47, -v66
	v_fmac_f32_e32 v66, 0x3377d1cf, v63
	v_fmac_f32_e32 v66, 0x3f317217, v63
	v_cmp_lt_f32_e64 vcc, |v63|, s49
	v_mul_f32_e32 v16, 0xbfb8aa3b, v16
	v_exp_f32_e32 v16, v16
	v_cndmask_b32_e32 v63, v63, v66, vcc
	v_fma_f32 v66, -v67, v68, 1.0
	v_fmac_f32_e32 v68, v66, v68
	v_div_scale_f32 v66, vcc, 1.0, v56, 1.0
	v_mul_f32_e32 v69, v66, v68
	v_fma_f32 v70, -v67, v69, v66
	v_fmac_f32_e32 v69, v70, v68
	v_fma_f32 v66, -v67, v69, v66
	v_div_fmas_f32 v66, v66, v68, v69
	v_div_fixup_f32 v56, v66, v56, 1.0
	v_fma_f32 v56, v56, v151, v150
	v_cmp_gt_f32_e32 vcc, s46, v56
	v_add_f32_e32 v16, 1.0, v16
	v_mul_f32_e32 v17, 0xbfb8aa3b, v17
	v_cndmask_b32_e64 v66, 0, 32, vcc
	v_ldexp_f32 v56, v56, v66
	v_log_f32_e32 v56, v56
	v_cndmask_b32_e64 v66, 0, v193, s[0:1]
	v_sub_f32_e32 v63, v63, v66
	global_store_dwordx4 v[64:65], v[60:63], off offset:-4096
	v_exp_f32_e32 v17, v17
	v_mul_f32_e32 v18, 0xbfb8aa3b, v18
	v_div_scale_f32 v61, s[0:1], v57, v57, 1.0
	v_rcp_f32_e32 v62, v61
	v_mul_f32_e32 v60, 0x3f317217, v56
	v_fma_f32 v60, v56, s47, -v60
	v_fmac_f32_e32 v60, 0x3377d1cf, v56
	v_fmac_f32_e32 v60, 0x3f317217, v56
	v_cmp_lt_f32_e64 s[0:1], |v56|, s49
	v_fma_f32 v63, -v61, v62, 1.0
	v_fmac_f32_e32 v62, v63, v62
	v_cndmask_b32_e64 v56, v56, v60, s[0:1]
	v_cndmask_b32_e32 v60, 0, v193, vcc
	v_div_scale_f32 v63, vcc, 1.0, v57, 1.0
	v_mul_f32_e32 v66, v63, v62
	v_fma_f32 v67, -v61, v66, v63
	v_fmac_f32_e32 v66, v67, v62
	v_fma_f32 v61, -v61, v66, v63
	v_div_fmas_f32 v61, v61, v62, v66
	v_div_fixup_f32 v57, v61, v57, 1.0
;     __device__ __forceinline__ void operator()(const f32x4 (&acc)[2][2][4][2], const Unit& u, int wr, int wc, int fr, int fq) const {
;     ...
;                         for (int n = 0; n < 2; ++n) { f32x4 z = acc[ai][bj][m][n], o;
; #pragma unroll
;                             for (int e = 0; e < 4; ++e) { const float lb = lbv[bj][4 * n + e]; const float sg = 1.0f / (1.0f + __expf(-z[e])); o[e] = __logf(lb + (1.0f - lb) * sg); }
;                             *(f32x4*)(rowp + bj * HALF + 4 * n) = o; } }
	v_fma_f32 v57, v57, v125, v124
	v_cmp_gt_f32_e64 s[0:1], s46, v57
	v_sub_f32_e32 v56, v56, v60
	v_add_f32_e32 v17, 1.0, v17
	v_cndmask_b32_e64 v61, 0, 32, s[0:1]
	v_ldexp_f32 v57, v57, v61
	v_log_f32_e32 v57, v57
	v_div_scale_f32 v61, s[2:3], v58, v58, 1.0
	v_rcp_f32_e32 v62, v61
	v_mul_f32_e32 v60, 0x3f317217, v57
	v_fma_f32 v60, v57, s47, -v60
	v_fmac_f32_e32 v60, 0x3377d1cf, v57
	v_fmac_f32_e32 v60, 0x3f317217, v57
	v_cmp_lt_f32_e64 vcc, |v57|, s49
	v_exp_f32_e32 v18, v18
	v_mul_f32_e32 v19, 0xbfb8aa3b, v19
	v_cndmask_b32_e32 v57, v57, v60, vcc
	v_fma_f32 v60, -v61, v62, 1.0
	v_fmac_f32_e32 v62, v60, v62
	v_div_scale_f32 v60, vcc, 1.0, v58, 1.0
	v_mul_f32_e32 v63, v60, v62
	v_fma_f32 v66, -v61, v63, v60
	v_fmac_f32_e32 v63, v66, v62
	v_fma_f32 v60, -v61, v63, v60
	v_div_fmas_f32 v60, v60, v62, v63
	v_div_fixup_f32 v58, v60, v58, 1.0
	v_fma_f32 v58, v58, v127, v126
	v_cmp_gt_f32_e64 s[4:5], s46, v58
	v_add_f32_e32 v18, 1.0, v18
	v_exp_f32_e32 v19, v19
	v_cndmask_b32_e64 v60, 0, 32, s[4:5]
	v_ldexp_f32 v58, v58, v60
	v_cndmask_b32_e64 v60, 0, v193, s[0:1]
	v_div_scale_f32 v61, s[0:1], v59, v59, 1.0
	v_rcp_f32_e32 v62, v61
	v_log_f32_e32 v58, v58
	v_sub_f32_e32 v57, v57, v60
	v_add_f32_e32 v19, 1.0, v19
	v_fma_f32 v63, -v61, v62, 1.0
	v_fmac_f32_e32 v62, v63, v62
	v_div_scale_f32 v63, vcc, 1.0, v59, 1.0
	v_mul_f32_e32 v66, v63, v62
	v_fma_f32 v67, -v61, v66, v63
	v_fmac_f32_e32 v66, v67, v62
	v_fma_f32 v61, -v61, v66, v63
	v_div_fmas_f32 v61, v61, v62, v66
	v_div_fixup_f32 v59, v61, v59, 1.0
	v_fma_f32 v59, v59, v145, v144
	v_cmp_gt_f32_e32 vcc, s46, v59
	v_mul_f32_e32 v60, 0x3f317217, v58
	v_fma_f32 v60, v58, s47, -v60
	v_cndmask_b32_e64 v61, 0, 32, vcc
	v_ldexp_f32 v59, v59, v61
	v_log_f32_e32 v59, v59
	v_fmac_f32_e32 v60, 0x3377d1cf, v58
	v_fmac_f32_e32 v60, 0x3f317217, v58
	v_cmp_lt_f32_e64 s[0:1], |v58|, s49
	v_mul_f32_e32 v12, 0xbfb8aa3b, v12
	v_exp_f32_e32 v12, v12
	v_cndmask_b32_e64 v58, v58, v60, s[0:1]
	v_cndmask_b32_e64 v60, 0, v193, s[4:5]
	v_sub_f32_e32 v58, v58, v60
	v_mul_f32_e32 v60, 0x3f317217, v59
	v_div_scale_f32 v61, s[0:1], v52, v52, 1.0
	v_fma_f32 v60, v59, s47, -v60
	v_rcp_f32_e32 v62, v61
	v_fmac_f32_e32 v60, 0x3377d1cf, v59
	v_fmac_f32_e32 v60, 0x3f317217, v59
	v_cmp_lt_f32_e64 s[0:1], |v59|, s49
	v_add_f32_e32 v12, 1.0, v12
	v_mul_f32_e32 v13, 0xbfb8aa3b, v13
	v_cndmask_b32_e64 v59, v59, v60, s[0:1]
	v_cndmask_b32_e32 v60, 0, v193, vcc
	v_sub_f32_e32 v59, v59, v60
	v_fma_f32 v60, -v61, v62, 1.0
	v_fmac_f32_e32 v62, v60, v62
	v_div_scale_f32 v60, vcc, 1.0, v52, 1.0
	v_mul_f32_e32 v63, v60, v62
	v_fma_f32 v66, -v61, v63, v60
	v_fmac_f32_e32 v63, v66, v62
	v_fma_f32 v60, -v61, v63, v60
	v_div_fmas_f32 v60, v60, v62, v63
	v_div_fixup_f32 v52, v60, v52, 1.0
	v_fma_f32 v52, v52, v143, v142
	v_cmp_gt_f32_e64 s[0:1], s46, v52
	global_store_dwordx4 v[64:65], v[56:59], off offset:-4080
	v_exp_f32_e32 v13, v13
	v_cndmask_b32_e64 v60, 0, 32, s[0:1]
	v_ldexp_f32 v52, v52, v60
	v_log_f32_e32 v52, v52
	v_div_scale_f32 v57, s[2:3], v53, v53, 1.0
	v_rcp_f32_e32 v58, v57
	v_mul_f32_e32 v56, 0x3f317217, v52
	v_fma_f32 v56, v52, s47, -v56
	v_fmac_f32_e32 v56, 0x3377d1cf, v52
	v_fmac_f32_e32 v56, 0x3f317217, v52
	v_cmp_lt_f32_e64 vcc, |v52|, s49
	v_add_f32_e32 v13, 1.0, v13
	v_mul_f32_e32 v14, 0xbfb8aa3b, v14
	v_cndmask_b32_e32 v52, v52, v56, vcc
	v_fma_f32 v56, -v57, v58, 1.0
	v_fmac_f32_e32 v58, v56, v58
	v_div_scale_f32 v56, vcc, 1.0, v53, 1.0
	v_mul_f32_e32 v59, v56, v58
	v_fma_f32 v60, -v57, v59, v56
	v_fmac_f32_e32 v59, v60, v58
	v_fma_f32 v56, -v57, v59, v56
	v_div_fmas_f32 v56, v56, v58, v59
	v_div_fixup_f32 v53, v56, v53, 1.0
	v_fma_f32 v53, v53, v121, v120
	v_cmp_gt_f32_e64 s[4:5], s46, v53
	v_exp_f32_e32 v14, v14
	v_mul_f32_e32 v15, 0xbfb8aa3b, v15
	v_cndmask_b32_e64 v56, 0, 32, s[4:5]
	v_ldexp_f32 v53, v53, v56
	v_cndmask_b32_e64 v56, 0, v193, s[0:1]
	v_div_scale_f32 v57, s[0:1], v54, v54, 1.0
	v_rcp_f32_e32 v58, v57
	v_log_f32_e32 v53, v53
	v_sub_f32_e32 v52, v52, v56
	v_add_f32_e32 v14, 1.0, v14
	v_fma_f32 v59, -v57, v58, 1.0
	v_fmac_f32_e32 v58, v59, v58
	v_div_scale_f32 v59, vcc, 1.0, v54, 1.0
	v_mul_f32_e32 v60, v59, v58
	v_fma_f32 v61, -v57, v60, v59
	v_fmac_f32_e32 v60, v61, v58
	v_fma_f32 v57, -v57, v60, v59
	v_div_fmas_f32 v57, v57, v58, v60
	v_div_fixup_f32 v54, v57, v54, 1.0
	v_fma_f32 v54, v54, v123, v122
	v_cmp_gt_f32_e32 vcc, s46, v54
	v_mul_f32_e32 v56, 0x3f317217, v53
	v_fma_f32 v56, v53, s47, -v56
	v_cndmask_b32_e64 v57, 0, 32, vcc
	v_ldexp_f32 v54, v54, v57
	v_fmac_f32_e32 v56, 0x3377d1cf, v53
	v_log_f32_e32 v54, v54
	v_fmac_f32_e32 v56, 0x3f317217, v53
	v_cmp_lt_f32_e64 s[0:1], |v53|, s49
	v_exp_f32_e32 v15, v15
	v_mul_f32_e32 v8, 0xbfb8aa3b, v8
	v_cndmask_b32_e64 v53, v53, v56, s[0:1]
	v_div_scale_f32 v57, s[0:1], v55, v55, 1.0
	v_cndmask_b32_e64 v56, 0, v193, s[4:5]
	v_rcp_f32_e32 v58, v57
	v_sub_f32_e32 v53, v53, v56
	v_mul_f32_e32 v56, 0x3f317217, v54
	v_fma_f32 v56, v54, s47, -v56
	v_fmac_f32_e32 v56, 0x3377d1cf, v54
	v_fmac_f32_e32 v56, 0x3f317217, v54
	v_cmp_lt_f32_e64 s[0:1], |v54|, s49
	v_fma_f32 v59, -v57, v58, 1.0
	v_fmac_f32_e32 v58, v59, v58
	v_cndmask_b32_e64 v54, v54, v56, s[0:1]
	v_cndmask_b32_e32 v56, 0, v193, vcc
	v_div_scale_f32 v59, vcc, 1.0, v55, 1.0
	v_mul_f32_e32 v60, v59, v58
	v_fma_f32 v61, -v57, v60, v59
	v_fmac_f32_e32 v60, v61, v58
	v_fma_f32 v57, -v57, v60, v59
	v_div_fmas_f32 v57, v57, v58, v60
	v_div_fixup_f32 v55, v57, v55, 1.0
	v_fma_f32 v55, v55, v137, v136
	v_cmp_gt_f32_e64 s[0:1], s46, v55
	v_sub_f32_e32 v54, v54, v56
	v_add_f32_e32 v15, 1.0, v15
	v_cndmask_b32_e64 v57, 0, 32, s[0:1]
	v_ldexp_f32 v55, v55, v57
	v_log_f32_e32 v55, v55
	v_div_scale_f32 v57, s[2:3], v48, v48, 1.0
;     __device__ __forceinline__ void operator()(const f32x4 (&acc)[2][2][4][2], const Unit& u, int wr, int wc, int fr, int fq) const {
;     ...
;                         for (int n = 0; n < 2; ++n) { f32x4 z = acc[ai][bj][m][n], o;
; #pragma unroll
;                             for (int e = 0; e < 4; ++e) { const float lb = lbv[bj][4 * n + e]; const float sg = 1.0f / (1.0f + __expf(-z[e])); o[e] = __logf(lb + (1.0f - lb) * sg); }
;                             *(f32x4*)(rowp + bj * HALF + 4 * n) = o; } }
	v_rcp_f32_e32 v58, v57
	v_mul_f32_e32 v56, 0x3f317217, v55
	v_fma_f32 v56, v55, s47, -v56
	v_fmac_f32_e32 v56, 0x3377d1cf, v55
	v_fmac_f32_e32 v56, 0x3f317217, v55
	v_cmp_lt_f32_e64 vcc, |v55|, s49
	v_exp_f32_e32 v8, v8
	v_mul_f32_e32 v9, 0xbfb8aa3b, v9
	v_cndmask_b32_e32 v55, v55, v56, vcc
	v_fma_f32 v56, -v57, v58, 1.0
	v_fmac_f32_e32 v58, v56, v58
	v_div_scale_f32 v56, vcc, 1.0, v48, 1.0
	v_mul_f32_e32 v59, v56, v58
	v_fma_f32 v60, -v57, v59, v56
	v_fmac_f32_e32 v59, v60, v58
	v_fma_f32 v56, -v57, v59, v56
	v_div_fmas_f32 v56, v56, v58, v59
	v_div_fixup_f32 v48, v56, v48, 1.0
	v_fma_f32 v48, v48, v135, v134
	v_cmp_gt_f32_e32 vcc, s46, v48
	v_add_f32_e32 v8, 1.0, v8
	v_exp_f32_e32 v9, v9
	v_cndmask_b32_e64 v56, 0, 32, vcc
	v_ldexp_f32 v48, v48, v56
	v_log_f32_e32 v48, v48
	v_cndmask_b32_e64 v56, 0, v193, s[0:1]
	v_sub_f32_e32 v55, v55, v56
	global_store_dwordx4 v[64:65], v[52:55], off offset:-3584
	v_add_f32_e32 v9, 1.0, v9
	v_mul_f32_e32 v10, 0xbfb8aa3b, v10
	v_div_scale_f32 v53, s[0:1], v49, v49, 1.0
	v_rcp_f32_e32 v54, v53
	v_mul_f32_e32 v52, 0x3f317217, v48
	v_fma_f32 v52, v48, s47, -v52
	v_fmac_f32_e32 v52, 0x3377d1cf, v48
	v_fmac_f32_e32 v52, 0x3f317217, v48
	v_cmp_lt_f32_e64 s[0:1], |v48|, s49
	v_fma_f32 v55, -v53, v54, 1.0
	v_fmac_f32_e32 v54, v55, v54
	v_cndmask_b32_e64 v48, v48, v52, s[0:1]
	v_cndmask_b32_e32 v52, 0, v193, vcc
	v_div_scale_f32 v55, vcc, 1.0, v49, 1.0
	v_mul_f32_e32 v56, v55, v54
	v_fma_f32 v57, -v53, v56, v55
	v_fmac_f32_e32 v56, v57, v54
	v_fma_f32 v53, -v53, v56, v55
	v_div_fmas_f32 v53, v53, v54, v56
	v_div_fixup_f32 v49, v53, v49, 1.0
	v_fma_f32 v49, v49, v117, v116
	v_cmp_gt_f32_e64 s[0:1], s46, v49
	v_sub_f32_e32 v48, v48, v52
	v_exp_f32_e32 v10, v10
	v_cndmask_b32_e64 v53, 0, 32, s[0:1]
	v_ldexp_f32 v49, v49, v53
	v_log_f32_e32 v49, v49
	v_div_scale_f32 v53, s[2:3], v50, v50, 1.0
	v_rcp_f32_e32 v54, v53
	v_mul_f32_e32 v52, 0x3f317217, v49
	v_fma_f32 v52, v49, s47, -v52
	v_fmac_f32_e32 v52, 0x3377d1cf, v49
	v_fmac_f32_e32 v52, 0x3f317217, v49
	v_cmp_lt_f32_e64 vcc, |v49|, s49
	s_mov_b64 s[2:3], 0x90000
	v_add_f32_e32 v10, 1.0, v10
	v_cndmask_b32_e32 v49, v49, v52, vcc
	v_fma_f32 v52, -v53, v54, 1.0
	v_fmac_f32_e32 v54, v52, v54
	v_div_scale_f32 v52, vcc, 1.0, v50, 1.0
	v_mul_f32_e32 v55, v52, v54
	v_fma_f32 v56, -v53, v55, v52
	v_fmac_f32_e32 v55, v56, v54
	v_fma_f32 v52, -v53, v55, v52
	v_div_fmas_f32 v52, v52, v54, v55
	v_div_fixup_f32 v50, v52, v50, 1.0
	v_fma_f32 v50, v50, v119, v118
	v_cmp_gt_f32_e64 s[4:5], s46, v50
	v_mul_f32_e32 v11, 0xbfb8aa3b, v11
	v_exp_f32_e32 v11, v11
	v_cndmask_b32_e64 v52, 0, 32, s[4:5]
	v_ldexp_f32 v50, v50, v52
	v_cndmask_b32_e64 v52, 0, v193, s[0:1]
	v_div_scale_f32 v53, s[0:1], v51, v51, 1.0
	v_rcp_f32_e32 v54, v53
	v_log_f32_e32 v50, v50
	v_sub_f32_e32 v49, v49, v52
	v_add_f32_e32 v11, 1.0, v11
	v_fma_f32 v55, -v53, v54, 1.0
	v_fmac_f32_e32 v54, v55, v54
	v_div_scale_f32 v55, vcc, 1.0, v51, 1.0
	v_mul_f32_e32 v56, v55, v54
	v_fma_f32 v57, -v53, v56, v55
	v_fmac_f32_e32 v56, v57, v54
	v_fma_f32 v53, -v53, v56, v55
	v_div_fmas_f32 v53, v53, v54, v56
	v_div_fixup_f32 v51, v53, v51, 1.0
	v_fma_f32 v51, v51, v129, v128
	v_cmp_gt_f32_e32 vcc, s46, v51
	v_mul_f32_e32 v52, 0x3f317217, v50
	v_fma_f32 v52, v50, s47, -v52
	v_cndmask_b32_e64 v53, 0, 32, vcc
	v_ldexp_f32 v51, v51, v53
	v_log_f32_e32 v51, v51
	v_fmac_f32_e32 v52, 0x3377d1cf, v50
	v_fmac_f32_e32 v52, 0x3f317217, v50
	v_cmp_lt_f32_e64 s[0:1], |v50|, s49
	v_mul_f32_e32 v4, 0xbfb8aa3b, v4
	v_exp_f32_e32 v4, v4
	v_cndmask_b32_e64 v50, v50, v52, s[0:1]
	v_cndmask_b32_e64 v52, 0, v193, s[4:5]
	v_sub_f32_e32 v50, v50, v52
	v_mul_f32_e32 v52, 0x3f317217, v51
	v_fma_f32 v52, v51, s47, -v52
	v_fmac_f32_e32 v52, 0x3377d1cf, v51
	v_fmac_f32_e32 v52, 0x3f317217, v51
	v_cmp_lt_f32_e64 s[0:1], |v51|, s49
	v_add_f32_e32 v4, 1.0, v4
	v_mul_f32_e32 v5, 0xbfb8aa3b, v5
	v_cndmask_b32_e64 v51, v51, v52, s[0:1]
	v_cndmask_b32_e32 v52, 0, v193, vcc
	v_sub_f32_e32 v51, v51, v52
	v_div_scale_f32 v52, s[0:1], v44, v44, 1.0
	v_rcp_f32_e32 v53, v52
	global_store_dwordx4 v[64:65], v[48:51], off offset:-3568
	v_exp_f32_e32 v5, v5
	v_mul_f32_e32 v6, 0xbfb8aa3b, v6
	v_fma_f32 v48, -v52, v53, 1.0
	v_fmac_f32_e32 v53, v48, v53
	v_div_scale_f32 v48, vcc, 1.0, v44, 1.0
	v_mul_f32_e32 v49, v48, v53
	v_fma_f32 v50, -v52, v49, v48
	v_fmac_f32_e32 v49, v50, v53
	v_fma_f32 v48, -v52, v49, v48
	v_div_fmas_f32 v48, v48, v53, v49
	v_div_fixup_f32 v44, v48, v44, 1.0
	v_fma_f32 v44, v44, v157, v156
	v_cmp_gt_f32_e64 s[0:1], s46, v44
	v_add_f32_e32 v5, 1.0, v5
	v_exp_f32_e32 v6, v6
	v_cndmask_b32_e64 v48, 0, 32, s[0:1]
	v_ldexp_f32 v44, v44, v48
	v_log_f32_e32 v44, v44
	v_lshl_add_u64 v[48:49], v[180:181], 0, s[2:3]
	v_div_scale_f32 v51, s[2:3], v45, v45, 1.0
	v_mul_f32_e32 v50, 0x3f317217, v44
	v_rcp_f32_e32 v52, v51
	v_fma_f32 v50, v44, s47, -v50
	v_fmac_f32_e32 v50, 0x3377d1cf, v44
	v_fmac_f32_e32 v50, 0x3f317217, v44
	v_cmp_lt_f32_e64 vcc, |v44|, s49
	v_add_f32_e32 v6, 1.0, v6
	v_mul_f32_e32 v7, 0xbfb8aa3b, v7
	v_cndmask_b32_e32 v44, v44, v50, vcc
	v_fma_f32 v50, -v51, v52, 1.0
	v_fmac_f32_e32 v52, v50, v52
	v_div_scale_f32 v50, vcc, 1.0, v45, 1.0
	v_mul_f32_e32 v53, v50, v52
	v_fma_f32 v54, -v51, v53, v50
	v_fmac_f32_e32 v53, v54, v52
	v_fma_f32 v50, -v51, v53, v50
	v_div_fmas_f32 v50, v50, v52, v53
	v_div_fixup_f32 v45, v50, v45, 1.0
	v_fma_f32 v45, v45, v159, v158
	v_cmp_gt_f32_e64 s[4:5], s46, v45
	v_exp_f32_e32 v7, v7
	v_mul_f32_e32 v0, 0xbfb8aa3b, v0
	v_cndmask_b32_e64 v50, 0, 32, s[4:5]
	v_ldexp_f32 v45, v45, v50
	v_cndmask_b32_e64 v50, 0, v193, s[0:1]
	v_div_scale_f32 v51, s[0:1], v46, v46, 1.0
	v_rcp_f32_e32 v52, v51
	v_log_f32_e32 v45, v45
;     __device__ __forceinline__ void operator()(const f32x4 (&acc)[2][2][4][2], const Unit& u, int wr, int wc, int fr, int fq) const {
;     ...
;                         for (int n = 0; n < 2; ++n) { f32x4 z = acc[ai][bj][m][n], o;
; #pragma unroll
;                             for (int e = 0; e < 4; ++e) { const float lb = lbv[bj][4 * n + e]; const float sg = 1.0f / (1.0f + __expf(-z[e])); o[e] = __logf(lb + (1.0f - lb) * sg); }
;                             *(f32x4*)(rowp + bj * HALF + 4 * n) = o; } }
	v_sub_f32_e32 v44, v44, v50
	v_add_f32_e32 v7, 1.0, v7
	v_fma_f32 v53, -v51, v52, 1.0
	v_fmac_f32_e32 v52, v53, v52
	v_div_scale_f32 v53, vcc, 1.0, v46, 1.0
	v_mul_f32_e32 v54, v53, v52
	v_fma_f32 v55, -v51, v54, v53
	v_fmac_f32_e32 v54, v55, v52
	v_fma_f32 v51, -v51, v54, v53
	v_div_fmas_f32 v51, v51, v52, v54
	v_div_fixup_f32 v46, v51, v46, 1.0
	v_fma_f32 v46, v46, v155, v154
	v_cmp_gt_f32_e32 vcc, s46, v46
	v_mul_f32_e32 v50, 0x3f317217, v45
	v_fma_f32 v50, v45, s47, -v50
	v_cndmask_b32_e64 v51, 0, 32, vcc
	v_ldexp_f32 v46, v46, v51
	v_fmac_f32_e32 v50, 0x3377d1cf, v45
	v_log_f32_e32 v46, v46
	v_fmac_f32_e32 v50, 0x3f317217, v45
	v_cmp_lt_f32_e64 s[0:1], |v45|, s49
	v_exp_f32_e32 v0, v0
	v_mul_f32_e32 v1, 0xbfb8aa3b, v1
	v_cndmask_b32_e64 v45, v45, v50, s[0:1]
	v_div_scale_f32 v51, s[0:1], v47, v47, 1.0
	v_cndmask_b32_e64 v50, 0, v193, s[4:5]
	v_rcp_f32_e32 v52, v51
	v_sub_f32_e32 v45, v45, v50
	v_mul_f32_e32 v50, 0x3f317217, v46
	v_fma_f32 v50, v46, s47, -v50
	v_fmac_f32_e32 v50, 0x3377d1cf, v46
	v_fmac_f32_e32 v50, 0x3f317217, v46
	v_cmp_lt_f32_e64 s[0:1], |v46|, s49
	v_fma_f32 v53, -v51, v52, 1.0
	v_fmac_f32_e32 v52, v53, v52
	v_cndmask_b32_e64 v46, v46, v50, s[0:1]
	v_cndmask_b32_e32 v50, 0, v193, vcc
	v_div_scale_f32 v53, vcc, 1.0, v47, 1.0
	v_mul_f32_e32 v54, v53, v52
	v_fma_f32 v55, -v51, v54, v53
	v_fmac_f32_e32 v54, v55, v52
	v_fma_f32 v51, -v51, v54, v53
	v_div_fmas_f32 v51, v51, v52, v54
	v_div_fixup_f32 v47, v51, v47, 1.0
	v_fma_f32 v47, v47, v153, v152
	v_cmp_gt_f32_e64 s[0:1], s46, v47
	v_sub_f32_e32 v46, v46, v50
	v_add_f32_e32 v0, 1.0, v0
	v_cndmask_b32_e64 v51, 0, 32, s[0:1]
	v_ldexp_f32 v47, v47, v51
	v_log_f32_e32 v47, v47
	v_div_scale_f32 v51, s[2:3], v40, v40, 1.0
	v_rcp_f32_e32 v52, v51
	v_mul_f32_e32 v50, 0x3f317217, v47
	v_fma_f32 v50, v47, s47, -v50
	v_fmac_f32_e32 v50, 0x3377d1cf, v47
	v_fmac_f32_e32 v50, 0x3f317217, v47
	v_cmp_lt_f32_e64 vcc, |v47|, s49
	v_exp_f32_e32 v1, v1
	v_mul_f32_e32 v2, 0xbfb8aa3b, v2
	v_cndmask_b32_e32 v47, v47, v50, vcc
	v_fma_f32 v50, -v51, v52, 1.0
	v_fmac_f32_e32 v52, v50, v52
	v_div_scale_f32 v50, vcc, 1.0, v40, 1.0
	v_mul_f32_e32 v53, v50, v52
	v_fma_f32 v54, -v51, v53, v50
	v_fmac_f32_e32 v53, v54, v52
	v_fma_f32 v50, -v51, v53, v50
	v_div_fmas_f32 v50, v50, v52, v53
	v_div_fixup_f32 v40, v50, v40, 1.0
	v_fma_f32 v40, v40, v151, v150
	v_cmp_gt_f32_e32 vcc, s46, v40
	v_add_f32_e32 v1, 1.0, v1
	v_exp_f32_e32 v2, v2
	v_cndmask_b32_e64 v50, 0, 32, vcc
	v_ldexp_f32 v40, v40, v50
	v_log_f32_e32 v40, v40
	v_cndmask_b32_e64 v50, 0, v193, s[0:1]
	v_sub_f32_e32 v47, v47, v50
	global_store_dwordx4 v[48:49], v[44:47], off offset:-4096
	v_add_f32_e32 v2, 1.0, v2
	v_mul_f32_e32 v3, 0xbfb8aa3b, v3
	v_div_scale_f32 v45, s[0:1], v41, v41, 1.0
	v_rcp_f32_e32 v46, v45
	v_mul_f32_e32 v44, 0x3f317217, v40
	v_fma_f32 v44, v40, s47, -v44
	v_fmac_f32_e32 v44, 0x3377d1cf, v40
	v_fmac_f32_e32 v44, 0x3f317217, v40
	v_cmp_lt_f32_e64 s[0:1], |v40|, s49
	v_fma_f32 v47, -v45, v46, 1.0
	v_fmac_f32_e32 v46, v47, v46
	v_cndmask_b32_e64 v40, v40, v44, s[0:1]
	v_cndmask_b32_e32 v44, 0, v193, vcc
	v_div_scale_f32 v47, vcc, 1.0, v41, 1.0
	v_mul_f32_e32 v50, v47, v46
	v_fma_f32 v51, -v45, v50, v47
	v_fmac_f32_e32 v50, v51, v46
	v_fma_f32 v45, -v45, v50, v47
	v_div_fmas_f32 v45, v45, v46, v50
	v_div_fixup_f32 v41, v45, v41, 1.0
	v_fma_f32 v41, v41, v125, v124
	v_cmp_gt_f32_e64 s[0:1], s46, v41
	v_sub_f32_e32 v40, v40, v44
	v_exp_f32_e32 v3, v3
	v_cndmask_b32_e64 v45, 0, 32, s[0:1]
	v_ldexp_f32 v41, v41, v45
	v_log_f32_e32 v41, v41
	v_div_scale_f32 v45, s[2:3], v42, v42, 1.0
	v_rcp_f32_e32 v46, v45
	v_mul_f32_e32 v44, 0x3f317217, v41
	v_fma_f32 v44, v41, s47, -v44
	v_fmac_f32_e32 v44, 0x3377d1cf, v41
	v_fmac_f32_e32 v44, 0x3f317217, v41
	v_cmp_lt_f32_e64 vcc, |v41|, s49
	v_add_f32_e32 v3, 1.0, v3
	v_readlane_b32 s77, v236, 8
	v_cndmask_b32_e32 v41, v41, v44, vcc
	v_fma_f32 v44, -v45, v46, 1.0
	v_fmac_f32_e32 v46, v44, v46
	v_div_scale_f32 v44, vcc, 1.0, v42, 1.0
	v_mul_f32_e32 v47, v44, v46
	v_fma_f32 v50, -v45, v47, v44
	v_fmac_f32_e32 v47, v50, v46
	v_fma_f32 v44, -v45, v47, v44
	v_div_fmas_f32 v44, v44, v46, v47
	v_div_fixup_f32 v42, v44, v42, 1.0
	v_fma_f32 v42, v42, v127, v126
	v_cmp_gt_f32_e64 s[4:5], s46, v42
	v_readlane_b32 s78, v236, 9
	v_readlane_b32 s79, v236, 10
	v_cndmask_b32_e64 v44, 0, 32, s[4:5]
	v_ldexp_f32 v42, v42, v44
	v_cndmask_b32_e64 v44, 0, v193, s[0:1]
	v_div_scale_f32 v45, s[0:1], v43, v43, 1.0
	v_rcp_f32_e32 v46, v45
	v_log_f32_e32 v42, v42
	v_sub_f32_e32 v41, v41, v44
	v_readlane_b32 s80, v236, 11
	v_fma_f32 v47, -v45, v46, 1.0
	v_fmac_f32_e32 v46, v47, v46
	v_div_scale_f32 v47, vcc, 1.0, v43, 1.0
	v_mul_f32_e32 v50, v47, v46
	v_fma_f32 v51, -v45, v50, v47
	v_fmac_f32_e32 v50, v51, v46
	v_fma_f32 v45, -v45, v50, v47
	v_div_fmas_f32 v45, v45, v46, v50
	v_div_fixup_f32 v43, v45, v43, 1.0
	v_fma_f32 v43, v43, v145, v144
	v_cmp_gt_f32_e32 vcc, s46, v43
	v_mul_f32_e32 v44, 0x3f317217, v42
	v_fma_f32 v44, v42, s47, -v44
	v_cndmask_b32_e64 v45, 0, 32, vcc
	v_ldexp_f32 v43, v43, v45
	v_log_f32_e32 v43, v43
	v_fmac_f32_e32 v44, 0x3377d1cf, v42
	v_fmac_f32_e32 v44, 0x3f317217, v42
	v_cmp_lt_f32_e64 s[0:1], |v42|, s49
	v_readlane_b32 s81, v236, 12
	v_readlane_b32 s82, v236, 13
	v_cndmask_b32_e64 v42, v42, v44, s[0:1]
	v_cndmask_b32_e64 v44, 0, v193, s[4:5]
	v_sub_f32_e32 v42, v42, v44
	v_mul_f32_e32 v44, 0x3f317217, v43
	v_div_scale_f32 v45, s[0:1], v36, v36, 1.0
	v_fma_f32 v44, v43, s47, -v44
	v_rcp_f32_e32 v46, v45
	v_fmac_f32_e32 v44, 0x3377d1cf, v43
	v_fmac_f32_e32 v44, 0x3f317217, v43
	v_cmp_lt_f32_e64 s[0:1], |v43|, s49
	v_readlane_b32 s83, v236, 14
	v_readlane_b32 s84, v236, 15
;     __device__ __forceinline__ void operator()(const f32x4 (&acc)[2][2][4][2], const Unit& u, int wr, int wc, int fr, int fq) const {
;     ...
;                         for (int n = 0; n < 2; ++n) { f32x4 z = acc[ai][bj][m][n], o;
; #pragma unroll
;                             for (int e = 0; e < 4; ++e) { const float lb = lbv[bj][4 * n + e]; const float sg = 1.0f / (1.0f + __expf(-z[e])); o[e] = __logf(lb + (1.0f - lb) * sg); }
;                             *(f32x4*)(rowp + bj * HALF + 4 * n) = o; } }
	v_cndmask_b32_e64 v43, v43, v44, s[0:1]
	v_cndmask_b32_e32 v44, 0, v193, vcc
	v_sub_f32_e32 v43, v43, v44
	v_fma_f32 v44, -v45, v46, 1.0
	v_fmac_f32_e32 v46, v44, v46
	v_div_scale_f32 v44, vcc, 1.0, v36, 1.0
	v_mul_f32_e32 v47, v44, v46
	v_fma_f32 v50, -v45, v47, v44
	v_fmac_f32_e32 v47, v50, v46
	v_fma_f32 v44, -v45, v47, v44
	v_div_fmas_f32 v44, v44, v46, v47
	v_div_fixup_f32 v36, v44, v36, 1.0
	v_fma_f32 v36, v36, v143, v142
	v_cmp_gt_f32_e64 s[0:1], s46, v36
	global_store_dwordx4 v[48:49], v[40:43], off offset:-4080
	v_readlane_b32 s85, v236, 16
	v_cndmask_b32_e64 v44, 0, 32, s[0:1]
	v_ldexp_f32 v36, v36, v44
	v_log_f32_e32 v36, v36
	v_div_scale_f32 v41, s[2:3], v37, v37, 1.0
	v_rcp_f32_e32 v42, v41
	v_mul_f32_e32 v40, 0x3f317217, v36
	v_fma_f32 v40, v36, s47, -v40
	v_fmac_f32_e32 v40, 0x3377d1cf, v36
	v_fmac_f32_e32 v40, 0x3f317217, v36
	v_cmp_lt_f32_e64 vcc, |v36|, s49
	v_readlane_b32 s86, v236, 17
	v_readlane_b32 s87, v236, 18
	v_cndmask_b32_e32 v36, v36, v40, vcc
	v_fma_f32 v40, -v41, v42, 1.0
	v_fmac_f32_e32 v42, v40, v42
	v_div_scale_f32 v40, vcc, 1.0, v37, 1.0
	v_mul_f32_e32 v43, v40, v42
	v_fma_f32 v44, -v41, v43, v40
	v_fmac_f32_e32 v43, v44, v42
	v_fma_f32 v40, -v41, v43, v40
	v_div_fmas_f32 v40, v40, v42, v43
	v_div_fixup_f32 v37, v40, v37, 1.0
	v_fma_f32 v37, v37, v121, v120
	v_cmp_gt_f32_e64 s[4:5], s46, v37
	v_readlane_b32 s90, v236, 21
	v_readlane_b32 s91, v236, 22
	v_cndmask_b32_e64 v40, 0, 32, s[4:5]
	v_ldexp_f32 v37, v37, v40
	v_cndmask_b32_e64 v40, 0, v193, s[0:1]
	v_div_scale_f32 v41, s[0:1], v38, v38, 1.0
	v_rcp_f32_e32 v42, v41
	v_log_f32_e32 v37, v37
	v_sub_f32_e32 v36, v36, v40
	v_fma_f32 v43, -v41, v42, 1.0
	v_fmac_f32_e32 v42, v43, v42
	v_div_scale_f32 v43, vcc, 1.0, v38, 1.0
	v_mul_f32_e32 v44, v43, v42
	v_fma_f32 v45, -v41, v44, v43
	v_fmac_f32_e32 v44, v45, v42
	v_fma_f32 v41, -v41, v44, v43
	v_div_fmas_f32 v41, v41, v42, v44
	v_div_fixup_f32 v38, v41, v38, 1.0
	v_fma_f32 v38, v38, v123, v122
	v_cmp_gt_f32_e32 vcc, s46, v38
	v_mul_f32_e32 v40, 0x3f317217, v37
	v_fma_f32 v40, v37, s47, -v40
	v_cndmask_b32_e64 v41, 0, 32, vcc
	v_ldexp_f32 v38, v38, v41
	v_fmac_f32_e32 v40, 0x3377d1cf, v37
	v_log_f32_e32 v38, v38
	v_fmac_f32_e32 v40, 0x3f317217, v37
	v_cmp_lt_f32_e64 s[0:1], |v37|, s49
	s_nop 1
	v_cndmask_b32_e64 v37, v37, v40, s[0:1]
	v_div_scale_f32 v41, s[0:1], v39, v39, 1.0
	v_cndmask_b32_e64 v40, 0, v193, s[4:5]
	v_rcp_f32_e32 v42, v41
	v_sub_f32_e32 v37, v37, v40
	v_mul_f32_e32 v40, 0x3f317217, v38
	v_fma_f32 v40, v38, s47, -v40
	v_fmac_f32_e32 v40, 0x3377d1cf, v38
	v_fmac_f32_e32 v40, 0x3f317217, v38
	v_cmp_lt_f32_e64 s[0:1], |v38|, s49
	v_fma_f32 v43, -v41, v42, 1.0
	v_fmac_f32_e32 v42, v43, v42
	v_cndmask_b32_e64 v38, v38, v40, s[0:1]
	v_cndmask_b32_e32 v40, 0, v193, vcc
	v_div_scale_f32 v43, vcc, 1.0, v39, 1.0
	v_mul_f32_e32 v44, v43, v42
	v_fma_f32 v45, -v41, v44, v43
	v_fmac_f32_e32 v44, v45, v42
	v_fma_f32 v41, -v41, v44, v43
	v_div_fmas_f32 v41, v41, v42, v44
	v_div_fixup_f32 v39, v41, v39, 1.0
	v_fma_f32 v39, v39, v137, v136
	v_cmp_gt_f32_e64 s[0:1], s46, v39
	v_sub_f32_e32 v38, v38, v40
	s_nop 0
	v_cndmask_b32_e64 v41, 0, 32, s[0:1]
	v_ldexp_f32 v39, v39, v41
	v_log_f32_e32 v39, v39
	v_div_scale_f32 v41, s[2:3], v32, v32, 1.0
	v_rcp_f32_e32 v42, v41
	v_mul_f32_e32 v40, 0x3f317217, v39
	v_fma_f32 v40, v39, s47, -v40
	v_fmac_f32_e32 v40, 0x3377d1cf, v39
	v_fmac_f32_e32 v40, 0x3f317217, v39
	v_cmp_lt_f32_e64 vcc, |v39|, s49
	s_nop 1
	v_cndmask_b32_e32 v39, v39, v40, vcc
	v_fma_f32 v40, -v41, v42, 1.0
	v_fmac_f32_e32 v42, v40, v42
	v_div_scale_f32 v40, vcc, 1.0, v32, 1.0
	v_mul_f32_e32 v43, v40, v42
	v_fma_f32 v44, -v41, v43, v40
	v_fmac_f32_e32 v43, v44, v42
	v_fma_f32 v40, -v41, v43, v40
	v_div_fmas_f32 v40, v40, v42, v43
	v_div_fixup_f32 v32, v40, v32, 1.0
	v_fma_f32 v32, v32, v135, v134
	v_cmp_gt_f32_e32 vcc, s46, v32
	s_nop 1
	v_cndmask_b32_e64 v40, 0, 32, vcc
	v_ldexp_f32 v32, v32, v40
	v_log_f32_e32 v32, v32
	v_cndmask_b32_e64 v40, 0, v193, s[0:1]
	v_sub_f32_e32 v39, v39, v40
	global_store_dwordx4 v[48:49], v[36:39], off offset:-3584
	s_nop 1
	v_div_scale_f32 v37, s[0:1], v33, v33, 1.0
	v_rcp_f32_e32 v38, v37
	v_mul_f32_e32 v36, 0x3f317217, v32
	v_fma_f32 v36, v32, s47, -v36
	v_fmac_f32_e32 v36, 0x3377d1cf, v32
	v_fmac_f32_e32 v36, 0x3f317217, v32
	v_cmp_lt_f32_e64 s[0:1], |v32|, s49
	v_fma_f32 v39, -v37, v38, 1.0
	v_fmac_f32_e32 v38, v39, v38
	v_cndmask_b32_e64 v32, v32, v36, s[0:1]
	v_cndmask_b32_e32 v36, 0, v193, vcc
	v_div_scale_f32 v39, vcc, 1.0, v33, 1.0
	v_mul_f32_e32 v40, v39, v38
	v_fma_f32 v41, -v37, v40, v39
	v_fmac_f32_e32 v40, v41, v38
	v_fma_f32 v37, -v37, v40, v39
	v_div_fmas_f32 v37, v37, v38, v40
	v_div_fixup_f32 v33, v37, v33, 1.0
	v_fma_f32 v33, v33, v117, v116
	v_cmp_gt_f32_e64 s[0:1], s46, v33
	v_sub_f32_e32 v32, v32, v36
	s_nop 0
	v_cndmask_b32_e64 v37, 0, 32, s[0:1]
	v_ldexp_f32 v33, v33, v37
	v_log_f32_e32 v33, v33
	v_div_scale_f32 v37, s[2:3], v34, v34, 1.0
	v_rcp_f32_e32 v38, v37
	v_mul_f32_e32 v36, 0x3f317217, v33
	v_fma_f32 v36, v33, s47, -v36
	v_fmac_f32_e32 v36, 0x3377d1cf, v33
	v_fmac_f32_e32 v36, 0x3f317217, v33
	v_cmp_lt_f32_e64 vcc, |v33|, s49
	s_mov_b64 s[2:3], 0xa0000
	s_nop 0
	v_cndmask_b32_e32 v33, v33, v36, vcc
	v_fma_f32 v36, -v37, v38, 1.0
	v_fmac_f32_e32 v38, v36, v38
	v_div_scale_f32 v36, vcc, 1.0, v34, 1.0
	v_mul_f32_e32 v39, v36, v38
	v_fma_f32 v40, -v37, v39, v36
	v_fmac_f32_e32 v39, v40, v38
	v_fma_f32 v36, -v37, v39, v36
	v_div_fmas_f32 v36, v36, v38, v39
	v_div_fixup_f32 v34, v36, v34, 1.0
	v_fma_f32 v34, v34, v119, v118
	v_cmp_gt_f32_e64 s[4:5], s46, v34
	s_nop 1
	v_cndmask_b32_e64 v36, 0, 32, s[4:5]
	v_ldexp_f32 v34, v34, v36
;     __device__ __forceinline__ void operator()(const f32x4 (&acc)[2][2][4][2], const Unit& u, int wr, int wc, int fr, int fq) const {
;     ...
;                         for (int n = 0; n < 2; ++n) { f32x4 z = acc[ai][bj][m][n], o;
; #pragma unroll
;                             for (int e = 0; e < 4; ++e) { const float lb = lbv[bj][4 * n + e]; const float sg = 1.0f / (1.0f + __expf(-z[e])); o[e] = __logf(lb + (1.0f - lb) * sg); }
;                             *(f32x4*)(rowp + bj * HALF + 4 * n) = o; } }
	v_cndmask_b32_e64 v36, 0, v193, s[0:1]
	v_div_scale_f32 v37, s[0:1], v35, v35, 1.0
	v_rcp_f32_e32 v38, v37
	v_log_f32_e32 v34, v34
	v_sub_f32_e32 v33, v33, v36
	v_fma_f32 v39, -v37, v38, 1.0
	v_fmac_f32_e32 v38, v39, v38
	v_div_scale_f32 v39, vcc, 1.0, v35, 1.0
	v_mul_f32_e32 v40, v39, v38
	v_fma_f32 v41, -v37, v40, v39
	v_fmac_f32_e32 v40, v41, v38
	v_fma_f32 v37, -v37, v40, v39
	v_div_fmas_f32 v37, v37, v38, v40
	v_div_fixup_f32 v35, v37, v35, 1.0
	v_fma_f32 v35, v35, v129, v128
	v_cmp_gt_f32_e32 vcc, s46, v35
	v_mul_f32_e32 v36, 0x3f317217, v34
	v_fma_f32 v36, v34, s47, -v36
	v_cndmask_b32_e64 v37, 0, 32, vcc
	v_ldexp_f32 v35, v35, v37
	v_log_f32_e32 v35, v35
	v_fmac_f32_e32 v36, 0x3377d1cf, v34
	v_fmac_f32_e32 v36, 0x3f317217, v34
	v_cmp_lt_f32_e64 s[0:1], |v34|, s49
	s_nop 1
	v_cndmask_b32_e64 v34, v34, v36, s[0:1]
	v_cndmask_b32_e64 v36, 0, v193, s[4:5]
	v_sub_f32_e32 v34, v34, v36
	v_mul_f32_e32 v36, 0x3f317217, v35
	v_fma_f32 v36, v35, s47, -v36
	v_fmac_f32_e32 v36, 0x3377d1cf, v35
	v_fmac_f32_e32 v36, 0x3f317217, v35
	v_cmp_lt_f32_e64 s[0:1], |v35|, s49
	s_nop 1
	v_cndmask_b32_e64 v35, v35, v36, s[0:1]
	v_cndmask_b32_e32 v36, 0, v193, vcc
	v_sub_f32_e32 v35, v35, v36
	v_div_scale_f32 v36, s[0:1], v28, v28, 1.0
	v_rcp_f32_e32 v37, v36
	global_store_dwordx4 v[48:49], v[32:35], off offset:-3568
	s_nop 1
	v_fma_f32 v32, -v36, v37, 1.0
	v_fmac_f32_e32 v37, v32, v37
	v_div_scale_f32 v32, vcc, 1.0, v28, 1.0
	v_mul_f32_e32 v33, v32, v37
	v_fma_f32 v34, -v36, v33, v32
	v_fmac_f32_e32 v33, v34, v37
	v_fma_f32 v32, -v36, v33, v32
	v_div_fmas_f32 v32, v32, v37, v33
	v_div_fixup_f32 v28, v32, v28, 1.0
	v_fma_f32 v28, v28, v157, v156
	v_cmp_gt_f32_e64 s[0:1], s46, v28
	s_nop 1
	v_cndmask_b32_e64 v32, 0, 32, s[0:1]
	v_ldexp_f32 v28, v28, v32
	v_log_f32_e32 v28, v28
	v_lshl_add_u64 v[32:33], v[180:181], 0, s[2:3]
	v_div_scale_f32 v35, s[2:3], v29, v29, 1.0
	v_mul_f32_e32 v34, 0x3f317217, v28
	v_rcp_f32_e32 v36, v35
	v_fma_f32 v34, v28, s47, -v34
	v_fmac_f32_e32 v34, 0x3377d1cf, v28
	v_fmac_f32_e32 v34, 0x3f317217, v28
	v_cmp_lt_f32_e64 vcc, |v28|, s49
	s_nop 1
	v_cndmask_b32_e32 v28, v28, v34, vcc
	v_fma_f32 v34, -v35, v36, 1.0
	v_fmac_f32_e32 v36, v34, v36
	v_div_scale_f32 v34, vcc, 1.0, v29, 1.0
	v_mul_f32_e32 v37, v34, v36
	v_fma_f32 v38, -v35, v37, v34
	v_fmac_f32_e32 v37, v38, v36
	v_fma_f32 v34, -v35, v37, v34
	v_div_fmas_f32 v34, v34, v36, v37
	v_div_fixup_f32 v29, v34, v29, 1.0
	v_fma_f32 v29, v29, v159, v158
	v_cmp_gt_f32_e64 s[4:5], s46, v29
	s_nop 1
	v_cndmask_b32_e64 v34, 0, 32, s[4:5]
	v_ldexp_f32 v29, v29, v34
	v_cndmask_b32_e64 v34, 0, v193, s[0:1]
	v_div_scale_f32 v35, s[0:1], v30, v30, 1.0
	v_rcp_f32_e32 v36, v35
	v_log_f32_e32 v29, v29
	v_sub_f32_e32 v28, v28, v34
	v_fma_f32 v37, -v35, v36, 1.0
	v_fmac_f32_e32 v36, v37, v36
	v_div_scale_f32 v37, vcc, 1.0, v30, 1.0
	v_mul_f32_e32 v38, v37, v36
	v_fma_f32 v39, -v35, v38, v37
	v_fmac_f32_e32 v38, v39, v36
	v_fma_f32 v35, -v35, v38, v37
	v_div_fmas_f32 v35, v35, v36, v38
	v_div_fixup_f32 v30, v35, v30, 1.0
	v_fma_f32 v30, v30, v155, v154
	v_cmp_gt_f32_e32 vcc, s46, v30
	v_mul_f32_e32 v34, 0x3f317217, v29
	v_fma_f32 v34, v29, s47, -v34
	v_cndmask_b32_e64 v35, 0, 32, vcc
	v_ldexp_f32 v30, v30, v35
	v_fmac_f32_e32 v34, 0x3377d1cf, v29
	v_log_f32_e32 v30, v30
	v_fmac_f32_e32 v34, 0x3f317217, v29
	v_cmp_lt_f32_e64 s[0:1], |v29|, s49
	s_nop 1
	v_cndmask_b32_e64 v29, v29, v34, s[0:1]
	v_div_scale_f32 v35, s[0:1], v31, v31, 1.0
	v_cndmask_b32_e64 v34, 0, v193, s[4:5]
	v_rcp_f32_e32 v36, v35
	v_sub_f32_e32 v29, v29, v34
	v_mul_f32_e32 v34, 0x3f317217, v30
	v_fma_f32 v34, v30, s47, -v34
	v_fmac_f32_e32 v34, 0x3377d1cf, v30
	v_fmac_f32_e32 v34, 0x3f317217, v30
	v_cmp_lt_f32_e64 s[0:1], |v30|, s49
	v_fma_f32 v37, -v35, v36, 1.0
	v_fmac_f32_e32 v36, v37, v36
	v_cndmask_b32_e64 v30, v30, v34, s[0:1]
	v_cndmask_b32_e32 v34, 0, v193, vcc
	v_div_scale_f32 v37, vcc, 1.0, v31, 1.0
	v_mul_f32_e32 v38, v37, v36
	v_fma_f32 v39, -v35, v38, v37
	v_fmac_f32_e32 v38, v39, v36
	v_fma_f32 v35, -v35, v38, v37
	v_div_fmas_f32 v35, v35, v36, v38
	v_div_fixup_f32 v31, v35, v31, 1.0
	v_fma_f32 v31, v31, v153, v152
	v_cmp_gt_f32_e64 s[0:1], s46, v31
	v_sub_f32_e32 v30, v30, v34
	s_nop 0
	v_cndmask_b32_e64 v35, 0, 32, s[0:1]
	v_ldexp_f32 v31, v31, v35
	v_log_f32_e32 v31, v31
	v_div_scale_f32 v35, s[2:3], v24, v24, 1.0
	v_rcp_f32_e32 v36, v35
	v_mul_f32_e32 v34, 0x3f317217, v31
	v_fma_f32 v34, v31, s47, -v34
	v_fmac_f32_e32 v34, 0x3377d1cf, v31
	v_fmac_f32_e32 v34, 0x3f317217, v31
	v_cmp_lt_f32_e64 vcc, |v31|, s49
	s_nop 1
	v_cndmask_b32_e32 v31, v31, v34, vcc
	v_fma_f32 v34, -v35, v36, 1.0
	v_fmac_f32_e32 v36, v34, v36
	v_div_scale_f32 v34, vcc, 1.0, v24, 1.0
	v_mul_f32_e32 v37, v34, v36
	v_fma_f32 v38, -v35, v37, v34
	v_fmac_f32_e32 v37, v38, v36
	v_fma_f32 v34, -v35, v37, v34
	v_div_fmas_f32 v34, v34, v36, v37
	v_div_fixup_f32 v24, v34, v24, 1.0
	v_fma_f32 v24, v24, v151, v150
	v_cmp_gt_f32_e32 vcc, s46, v24
	s_nop 1
	v_cndmask_b32_e64 v34, 0, 32, vcc
	v_ldexp_f32 v24, v24, v34
	v_log_f32_e32 v24, v24
	v_cndmask_b32_e64 v34, 0, v193, s[0:1]
	v_sub_f32_e32 v31, v31, v34
	global_store_dwordx4 v[32:33], v[28:31], off offset:-4096
	s_nop 1
	v_div_scale_f32 v29, s[0:1], v25, v25, 1.0
	v_rcp_f32_e32 v30, v29
	v_mul_f32_e32 v28, 0x3f317217, v24
	v_fma_f32 v28, v24, s47, -v28
	v_fmac_f32_e32 v28, 0x3377d1cf, v24
	v_fmac_f32_e32 v28, 0x3f317217, v24
	v_cmp_lt_f32_e64 s[0:1], |v24|, s49
	v_fma_f32 v31, -v29, v30, 1.0
	v_fmac_f32_e32 v30, v31, v30
	v_cndmask_b32_e64 v24, v24, v28, s[0:1]
	v_cndmask_b32_e32 v28, 0, v193, vcc
	v_div_scale_f32 v31, vcc, 1.0, v25, 1.0
	v_mul_f32_e32 v34, v31, v30
	v_fma_f32 v35, -v29, v34, v31
;     __device__ __forceinline__ void operator()(const f32x4 (&acc)[2][2][4][2], const Unit& u, int wr, int wc, int fr, int fq) const {
;     ...
;                         for (int n = 0; n < 2; ++n) { f32x4 z = acc[ai][bj][m][n], o;
; #pragma unroll
;                             for (int e = 0; e < 4; ++e) { const float lb = lbv[bj][4 * n + e]; const float sg = 1.0f / (1.0f + __expf(-z[e])); o[e] = __logf(lb + (1.0f - lb) * sg); }
;                             *(f32x4*)(rowp + bj * HALF + 4 * n) = o; } }
	v_fmac_f32_e32 v34, v35, v30
	v_fma_f32 v29, -v29, v34, v31
	v_div_fmas_f32 v29, v29, v30, v34
	v_div_fixup_f32 v25, v29, v25, 1.0
	v_fma_f32 v25, v25, v125, v124
	v_cmp_gt_f32_e64 s[0:1], s46, v25
	v_sub_f32_e32 v24, v24, v28
	s_nop 0
	v_cndmask_b32_e64 v29, 0, 32, s[0:1]
	v_ldexp_f32 v25, v25, v29
	v_log_f32_e32 v25, v25
	v_div_scale_f32 v29, s[2:3], v26, v26, 1.0
	v_rcp_f32_e32 v30, v29
	v_mul_f32_e32 v28, 0x3f317217, v25
	v_fma_f32 v28, v25, s47, -v28
	v_fmac_f32_e32 v28, 0x3377d1cf, v25
	v_fmac_f32_e32 v28, 0x3f317217, v25
	v_cmp_lt_f32_e64 vcc, |v25|, s49
	s_nop 1
	v_cndmask_b32_e32 v25, v25, v28, vcc
	v_fma_f32 v28, -v29, v30, 1.0
	v_fmac_f32_e32 v30, v28, v30
	v_div_scale_f32 v28, vcc, 1.0, v26, 1.0
	v_mul_f32_e32 v31, v28, v30
	v_fma_f32 v34, -v29, v31, v28
	v_fmac_f32_e32 v31, v34, v30
	v_fma_f32 v28, -v29, v31, v28
	v_div_fmas_f32 v28, v28, v30, v31
	v_div_fixup_f32 v26, v28, v26, 1.0
	v_fma_f32 v26, v26, v127, v126
	v_cmp_gt_f32_e64 s[4:5], s46, v26
	s_nop 1
	v_cndmask_b32_e64 v28, 0, 32, s[4:5]
	v_ldexp_f32 v26, v26, v28
	v_cndmask_b32_e64 v28, 0, v193, s[0:1]
	v_div_scale_f32 v29, s[0:1], v27, v27, 1.0
	v_rcp_f32_e32 v30, v29
	v_log_f32_e32 v26, v26
	v_sub_f32_e32 v25, v25, v28
	v_fma_f32 v31, -v29, v30, 1.0
	v_fmac_f32_e32 v30, v31, v30
	v_div_scale_f32 v31, vcc, 1.0, v27, 1.0
	v_mul_f32_e32 v34, v31, v30
	v_fma_f32 v35, -v29, v34, v31
	v_fmac_f32_e32 v34, v35, v30
	v_fma_f32 v29, -v29, v34, v31
	v_div_fmas_f32 v29, v29, v30, v34
	v_div_fixup_f32 v27, v29, v27, 1.0
	v_fma_f32 v27, v27, v145, v144
	v_cmp_gt_f32_e32 vcc, s46, v27
	v_mul_f32_e32 v28, 0x3f317217, v26
	v_fma_f32 v28, v26, s47, -v28
	v_cndmask_b32_e64 v29, 0, 32, vcc
	v_ldexp_f32 v27, v27, v29
	v_log_f32_e32 v27, v27
	v_fmac_f32_e32 v28, 0x3377d1cf, v26
	v_fmac_f32_e32 v28, 0x3f317217, v26
	v_cmp_lt_f32_e64 s[0:1], |v26|, s49
	s_nop 1
	v_cndmask_b32_e64 v26, v26, v28, s[0:1]
	v_cndmask_b32_e64 v28, 0, v193, s[4:5]
	v_sub_f32_e32 v26, v26, v28
	v_mul_f32_e32 v28, 0x3f317217, v27
	v_div_scale_f32 v29, s[0:1], v20, v20, 1.0
	v_fma_f32 v28, v27, s47, -v28
	v_rcp_f32_e32 v30, v29
	v_fmac_f32_e32 v28, 0x3377d1cf, v27
	v_fmac_f32_e32 v28, 0x3f317217, v27
	v_cmp_lt_f32_e64 s[0:1], |v27|, s49
	s_nop 1
	v_cndmask_b32_e64 v27, v27, v28, s[0:1]
	v_cndmask_b32_e32 v28, 0, v193, vcc
	v_sub_f32_e32 v27, v27, v28
	v_fma_f32 v28, -v29, v30, 1.0
	v_fmac_f32_e32 v30, v28, v30
	v_div_scale_f32 v28, vcc, 1.0, v20, 1.0
	v_mul_f32_e32 v31, v28, v30
	v_fma_f32 v34, -v29, v31, v28
	v_fmac_f32_e32 v31, v34, v30
	v_fma_f32 v28, -v29, v31, v28
	v_div_fmas_f32 v28, v28, v30, v31
	v_div_fixup_f32 v20, v28, v20, 1.0
	v_fma_f32 v20, v20, v143, v142
	v_cmp_gt_f32_e64 s[0:1], s46, v20
	global_store_dwordx4 v[32:33], v[24:27], off offset:-4080
	s_nop 0
	v_cndmask_b32_e64 v28, 0, 32, s[0:1]
	v_ldexp_f32 v20, v20, v28
	v_log_f32_e32 v20, v20
	v_div_scale_f32 v25, s[2:3], v21, v21, 1.0
	v_rcp_f32_e32 v26, v25
	v_mul_f32_e32 v24, 0x3f317217, v20
	v_fma_f32 v24, v20, s47, -v24
	v_fmac_f32_e32 v24, 0x3377d1cf, v20
	v_fmac_f32_e32 v24, 0x3f317217, v20
	v_cmp_lt_f32_e64 vcc, |v20|, s49
	s_nop 1
	v_cndmask_b32_e32 v20, v20, v24, vcc
	v_fma_f32 v24, -v25, v26, 1.0
	v_fmac_f32_e32 v26, v24, v26
	v_div_scale_f32 v24, vcc, 1.0, v21, 1.0
	v_mul_f32_e32 v27, v24, v26
	v_fma_f32 v28, -v25, v27, v24
	v_fmac_f32_e32 v27, v28, v26
	v_fma_f32 v24, -v25, v27, v24
	v_div_fmas_f32 v24, v24, v26, v27
	v_div_fixup_f32 v21, v24, v21, 1.0
	v_fma_f32 v21, v21, v121, v120
	v_cmp_gt_f32_e64 s[4:5], s46, v21
	s_nop 1
	v_cndmask_b32_e64 v24, 0, 32, s[4:5]
	v_ldexp_f32 v21, v21, v24
	v_cndmask_b32_e64 v24, 0, v193, s[0:1]
	v_div_scale_f32 v25, s[0:1], v22, v22, 1.0
	v_rcp_f32_e32 v26, v25
	v_log_f32_e32 v21, v21
	v_sub_f32_e32 v20, v20, v24
	v_fma_f32 v27, -v25, v26, 1.0
	v_fmac_f32_e32 v26, v27, v26
	v_div_scale_f32 v27, vcc, 1.0, v22, 1.0
	v_mul_f32_e32 v28, v27, v26
	v_fma_f32 v29, -v25, v28, v27
	v_fmac_f32_e32 v28, v29, v26
	v_fma_f32 v25, -v25, v28, v27
	v_div_fmas_f32 v25, v25, v26, v28
	v_div_fixup_f32 v22, v25, v22, 1.0
	v_fma_f32 v22, v22, v123, v122
	v_cmp_gt_f32_e32 vcc, s46, v22
	v_mul_f32_e32 v24, 0x3f317217, v21
	v_fma_f32 v24, v21, s47, -v24
	v_cndmask_b32_e64 v25, 0, 32, vcc
	v_ldexp_f32 v22, v22, v25
	v_fmac_f32_e32 v24, 0x3377d1cf, v21
	v_log_f32_e32 v22, v22
	v_fmac_f32_e32 v24, 0x3f317217, v21
	v_cmp_lt_f32_e64 s[0:1], |v21|, s49
	s_nop 1
	v_cndmask_b32_e64 v21, v21, v24, s[0:1]
	v_div_scale_f32 v25, s[0:1], v23, v23, 1.0
	v_cndmask_b32_e64 v24, 0, v193, s[4:5]
	v_rcp_f32_e32 v26, v25
	v_sub_f32_e32 v21, v21, v24
	v_mul_f32_e32 v24, 0x3f317217, v22
	v_fma_f32 v24, v22, s47, -v24
	v_fmac_f32_e32 v24, 0x3377d1cf, v22
	v_fmac_f32_e32 v24, 0x3f317217, v22
	v_cmp_lt_f32_e64 s[0:1], |v22|, s49
	v_fma_f32 v27, -v25, v26, 1.0
	v_fmac_f32_e32 v26, v27, v26
	v_cndmask_b32_e64 v22, v22, v24, s[0:1]
	v_cndmask_b32_e32 v24, 0, v193, vcc
	v_div_scale_f32 v27, vcc, 1.0, v23, 1.0
	v_mul_f32_e32 v28, v27, v26
	v_fma_f32 v29, -v25, v28, v27
	v_fmac_f32_e32 v28, v29, v26
	v_fma_f32 v25, -v25, v28, v27
	v_div_fmas_f32 v25, v25, v26, v28
	v_div_fixup_f32 v23, v25, v23, 1.0
	v_fma_f32 v23, v23, v137, v136
	v_cmp_gt_f32_e64 s[0:1], s46, v23
	v_sub_f32_e32 v22, v22, v24
	s_nop 0
	v_cndmask_b32_e64 v25, 0, 32, s[0:1]
	v_ldexp_f32 v23, v23, v25
	v_log_f32_e32 v23, v23
	v_div_scale_f32 v25, s[2:3], v16, v16, 1.0
	v_rcp_f32_e32 v26, v25
	v_mul_f32_e32 v24, 0x3f317217, v23
	v_fma_f32 v24, v23, s47, -v24
	v_fmac_f32_e32 v24, 0x3377d1cf, v23
	v_fmac_f32_e32 v24, 0x3f317217, v23
	v_cmp_lt_f32_e64 vcc, |v23|, s49
	s_nop 1
	v_cndmask_b32_e32 v23, v23, v24, vcc
	v_fma_f32 v24, -v25, v26, 1.0
	v_fmac_f32_e32 v26, v24, v26
;     __device__ __forceinline__ void operator()(const f32x4 (&acc)[2][2][4][2], const Unit& u, int wr, int wc, int fr, int fq) const {
;     ...
;                         for (int n = 0; n < 2; ++n) { f32x4 z = acc[ai][bj][m][n], o;
; #pragma unroll
;                             for (int e = 0; e < 4; ++e) { const float lb = lbv[bj][4 * n + e]; const float sg = 1.0f / (1.0f + __expf(-z[e])); o[e] = __logf(lb + (1.0f - lb) * sg); }
;                             *(f32x4*)(rowp + bj * HALF + 4 * n) = o; } }
	v_div_scale_f32 v24, vcc, 1.0, v16, 1.0
	v_mul_f32_e32 v27, v24, v26
	v_fma_f32 v28, -v25, v27, v24
	v_fmac_f32_e32 v27, v28, v26
	v_fma_f32 v24, -v25, v27, v24
	v_div_fmas_f32 v24, v24, v26, v27
	v_div_fixup_f32 v16, v24, v16, 1.0
	v_fma_f32 v16, v16, v135, v134
	v_cmp_gt_f32_e32 vcc, s46, v16
	s_nop 1
	v_cndmask_b32_e64 v24, 0, 32, vcc
	v_ldexp_f32 v16, v16, v24
	v_log_f32_e32 v16, v16
	v_cndmask_b32_e64 v24, 0, v193, s[0:1]
	v_sub_f32_e32 v23, v23, v24
	global_store_dwordx4 v[32:33], v[20:23], off offset:-3584
	s_nop 1
	v_div_scale_f32 v21, s[0:1], v17, v17, 1.0
	v_rcp_f32_e32 v22, v21
	v_mul_f32_e32 v20, 0x3f317217, v16
	v_fma_f32 v20, v16, s47, -v20
	v_fmac_f32_e32 v20, 0x3377d1cf, v16
	v_fmac_f32_e32 v20, 0x3f317217, v16
	v_cmp_lt_f32_e64 s[0:1], |v16|, s49
	v_fma_f32 v23, -v21, v22, 1.0
	v_fmac_f32_e32 v22, v23, v22
	v_cndmask_b32_e64 v16, v16, v20, s[0:1]
	v_cndmask_b32_e32 v20, 0, v193, vcc
	v_div_scale_f32 v23, vcc, 1.0, v17, 1.0
	v_mul_f32_e32 v24, v23, v22
	v_fma_f32 v25, -v21, v24, v23
	v_fmac_f32_e32 v24, v25, v22
	v_fma_f32 v21, -v21, v24, v23
	v_div_fmas_f32 v21, v21, v22, v24
	v_div_fixup_f32 v17, v21, v17, 1.0
	v_fma_f32 v17, v17, v117, v116
	v_cmp_gt_f32_e64 s[0:1], s46, v17
	v_sub_f32_e32 v16, v16, v20
	s_nop 0
	v_cndmask_b32_e64 v21, 0, 32, s[0:1]
	v_ldexp_f32 v17, v17, v21
	v_log_f32_e32 v17, v17
	v_div_scale_f32 v21, s[2:3], v18, v18, 1.0
	v_rcp_f32_e32 v22, v21
	v_mul_f32_e32 v20, 0x3f317217, v17
	v_fma_f32 v20, v17, s47, -v20
	v_fmac_f32_e32 v20, 0x3377d1cf, v17
	v_fmac_f32_e32 v20, 0x3f317217, v17
	v_cmp_lt_f32_e64 vcc, |v17|, s49
	s_mov_b64 s[2:3], 0xb0000
	s_nop 0
	v_cndmask_b32_e32 v17, v17, v20, vcc
	v_fma_f32 v20, -v21, v22, 1.0
	v_fmac_f32_e32 v22, v20, v22
	v_div_scale_f32 v20, vcc, 1.0, v18, 1.0
	v_mul_f32_e32 v23, v20, v22
	v_fma_f32 v24, -v21, v23, v20
	v_fmac_f32_e32 v23, v24, v22
	v_fma_f32 v20, -v21, v23, v20
	v_div_fmas_f32 v20, v20, v22, v23
	v_div_fixup_f32 v18, v20, v18, 1.0
	v_fma_f32 v18, v18, v119, v118
	v_cmp_gt_f32_e64 s[4:5], s46, v18
	s_nop 1
	v_cndmask_b32_e64 v20, 0, 32, s[4:5]
	v_ldexp_f32 v18, v18, v20
	v_cndmask_b32_e64 v20, 0, v193, s[0:1]
	v_div_scale_f32 v21, s[0:1], v19, v19, 1.0
	v_rcp_f32_e32 v22, v21
	v_log_f32_e32 v18, v18
	v_sub_f32_e32 v17, v17, v20
	v_fma_f32 v23, -v21, v22, 1.0
	v_fmac_f32_e32 v22, v23, v22
	v_div_scale_f32 v23, vcc, 1.0, v19, 1.0
	v_mul_f32_e32 v24, v23, v22
	v_fma_f32 v25, -v21, v24, v23
	v_fmac_f32_e32 v24, v25, v22
	v_fma_f32 v21, -v21, v24, v23
	v_div_fmas_f32 v21, v21, v22, v24
	v_div_fixup_f32 v19, v21, v19, 1.0
	v_fma_f32 v19, v19, v129, v128
	v_cmp_gt_f32_e32 vcc, s46, v19
	v_mul_f32_e32 v20, 0x3f317217, v18
	v_fma_f32 v20, v18, s47, -v20
	v_cndmask_b32_e64 v21, 0, 32, vcc
	v_ldexp_f32 v19, v19, v21
	v_log_f32_e32 v19, v19
	v_fmac_f32_e32 v20, 0x3377d1cf, v18
	v_fmac_f32_e32 v20, 0x3f317217, v18
	v_cmp_lt_f32_e64 s[0:1], |v18|, s49
	s_nop 1
	v_cndmask_b32_e64 v18, v18, v20, s[0:1]
	v_cndmask_b32_e64 v20, 0, v193, s[4:5]
	v_sub_f32_e32 v18, v18, v20
	v_mul_f32_e32 v20, 0x3f317217, v19
	v_fma_f32 v20, v19, s47, -v20
	v_fmac_f32_e32 v20, 0x3377d1cf, v19
	v_fmac_f32_e32 v20, 0x3f317217, v19
	v_cmp_lt_f32_e64 s[0:1], |v19|, s49
	s_nop 1
	v_cndmask_b32_e64 v19, v19, v20, s[0:1]
	v_cndmask_b32_e32 v20, 0, v193, vcc
	v_sub_f32_e32 v19, v19, v20
	v_div_scale_f32 v20, s[0:1], v12, v12, 1.0
	v_rcp_f32_e32 v21, v20
	global_store_dwordx4 v[32:33], v[16:19], off offset:-3568
	s_nop 1
	v_fma_f32 v16, -v20, v21, 1.0
	v_fmac_f32_e32 v21, v16, v21
	v_div_scale_f32 v16, vcc, 1.0, v12, 1.0
	v_mul_f32_e32 v17, v16, v21
	v_fma_f32 v18, -v20, v17, v16
	v_fmac_f32_e32 v17, v18, v21
	v_fma_f32 v16, -v20, v17, v16
	v_div_fmas_f32 v16, v16, v21, v17
	v_div_fixup_f32 v12, v16, v12, 1.0
	v_fmac_f32_e32 v156, v12, v157
	v_cmp_gt_f32_e64 s[0:1], s46, v156
	v_lshl_add_u64 v[16:17], v[180:181], 0, s[2:3]
	v_div_scale_f32 v19, s[2:3], v13, v13, 1.0
	v_cndmask_b32_e64 v12, 0, 32, s[0:1]
	v_ldexp_f32 v12, v156, v12
	v_log_f32_e32 v12, v12
	v_rcp_f32_e32 v20, v19
	v_mul_f32_e32 v18, 0x3f317217, v12
	v_fma_f32 v18, v12, s47, -v18
	v_fmac_f32_e32 v18, 0x3377d1cf, v12
	v_fmac_f32_e32 v18, 0x3f317217, v12
	v_cmp_lt_f32_e64 vcc, |v12|, s49
	s_nop 1
	v_cndmask_b32_e32 v12, v12, v18, vcc
	v_fma_f32 v18, -v19, v20, 1.0
	v_fmac_f32_e32 v20, v18, v20
	v_div_scale_f32 v18, vcc, 1.0, v13, 1.0
	v_mul_f32_e32 v21, v18, v20
	v_fma_f32 v22, -v19, v21, v18
	v_fmac_f32_e32 v21, v22, v20
	v_fma_f32 v18, -v19, v21, v18
	v_div_fmas_f32 v18, v18, v20, v21
	v_div_fixup_f32 v13, v18, v13, 1.0
	v_cndmask_b32_e64 v18, 0, v193, s[0:1]
	v_div_scale_f32 v19, s[0:1], v14, v14, 1.0
	v_rcp_f32_e32 v20, v19
	v_fmac_f32_e32 v158, v13, v159
	v_cmp_gt_f32_e64 s[4:5], s46, v158
	v_sub_f32_e32 v12, v12, v18
	v_fma_f32 v21, -v19, v20, 1.0
	v_fmac_f32_e32 v20, v21, v20
	v_div_scale_f32 v21, vcc, 1.0, v14, 1.0
	v_mul_f32_e32 v22, v21, v20
	v_fma_f32 v23, -v19, v22, v21
	v_cndmask_b32_e64 v13, 0, 32, s[4:5]
	v_fmac_f32_e32 v22, v23, v20
	v_ldexp_f32 v13, v158, v13
	v_fma_f32 v19, -v19, v22, v21
	v_log_f32_e32 v13, v13
	v_div_fmas_f32 v19, v19, v20, v22
	v_div_fixup_f32 v14, v19, v14, 1.0
	v_fmac_f32_e32 v154, v14, v155
	v_cmp_gt_f32_e32 vcc, s46, v154
	v_mul_f32_e32 v18, 0x3f317217, v13
	v_fma_f32 v18, v13, s47, -v18
	v_cndmask_b32_e64 v14, 0, 32, vcc
	v_ldexp_f32 v14, v154, v14
	v_fmac_f32_e32 v18, 0x3377d1cf, v13
	v_log_f32_e32 v14, v14
	v_fmac_f32_e32 v18, 0x3f317217, v13
	v_cmp_lt_f32_e64 s[0:1], |v13|, s49
	s_nop 1
	v_cndmask_b32_e64 v13, v13, v18, s[0:1]
	v_div_scale_f32 v19, s[0:1], v15, v15, 1.0
	v_cndmask_b32_e64 v18, 0, v193, s[4:5]
	v_rcp_f32_e32 v20, v19
	v_sub_f32_e32 v13, v13, v18
	v_mul_f32_e32 v18, 0x3f317217, v14
;     __device__ __forceinline__ void operator()(const f32x4 (&acc)[2][2][4][2], const Unit& u, int wr, int wc, int fr, int fq) const {
;     ...
;                         for (int n = 0; n < 2; ++n) { f32x4 z = acc[ai][bj][m][n], o;
; #pragma unroll
;                             for (int e = 0; e < 4; ++e) { const float lb = lbv[bj][4 * n + e]; const float sg = 1.0f / (1.0f + __expf(-z[e])); o[e] = __logf(lb + (1.0f - lb) * sg); }
;                             *(f32x4*)(rowp + bj * HALF + 4 * n) = o; } }
	v_fma_f32 v18, v14, s47, -v18
	v_fmac_f32_e32 v18, 0x3377d1cf, v14
	v_fmac_f32_e32 v18, 0x3f317217, v14
	v_cmp_lt_f32_e64 s[0:1], |v14|, s49
	v_fma_f32 v21, -v19, v20, 1.0
	v_fmac_f32_e32 v20, v21, v20
	v_cndmask_b32_e64 v14, v14, v18, s[0:1]
	v_cndmask_b32_e32 v18, 0, v193, vcc
	v_div_scale_f32 v21, vcc, 1.0, v15, 1.0
	v_mul_f32_e32 v22, v21, v20
	v_fma_f32 v23, -v19, v22, v21
	v_fmac_f32_e32 v22, v23, v20
	v_fma_f32 v19, -v19, v22, v21
	v_div_fmas_f32 v19, v19, v20, v22
	v_div_fixup_f32 v15, v19, v15, 1.0
	v_fmac_f32_e32 v152, v15, v153
	v_cmp_gt_f32_e64 s[0:1], s46, v152
	v_div_scale_f32 v19, s[2:3], v8, v8, 1.0
	s_nop 0
	v_cndmask_b32_e64 v15, 0, 32, s[0:1]
	v_ldexp_f32 v15, v152, v15
	v_log_f32_e32 v15, v15
	v_sub_f32_e32 v14, v14, v18
	v_rcp_f32_e32 v20, v19
	v_mul_f32_e32 v18, 0x3f317217, v15
	v_fma_f32 v18, v15, s47, -v18
	v_fmac_f32_e32 v18, 0x3377d1cf, v15
	v_fmac_f32_e32 v18, 0x3f317217, v15
	v_cmp_lt_f32_e64 vcc, |v15|, s49
	s_nop 1
	v_cndmask_b32_e32 v15, v15, v18, vcc
	v_fma_f32 v18, -v19, v20, 1.0
	v_fmac_f32_e32 v20, v18, v20
	v_div_scale_f32 v18, vcc, 1.0, v8, 1.0
	v_mul_f32_e32 v21, v18, v20
	v_fma_f32 v22, -v19, v21, v18
	v_fmac_f32_e32 v21, v22, v20
	v_fma_f32 v18, -v19, v21, v18
	v_div_fmas_f32 v18, v18, v20, v21
	v_div_fixup_f32 v8, v18, v8, 1.0
	v_fmac_f32_e32 v150, v8, v151
	v_cmp_gt_f32_e32 vcc, s46, v150
	v_cndmask_b32_e64 v18, 0, v193, s[0:1]
	v_sub_f32_e32 v15, v15, v18
	v_cndmask_b32_e64 v8, 0, 32, vcc
	v_ldexp_f32 v8, v150, v8
	v_log_f32_e32 v8, v8
	global_store_dwordx4 v[16:17], v[12:15], off offset:-4096
	s_nop 1
	v_div_scale_f32 v13, s[0:1], v9, v9, 1.0
	v_rcp_f32_e32 v14, v13
	v_mul_f32_e32 v12, 0x3f317217, v8
	v_fma_f32 v12, v8, s47, -v12
	v_fmac_f32_e32 v12, 0x3377d1cf, v8
	v_fmac_f32_e32 v12, 0x3f317217, v8
	v_cmp_lt_f32_e64 s[0:1], |v8|, s49
	v_fma_f32 v15, -v13, v14, 1.0
	v_fmac_f32_e32 v14, v15, v14
	v_cndmask_b32_e64 v8, v8, v12, s[0:1]
	v_cndmask_b32_e32 v12, 0, v193, vcc
	v_div_scale_f32 v15, vcc, 1.0, v9, 1.0
	v_mul_f32_e32 v18, v15, v14
	v_fma_f32 v19, -v13, v18, v15
	v_fmac_f32_e32 v18, v19, v14
	v_fma_f32 v13, -v13, v18, v15
	v_div_fmas_f32 v13, v13, v14, v18
	v_div_fixup_f32 v9, v13, v9, 1.0
	v_fmac_f32_e32 v124, v9, v125
	v_cmp_gt_f32_e64 s[0:1], s46, v124
	v_div_scale_f32 v13, s[2:3], v10, v10, 1.0
	s_nop 0
	v_cndmask_b32_e64 v9, 0, 32, s[0:1]
	v_ldexp_f32 v9, v124, v9
	v_log_f32_e32 v9, v9
	v_sub_f32_e32 v8, v8, v12
	v_rcp_f32_e32 v14, v13
	v_mul_f32_e32 v12, 0x3f317217, v9
	v_fma_f32 v12, v9, s47, -v12
	v_fmac_f32_e32 v12, 0x3377d1cf, v9
	v_fmac_f32_e32 v12, 0x3f317217, v9
	v_cmp_lt_f32_e64 vcc, |v9|, s49
	s_nop 1
	v_cndmask_b32_e32 v9, v9, v12, vcc
	v_fma_f32 v12, -v13, v14, 1.0
	v_fmac_f32_e32 v14, v12, v14
	v_div_scale_f32 v12, vcc, 1.0, v10, 1.0
	v_mul_f32_e32 v15, v12, v14
	v_fma_f32 v18, -v13, v15, v12
	v_fmac_f32_e32 v15, v18, v14
	v_fma_f32 v12, -v13, v15, v12
	v_div_fmas_f32 v12, v12, v14, v15
	v_div_fixup_f32 v10, v12, v10, 1.0
	v_cndmask_b32_e64 v12, 0, v193, s[0:1]
	v_div_scale_f32 v13, s[0:1], v11, v11, 1.0
	v_rcp_f32_e32 v14, v13
	v_fmac_f32_e32 v126, v10, v127
	v_cmp_gt_f32_e64 s[4:5], s46, v126
	v_sub_f32_e32 v9, v9, v12
	v_fma_f32 v15, -v13, v14, 1.0
	v_fmac_f32_e32 v14, v15, v14
	v_div_scale_f32 v15, vcc, 1.0, v11, 1.0
	v_mul_f32_e32 v18, v15, v14
	v_fma_f32 v19, -v13, v18, v15
	v_fmac_f32_e32 v18, v19, v14
	v_cndmask_b32_e64 v10, 0, 32, s[4:5]
	v_fma_f32 v13, -v13, v18, v15
	v_ldexp_f32 v10, v126, v10
	v_div_fmas_f32 v13, v13, v14, v18
	v_log_f32_e32 v10, v10
	v_div_fixup_f32 v11, v13, v11, 1.0
	v_fmac_f32_e32 v144, v11, v145
	v_cmp_gt_f32_e32 vcc, s46, v144
	v_mul_f32_e32 v12, 0x3f317217, v10
	v_fma_f32 v12, v10, s47, -v12
	v_cndmask_b32_e64 v11, 0, 32, vcc
	v_ldexp_f32 v11, v144, v11
	v_log_f32_e32 v11, v11
	v_fmac_f32_e32 v12, 0x3377d1cf, v10
	v_fmac_f32_e32 v12, 0x3f317217, v10
	v_cmp_lt_f32_e64 s[0:1], |v10|, s49
	s_nop 1
	v_cndmask_b32_e64 v10, v10, v12, s[0:1]
	v_cndmask_b32_e64 v12, 0, v193, s[4:5]
	v_sub_f32_e32 v10, v10, v12
	v_mul_f32_e32 v12, 0x3f317217, v11
	v_div_scale_f32 v13, s[0:1], v4, v4, 1.0
	v_fma_f32 v12, v11, s47, -v12
	v_rcp_f32_e32 v14, v13
	v_fmac_f32_e32 v12, 0x3377d1cf, v11
	v_fmac_f32_e32 v12, 0x3f317217, v11
	v_cmp_lt_f32_e64 s[0:1], |v11|, s49
	s_nop 1
	v_cndmask_b32_e64 v11, v11, v12, s[0:1]
	v_cndmask_b32_e32 v12, 0, v193, vcc
	v_sub_f32_e32 v11, v11, v12
	v_fma_f32 v12, -v13, v14, 1.0
	v_fmac_f32_e32 v14, v12, v14
	v_div_scale_f32 v12, vcc, 1.0, v4, 1.0
	v_mul_f32_e32 v15, v12, v14
	v_fma_f32 v18, -v13, v15, v12
	v_fmac_f32_e32 v15, v18, v14
	v_fma_f32 v12, -v13, v15, v12
	v_div_fmas_f32 v12, v12, v14, v15
	v_div_fixup_f32 v4, v12, v4, 1.0
	v_fmac_f32_e32 v142, v4, v143
	v_cmp_gt_f32_e64 s[0:1], s46, v142
	global_store_dwordx4 v[16:17], v[8:11], off offset:-4080
	s_nop 0
	v_cndmask_b32_e64 v4, 0, 32, s[0:1]
	v_ldexp_f32 v4, v142, v4
	v_log_f32_e32 v4, v4
	v_div_scale_f32 v9, s[2:3], v5, v5, 1.0
	v_rcp_f32_e32 v10, v9
	v_mul_f32_e32 v8, 0x3f317217, v4
	v_fma_f32 v8, v4, s47, -v8
	v_fmac_f32_e32 v8, 0x3377d1cf, v4
	v_fmac_f32_e32 v8, 0x3f317217, v4
	v_cmp_lt_f32_e64 vcc, |v4|, s49
	s_nop 1
	v_cndmask_b32_e32 v4, v4, v8, vcc
	v_fma_f32 v8, -v9, v10, 1.0
	v_fmac_f32_e32 v10, v8, v10
	v_div_scale_f32 v8, vcc, 1.0, v5, 1.0
	v_mul_f32_e32 v11, v8, v10
	v_fma_f32 v12, -v9, v11, v8
	v_fmac_f32_e32 v11, v12, v10
	v_fma_f32 v8, -v9, v11, v8
;     __device__ __forceinline__ void operator()(const f32x4 (&acc)[2][2][4][2], const Unit& u, int wr, int wc, int fr, int fq) const {
;     ...
;                         for (int n = 0; n < 2; ++n) { f32x4 z = acc[ai][bj][m][n], o;
; #pragma unroll
;                             for (int e = 0; e < 4; ++e) { const float lb = lbv[bj][4 * n + e]; const float sg = 1.0f / (1.0f + __expf(-z[e])); o[e] = __logf(lb + (1.0f - lb) * sg); }
;                             *(f32x4*)(rowp + bj * HALF + 4 * n) = o; } }
; template <class Epi, class Sched, bool ALIGN_EPI = false, bool SP2 = false>
; __device__ __forceinline__ void gemm_phase(PG8_LAS unsigned char* lds, const Gemm g, const Sched& S, const Epi& E) {
;     ...
;         if constexpr (!Epi::AFTER_DRAIN) { E(acc, cur, wr, wc, fr, fq); S.done(cur); }
;         if (!has_next) break;
	v_div_fmas_f32 v8, v8, v10, v11
	v_div_fixup_f32 v5, v8, v5, 1.0
	v_cndmask_b32_e64 v8, 0, v193, s[0:1]
	v_div_scale_f32 v9, s[0:1], v6, v6, 1.0
	v_rcp_f32_e32 v10, v9
	v_fmac_f32_e32 v120, v5, v121
	v_cmp_gt_f32_e64 s[4:5], s46, v120
	v_sub_f32_e32 v4, v4, v8
	v_fma_f32 v11, -v9, v10, 1.0
	v_fmac_f32_e32 v10, v11, v10
	v_div_scale_f32 v11, vcc, 1.0, v6, 1.0
	v_mul_f32_e32 v12, v11, v10
	v_fma_f32 v13, -v9, v12, v11
	v_cndmask_b32_e64 v5, 0, 32, s[4:5]
	v_fmac_f32_e32 v12, v13, v10
	v_ldexp_f32 v5, v120, v5
	v_fma_f32 v9, -v9, v12, v11
	v_log_f32_e32 v5, v5
	v_div_fmas_f32 v9, v9, v10, v12
	v_div_fixup_f32 v6, v9, v6, 1.0
	v_fmac_f32_e32 v122, v6, v123
	v_cmp_gt_f32_e32 vcc, s46, v122
	v_mul_f32_e32 v8, 0x3f317217, v5
	v_fma_f32 v8, v5, s47, -v8
	v_cndmask_b32_e64 v6, 0, 32, vcc
	v_ldexp_f32 v6, v122, v6
	v_fmac_f32_e32 v8, 0x3377d1cf, v5
	v_log_f32_e32 v6, v6
	v_fmac_f32_e32 v8, 0x3f317217, v5
	v_cmp_lt_f32_e64 s[0:1], |v5|, s49
	s_nop 1
	v_cndmask_b32_e64 v5, v5, v8, s[0:1]
	v_div_scale_f32 v9, s[0:1], v7, v7, 1.0
	v_cndmask_b32_e64 v8, 0, v193, s[4:5]
	v_rcp_f32_e32 v10, v9
	v_sub_f32_e32 v5, v5, v8
	v_mul_f32_e32 v8, 0x3f317217, v6
	v_fma_f32 v8, v6, s47, -v8
	v_fmac_f32_e32 v8, 0x3377d1cf, v6
	v_fmac_f32_e32 v8, 0x3f317217, v6
	v_cmp_lt_f32_e64 s[0:1], |v6|, s49
	v_fma_f32 v11, -v9, v10, 1.0
	v_fmac_f32_e32 v10, v11, v10
	v_cndmask_b32_e64 v6, v6, v8, s[0:1]
	v_cndmask_b32_e32 v8, 0, v193, vcc
	v_div_scale_f32 v11, vcc, 1.0, v7, 1.0
	v_mul_f32_e32 v12, v11, v10
	v_fma_f32 v13, -v9, v12, v11
	v_fmac_f32_e32 v12, v13, v10
	v_fma_f32 v9, -v9, v12, v11
	v_div_fmas_f32 v9, v9, v10, v12
	v_div_fixup_f32 v7, v9, v7, 1.0
	v_fmac_f32_e32 v136, v7, v137
	v_cmp_gt_f32_e64 s[0:1], s46, v136
	v_div_scale_f32 v9, s[2:3], v0, v0, 1.0
	s_nop 0
	v_cndmask_b32_e64 v7, 0, 32, s[0:1]
	v_ldexp_f32 v7, v136, v7
	v_log_f32_e32 v7, v7
	v_sub_f32_e32 v6, v6, v8
	v_rcp_f32_e32 v10, v9
	v_mul_f32_e32 v8, 0x3f317217, v7
	v_fma_f32 v8, v7, s47, -v8
	v_fmac_f32_e32 v8, 0x3377d1cf, v7
	v_fmac_f32_e32 v8, 0x3f317217, v7
	v_cmp_lt_f32_e64 vcc, |v7|, s49
	s_nop 1
	v_cndmask_b32_e32 v7, v7, v8, vcc
	v_fma_f32 v8, -v9, v10, 1.0
	v_fmac_f32_e32 v10, v8, v10
	v_div_scale_f32 v8, vcc, 1.0, v0, 1.0
	v_mul_f32_e32 v11, v8, v10
	v_fma_f32 v12, -v9, v11, v8
	v_fmac_f32_e32 v11, v12, v10
	v_fma_f32 v8, -v9, v11, v8
	v_div_fmas_f32 v8, v8, v10, v11
	v_div_fixup_f32 v0, v8, v0, 1.0
	v_fmac_f32_e32 v134, v0, v135
	v_cmp_gt_f32_e32 vcc, s46, v134
	v_cndmask_b32_e64 v8, 0, v193, s[0:1]
	v_sub_f32_e32 v7, v7, v8
	v_cndmask_b32_e64 v0, 0, 32, vcc
	v_ldexp_f32 v0, v134, v0
	v_log_f32_e32 v0, v0
	global_store_dwordx4 v[16:17], v[4:7], off offset:-3584
	s_nop 1
	v_div_scale_f32 v5, s[0:1], v1, v1, 1.0
	v_rcp_f32_e32 v6, v5
	v_mul_f32_e32 v4, 0x3f317217, v0
	v_fma_f32 v4, v0, s47, -v4
	v_fmac_f32_e32 v4, 0x3377d1cf, v0
	v_fmac_f32_e32 v4, 0x3f317217, v0
	v_cmp_lt_f32_e64 s[0:1], |v0|, s49
	v_fma_f32 v7, -v5, v6, 1.0
	v_fmac_f32_e32 v6, v7, v6
	v_cndmask_b32_e64 v0, v0, v4, s[0:1]
	v_cndmask_b32_e32 v4, 0, v193, vcc
	v_div_scale_f32 v7, vcc, 1.0, v1, 1.0
	v_mul_f32_e32 v8, v7, v6
	v_fma_f32 v9, -v5, v8, v7
	v_fmac_f32_e32 v8, v9, v6
	v_fma_f32 v5, -v5, v8, v7
	v_div_fmas_f32 v5, v5, v6, v8
	v_div_fixup_f32 v1, v5, v1, 1.0
	v_fmac_f32_e32 v116, v1, v117
	v_cmp_gt_f32_e64 s[0:1], s46, v116
	v_div_scale_f32 v5, s[2:3], v2, v2, 1.0
	s_nop 0
	v_cndmask_b32_e64 v1, 0, 32, s[0:1]
	v_ldexp_f32 v1, v116, v1
	v_log_f32_e32 v1, v1
	v_sub_f32_e32 v0, v0, v4
	v_rcp_f32_e32 v6, v5
	v_mul_f32_e32 v4, 0x3f317217, v1
	v_fma_f32 v4, v1, s47, -v4
	v_fmac_f32_e32 v4, 0x3377d1cf, v1
	v_fmac_f32_e32 v4, 0x3f317217, v1
	v_cmp_lt_f32_e64 vcc, |v1|, s49
	s_nop 1
	v_cndmask_b32_e32 v1, v1, v4, vcc
	v_fma_f32 v4, -v5, v6, 1.0
	v_fmac_f32_e32 v6, v4, v6
	v_div_scale_f32 v4, vcc, 1.0, v2, 1.0
	v_mul_f32_e32 v7, v4, v6
	v_fma_f32 v8, -v5, v7, v4
	v_fmac_f32_e32 v7, v8, v6
	v_fma_f32 v4, -v5, v7, v4
	v_div_fmas_f32 v4, v4, v6, v7
	v_div_fixup_f32 v2, v4, v2, 1.0
	v_cndmask_b32_e64 v4, 0, v193, s[0:1]
	v_div_scale_f32 v5, s[0:1], v3, v3, 1.0
	v_rcp_f32_e32 v6, v5
	v_fmac_f32_e32 v118, v2, v119
	v_cmp_gt_f32_e64 s[4:5], s46, v118
	v_sub_f32_e32 v1, v1, v4
	v_fma_f32 v7, -v5, v6, 1.0
	v_fmac_f32_e32 v6, v7, v6
	v_div_scale_f32 v7, vcc, 1.0, v3, 1.0
	v_mul_f32_e32 v8, v7, v6
	v_fma_f32 v9, -v5, v8, v7
	v_fmac_f32_e32 v8, v9, v6
	v_cndmask_b32_e64 v2, 0, 32, s[4:5]
	v_fma_f32 v5, -v5, v8, v7
	v_ldexp_f32 v2, v118, v2
	v_div_fmas_f32 v5, v5, v6, v8
	v_log_f32_e32 v2, v2
	v_div_fixup_f32 v3, v5, v3, 1.0
	v_fmac_f32_e32 v128, v3, v129
	v_cmp_gt_f32_e32 vcc, s46, v128
	v_mul_f32_e32 v4, 0x3f317217, v2
	v_fma_f32 v4, v2, s47, -v4
	v_cndmask_b32_e64 v3, 0, 32, vcc
	v_ldexp_f32 v3, v128, v3
	v_log_f32_e32 v3, v3
	v_fmac_f32_e32 v4, 0x3377d1cf, v2
	v_fmac_f32_e32 v4, 0x3f317217, v2
	v_cmp_lt_f32_e64 s[0:1], |v2|, s49
	s_nop 1
	v_cndmask_b32_e64 v2, v2, v4, s[0:1]
	v_cndmask_b32_e64 v4, 0, v193, s[4:5]
	v_sub_f32_e32 v2, v2, v4
	v_mul_f32_e32 v4, 0x3f317217, v3
	v_fma_f32 v4, v3, s47, -v4
	v_fmac_f32_e32 v4, 0x3377d1cf, v3
	v_fmac_f32_e32 v4, 0x3f317217, v3
	v_cmp_lt_f32_e64 s[0:1], |v3|, s49
	s_nop 1
	v_cndmask_b32_e64 v3, v3, v4, s[0:1]
	v_cndmask_b32_e32 v4, 0, v193, vcc
	v_sub_f32_e32 v3, v3, v4
	global_store_dwordx4 v[16:17], v[0:3], off offset:-3568
	s_andn2_b64 vcc, exec, s[8:9]
	s_mov_b64 s[0:1], -1
	s_mov_b32 s99, 1
	s_cbranch_vccnz .LBB0_198

; #define PG8_STAGE(bufoff, gbase, voff) do { _Pragma("unroll") for (int _i = 0; _i < 2; ++_i) \
;         __builtin_amdgcn_global_load_lds((const unsigned*)((const char*)(gbase) + (voff)[_i]), (PG8_LAS unsigned*)(lds + (bufoff) + ldsw + _i * 8192), 16, 0, 0); } while (0)
; #define PG8_WAIT_V(n) asm volatile("s_waitcnt vmcnt(" #n ")" ::: "memory")
; #define PG8_BAR __builtin_amdgcn_s_barrier()
; template <class Epi, class Sched, bool ALIGN_EPI = false, bool SP2 = false>
; __device__ __forceinline__ void gemm_phase(PG8_LAS unsigned char* lds, const Gemm g, const Sched& S, const Epi& E) {
;     ...
;     const unsigned ldsw = (unsigned)wid * 1024u;
;     const int aoff = lds_byte(wr * 64 + fr, fq * 8), boff = lds_byte(wc * 32 + fr, fq * 8);
;     ...
;     if constexpr (SP2) {
;         PG8_STAGE(PG8_SB(0, 0), cB, voffB); PG8_STAGE(PG8_SB(0, 1), cB + hstep, voffB); PG8_STAGE(PG8_SA(0, 0), cA, voffA); PG8_STAGE(PG8_SA(0, 1), cA + hstep, voffA);
;         if (wr == 1) PG8_BAR;
;         PG8_WAIT_V(2); PG8_BAR;
;         PG8_STAGE(PG8_SB(1, 0), cB + kstep, voffB); PG8_STAGE(PG8_SA(1, 0), cA + kstep, voffA); PG8_STAGE(PG8_SB(1, 1), cB + hstep + kstep, voffB);
;         PG8_WAIT_V(6); PG8_BAR;
.LBB0_562:
	s_mov_b32 s99, 0
	s_lshl_b32 s8, s8, 5
	s_and_b32 s13, s8, 0x60
	s_mov_b64 s[8:9], 0x80
	s_add_i32 m0, s31, 0x18000
	v_lshl_add_u64 v[6:7], v[6:7], 0, s[8:9]
	s_lshl_b32 s12, s5, 13
	s_lshl_b32 s14, s13, 7
	s_waitcnt vmcnt(2)
	s_barrier
	global_load_lds_dwordx4 v[6:7], off
	v_lshl_add_u64 v[4:5], v[4:5], 0, s[8:9]
	s_add_i32 m0, s31, 0x1a000
	s_add_i32 s36, s31, 0x8000
	s_add_i32 s37, s31, 0xa000
	global_load_lds_dwordx4 v[4:5], off
	v_lshl_add_u64 v[0:1], v[0:1], 0, s[8:9]
	s_mov_b32 m0, s36
	s_add_u32 s10, s24, 0x40080
	global_load_lds_dwordx4 v[0:1], off
	v_lshl_add_u64 v[0:1], v[2:3], 0, s[8:9]
	s_mov_b32 m0, s37
	s_addc_u32 s11, s25, 0
	global_load_lds_dwordx4 v[0:1], off
	s_add_i32 m0, s31, 0x1c000
	v_lshl_add_u64 v[0:1], s[10:11], 0, v[130:131]
	global_load_lds_dwordx4 v[0:1], off
	v_lshl_add_u64 v[0:1], s[10:11], 0, v[134:135]
	s_add_i32 m0, s31, 0x1e000
	s_cmpk_lt_u32 s4, 0x100
	global_load_lds_dwordx4 v[0:1], off
	v_lshrrev_b32_e32 v1, 1, v8
	v_and_b32_e32 v1, 24, v1
	v_and_b32_e32 v0, 15, v8
	v_lshlrev_b32_e32 v2, 1, v1
	v_lshl_or_b32 v156, s5, 6, v0
	v_lshl_or_b32 v0, v0, 6, v2
	v_lshlrev_b32_e32 v2, 2, v8
	v_and_b32_e32 v2, 32, v2
	v_bitop3_b32 v3, v0, s12, v2 bitop3:0xde
	v_bitop3_b32 v157, v0, s14, v2 bitop3:0xde
	v_lshlrev_b32_e32 v0, 14, v9
	v_and_b32_e32 v0, 0xffff8000, v0
	v_or_b32_e32 v158, s13, v1
	v_lshl_add_u32 v0, v10, 11, v0
	v_and_b32_e32 v1, 1, v9
	v_lshl_or_b32 v0, v1, 6, v0
	v_lshl_add_u32 v138, v11, 1, v0
	v_lshlrev_b32_e32 v0, 14, v12
	v_and_b32_e32 v0, 0xffff8000, v0
	s_waitcnt vmcnt(6)
	v_lshl_add_u32 v0, v13, 11, v0
	v_and_b32_e32 v1, 1, v12
	s_cselect_b64 s[10:11], -1, 0
	v_lshl_or_b32 v0, v1, 6, v0
	s_add_i32 s39, 0, 0x10000
	s_add_i32 s40, 0, 0x14000
	s_ashr_i32 s38, s62, 31
	v_mov_b32_e32 v139, v137
	v_lshl_add_u32 v140, v14, 1, v0
	v_mov_b32_e32 v141, v137
	v_mov_b64_e32 v[142:143], 0x200
	v_mov_b64_e32 v[144:145], 0x1ff
	v_add_u32_e32 v159, s39, v157
	v_add_u32_e32 v161, s40, v157
	v_add_u32_e32 v162, 0, v3
	s_movk_i32 s41, 0x1200
	s_movk_i32 s42, 0x4400
	s_barrier
	s_branch .LBB0_565

;     __device__ __forceinline__ bool next(int i, Unit& u) const { if (!base.next(i >> 1, u)) return false; if (i & 1) { u.pm += 64; u.pn += 8; } return true; }
; #define PG8_STAGE(bufoff, gbase, voff) do { _Pragma("unroll") for (int _i = 0; _i < 2; ++_i) \
;         __builtin_amdgcn_global_load_lds((const unsigned*)((const char*)(gbase) + (voff)[_i]), (PG8_LAS unsigned*)(lds + (bufoff) + ldsw + _i * 8192), 16, 0, 0); } while (0)
; #define PG8_LDA(dst, b, h) do { _Pragma("unroll") for (int m = 0; m < 4; ++m) _Pragma("unroll") for (int k = 0; k < 2; ++k) dst[m][k] = *(const PG8_LAS bf16x8*)(lds + PG8_SA(b, h) + aoff + m * 2048 + k * 1024); } while (0)
; #define PG8_LDB(dst, b, h) do { _Pragma("unroll") for (int n = 0; n < 2; ++n) _Pragma("unroll") for (int k = 0; k < 2; ++k) dst[n][k] = *(const PG8_LAS bf16x8*)(lds + PG8_SB(b, h) + boff + n * 2048 + k * 1024); } while (0)
; #define PG8_WAIT_V(n) asm volatile("s_waitcnt vmcnt(" #n ")" ::: "memory")
; template <class Epi, class Sched, bool ALIGN_EPI = false, bool SP2 = false>
; __device__ __forceinline__ void gemm_phase(PG8_LAS unsigned char* lds, const Gemm g, const Sched& S, const Epi& E) {
;     ...
;         const bool has_next = S.next(ui + 1, nxt);
;         const char* nA = has_next ? (const char*)g.A + (size_t)nxt.pm * tstep : cA; const char* nB = has_next ? (const char*)g.Bt + (size_t)nxt.pn * tstep : cB;
;         for (int t = 0; t < nt; t += 2) {
;             const bool last = (t == nt - 2);
;             const char* a1 = cA + (size_t)(t + 1) * kstep;
;             const char* a2 = last ? nA : cA + (size_t)(t + 2) * kstep; const char* b2 = last ? nB : cB + (size_t)(t + 2) * kstep;
;             const char* a3 = a2 + kstep; const char* b3 = b2 + kstep;
;             if (last && has_next) S.a_ready(nxt);
;             if constexpr (SP2) {
;             PG8_LDB(B0, 0, 0); PG8_LDB(B1, 0, 1); PG8_SCHED; PG8_LDA(At, 0, 0); PG8_STAGE(PG8_SA(1, 1), a1 + hstep, voffA);
;             PG8_WAIT_V(8); PG8_WAIT_L(0); PG8_BAR; PG8_MMA(0, 0, At, B0); PG8_MMA(0, 1, At, B1); PG8_BAR; PG8_SCHED;
;     ...
;         for (int a = 0; a < 2; ++a)
; #pragma unroll
;             for (int b = 0; b < 2; ++b)
; #pragma unroll
;                 for (int m = 0; m < 4; ++m)
; #pragma unroll
;                     for (int n = 0; n < 2; ++n) acc[a][b][m][n] = (f32x4){0.f, 0.f, 0.f, 0.f};
;         cur = nxt; cA = nA; cB = nB; ++ui;
.LBB0_571:
	s_bitcmp0_b32 s7, 0
	s_cselect_b64 s[16:17], -1, 0
	s_and_b64 s[16:17], s[16:17], s[4:5]
	s_add_i32 s7, s14, 64
	s_add_i32 s13, s12, 8
	s_and_b64 s[16:17], s[16:17], exec
	s_cselect_b32 s14, s7, s14
	s_cselect_b32 s12, s13, s12
	s_ashr_i32 s15, s14, 31
	s_lshl_b64 s[16:17], s[14:15], 19
	s_add_u32 s16, s29, s16
	s_addc_u32 s17, s30, s17
	s_and_b64 s[18:19], s[4:5], exec
	s_cselect_b32 s7, s17, s23
	s_cselect_b32 s15, s16, s22
	s_ashr_i32 s13, s12, 31
	s_lshl_b64 s[18:19], s[12:13], 19
	v_readlane_b32 s26, v236, 41
	v_readlane_b32 s27, v236, 42
	s_add_u32 s18, s26, s18
	s_addc_u32 s19, s27, s19
	s_and_b64 s[26:27], s[4:5], exec
	s_cselect_b32 s13, s19, s25
	s_cselect_b32 s21, s18, s24
	s_add_u32 s22, s22, 0x40080
	s_addc_u32 s23, s23, 0
	s_add_u32 s44, s24, 0x100
	v_mov_b32_e32 v0, 0
	s_addc_u32 s45, s25, 0
	s_mov_b32 s46, -2
	v_mov_b32_e32 v1, v0
	v_mov_b32_e32 v2, v0
	v_mov_b32_e32 v3, v0
	v_mov_b32_e32 v4, v0
	v_mov_b32_e32 v5, v0
	v_mov_b32_e32 v6, v0
	v_mov_b32_e32 v7, v0
	v_mov_b32_e32 v16, v0
	v_mov_b32_e32 v17, v0
	v_mov_b32_e32 v18, v0
	v_mov_b32_e32 v19, v0
	v_mov_b32_e32 v20, v0
	v_mov_b32_e32 v21, v0
	v_mov_b32_e32 v22, v0
	v_mov_b32_e32 v23, v0
	v_mov_b32_e32 v32, v0
	v_mov_b32_e32 v33, v0
	v_mov_b32_e32 v34, v0
	v_mov_b32_e32 v35, v0
	v_mov_b32_e32 v36, v0
	v_mov_b32_e32 v37, v0
	v_mov_b32_e32 v38, v0
	v_mov_b32_e32 v39, v0
	v_mov_b32_e32 v48, v0
	v_mov_b32_e32 v49, v0
	v_mov_b32_e32 v50, v0
	v_mov_b32_e32 v51, v0
	v_mov_b32_e32 v52, v0
	v_mov_b32_e32 v53, v0
	v_mov_b32_e32 v54, v0
	v_mov_b32_e32 v55, v0
	v_mov_b32_e32 v8, v0
	v_mov_b32_e32 v9, v0
	v_mov_b32_e32 v10, v0
	v_mov_b32_e32 v11, v0
	v_mov_b32_e32 v12, v0
	v_mov_b32_e32 v13, v0
	v_mov_b32_e32 v14, v0
	v_mov_b32_e32 v15, v0
	v_mov_b32_e32 v24, v0
	v_mov_b32_e32 v25, v0
	v_mov_b32_e32 v26, v0
	v_mov_b32_e32 v27, v0
	v_mov_b32_e32 v28, v0
	v_mov_b32_e32 v29, v0
	v_mov_b32_e32 v30, v0
	v_mov_b32_e32 v31, v0
	v_mov_b32_e32 v40, v0
	v_mov_b32_e32 v41, v0
	v_mov_b32_e32 v42, v0
	v_mov_b32_e32 v43, v0
	v_mov_b32_e32 v44, v0
	v_mov_b32_e32 v45, v0
	v_mov_b32_e32 v46, v0
	v_mov_b32_e32 v47, v0
	v_mov_b32_e32 v56, v0
	v_mov_b32_e32 v57, v0
	v_mov_b32_e32 v58, v0
	v_mov_b32_e32 v59, v0
	v_mov_b32_e32 v60, v0
	v_mov_b32_e32 v61, v0
	v_mov_b32_e32 v62, v0
	v_mov_b32_e32 v63, v0
	v_mov_b32_e32 v64, v0
	v_mov_b32_e32 v65, v0
	v_mov_b32_e32 v66, v0
	v_mov_b32_e32 v67, v0
	v_mov_b32_e32 v68, v0
	v_mov_b32_e32 v69, v0
	v_mov_b32_e32 v70, v0
	v_mov_b32_e32 v71, v0
	v_mov_b32_e32 v80, v0
	v_mov_b32_e32 v81, v0
	v_mov_b32_e32 v82, v0
	v_mov_b32_e32 v83, v0
	v_mov_b32_e32 v84, v0
	v_mov_b32_e32 v85, v0
	v_mov_b32_e32 v86, v0
	v_mov_b32_e32 v87, v0
	v_mov_b32_e32 v96, v0
	v_mov_b32_e32 v97, v0
	v_mov_b32_e32 v98, v0
	v_mov_b32_e32 v99, v0
	v_mov_b32_e32 v100, v0
	v_mov_b32_e32 v101, v0
	v_mov_b32_e32 v102, v0
	v_mov_b32_e32 v103, v0
	v_mov_b32_e32 v112, v0
	v_mov_b32_e32 v113, v0
	v_mov_b32_e32 v114, v0
	v_mov_b32_e32 v115, v0
	v_mov_b32_e32 v116, v0
	v_mov_b32_e32 v117, v0
	v_mov_b32_e32 v118, v0
	v_mov_b32_e32 v119, v0
	v_mov_b32_e32 v72, v0
	v_mov_b32_e32 v73, v0
	v_mov_b32_e32 v74, v0
	v_mov_b32_e32 v75, v0
	v_mov_b32_e32 v76, v0
	v_mov_b32_e32 v77, v0
	v_mov_b32_e32 v78, v0
	v_mov_b32_e32 v79, v0
	v_mov_b32_e32 v88, v0
	v_mov_b32_e32 v89, v0
	v_mov_b32_e32 v90, v0
	v_mov_b32_e32 v91, v0
	v_mov_b32_e32 v92, v0
	v_mov_b32_e32 v93, v0
	v_mov_b32_e32 v94, v0
	v_mov_b32_e32 v95, v0
	v_mov_b32_e32 v104, v0
	v_mov_b32_e32 v105, v0
	v_mov_b32_e32 v106, v0
	v_mov_b32_e32 v107, v0
	v_mov_b32_e32 v108, v0
	v_mov_b32_e32 v109, v0
	v_mov_b32_e32 v110, v0
	v_mov_b32_e32 v111, v0
	v_mov_b32_e32 v120, v0
	v_mov_b32_e32 v121, v0
	v_mov_b32_e32 v122, v0
	v_mov_b32_e32 v123, v0
	v_mov_b32_e32 v124, v0
	v_mov_b32_e32 v125, v0
	v_mov_b32_e32 v126, v0
	v_mov_b32_e32 v127, v0
	s_cmp_eq_u32 s99, 0
	s_cbranch_scc1 .LBB0_572
	ds_read_b128 v[146:149], v159
	ds_read_b128 v[150:153], v159 offset:1024
	ds_read_b128 v[164:167], v159 offset:2048
	ds_read_b128 v[168:171], v159 offset:3072
	ds_read_b128 v[172:175], v161
	ds_read_b128 v[176:179], v161 offset:1024
	ds_read_b128 v[180:183], v161 offset:2048
	ds_read_b128 v[188:191], v161 offset:3072
	s_add_u32 s24, s22, 0xfffc0080
	s_addc_u32 s25, s23, -1
	s_cmp_eq_u32 s46, 12
	s_cselect_b32 s27, s7, s25
	s_cselect_b32 s26, s15, s24
	s_cselect_b32 s25, s13, s45
	s_cselect_b32 s24, s21, s44
	v_lshl_add_u64 v[154:155], s[22:23], 0, v[138:139]
	s_add_i32 m0, s31, 0xc000
	ds_read_b128 v[192:195], v162
	ds_read_b128 v[196:199], v162 offset:1024
	ds_read_b128 v[200:203], v162 offset:2048
	ds_read_b128 v[204:207], v162 offset:3072
	ds_read_b128 v[208:211], v162 offset:4096
	ds_read_b128 v[212:215], v162 offset:5120
	ds_read_b128 v[216:219], v162 offset:6144
	ds_read_b128 v[220:223], v162 offset:7168
	global_load_lds_dwordx4 v[154:155], off
	v_lshl_add_u64 v[154:155], s[22:23], 0, v[140:141]
	s_add_i32 m0, s31, 0xe000
	s_nop 0
	global_load_lds_dwordx4 v[154:155], off
	s_waitcnt vmcnt(24)
	s_waitcnt lgkmcnt(0)
	s_barrier
; #define PG8_STAGE(bufoff, gbase, voff) do { _Pragma("unroll") for (int _i = 0; _i < 2; ++_i) \
;         __builtin_amdgcn_global_load_lds((const unsigned*)((const char*)(gbase) + (voff)[_i]), (PG8_LAS unsigned*)(lds + (bufoff) + ldsw + _i * 8192), 16, 0, 0); } while (0)
; #define PG8_LDA(dst, b, h) do { _Pragma("unroll") for (int m = 0; m < 4; ++m) _Pragma("unroll") for (int k = 0; k < 2; ++k) dst[m][k] = *(const PG8_LAS bf16x8*)(lds + PG8_SA(b, h) + aoff + m * 2048 + k * 1024); } while (0)
; #define PG8_MMA(ai, bj, At, Bt) do { __builtin_amdgcn_s_setprio(1); _Pragma("unroll") for (int m = 0; m < 4; ++m) _Pragma("unroll") for (int n = 0; n < 2; ++n) _Pragma("unroll") for (int k = 0; k < 2; ++k) \
;         acc[ai][bj][m][n] = __builtin_amdgcn_mfma_f32_16x16x32_bf16(Bt[n][k], At[m][k], acc[ai][bj][m][n], 0, 0, 0); __builtin_amdgcn_s_setprio(0); } while (0)
; #define PG8_WAIT_V(n) asm volatile("s_waitcnt vmcnt(" #n ")" ::: "memory")
; #define PG8_WAIT_L(n) asm volatile("s_waitcnt lgkmcnt(" #n ")" ::: "memory")
; #define PG8_BAR __builtin_amdgcn_s_barrier()
; #define PG8_SCHED __builtin_amdgcn_sched_barrier(0)
; template <class Epi, class Sched, bool ALIGN_EPI = false, bool SP2 = false>
; __device__ __forceinline__ void gemm_phase(PG8_LAS unsigned char* lds, const Gemm g, const Sched& S, const Epi& E) {
;     ...
;             PG8_WAIT_V(8); PG8_WAIT_L(0); PG8_BAR; PG8_MMA(0, 0, At, B0); PG8_MMA(0, 1, At, B1); PG8_BAR; PG8_SCHED;
;             PG8_LDA(At, 0, 1); PG8_STAGE(PG8_SB(0, 0), b2, voffB); PG8_STAGE(PG8_SB(0, 1), b2 + hstep, voffB); PG8_STAGE(PG8_SA(0, 0), a2, voffA);
;             PG8_WAIT_V(8); PG8_WAIT_L(0); PG8_BAR; PG8_MMA(1, 0, At, B0); PG8_MMA(1, 1, At, B1); PG8_BAR; PG8_SCHED;
	s_setprio 1
	s_waitcnt lgkmcnt(0)
	v_mfma_f32_16x16x32_bf16 v[124:127], v[146:149], v[192:195], v[124:127]
	v_mfma_f32_16x16x32_bf16 v[120:123], v[164:167], v[192:195], v[120:123]
	v_mfma_f32_16x16x32_bf16 v[108:111], v[146:149], v[200:203], v[108:111]
	v_mfma_f32_16x16x32_bf16 v[104:107], v[164:167], v[200:203], v[104:107]
	v_mfma_f32_16x16x32_bf16 v[92:95], v[146:149], v[208:211], v[92:95]
	v_mfma_f32_16x16x32_bf16 v[88:91], v[164:167], v[208:211], v[88:91]
	v_mfma_f32_16x16x32_bf16 v[76:79], v[146:149], v[216:219], v[76:79]
	v_mfma_f32_16x16x32_bf16 v[72:75], v[164:167], v[216:219], v[72:75]
	v_mfma_f32_16x16x32_bf16 v[124:127], v[150:153], v[196:199], v[124:127]
	v_mfma_f32_16x16x32_bf16 v[120:123], v[168:171], v[196:199], v[120:123]
	v_mfma_f32_16x16x32_bf16 v[108:111], v[150:153], v[204:207], v[108:111]
	v_mfma_f32_16x16x32_bf16 v[104:107], v[168:171], v[204:207], v[104:107]
	v_mfma_f32_16x16x32_bf16 v[92:95], v[150:153], v[212:215], v[92:95]
	v_mfma_f32_16x16x32_bf16 v[88:91], v[168:171], v[212:215], v[88:91]
	v_mfma_f32_16x16x32_bf16 v[76:79], v[150:153], v[220:223], v[76:79]
	v_mfma_f32_16x16x32_bf16 v[72:75], v[168:171], v[220:223], v[72:75]
	s_setprio 0
	s_setprio 1
	v_mfma_f32_16x16x32_bf16 v[116:119], v[172:175], v[192:195], v[116:119]
	v_mfma_f32_16x16x32_bf16 v[112:115], v[180:183], v[192:195], v[112:115]
	v_mfma_f32_16x16x32_bf16 v[100:103], v[172:175], v[200:203], v[100:103]
	v_mfma_f32_16x16x32_bf16 v[96:99], v[180:183], v[200:203], v[96:99]
	v_mfma_f32_16x16x32_bf16 v[84:87], v[172:175], v[208:211], v[84:87]
	v_mfma_f32_16x16x32_bf16 v[80:83], v[180:183], v[208:211], v[80:83]
	v_mfma_f32_16x16x32_bf16 v[68:71], v[172:175], v[216:219], v[68:71]
	v_mfma_f32_16x16x32_bf16 v[64:67], v[180:183], v[216:219], v[64:67]
	v_mfma_f32_16x16x32_bf16 v[116:119], v[176:179], v[196:199], v[116:119]
	v_mfma_f32_16x16x32_bf16 v[112:115], v[188:191], v[196:199], v[112:115]
	v_mfma_f32_16x16x32_bf16 v[100:103], v[176:179], v[204:207], v[100:103]
	v_mfma_f32_16x16x32_bf16 v[96:99], v[188:191], v[204:207], v[96:99]
	v_mfma_f32_16x16x32_bf16 v[84:87], v[176:179], v[212:215], v[84:87]
	v_mfma_f32_16x16x32_bf16 v[80:83], v[188:191], v[212:215], v[80:83]
	v_mfma_f32_16x16x32_bf16 v[68:71], v[176:179], v[220:223], v[68:71]
	v_mfma_f32_16x16x32_bf16 v[64:67], v[188:191], v[220:223], v[64:67]
	s_setprio 0
	s_barrier
	s_add_i32 s47, s39, s28
	v_lshl_add_u64 v[154:155], s[24:25], 0, v[130:131]
	s_mov_b32 m0, s47
	ds_read_b128 v[192:195], v162 offset:16384
	ds_read_b128 v[196:199], v162 offset:17408
	ds_read_b128 v[200:203], v162 offset:18432
	ds_read_b128 v[204:207], v162 offset:19456
	ds_read_b128 v[208:211], v162 offset:20480
	ds_read_b128 v[212:215], v162 offset:21504
	ds_read_b128 v[216:219], v162 offset:22528
	ds_read_b128 v[220:223], v162 offset:23552
	global_load_lds_dwordx4 v[154:155], off
	s_add_i32 m0, s47, 0x2000
	s_add_u32 s48, s24, 0x40000
	v_lshl_add_u64 v[184:185], s[24:25], 0, v[134:135]
	s_addc_u32 s49, s25, 0
	s_add_i32 s47, s40, s28
	global_load_lds_dwordx4 v[184:185], off
	v_lshl_add_u64 v[224:225], s[48:49], 0, v[130:131]
	s_mov_b32 m0, s47
	v_lshl_add_u64 v[226:227], s[26:27], 0, v[132:133]
	global_load_lds_dwordx4 v[224:225], off
	v_lshl_add_u64 v[224:225], s[48:49], 0, v[134:135]
	s_add_i32 m0, s47, 0x2000
	s_nop 0
	global_load_lds_dwordx4 v[224:225], off
	v_lshl_add_u64 v[224:225], s[26:27], 0, v[128:129]
	s_mov_b32 m0, s31
	s_nop 0
	global_load_lds_dwordx4 v[224:225], off
	s_mov_b32 m0, s33
	s_nop 0
	global_load_lds_dwordx4 v[226:227], off
	s_waitcnt vmcnt(24)
	s_waitcnt lgkmcnt(0)
	s_barrier
	s_setprio 1
	s_waitcnt lgkmcnt(0)
	v_mfma_f32_16x16x32_bf16 v[60:63], v[146:149], v[192:195], v[60:63]
	v_mfma_f32_16x16x32_bf16 v[56:59], v[164:167], v[192:195], v[56:59]
	v_mfma_f32_16x16x32_bf16 v[44:47], v[146:149], v[200:203], v[44:47]
	v_mfma_f32_16x16x32_bf16 v[40:43], v[164:167], v[200:203], v[40:43]
	v_mfma_f32_16x16x32_bf16 v[28:31], v[146:149], v[208:211], v[28:31]
	v_mfma_f32_16x16x32_bf16 v[24:27], v[164:167], v[208:211], v[24:27]
	v_mfma_f32_16x16x32_bf16 v[12:15], v[146:149], v[216:219], v[12:15]
	v_mfma_f32_16x16x32_bf16 v[8:11], v[164:167], v[216:219], v[8:11]
	v_mfma_f32_16x16x32_bf16 v[60:63], v[150:153], v[196:199], v[60:63]
	v_mfma_f32_16x16x32_bf16 v[56:59], v[168:171], v[196:199], v[56:59]
	v_mfma_f32_16x16x32_bf16 v[44:47], v[150:153], v[204:207], v[44:47]
	v_mfma_f32_16x16x32_bf16 v[40:43], v[168:171], v[204:207], v[40:43]
	v_mfma_f32_16x16x32_bf16 v[28:31], v[150:153], v[212:215], v[28:31]
	v_mfma_f32_16x16x32_bf16 v[24:27], v[168:171], v[212:215], v[24:27]
	v_mfma_f32_16x16x32_bf16 v[12:15], v[150:153], v[220:223], v[12:15]
	v_mfma_f32_16x16x32_bf16 v[8:11], v[168:171], v[220:223], v[8:11]
	s_setprio 0
	s_setprio 1
	v_mfma_f32_16x16x32_bf16 v[52:55], v[172:175], v[192:195], v[52:55]
	v_mfma_f32_16x16x32_bf16 v[48:51], v[180:183], v[192:195], v[48:51]
	v_mfma_f32_16x16x32_bf16 v[36:39], v[172:175], v[200:203], v[36:39]
	v_mfma_f32_16x16x32_bf16 v[32:35], v[180:183], v[200:203], v[32:35]
	v_mfma_f32_16x16x32_bf16 v[20:23], v[172:175], v[208:211], v[20:23]
	v_mfma_f32_16x16x32_bf16 v[16:19], v[180:183], v[208:211], v[16:19]
	v_mfma_f32_16x16x32_bf16 v[4:7], v[172:175], v[216:219], v[4:7]
	v_mfma_f32_16x16x32_bf16 v[0:3], v[180:183], v[216:219], v[0:3]
	v_mfma_f32_16x16x32_bf16 v[52:55], v[176:179], v[196:199], v[52:55]
	v_mfma_f32_16x16x32_bf16 v[48:51], v[188:191], v[196:199], v[48:51]
	v_mfma_f32_16x16x32_bf16 v[36:39], v[176:179], v[204:207], v[36:39]
	v_mfma_f32_16x16x32_bf16 v[32:35], v[188:191], v[204:207], v[32:35]
	v_mfma_f32_16x16x32_bf16 v[20:23], v[176:179], v[212:215], v[20:23]
	v_mfma_f32_16x16x32_bf16 v[16:19], v[188:191], v[212:215], v[16:19]
	v_mfma_f32_16x16x32_bf16 v[4:7], v[176:179], v[220:223], v[4:7]
	v_mfma_f32_16x16x32_bf16 v[0:3], v[188:191], v[220:223], v[0:3]
	s_setprio 0
	s_barrier
; #define PG8_STAGE(bufoff, gbase, voff) do { _Pragma("unroll") for (int _i = 0; _i < 2; ++_i) \
;         __builtin_amdgcn_global_load_lds((const unsigned*)((const char*)(gbase) + (voff)[_i]), (PG8_LAS unsigned*)(lds + (bufoff) + ldsw + _i * 8192), 16, 0, 0); } while (0)
; #define PG8_LDA(dst, b, h) do { _Pragma("unroll") for (int m = 0; m < 4; ++m) _Pragma("unroll") for (int k = 0; k < 2; ++k) dst[m][k] = *(const PG8_LAS bf16x8*)(lds + PG8_SA(b, h) + aoff + m * 2048 + k * 1024); } while (0)
; #define PG8_LDB(dst, b, h) do { _Pragma("unroll") for (int n = 0; n < 2; ++n) _Pragma("unroll") for (int k = 0; k < 2; ++k) dst[n][k] = *(const PG8_LAS bf16x8*)(lds + PG8_SB(b, h) + boff + n * 2048 + k * 1024); } while (0)
; #define PG8_MMA(ai, bj, At, Bt) do { __builtin_amdgcn_s_setprio(1); _Pragma("unroll") for (int m = 0; m < 4; ++m) _Pragma("unroll") for (int n = 0; n < 2; ++n) _Pragma("unroll") for (int k = 0; k < 2; ++k) \
;         acc[ai][bj][m][n] = __builtin_amdgcn_mfma_f32_16x16x32_bf16(Bt[n][k], At[m][k], acc[ai][bj][m][n], 0, 0, 0); __builtin_amdgcn_s_setprio(0); } while (0)
; #define PG8_WAIT_V(n) asm volatile("s_waitcnt vmcnt(" #n ")" ::: "memory")
; #define PG8_WAIT_L(n) asm volatile("s_waitcnt lgkmcnt(" #n ")" ::: "memory")
; #define PG8_BAR __builtin_amdgcn_s_barrier()
; #define PG8_SCHED __builtin_amdgcn_sched_barrier(0)
; template <class Epi, class Sched, bool ALIGN_EPI = false, bool SP2 = false>
; __device__ __forceinline__ void gemm_phase(PG8_LAS unsigned char* lds, const Gemm g, const Sched& S, const Epi& E) {
;     ...
;             PG8_LDB(B0, 1, 0); PG8_LDB(B1, 1, 1); PG8_SCHED; PG8_LDA(At, 1, 0); PG8_STAGE(PG8_SA(0, 1), a2 + hstep, voffA);
;             PG8_WAIT_V(8); PG8_WAIT_L(0); PG8_BAR; PG8_MMA(0, 0, At, B0); PG8_MMA(0, 1, At, B1); PG8_BAR; PG8_SCHED;
	s_add_i32 s47, 0, 0x18000
	v_add_u32_e32 v136, s47, v157
	s_add_i32 s48, 0, 0x1c000
	ds_read_b128 v[146:149], v136
	ds_read_b128 v[150:153], v136 offset:1024
	ds_read_b128 v[164:167], v136 offset:2048
	ds_read_b128 v[168:171], v136 offset:3072
	v_add_u32_e32 v136, s48, v157
	ds_read_b128 v[172:175], v136
	ds_read_b128 v[176:179], v136 offset:1024
	ds_read_b128 v[180:183], v136 offset:2048
	ds_read_b128 v[188:191], v136 offset:3072
	s_add_u32 s26, s26, 0x40000
	s_addc_u32 s27, s27, 0
	s_mov_b32 m0, s34
	v_lshl_add_u64 v[228:229], s[26:27], 0, v[128:129]
	ds_read_b128 v[192:195], v162 offset:32768
	ds_read_b128 v[196:199], v162 offset:33792
	ds_read_b128 v[200:203], v162 offset:34816
	ds_read_b128 v[204:207], v162 offset:35840
	ds_read_b128 v[208:211], v162 offset:36864
	ds_read_b128 v[212:215], v162 offset:37888
	ds_read_b128 v[216:219], v162 offset:38912
	ds_read_b128 v[220:223], v162 offset:39936
	global_load_lds_dwordx4 v[228:229], off
	v_lshl_add_u64 v[228:229], s[26:27], 0, v[132:133]
	s_mov_b32 m0, s35
	s_nop 0
	global_load_lds_dwordx4 v[228:229], off
	s_waitcnt vmcnt(8)
	s_waitcnt lgkmcnt(0)
	s_barrier
	s_setprio 1
	s_waitcnt lgkmcnt(0)
	v_mfma_f32_16x16x32_bf16 v[124:127], v[146:149], v[192:195], v[124:127]
	v_mfma_f32_16x16x32_bf16 v[120:123], v[164:167], v[192:195], v[120:123]
	v_mfma_f32_16x16x32_bf16 v[108:111], v[146:149], v[200:203], v[108:111]
	v_mfma_f32_16x16x32_bf16 v[104:107], v[164:167], v[200:203], v[104:107]
	v_mfma_f32_16x16x32_bf16 v[92:95], v[146:149], v[208:211], v[92:95]
	v_mfma_f32_16x16x32_bf16 v[88:91], v[164:167], v[208:211], v[88:91]
	v_mfma_f32_16x16x32_bf16 v[76:79], v[146:149], v[216:219], v[76:79]
	v_mfma_f32_16x16x32_bf16 v[72:75], v[164:167], v[216:219], v[72:75]
	v_mfma_f32_16x16x32_bf16 v[124:127], v[150:153], v[196:199], v[124:127]
	v_mfma_f32_16x16x32_bf16 v[120:123], v[168:171], v[196:199], v[120:123]
	v_mfma_f32_16x16x32_bf16 v[108:111], v[150:153], v[204:207], v[108:111]
	v_mfma_f32_16x16x32_bf16 v[104:107], v[168:171], v[204:207], v[104:107]
	v_mfma_f32_16x16x32_bf16 v[92:95], v[150:153], v[212:215], v[92:95]
	v_mfma_f32_16x16x32_bf16 v[88:91], v[168:171], v[212:215], v[88:91]
	v_mfma_f32_16x16x32_bf16 v[76:79], v[150:153], v[220:223], v[76:79]
	v_mfma_f32_16x16x32_bf16 v[72:75], v[168:171], v[220:223], v[72:75]
	s_setprio 0
	s_setprio 1
	v_mfma_f32_16x16x32_bf16 v[116:119], v[172:175], v[192:195], v[116:119]
	v_mfma_f32_16x16x32_bf16 v[112:115], v[180:183], v[192:195], v[112:115]
	v_mfma_f32_16x16x32_bf16 v[100:103], v[172:175], v[200:203], v[100:103]
	v_mfma_f32_16x16x32_bf16 v[96:99], v[180:183], v[200:203], v[96:99]
	v_mfma_f32_16x16x32_bf16 v[84:87], v[172:175], v[208:211], v[84:87]
	v_mfma_f32_16x16x32_bf16 v[80:83], v[180:183], v[208:211], v[80:83]
	v_mfma_f32_16x16x32_bf16 v[68:71], v[172:175], v[216:219], v[68:71]
	v_mfma_f32_16x16x32_bf16 v[64:67], v[180:183], v[216:219], v[64:67]
	v_mfma_f32_16x16x32_bf16 v[116:119], v[176:179], v[196:199], v[116:119]
	v_mfma_f32_16x16x32_bf16 v[112:115], v[188:191], v[196:199], v[112:115]
	v_mfma_f32_16x16x32_bf16 v[100:103], v[176:179], v[204:207], v[100:103]
	v_mfma_f32_16x16x32_bf16 v[96:99], v[188:191], v[204:207], v[96:99]
	v_mfma_f32_16x16x32_bf16 v[84:87], v[176:179], v[212:215], v[84:87]
	v_mfma_f32_16x16x32_bf16 v[80:83], v[188:191], v[212:215], v[80:83]
	v_mfma_f32_16x16x32_bf16 v[68:71], v[176:179], v[220:223], v[68:71]
	v_mfma_f32_16x16x32_bf16 v[64:67], v[188:191], v[220:223], v[64:67]
	s_setprio 0
	s_barrier
; #define PG8_STAGE(bufoff, gbase, voff) do { _Pragma("unroll") for (int _i = 0; _i < 2; ++_i) \
;         __builtin_amdgcn_global_load_lds((const unsigned*)((const char*)(gbase) + (voff)[_i]), (PG8_LAS unsigned*)(lds + (bufoff) + ldsw + _i * 8192), 16, 0, 0); } while (0)
; #define PG8_LDA(dst, b, h) do { _Pragma("unroll") for (int m = 0; m < 4; ++m) _Pragma("unroll") for (int k = 0; k < 2; ++k) dst[m][k] = *(const PG8_LAS bf16x8*)(lds + PG8_SA(b, h) + aoff + m * 2048 + k * 1024); } while (0)
; #define PG8_MMA(ai, bj, At, Bt) do { __builtin_amdgcn_s_setprio(1); _Pragma("unroll") for (int m = 0; m < 4; ++m) _Pragma("unroll") for (int n = 0; n < 2; ++n) _Pragma("unroll") for (int k = 0; k < 2; ++k) \
;         acc[ai][bj][m][n] = __builtin_amdgcn_mfma_f32_16x16x32_bf16(Bt[n][k], At[m][k], acc[ai][bj][m][n], 0, 0, 0); __builtin_amdgcn_s_setprio(0); } while (0)
; #define PG8_WAIT_V(n) asm volatile("s_waitcnt vmcnt(" #n ")" ::: "memory")
; #define PG8_WAIT_L(n) asm volatile("s_waitcnt lgkmcnt(" #n ")" ::: "memory")
; #define PG8_BAR __builtin_amdgcn_s_barrier()
; #define PG8_SCHED __builtin_amdgcn_sched_barrier(0)
; template <class Epi, class Sched, bool ALIGN_EPI = false, bool SP2 = false>
; __device__ __forceinline__ void gemm_phase(PG8_LAS unsigned char* lds, const Gemm g, const Sched& S, const Epi& E) {
;     ...
;             PG8_LDA(At, 1, 1); PG8_STAGE(PG8_SB(1, 0), b3, voffB); PG8_STAGE(PG8_SB(1, 1), b3 + hstep, voffB); PG8_STAGE(PG8_SA(1, 0), a3, voffA);
;             PG8_WAIT_V(8); PG8_WAIT_L(0); PG8_BAR; PG8_MMA(1, 0, At, B0); PG8_MMA(1, 1, At, B1); PG8_BAR; PG8_SCHED;
	s_add_i32 s26, s47, s28
	v_lshl_add_u64 v[154:155], v[154:155], 0, s[8:9]
	s_mov_b32 m0, s26
	ds_read_b128 v[192:195], v162 offset:49152
	ds_read_b128 v[196:199], v162 offset:50176
	ds_read_b128 v[200:203], v162 offset:51200
	ds_read_b128 v[204:207], v162 offset:52224
	ds_read_b128 v[208:211], v162 offset:53248
	ds_read_b128 v[212:215], v162 offset:54272
	ds_read_b128 v[216:219], v162 offset:55296
	ds_read_b128 v[220:223], v162 offset:56320
	global_load_lds_dwordx4 v[154:155], off
	s_add_i32 m0, s26, 0x2000
	s_add_u32 s24, s24, 0x40080
	v_lshl_add_u64 v[154:155], v[184:185], 0, s[8:9]
	s_addc_u32 s25, s25, 0
	s_add_i32 s26, s48, s28
	global_load_lds_dwordx4 v[154:155], off
	v_lshl_add_u64 v[154:155], s[24:25], 0, v[130:131]
	s_mov_b32 m0, s26
	s_nop 0
	global_load_lds_dwordx4 v[154:155], off
	v_lshl_add_u64 v[154:155], s[24:25], 0, v[134:135]
	s_add_i32 m0, s26, 0x2000
	s_nop 0
	global_load_lds_dwordx4 v[154:155], off
	v_lshl_add_u64 v[154:155], v[224:225], 0, s[8:9]
	s_mov_b32 m0, s36
	s_nop 0
	global_load_lds_dwordx4 v[154:155], off
	v_lshl_add_u64 v[154:155], v[226:227], 0, s[8:9]
	s_mov_b32 m0, s37
	s_nop 0
	global_load_lds_dwordx4 v[154:155], off
	s_waitcnt vmcnt(8)
	s_waitcnt lgkmcnt(0)
	s_barrier
	s_setprio 1
	s_waitcnt lgkmcnt(0)
	v_mfma_f32_16x16x32_bf16 v[60:63], v[146:149], v[192:195], v[60:63]
	v_mfma_f32_16x16x32_bf16 v[56:59], v[164:167], v[192:195], v[56:59]
	v_mfma_f32_16x16x32_bf16 v[44:47], v[146:149], v[200:203], v[44:47]
	v_mfma_f32_16x16x32_bf16 v[40:43], v[164:167], v[200:203], v[40:43]
	v_mfma_f32_16x16x32_bf16 v[28:31], v[146:149], v[208:211], v[28:31]
	v_mfma_f32_16x16x32_bf16 v[24:27], v[164:167], v[208:211], v[24:27]
	v_mfma_f32_16x16x32_bf16 v[12:15], v[146:149], v[216:219], v[12:15]
	v_mfma_f32_16x16x32_bf16 v[8:11], v[164:167], v[216:219], v[8:11]
	v_mfma_f32_16x16x32_bf16 v[60:63], v[150:153], v[196:199], v[60:63]
	v_mfma_f32_16x16x32_bf16 v[56:59], v[168:171], v[196:199], v[56:59]
	v_mfma_f32_16x16x32_bf16 v[44:47], v[150:153], v[204:207], v[44:47]
	v_mfma_f32_16x16x32_bf16 v[40:43], v[168:171], v[204:207], v[40:43]
	v_mfma_f32_16x16x32_bf16 v[28:31], v[150:153], v[212:215], v[28:31]
	v_mfma_f32_16x16x32_bf16 v[24:27], v[168:171], v[212:215], v[24:27]
	v_mfma_f32_16x16x32_bf16 v[12:15], v[150:153], v[220:223], v[12:15]
	v_mfma_f32_16x16x32_bf16 v[8:11], v[168:171], v[220:223], v[8:11]
	s_setprio 0
	s_setprio 1
	v_mfma_f32_16x16x32_bf16 v[52:55], v[172:175], v[192:195], v[52:55]
	v_mfma_f32_16x16x32_bf16 v[48:51], v[180:183], v[192:195], v[48:51]
	v_mfma_f32_16x16x32_bf16 v[36:39], v[172:175], v[200:203], v[36:39]
	v_mfma_f32_16x16x32_bf16 v[32:35], v[180:183], v[200:203], v[32:35]
	v_mfma_f32_16x16x32_bf16 v[20:23], v[172:175], v[208:211], v[20:23]
	v_mfma_f32_16x16x32_bf16 v[16:19], v[180:183], v[208:211], v[16:19]
	v_mfma_f32_16x16x32_bf16 v[4:7], v[172:175], v[216:219], v[4:7]
	v_mfma_f32_16x16x32_bf16 v[0:3], v[180:183], v[216:219], v[0:3]
	v_mfma_f32_16x16x32_bf16 v[52:55], v[176:179], v[196:199], v[52:55]
	v_mfma_f32_16x16x32_bf16 v[48:51], v[188:191], v[196:199], v[48:51]
	v_mfma_f32_16x16x32_bf16 v[36:39], v[176:179], v[204:207], v[36:39]
	v_mfma_f32_16x16x32_bf16 v[32:35], v[188:191], v[204:207], v[32:35]
	v_mfma_f32_16x16x32_bf16 v[20:23], v[176:179], v[212:215], v[20:23]
	v_mfma_f32_16x16x32_bf16 v[16:19], v[188:191], v[212:215], v[16:19]
	v_mfma_f32_16x16x32_bf16 v[4:7], v[176:179], v[220:223], v[4:7]
	v_mfma_f32_16x16x32_bf16 v[0:3], v[188:191], v[220:223], v[0:3]
	s_setprio 0
	s_barrier
	s_add_i32 s46, s46, 2
	s_add_u32 s22, s22, 0x100
	s_addc_u32 s23, s23, 0
	s_add_u32 s44, s44, 0x100
	s_addc_u32 s45, s45, 0
	s_cmp_gt_u32 s46, 13

; #define PG8_BAR __builtin_amdgcn_s_barrier()
; template <class Epi, class Sched, bool ALIGN_EPI = false, bool SP2 = false>
; __device__ __forceinline__ void gemm_phase(PG8_LAS unsigned char* lds, const Gemm g, const Sched& S, const Epi& E) {
;     ...
;         if constexpr (!Epi::AFTER_DRAIN) { E(acc, cur, wr, wc, fr, fq); S.done(cur); }
;         if (!has_next) break;
; #pragma unroll
;         for (int a = 0; a < 2; ++a)
; #pragma unroll
;             for (int b = 0; b < 2; ++b)
; #pragma unroll
;                 for (int m = 0; m < 4; ++m)
; #pragma unroll
;                     for (int n = 0; n < 2; ++n) acc[a][b][m][n] = (f32x4){0.f, 0.f, 0.f, 0.f};
;         cur = nxt; cA = nA; cB = nB; ++ui;
;         if constexpr (ALIGN_EPI) { if (wr == 1) PG8_BAR; }
;     }
.Lp4epi_done:
	s_andn2_b64 vcc, exec, s[4:5]
	s_mov_b64 s[4:5], -1
	s_mov_b32 s99, 1
	s_cbranch_vccnz .LBB0_564
	s_andn2_b64 vcc, exec, s[2:3]
	s_cbranch_vccnz .LBB0_563
	s_barrier
	s_branch .LBB0_563

; #define PG8_STAGE(bufoff, gbase, voff) do { _Pragma("unroll") for (int _i = 0; _i < 2; ++_i) \
;         __builtin_amdgcn_global_load_lds((const unsigned*)((const char*)(gbase) + (voff)[_i]), (PG8_LAS unsigned*)(lds + (bufoff) + ldsw + _i * 8192), 16, 0, 0); } while (0)
; #define PG8_WAIT_V(n) asm volatile("s_waitcnt vmcnt(" #n ")" ::: "memory")
; #define PG8_BAR __builtin_amdgcn_s_barrier()
; template <class Epi, class Sched, bool ALIGN_EPI = false, bool SP2 = false>
; __device__ __forceinline__ void gemm_phase(PG8_LAS unsigned char* lds, const Gemm g, const Sched& S, const Epi& E) {
;     ...
;     const unsigned ldsw = (unsigned)wid * 1024u;
;     const int aoff = lds_byte(wr * 64 + fr, fq * 8), boff = lds_byte(wc * 32 + fr, fq * 8);
;     ...
;     if constexpr (SP2) {
;         PG8_STAGE(PG8_SB(0, 0), cB, voffB); PG8_STAGE(PG8_SB(0, 1), cB + hstep, voffB); PG8_STAGE(PG8_SA(0, 0), cA, voffA); PG8_STAGE(PG8_SA(0, 1), cA + hstep, voffA);
;         if (wr == 1) PG8_BAR;
;         PG8_WAIT_V(2); PG8_BAR;
;         PG8_STAGE(PG8_SB(1, 0), cB + kstep, voffB); PG8_STAGE(PG8_SA(1, 0), cA + kstep, voffA); PG8_STAGE(PG8_SB(1, 1), cB + hstep + kstep, voffB);
;         PG8_WAIT_V(6); PG8_BAR;
.LBB0_884:
	s_mov_b32 s99, 0
	s_and_b32 s47, s2, 3
	s_lshl_b32 s2, s5, 13
	s_lshl_b32 s14, s47, 12
	s_add_u32 s48, s68, 0x1f800000
	s_mov_b64 s[12:13], 0x80
	s_addc_u32 s49, s69, 0
	s_add_i32 m0, s37, 0x18000
	v_lshl_add_u64 v[6:7], v[6:7], 0, s[12:13]
	s_waitcnt vmcnt(2)
	s_barrier
	global_load_lds_dwordx4 v[6:7], off
	v_lshl_add_u64 v[4:5], v[4:5], 0, s[12:13]
	s_add_i32 m0, s37, 0x1a000
	s_add_i32 s50, s37, 0x8000
	s_add_i32 s51, s37, 0xa000
	global_load_lds_dwordx4 v[4:5], off
	v_lshl_add_u64 v[0:1], v[0:1], 0, s[12:13]
	s_mov_b32 m0, s50
	s_add_u32 s6, s40, 0x80080
	global_load_lds_dwordx4 v[0:1], off
	v_lshl_add_u64 v[0:1], v[2:3], 0, s[12:13]
	s_mov_b32 m0, s51
	s_addc_u32 s7, s41, 0
	global_load_lds_dwordx4 v[0:1], off
	s_add_i32 m0, s37, 0x1c000
	v_lshl_add_u64 v[0:1], s[6:7], 0, v[144:145]
	global_load_lds_dwordx4 v[0:1], off
	v_lshl_add_u64 v[0:1], s[6:7], 0, v[146:147]
	s_add_i32 m0, s37, 0x1e000
	s_cmpk_lt_u32 s4, 0x100
	global_load_lds_dwordx4 v[0:1], off
	v_bfe_u32 v1, v8, 4, 2
	v_and_b32_e32 v0, 15, v8
	v_lshlrev_b32_e32 v2, 4, v1
	v_lshl_or_b32 v166, s5, 6, v0
	v_lshl_or_b32 v0, v0, 6, v2
	v_lshlrev_b32_e32 v2, 2, v8
	v_and_b32_e32 v2, 32, v2
	v_bitop3_b32 v3, v0, s2, v2 bitop3:0xde
	v_bitop3_b32 v167, v0, s14, v2 bitop3:0xde
	v_lshlrev_b32_e32 v0, 2, v1
	v_lshl_or_b32 v168, s47, 5, v0
	v_lshlrev_b32_e32 v0, 15, v9
	v_and_b32_e32 v0, 0xffff0000, v0
	v_cmp_eq_u32_e64 s[4:5], 0, v1
	v_lshl_add_u32 v0, v10, 12, v0
	v_and_b32_e32 v1, 1, v9
	v_lshl_or_b32 v0, v1, 6, v0
	v_lshl_add_u32 v148, v11, 1, v0
	v_lshlrev_b32_e32 v0, 15, v12
	v_and_b32_e32 v0, 0xffff0000, v0
	v_lshl_add_u32 v0, v13, 12, v0
	v_and_b32_e32 v1, 1, v12
	s_waitcnt vmcnt(6)
	v_lshl_or_b32 v0, v1, 6, v0
	s_cselect_b64 s[14:15], -1, 0
	v_lshl_add_u32 v150, v14, 1, v0
	s_add_i32 s53, 0, 0x10000
	s_add_i32 s54, 0, 0x14000
	v_mbcnt_lo_u32_b32 v0, -1, 0
	s_ashr_i32 s52, s62, 31
	v_mov_b32_e32 v149, v145
	v_mov_b32_e32 v151, v145
	v_mov_b64_e32 v[152:153], 0x200
	v_mov_b64_e32 v[154:155], 0x1ff
	v_add_u32_e32 v169, s53, v167
	v_add_u32_e32 v170, s54, v167
	v_add_u32_e32 v171, 0, v3
	v_mbcnt_hi_u32_b32 v172, -1, v0
	s_mov_b64 s[16:17], 0x40000
	s_mov_b64 s[18:19], 0x48000
	s_mov_b64 s[20:21], 0x50000
	s_mov_b64 s[22:23], 0x58000
	s_mov_b32 s2, s3
	s_barrier
	s_branch .LBB0_887

;     __device__ __forceinline__ bool next(int i, Unit& u) const { if (!base.next(i >> 1, u)) return false; if (i & 1) { u.pm += 64; u.pn += 8; } return true; }
; #define PG8_STAGE(bufoff, gbase, voff) do { _Pragma("unroll") for (int _i = 0; _i < 2; ++_i) \
;         __builtin_amdgcn_global_load_lds((const unsigned*)((const char*)(gbase) + (voff)[_i]), (PG8_LAS unsigned*)(lds + (bufoff) + ldsw + _i * 8192), 16, 0, 0); } while (0)
; #define PG8_LDA(dst, b, h) do { _Pragma("unroll") for (int m = 0; m < 4; ++m) _Pragma("unroll") for (int k = 0; k < 2; ++k) dst[m][k] = *(const PG8_LAS bf16x8*)(lds + PG8_SA(b, h) + aoff + m * 2048 + k * 1024); } while (0)
; #define PG8_LDB(dst, b, h) do { _Pragma("unroll") for (int n = 0; n < 2; ++n) _Pragma("unroll") for (int k = 0; k < 2; ++k) dst[n][k] = *(const PG8_LAS bf16x8*)(lds + PG8_SB(b, h) + boff + n * 2048 + k * 1024); } while (0)
; #define PG8_WAIT_V(n) asm volatile("s_waitcnt vmcnt(" #n ")" ::: "memory")
; template <class Epi, class Sched, bool ALIGN_EPI = false, bool SP2 = false>
; __device__ __forceinline__ void gemm_phase(PG8_LAS unsigned char* lds, const Gemm g, const Sched& S, const Epi& E) {
;     ...
;         const bool has_next = S.next(ui + 1, nxt);
;         const char* nA = has_next ? (const char*)g.A + (size_t)nxt.pm * tstep : cA; const char* nB = has_next ? (const char*)g.Bt + (size_t)nxt.pn * tstep : cB;
;         for (int t = 0; t < nt; t += 2) {
;             const bool last = (t == nt - 2);
;             const char* a1 = cA + (size_t)(t + 1) * kstep;
;             const char* a2 = last ? nA : cA + (size_t)(t + 2) * kstep; const char* b2 = last ? nB : cB + (size_t)(t + 2) * kstep;
;             const char* a3 = a2 + kstep; const char* b3 = b2 + kstep;
;             if (last && has_next) S.a_ready(nxt);
;             if constexpr (SP2) {
;             PG8_LDB(B0, 0, 0); PG8_LDB(B1, 0, 1); PG8_SCHED; PG8_LDA(At, 0, 0); PG8_STAGE(PG8_SA(1, 1), a1 + hstep, voffA);
;             PG8_WAIT_V(8); PG8_WAIT_L(0); PG8_BAR; PG8_MMA(0, 0, At, B0); PG8_MMA(0, 1, At, B1); PG8_BAR; PG8_SCHED;
;     ...
;         for (int a = 0; a < 2; ++a)
; #pragma unroll
;             for (int b = 0; b < 2; ++b)
; #pragma unroll
;                 for (int m = 0; m < 4; ++m)
; #pragma unroll
;                     for (int n = 0; n < 2; ++n) acc[a][b][m][n] = (f32x4){0.f, 0.f, 0.f, 0.f};
;         cur = nxt; cA = nA; cB = nB; ++ui;
.LBB0_893:
	s_ashr_i32 s25, s24, 31
	s_lshl_b64 s[28:29], s[24:25], 20
	v_readlane_b32 s30, v236, 50
	v_readlane_b32 s31, v236, 51
	s_add_u32 s28, s30, s28
	s_addc_u32 s29, s31, s29
	s_and_b64 s[30:31], s[6:7], exec
	s_cselect_b32 s25, s29, s39
	s_cselect_b32 s35, s28, s38
	s_ashr_i32 s27, s26, 31
	s_lshl_b64 s[30:31], s[26:27], 20
	v_readlane_b32 s42, v236, 43
	v_readlane_b32 s43, v236, 44
	s_add_u32 s30, s42, s30
	s_addc_u32 s31, s43, s31
	s_and_b64 s[42:43], s[6:7], exec
	s_cselect_b32 s27, s31, s41
	s_cselect_b32 s55, s30, s40
	s_add_u32 s38, s38, 0x80080
	s_addc_u32 s39, s39, 0
	s_add_u32 s56, s40, 0x100
	v_mov_b32_e32 v0, 0
	s_addc_u32 s57, s41, 0
	s_mov_b32 s58, -2
	s_waitcnt lgkmcnt(0)
	v_mov_b32_e32 v1, v0
	v_mov_b32_e32 v2, v0
	v_mov_b32_e32 v3, v0
	v_mov_b32_e32 v4, v0
	v_mov_b32_e32 v5, v0
	v_mov_b32_e32 v6, v0
	v_mov_b32_e32 v7, v0
	v_mov_b32_e32 v16, v0
	v_mov_b32_e32 v17, v0
	v_mov_b32_e32 v18, v0
	v_mov_b32_e32 v19, v0
	v_mov_b32_e32 v20, v0
	v_mov_b32_e32 v21, v0
	v_mov_b32_e32 v22, v0
	v_mov_b32_e32 v23, v0
	v_mov_b32_e32 v32, v0
	v_mov_b32_e32 v33, v0
	v_mov_b32_e32 v34, v0
	v_mov_b32_e32 v35, v0
	v_mov_b32_e32 v36, v0
	v_mov_b32_e32 v37, v0
	v_mov_b32_e32 v38, v0
	v_mov_b32_e32 v39, v0
	v_mov_b32_e32 v48, v0
	v_mov_b32_e32 v49, v0
	v_mov_b32_e32 v50, v0
	v_mov_b32_e32 v51, v0
	v_mov_b32_e32 v52, v0
	v_mov_b32_e32 v53, v0
	v_mov_b32_e32 v54, v0
	v_mov_b32_e32 v55, v0
	v_mov_b32_e32 v8, v0
	v_mov_b32_e32 v9, v0
	v_mov_b32_e32 v10, v0
	v_mov_b32_e32 v11, v0
	v_mov_b32_e32 v12, v0
	v_mov_b32_e32 v13, v0
	v_mov_b32_e32 v14, v0
	v_mov_b32_e32 v15, v0
	v_mov_b32_e32 v24, v0
	v_mov_b32_e32 v25, v0
	v_mov_b32_e32 v26, v0
	v_mov_b32_e32 v27, v0
	v_mov_b32_e32 v28, v0
	v_mov_b32_e32 v29, v0
	v_mov_b32_e32 v30, v0
	v_mov_b32_e32 v31, v0
	v_mov_b32_e32 v40, v0
	v_mov_b32_e32 v41, v0
	v_mov_b32_e32 v42, v0
	v_mov_b32_e32 v43, v0
	v_mov_b32_e32 v44, v0
	v_mov_b32_e32 v45, v0
	v_mov_b32_e32 v46, v0
	v_mov_b32_e32 v47, v0
	v_mov_b32_e32 v56, v0
	v_mov_b32_e32 v57, v0
	v_mov_b32_e32 v58, v0
	v_mov_b32_e32 v59, v0
	v_mov_b32_e32 v60, v0
	v_mov_b32_e32 v61, v0
	v_mov_b32_e32 v62, v0
	v_mov_b32_e32 v63, v0
	v_mov_b32_e32 v64, v0
	v_mov_b32_e32 v65, v0
	v_mov_b32_e32 v66, v0
	v_mov_b32_e32 v67, v0
	v_mov_b32_e32 v68, v0
	v_mov_b32_e32 v69, v0
	v_mov_b32_e32 v70, v0
	v_mov_b32_e32 v71, v0
	v_mov_b32_e32 v88, v0
	v_mov_b32_e32 v89, v0
	v_mov_b32_e32 v90, v0
	v_mov_b32_e32 v91, v0
	v_mov_b32_e32 v100, v0
	v_mov_b32_e32 v101, v0
	v_mov_b32_e32 v102, v0
	v_mov_b32_e32 v103, v0
	v_mov_b32_e32 v112, v0
	v_mov_b32_e32 v113, v0
	v_mov_b32_e32 v114, v0
	v_mov_b32_e32 v115, v0
	v_mov_b32_e32 v116, v0
	v_mov_b32_e32 v117, v0
	v_mov_b32_e32 v118, v0
	v_mov_b32_e32 v119, v0
	v_mov_b32_e32 v128, v0
	v_mov_b32_e32 v129, v0
	v_mov_b32_e32 v130, v0
	v_mov_b32_e32 v131, v0
	v_mov_b32_e32 v132, v0
	v_mov_b32_e32 v133, v0
	v_mov_b32_e32 v134, v0
	v_mov_b32_e32 v135, v0
	v_mov_b32_e32 v76, v0
	v_mov_b32_e32 v77, v0
	v_mov_b32_e32 v78, v0
	v_mov_b32_e32 v79, v0
	v_mov_b32_e32 v80, v0
	v_mov_b32_e32 v81, v0
	v_mov_b32_e32 v82, v0
	v_mov_b32_e32 v83, v0
	v_mov_b32_e32 v104, v0
	v_mov_b32_e32 v105, v0
	v_mov_b32_e32 v106, v0
	v_mov_b32_e32 v107, v0
	v_mov_b32_e32 v108, v0
	v_mov_b32_e32 v109, v0
	v_mov_b32_e32 v110, v0
	v_mov_b32_e32 v111, v0
	v_mov_b32_e32 v120, v0
	v_mov_b32_e32 v121, v0
	v_mov_b32_e32 v122, v0
	v_mov_b32_e32 v123, v0
	v_mov_b32_e32 v124, v0
	v_mov_b32_e32 v125, v0
	v_mov_b32_e32 v126, v0
	v_mov_b32_e32 v127, v0
	v_mov_b32_e32 v136, v0
	v_mov_b32_e32 v137, v0
	v_mov_b32_e32 v138, v0
	v_mov_b32_e32 v139, v0
	v_mov_b32_e32 v140, v0
	v_mov_b32_e32 v141, v0
	v_mov_b32_e32 v142, v0
	v_mov_b32_e32 v143, v0
	s_cmp_eq_u32 s99, 0
	s_cbranch_scc1 .LBB0_894
	ds_read_b128 v[72:75], v169
	ds_read_b128 v[84:87], v169 offset:1024
	ds_read_b128 v[92:95], v169 offset:2048
	ds_read_b128 v[96:99], v169 offset:3072
	ds_read_b128 v[156:159], v170
	ds_read_b128 v[160:163], v170 offset:1024
	ds_read_b128 v[174:177], v170 offset:2048
	ds_read_b128 v[178:181], v170 offset:3072
	s_add_u32 s40, s38, 0xfff80080
	s_addc_u32 s41, s39, -1
	s_cmp_eq_u32 s58, 28
	s_cselect_b32 s43, s25, s41
	s_cselect_b32 s42, s35, s40
	s_cselect_b32 s41, s27, s57
	s_cselect_b32 s40, s55, s56
	v_lshl_add_u64 v[164:165], s[38:39], 0, v[148:149]
	s_add_i32 m0, s37, 0xc000
	ds_read_b128 v[182:185], v171
	ds_read_b128 v[188:191], v171 offset:1024
	ds_read_b128 v[192:195], v171 offset:2048
	ds_read_b128 v[196:199], v171 offset:3072
	ds_read_b128 v[200:203], v171 offset:4096
	ds_read_b128 v[204:207], v171 offset:5120
	ds_read_b128 v[208:211], v171 offset:6144
	ds_read_b128 v[212:215], v171 offset:7168
	global_load_lds_dwordx4 v[164:165], off
	v_lshl_add_u64 v[164:165], s[38:39], 0, v[150:151]
	s_add_i32 m0, s37, 0xe000
	s_nop 0
	global_load_lds_dwordx4 v[164:165], off
	s_waitcnt vmcnt(24)
	s_waitcnt lgkmcnt(0)
	s_barrier
; #define PG8_STAGE(bufoff, gbase, voff) do { _Pragma("unroll") for (int _i = 0; _i < 2; ++_i) \
;         __builtin_amdgcn_global_load_lds((const unsigned*)((const char*)(gbase) + (voff)[_i]), (PG8_LAS unsigned*)(lds + (bufoff) + ldsw + _i * 8192), 16, 0, 0); } while (0)
; #define PG8_LDA(dst, b, h) do { _Pragma("unroll") for (int m = 0; m < 4; ++m) _Pragma("unroll") for (int k = 0; k < 2; ++k) dst[m][k] = *(const PG8_LAS bf16x8*)(lds + PG8_SA(b, h) + aoff + m * 2048 + k * 1024); } while (0)
; #define PG8_MMA(ai, bj, At, Bt) do { __builtin_amdgcn_s_setprio(1); _Pragma("unroll") for (int m = 0; m < 4; ++m) _Pragma("unroll") for (int n = 0; n < 2; ++n) _Pragma("unroll") for (int k = 0; k < 2; ++k) \
;         acc[ai][bj][m][n] = __builtin_amdgcn_mfma_f32_16x16x32_bf16(Bt[n][k], At[m][k], acc[ai][bj][m][n], 0, 0, 0); __builtin_amdgcn_s_setprio(0); } while (0)
; #define PG8_WAIT_V(n) asm volatile("s_waitcnt vmcnt(" #n ")" ::: "memory")
; #define PG8_WAIT_L(n) asm volatile("s_waitcnt lgkmcnt(" #n ")" ::: "memory")
; #define PG8_BAR __builtin_amdgcn_s_barrier()
; #define PG8_SCHED __builtin_amdgcn_sched_barrier(0)
; template <class Epi, class Sched, bool ALIGN_EPI = false, bool SP2 = false>
; __device__ __forceinline__ void gemm_phase(PG8_LAS unsigned char* lds, const Gemm g, const Sched& S, const Epi& E) {
;     ...
;             PG8_WAIT_V(8); PG8_WAIT_L(0); PG8_BAR; PG8_MMA(0, 0, At, B0); PG8_MMA(0, 1, At, B1); PG8_BAR; PG8_SCHED;
;             PG8_LDA(At, 0, 1); PG8_STAGE(PG8_SB(0, 0), b2, voffB); PG8_STAGE(PG8_SB(0, 1), b2 + hstep, voffB); PG8_STAGE(PG8_SA(0, 0), a2, voffA);
;             PG8_WAIT_V(8); PG8_WAIT_L(0); PG8_BAR; PG8_MMA(1, 0, At, B0); PG8_MMA(1, 1, At, B1); PG8_BAR; PG8_SCHED;
	s_setprio 1
	s_waitcnt lgkmcnt(0)
	v_mfma_f32_16x16x32_bf16 v[140:143], v[72:75], v[182:185], v[140:143]
	v_mfma_f32_16x16x32_bf16 v[136:139], v[92:95], v[182:185], v[136:139]
	v_mfma_f32_16x16x32_bf16 v[124:127], v[72:75], v[192:195], v[124:127]
	v_mfma_f32_16x16x32_bf16 v[120:123], v[92:95], v[192:195], v[120:123]
	v_mfma_f32_16x16x32_bf16 v[108:111], v[72:75], v[200:203], v[108:111]
	v_mfma_f32_16x16x32_bf16 v[104:107], v[92:95], v[200:203], v[104:107]
	v_mfma_f32_16x16x32_bf16 v[80:83], v[72:75], v[208:211], v[80:83]
	v_mfma_f32_16x16x32_bf16 v[76:79], v[92:95], v[208:211], v[76:79]
	v_mfma_f32_16x16x32_bf16 v[140:143], v[84:87], v[188:191], v[140:143]
	v_mfma_f32_16x16x32_bf16 v[136:139], v[96:99], v[188:191], v[136:139]
	v_mfma_f32_16x16x32_bf16 v[124:127], v[84:87], v[196:199], v[124:127]
	v_mfma_f32_16x16x32_bf16 v[120:123], v[96:99], v[196:199], v[120:123]
	v_mfma_f32_16x16x32_bf16 v[108:111], v[84:87], v[204:207], v[108:111]
	v_mfma_f32_16x16x32_bf16 v[104:107], v[96:99], v[204:207], v[104:107]
	v_mfma_f32_16x16x32_bf16 v[80:83], v[84:87], v[212:215], v[80:83]
	v_mfma_f32_16x16x32_bf16 v[76:79], v[96:99], v[212:215], v[76:79]
	s_setprio 0
	s_setprio 1
	v_mfma_f32_16x16x32_bf16 v[132:135], v[156:159], v[182:185], v[132:135]
	v_mfma_f32_16x16x32_bf16 v[128:131], v[174:177], v[182:185], v[128:131]
	v_mfma_f32_16x16x32_bf16 v[116:119], v[156:159], v[192:195], v[116:119]
	v_mfma_f32_16x16x32_bf16 v[112:115], v[174:177], v[192:195], v[112:115]
	v_mfma_f32_16x16x32_bf16 v[100:103], v[156:159], v[200:203], v[100:103]
	v_mfma_f32_16x16x32_bf16 v[88:91], v[174:177], v[200:203], v[88:91]
	v_mfma_f32_16x16x32_bf16 v[68:71], v[156:159], v[208:211], v[68:71]
	v_mfma_f32_16x16x32_bf16 v[64:67], v[174:177], v[208:211], v[64:67]
	v_mfma_f32_16x16x32_bf16 v[132:135], v[160:163], v[188:191], v[132:135]
	v_mfma_f32_16x16x32_bf16 v[128:131], v[178:181], v[188:191], v[128:131]
	v_mfma_f32_16x16x32_bf16 v[116:119], v[160:163], v[196:199], v[116:119]
	v_mfma_f32_16x16x32_bf16 v[112:115], v[178:181], v[196:199], v[112:115]
	v_mfma_f32_16x16x32_bf16 v[100:103], v[160:163], v[204:207], v[100:103]
	v_mfma_f32_16x16x32_bf16 v[88:91], v[178:181], v[204:207], v[88:91]
	v_mfma_f32_16x16x32_bf16 v[68:71], v[160:163], v[212:215], v[68:71]
	v_mfma_f32_16x16x32_bf16 v[64:67], v[178:181], v[212:215], v[64:67]
	s_setprio 0
	s_barrier
	s_add_i32 s59, s53, s33
	v_lshl_add_u64 v[164:165], s[40:41], 0, v[144:145]
	s_mov_b32 m0, s59
	ds_read_b128 v[182:185], v171 offset:16384
	ds_read_b128 v[188:191], v171 offset:17408
	ds_read_b128 v[192:195], v171 offset:18432
	ds_read_b128 v[196:199], v171 offset:19456
	ds_read_b128 v[200:203], v171 offset:20480
	ds_read_b128 v[204:207], v171 offset:21504
	ds_read_b128 v[208:211], v171 offset:22528
	ds_read_b128 v[212:215], v171 offset:23552
	global_load_lds_dwordx4 v[164:165], off
	s_add_i32 m0, s59, 0x2000
	s_add_u32 s60, s40, 0x80000
	v_lshl_add_u64 v[216:217], s[40:41], 0, v[146:147]
	s_addc_u32 s61, s41, 0
	s_add_i32 s59, s54, s33
	global_load_lds_dwordx4 v[216:217], off
	v_lshl_add_u64 v[218:219], s[60:61], 0, v[144:145]
	s_mov_b32 m0, s59
	v_lshl_add_u64 v[220:221], s[42:43], 0, v[146:147]
	global_load_lds_dwordx4 v[218:219], off
	v_lshl_add_u64 v[218:219], s[60:61], 0, v[146:147]
	s_add_i32 m0, s59, 0x2000
	s_nop 0
	global_load_lds_dwordx4 v[218:219], off
	v_lshl_add_u64 v[218:219], s[42:43], 0, v[144:145]
	s_mov_b32 m0, s37
	s_nop 0
	global_load_lds_dwordx4 v[218:219], off
	s_mov_b32 m0, s44
	s_nop 0
	global_load_lds_dwordx4 v[220:221], off
	s_waitcnt vmcnt(24)
	s_waitcnt lgkmcnt(0)
	s_barrier
	s_setprio 1
	s_waitcnt lgkmcnt(0)
	v_mfma_f32_16x16x32_bf16 v[60:63], v[72:75], v[182:185], v[60:63]
	v_mfma_f32_16x16x32_bf16 v[56:59], v[92:95], v[182:185], v[56:59]
	v_mfma_f32_16x16x32_bf16 v[44:47], v[72:75], v[192:195], v[44:47]
	v_mfma_f32_16x16x32_bf16 v[40:43], v[92:95], v[192:195], v[40:43]
	v_mfma_f32_16x16x32_bf16 v[28:31], v[72:75], v[200:203], v[28:31]
	v_mfma_f32_16x16x32_bf16 v[24:27], v[92:95], v[200:203], v[24:27]
	v_mfma_f32_16x16x32_bf16 v[12:15], v[72:75], v[208:211], v[12:15]
	v_mfma_f32_16x16x32_bf16 v[8:11], v[92:95], v[208:211], v[8:11]
	v_mfma_f32_16x16x32_bf16 v[60:63], v[84:87], v[188:191], v[60:63]
	v_mfma_f32_16x16x32_bf16 v[56:59], v[96:99], v[188:191], v[56:59]
	v_mfma_f32_16x16x32_bf16 v[44:47], v[84:87], v[196:199], v[44:47]
	v_mfma_f32_16x16x32_bf16 v[40:43], v[96:99], v[196:199], v[40:43]
	v_mfma_f32_16x16x32_bf16 v[28:31], v[84:87], v[204:207], v[28:31]
	v_mfma_f32_16x16x32_bf16 v[24:27], v[96:99], v[204:207], v[24:27]
	v_mfma_f32_16x16x32_bf16 v[12:15], v[84:87], v[212:215], v[12:15]
	v_mfma_f32_16x16x32_bf16 v[8:11], v[96:99], v[212:215], v[8:11]
	s_setprio 0
	s_setprio 1
	v_mfma_f32_16x16x32_bf16 v[52:55], v[156:159], v[182:185], v[52:55]
	v_mfma_f32_16x16x32_bf16 v[48:51], v[174:177], v[182:185], v[48:51]
	v_mfma_f32_16x16x32_bf16 v[36:39], v[156:159], v[192:195], v[36:39]
	v_mfma_f32_16x16x32_bf16 v[32:35], v[174:177], v[192:195], v[32:35]
	v_mfma_f32_16x16x32_bf16 v[20:23], v[156:159], v[200:203], v[20:23]
	v_mfma_f32_16x16x32_bf16 v[16:19], v[174:177], v[200:203], v[16:19]
	v_mfma_f32_16x16x32_bf16 v[4:7], v[156:159], v[208:211], v[4:7]
	v_mfma_f32_16x16x32_bf16 v[0:3], v[174:177], v[208:211], v[0:3]
	v_mfma_f32_16x16x32_bf16 v[52:55], v[160:163], v[188:191], v[52:55]
	v_mfma_f32_16x16x32_bf16 v[48:51], v[178:181], v[188:191], v[48:51]
	v_mfma_f32_16x16x32_bf16 v[36:39], v[160:163], v[196:199], v[36:39]
	v_mfma_f32_16x16x32_bf16 v[32:35], v[178:181], v[196:199], v[32:35]
	v_mfma_f32_16x16x32_bf16 v[20:23], v[160:163], v[204:207], v[20:23]
	v_mfma_f32_16x16x32_bf16 v[16:19], v[178:181], v[204:207], v[16:19]
	v_mfma_f32_16x16x32_bf16 v[4:7], v[160:163], v[212:215], v[4:7]
	v_mfma_f32_16x16x32_bf16 v[0:3], v[178:181], v[212:215], v[0:3]
	s_setprio 0
	s_barrier
; #define PG8_STAGE(bufoff, gbase, voff) do { _Pragma("unroll") for (int _i = 0; _i < 2; ++_i) \
;         __builtin_amdgcn_global_load_lds((const unsigned*)((const char*)(gbase) + (voff)[_i]), (PG8_LAS unsigned*)(lds + (bufoff) + ldsw + _i * 8192), 16, 0, 0); } while (0)
; #define PG8_LDA(dst, b, h) do { _Pragma("unroll") for (int m = 0; m < 4; ++m) _Pragma("unroll") for (int k = 0; k < 2; ++k) dst[m][k] = *(const PG8_LAS bf16x8*)(lds + PG8_SA(b, h) + aoff + m * 2048 + k * 1024); } while (0)
; #define PG8_LDB(dst, b, h) do { _Pragma("unroll") for (int n = 0; n < 2; ++n) _Pragma("unroll") for (int k = 0; k < 2; ++k) dst[n][k] = *(const PG8_LAS bf16x8*)(lds + PG8_SB(b, h) + boff + n * 2048 + k * 1024); } while (0)
; #define PG8_MMA(ai, bj, At, Bt) do { __builtin_amdgcn_s_setprio(1); _Pragma("unroll") for (int m = 0; m < 4; ++m) _Pragma("unroll") for (int n = 0; n < 2; ++n) _Pragma("unroll") for (int k = 0; k < 2; ++k) \
;         acc[ai][bj][m][n] = __builtin_amdgcn_mfma_f32_16x16x32_bf16(Bt[n][k], At[m][k], acc[ai][bj][m][n], 0, 0, 0); __builtin_amdgcn_s_setprio(0); } while (0)
; #define PG8_WAIT_V(n) asm volatile("s_waitcnt vmcnt(" #n ")" ::: "memory")
; #define PG8_WAIT_L(n) asm volatile("s_waitcnt lgkmcnt(" #n ")" ::: "memory")
; #define PG8_BAR __builtin_amdgcn_s_barrier()
; #define PG8_SCHED __builtin_amdgcn_sched_barrier(0)
; template <class Epi, class Sched, bool ALIGN_EPI = false, bool SP2 = false>
; __device__ __forceinline__ void gemm_phase(PG8_LAS unsigned char* lds, const Gemm g, const Sched& S, const Epi& E) {
;     ...
;             PG8_LDB(B0, 1, 0); PG8_LDB(B1, 1, 1); PG8_SCHED; PG8_LDA(At, 1, 0); PG8_STAGE(PG8_SA(0, 1), a2 + hstep, voffA);
;             PG8_WAIT_V(8); PG8_WAIT_L(0); PG8_BAR; PG8_MMA(0, 0, At, B0); PG8_MMA(0, 1, At, B1); PG8_BAR; PG8_SCHED;
	s_add_i32 s59, 0, 0x18000
	s_add_i32 s60, 0, 0x1c000
	v_add_u32_e32 v96, s59, v167
	v_add_u32_e32 v173, s60, v167
	ds_read_b128 v[72:75], v96
	ds_read_b128 v[84:87], v96 offset:1024
	ds_read_b128 v[92:95], v96 offset:2048
	ds_read_b128 v[96:99], v96 offset:3072
	ds_read_b128 v[156:159], v173
	ds_read_b128 v[160:163], v173 offset:1024
	ds_read_b128 v[174:177], v173 offset:2048
	ds_read_b128 v[178:181], v173 offset:3072
	s_add_u32 s42, s42, 0x80000
	s_addc_u32 s43, s43, 0
	s_mov_b32 m0, s45
	v_lshl_add_u64 v[222:223], s[42:43], 0, v[144:145]
	ds_read_b128 v[182:185], v171 offset:32768
	ds_read_b128 v[188:191], v171 offset:33792
	ds_read_b128 v[192:195], v171 offset:34816
	ds_read_b128 v[196:199], v171 offset:35840
	ds_read_b128 v[200:203], v171 offset:36864
	ds_read_b128 v[204:207], v171 offset:37888
	ds_read_b128 v[208:211], v171 offset:38912
	ds_read_b128 v[212:215], v171 offset:39936
	global_load_lds_dwordx4 v[222:223], off
	v_lshl_add_u64 v[222:223], s[42:43], 0, v[146:147]
	s_mov_b32 m0, s46
	s_nop 0
	global_load_lds_dwordx4 v[222:223], off
	s_waitcnt vmcnt(8)
	s_waitcnt lgkmcnt(0)
	s_barrier
	s_setprio 1
	s_waitcnt lgkmcnt(0)
	v_mfma_f32_16x16x32_bf16 v[140:143], v[72:75], v[182:185], v[140:143]
	v_mfma_f32_16x16x32_bf16 v[136:139], v[92:95], v[182:185], v[136:139]
	v_mfma_f32_16x16x32_bf16 v[124:127], v[72:75], v[192:195], v[124:127]
	v_mfma_f32_16x16x32_bf16 v[120:123], v[92:95], v[192:195], v[120:123]
	v_mfma_f32_16x16x32_bf16 v[108:111], v[72:75], v[200:203], v[108:111]
	v_mfma_f32_16x16x32_bf16 v[104:107], v[92:95], v[200:203], v[104:107]
	v_mfma_f32_16x16x32_bf16 v[80:83], v[72:75], v[208:211], v[80:83]
	v_mfma_f32_16x16x32_bf16 v[76:79], v[92:95], v[208:211], v[76:79]
	v_mfma_f32_16x16x32_bf16 v[140:143], v[84:87], v[188:191], v[140:143]
	v_mfma_f32_16x16x32_bf16 v[136:139], v[96:99], v[188:191], v[136:139]
	v_mfma_f32_16x16x32_bf16 v[124:127], v[84:87], v[196:199], v[124:127]
	v_mfma_f32_16x16x32_bf16 v[120:123], v[96:99], v[196:199], v[120:123]
	v_mfma_f32_16x16x32_bf16 v[108:111], v[84:87], v[204:207], v[108:111]
	v_mfma_f32_16x16x32_bf16 v[104:107], v[96:99], v[204:207], v[104:107]
	v_mfma_f32_16x16x32_bf16 v[80:83], v[84:87], v[212:215], v[80:83]
	v_mfma_f32_16x16x32_bf16 v[76:79], v[96:99], v[212:215], v[76:79]
	s_setprio 0
	s_setprio 1
	v_mfma_f32_16x16x32_bf16 v[132:135], v[156:159], v[182:185], v[132:135]
	v_mfma_f32_16x16x32_bf16 v[128:131], v[174:177], v[182:185], v[128:131]
	v_mfma_f32_16x16x32_bf16 v[116:119], v[156:159], v[192:195], v[116:119]
	v_mfma_f32_16x16x32_bf16 v[112:115], v[174:177], v[192:195], v[112:115]
	v_mfma_f32_16x16x32_bf16 v[100:103], v[156:159], v[200:203], v[100:103]
	v_mfma_f32_16x16x32_bf16 v[88:91], v[174:177], v[200:203], v[88:91]
	v_mfma_f32_16x16x32_bf16 v[68:71], v[156:159], v[208:211], v[68:71]
	v_mfma_f32_16x16x32_bf16 v[64:67], v[174:177], v[208:211], v[64:67]
	v_mfma_f32_16x16x32_bf16 v[132:135], v[160:163], v[188:191], v[132:135]
	v_mfma_f32_16x16x32_bf16 v[128:131], v[178:181], v[188:191], v[128:131]
	v_mfma_f32_16x16x32_bf16 v[116:119], v[160:163], v[196:199], v[116:119]
	v_mfma_f32_16x16x32_bf16 v[112:115], v[178:181], v[196:199], v[112:115]
	v_mfma_f32_16x16x32_bf16 v[100:103], v[160:163], v[204:207], v[100:103]
	v_mfma_f32_16x16x32_bf16 v[88:91], v[178:181], v[204:207], v[88:91]
	v_mfma_f32_16x16x32_bf16 v[68:71], v[160:163], v[212:215], v[68:71]
	v_mfma_f32_16x16x32_bf16 v[64:67], v[178:181], v[212:215], v[64:67]
	s_setprio 0
	s_barrier
; #define PG8_STAGE(bufoff, gbase, voff) do { _Pragma("unroll") for (int _i = 0; _i < 2; ++_i) \
;         __builtin_amdgcn_global_load_lds((const unsigned*)((const char*)(gbase) + (voff)[_i]), (PG8_LAS unsigned*)(lds + (bufoff) + ldsw + _i * 8192), 16, 0, 0); } while (0)
; #define PG8_LDA(dst, b, h) do { _Pragma("unroll") for (int m = 0; m < 4; ++m) _Pragma("unroll") for (int k = 0; k < 2; ++k) dst[m][k] = *(const PG8_LAS bf16x8*)(lds + PG8_SA(b, h) + aoff + m * 2048 + k * 1024); } while (0)
; #define PG8_MMA(ai, bj, At, Bt) do { __builtin_amdgcn_s_setprio(1); _Pragma("unroll") for (int m = 0; m < 4; ++m) _Pragma("unroll") for (int n = 0; n < 2; ++n) _Pragma("unroll") for (int k = 0; k < 2; ++k) \
;         acc[ai][bj][m][n] = __builtin_amdgcn_mfma_f32_16x16x32_bf16(Bt[n][k], At[m][k], acc[ai][bj][m][n], 0, 0, 0); __builtin_amdgcn_s_setprio(0); } while (0)
; #define PG8_WAIT_V(n) asm volatile("s_waitcnt vmcnt(" #n ")" ::: "memory")
; #define PG8_WAIT_L(n) asm volatile("s_waitcnt lgkmcnt(" #n ")" ::: "memory")
; #define PG8_BAR __builtin_amdgcn_s_barrier()
; #define PG8_SCHED __builtin_amdgcn_sched_barrier(0)
; template <class Epi, class Sched, bool ALIGN_EPI = false, bool SP2 = false>
; __device__ __forceinline__ void gemm_phase(PG8_LAS unsigned char* lds, const Gemm g, const Sched& S, const Epi& E) {
;     ...
;             PG8_LDA(At, 1, 1); PG8_STAGE(PG8_SB(1, 0), b3, voffB); PG8_STAGE(PG8_SB(1, 1), b3 + hstep, voffB); PG8_STAGE(PG8_SA(1, 0), a3, voffA);
;             PG8_WAIT_V(8); PG8_WAIT_L(0); PG8_BAR; PG8_MMA(1, 0, At, B0); PG8_MMA(1, 1, At, B1); PG8_BAR; PG8_SCHED;
	s_add_i32 s42, s59, s33
	v_lshl_add_u64 v[164:165], v[164:165], 0, s[12:13]
	s_mov_b32 m0, s42
	ds_read_b128 v[182:185], v171 offset:49152
	ds_read_b128 v[188:191], v171 offset:50176
	ds_read_b128 v[192:195], v171 offset:51200
	ds_read_b128 v[196:199], v171 offset:52224
	ds_read_b128 v[200:203], v171 offset:53248
	ds_read_b128 v[204:207], v171 offset:54272
	ds_read_b128 v[208:211], v171 offset:55296
	ds_read_b128 v[212:215], v171 offset:56320
	global_load_lds_dwordx4 v[164:165], off
	s_add_i32 m0, s42, 0x2000
	s_add_u32 s40, s40, 0x80080
	v_lshl_add_u64 v[164:165], v[216:217], 0, s[12:13]
	s_addc_u32 s41, s41, 0
	s_add_i32 s42, s60, s33
	global_load_lds_dwordx4 v[164:165], off
	v_lshl_add_u64 v[164:165], s[40:41], 0, v[144:145]
	s_mov_b32 m0, s42
	s_nop 0
	global_load_lds_dwordx4 v[164:165], off
	v_lshl_add_u64 v[164:165], s[40:41], 0, v[146:147]
	s_add_i32 m0, s42, 0x2000
	s_nop 0
	global_load_lds_dwordx4 v[164:165], off
	v_lshl_add_u64 v[164:165], v[218:219], 0, s[12:13]
	s_mov_b32 m0, s50
	s_nop 0
	global_load_lds_dwordx4 v[164:165], off
	v_lshl_add_u64 v[164:165], v[220:221], 0, s[12:13]
	s_mov_b32 m0, s51
	s_nop 0
	global_load_lds_dwordx4 v[164:165], off
	s_waitcnt vmcnt(8)
	s_waitcnt lgkmcnt(0)
	s_barrier
	s_setprio 1
	s_waitcnt lgkmcnt(0)
	v_mfma_f32_16x16x32_bf16 v[60:63], v[72:75], v[182:185], v[60:63]
	v_mfma_f32_16x16x32_bf16 v[56:59], v[92:95], v[182:185], v[56:59]
	v_mfma_f32_16x16x32_bf16 v[44:47], v[72:75], v[192:195], v[44:47]
	v_mfma_f32_16x16x32_bf16 v[40:43], v[92:95], v[192:195], v[40:43]
	v_mfma_f32_16x16x32_bf16 v[28:31], v[72:75], v[200:203], v[28:31]
	v_mfma_f32_16x16x32_bf16 v[24:27], v[92:95], v[200:203], v[24:27]
	v_mfma_f32_16x16x32_bf16 v[12:15], v[72:75], v[208:211], v[12:15]
	v_mfma_f32_16x16x32_bf16 v[8:11], v[92:95], v[208:211], v[8:11]
	v_mfma_f32_16x16x32_bf16 v[60:63], v[84:87], v[188:191], v[60:63]
	v_mfma_f32_16x16x32_bf16 v[56:59], v[96:99], v[188:191], v[56:59]
	v_mfma_f32_16x16x32_bf16 v[44:47], v[84:87], v[196:199], v[44:47]
	v_mfma_f32_16x16x32_bf16 v[40:43], v[96:99], v[196:199], v[40:43]
	v_mfma_f32_16x16x32_bf16 v[28:31], v[84:87], v[204:207], v[28:31]
	v_mfma_f32_16x16x32_bf16 v[24:27], v[96:99], v[204:207], v[24:27]
	v_mfma_f32_16x16x32_bf16 v[12:15], v[84:87], v[212:215], v[12:15]
	v_mfma_f32_16x16x32_bf16 v[8:11], v[96:99], v[212:215], v[8:11]
	s_setprio 0
	s_setprio 1
	v_mfma_f32_16x16x32_bf16 v[52:55], v[156:159], v[182:185], v[52:55]
	v_mfma_f32_16x16x32_bf16 v[48:51], v[174:177], v[182:185], v[48:51]
	v_mfma_f32_16x16x32_bf16 v[36:39], v[156:159], v[192:195], v[36:39]
	v_mfma_f32_16x16x32_bf16 v[32:35], v[174:177], v[192:195], v[32:35]
	v_mfma_f32_16x16x32_bf16 v[20:23], v[156:159], v[200:203], v[20:23]
	v_mfma_f32_16x16x32_bf16 v[16:19], v[174:177], v[200:203], v[16:19]
	v_mfma_f32_16x16x32_bf16 v[4:7], v[156:159], v[208:211], v[4:7]
	v_mfma_f32_16x16x32_bf16 v[0:3], v[174:177], v[208:211], v[0:3]
	v_mfma_f32_16x16x32_bf16 v[52:55], v[160:163], v[188:191], v[52:55]
	v_mfma_f32_16x16x32_bf16 v[48:51], v[178:181], v[188:191], v[48:51]
	v_mfma_f32_16x16x32_bf16 v[36:39], v[160:163], v[196:199], v[36:39]
	v_mfma_f32_16x16x32_bf16 v[32:35], v[178:181], v[196:199], v[32:35]
	v_mfma_f32_16x16x32_bf16 v[20:23], v[160:163], v[204:207], v[20:23]
	v_mfma_f32_16x16x32_bf16 v[16:19], v[178:181], v[204:207], v[16:19]
	v_mfma_f32_16x16x32_bf16 v[4:7], v[160:163], v[212:215], v[4:7]
	v_mfma_f32_16x16x32_bf16 v[0:3], v[178:181], v[212:215], v[0:3]
	s_setprio 0
	s_barrier
	s_add_i32 s58, s58, 2
	s_add_u32 s38, s38, 0x100
	s_addc_u32 s39, s39, 0
	s_add_u32 s56, s56, 0x100
	s_addc_u32 s57, s57, 0
	s_cmp_gt_u32 s58, 29

; __device__ __forceinline__ unsigned cvt_pk_bf16(float lo, float hi) { unsigned r; asm volatile("v_cvt_pk_bf16_f32 %0, %1, %2" : "=v"(r) : "v"(lo), "v"(hi)); return r; }
;     __device__ __forceinline__ void operator()(const f32x4 (&acc)[2][2][4][2], const Unit& u, int wr, int wc, int fr, int fq) const {
;         const int row0 = u.pm * BM + wr * 64 + fr, col0 = u.pn * BM + wc * 32 + 4 * fq, b = (u.pm * BM) >> 12;
;         f32x4 gv[2][2], Gv[2][2];
; #pragma unroll
;         for (int bj = 0; bj < 2; ++bj)
; #pragma unroll
;             for (int n = 0; n < 2; ++n) { const int c = col0 + bj * HALF + n * 16; gv[bj][n] = *(const f32x4*)(mod + (size_t)b * 12288 + 2 * 2048 + c);
;                 Gv[bj][n] = *(const f32x4*)(g2 + c) * (*(const f32x4*)(mod + (size_t)b * 12288 + 4 * 2048 + c) + 1.0f); }
;         float* prow = part + (size_t)(u.pn * 4 + wc) * 16384;
; #pragma unroll
;         for (int ai = 0; ai < 2; ++ai)
; #pragma unroll
;             for (int m = 0; m < 4; ++m) { const int row = row0 + ai * HALF + m * 16; const size_t off = (size_t)row * 2048 + col0; float ss = 0.f;
; #pragma unroll
;                 for (int bj = 0; bj < 2; ++bj)
; #pragma unroll
;                     for (int n = 0; n < 2; ++n) { const f32x4 bs = __builtin_nontemporal_load((const f32x4*)(base + off + bj * HALF + n * 16)); const f32x4 x1 = bs + gv[bj][n] * acc[ai][bj][m][n];
;                         *(f32x4*)(out + off + bj * HALF + n * 16) = x1; ss += (x1.x * x1.x + x1.y * x1.y) + (x1.z * x1.z + x1.w * x1.w);
;                         const f32x4 hh = x1 * Gv[bj][n]; u32x2 w; w.x = cvt_pk_bf16(hh.x, hh.y); w.y = cvt_pk_bf16(hh.z, hh.w); *(u32x2*)(A2 + off + bj * HALF + n * 16) = w; }
.LBB0_897:
	v_readlane_b32 s98, v236, 7
	v_readlane_b32 s99, v236, 8
	v_readlane_b32 s76, v236, 35
	v_readlane_b32 s77, v236, 36
	s_ashr_i32 s25, s36, 4
	s_mul_hi_i32 s27, s25, 0xc000
	s_mul_i32 s25, s25, 0xc000
	s_add_u32 s38, s68, s25
	s_addc_u32 s39, s69, s27
	s_add_u32 s40, s38, 0x8000
	s_addc_u32 s41, s39, 0
	s_add_u32 s38, s38, 0x4000
	s_addc_u32 s39, s39, 0
	v_lshl_add_u32 v164, s36, 8, v166
	v_lshl_or_b32 v165, s34, 8, v168
	v_lshlrev_b32_e32 v173, 2, v165
	v_xor_b32_e32 v216, 16, v172
	v_xor_b32_e32 v217, 32, v172
	v_lshlrev_b32_e32 v216, 2, v216
	v_lshlrev_b32_e32 v217, 2, v217
	global_load_dwordx4 v[72:75], v173, s[38:39]
	global_load_dwordx4 v[84:87], v173, s[38:39] offset:64
	global_load_dwordx4 v[92:95], v173, s[38:39] offset:512
	global_load_dwordx4 v[96:99], v173, s[38:39] offset:576
	global_load_dwordx4 v[156:159], v173, s[40:41]
	global_load_dwordx4 v[160:163], v173, s[40:41] offset:64
	global_load_dwordx4 v[174:177], v173, s[40:41] offset:512
	global_load_dwordx4 v[178:181], v173, s[40:41] offset:576
	global_load_dwordx4 v[182:185], v173, s[76:77]
	global_load_dwordx4 v[188:191], v173, s[76:77] offset:64
	global_load_dwordx4 v[192:195], v173, s[76:77] offset:512
	global_load_dwordx4 v[196:199], v173, s[76:77] offset:576
	v_lshl_add_u32 v164, v164, 13, v173
	v_mov_b32_e32 v165, v164
	v_lshrrev_b32_e32 v173, 1, v164
	global_load_dwordx4 v[200:203], v164, s[98:99] nt
	global_load_dwordx4 v[204:207], v164, s[98:99] offset:64 nt
	global_load_dwordx4 v[208:211], v164, s[98:99] offset:512 nt
	global_load_dwordx4 v[212:215], v164, s[98:99] offset:576 nt
	v_add_u32_e32 v164, 0x20000, v164
	s_waitcnt vmcnt(4)
	v_pk_add_f32 v[156:157], v[156:157], 1.0 op_sel_hi:[1,0]
	v_pk_add_f32 v[158:159], v[158:159], 1.0 op_sel_hi:[1,0]
	v_pk_mul_f32 v[182:183], v[182:183], v[156:157]
	v_pk_mul_f32 v[184:185], v[184:185], v[158:159]
	v_pk_add_f32 v[160:161], v[160:161], 1.0 op_sel_hi:[1,0]
	v_pk_add_f32 v[162:163], v[162:163], 1.0 op_sel_hi:[1,0]
	v_pk_mul_f32 v[188:189], v[188:189], v[160:161]
	v_pk_mul_f32 v[190:191], v[190:191], v[162:163]
	v_pk_add_f32 v[174:175], v[174:175], 1.0 op_sel_hi:[1,0]
	v_pk_add_f32 v[176:177], v[176:177], 1.0 op_sel_hi:[1,0]
	v_pk_mul_f32 v[192:193], v[192:193], v[174:175]
	v_pk_mul_f32 v[194:195], v[194:195], v[176:177]
	v_pk_add_f32 v[178:179], v[178:179], 1.0 op_sel_hi:[1,0]
	v_pk_add_f32 v[180:181], v[180:181], 1.0 op_sel_hi:[1,0]
	v_pk_mul_f32 v[196:197], v[196:197], v[178:179]
	v_pk_mul_f32 v[198:199], v[198:199], v[180:181]
	global_load_dwordx4 v[156:159], v164, s[98:99] nt
	global_load_dwordx4 v[160:163], v164, s[98:99] offset:64 nt
	global_load_dwordx4 v[174:177], v164, s[98:99] offset:512 nt
	global_load_dwordx4 v[178:181], v164, s[98:99] offset:576 nt
	v_add_u32_e32 v164, 0x20000, v164
	s_waitcnt vmcnt(7)
	v_pk_fma_f32 v[200:201], v[140:141], v[72:73], v[200:201]
	v_pk_fma_f32 v[202:203], v[142:143], v[74:75], v[202:203]
	global_store_dwordx4 v165, v[200:203], s[66:67]
	v_pk_mul_f32 v[140:141], v[200:201], v[182:183]
	v_pk_mul_f32 v[142:143], v[202:203], v[184:185]
	v_cvt_pk_bf16_f32 v140, v140, v141
	v_cvt_pk_bf16_f32 v141, v142, v143
	global_store_dwordx2 v173, v[140:141], s[8:9]
	v_mul_f32_e32 v142, v200, v200
	v_fmac_f32_e32 v142, v201, v201
	v_fmac_f32_e32 v142, v202, v202
	v_fmac_f32_e32 v142, v203, v203
	global_load_dwordx4 v[200:203], v164, s[98:99] nt
	s_waitcnt vmcnt(9)
	v_pk_fma_f32 v[204:205], v[136:137], v[84:85], v[204:205]
	v_pk_fma_f32 v[206:207], v[138:139], v[86:87], v[206:207]
	global_store_dwordx4 v165, v[204:207], s[66:67] offset:64
	v_pk_mul_f32 v[136:137], v[204:205], v[188:189]
	v_pk_mul_f32 v[138:139], v[206:207], v[190:191]
	v_cvt_pk_bf16_f32 v136, v136, v137
	v_cvt_pk_bf16_f32 v137, v138, v139
	global_store_dwordx2 v173, v[136:137], s[8:9] offset:32
	v_fmac_f32_e32 v142, v204, v204
	v_fmac_f32_e32 v142, v205, v205
	v_fmac_f32_e32 v142, v206, v206
	v_fmac_f32_e32 v142, v207, v207
	global_load_dwordx4 v[204:207], v164, s[98:99] offset:64 nt
	s_waitcnt vmcnt(11)
	v_pk_fma_f32 v[208:209], v[132:133], v[92:93], v[208:209]
	v_pk_fma_f32 v[210:211], v[134:135], v[94:95], v[210:211]
	global_store_dwordx4 v165, v[208:211], s[66:67] offset:512
	v_pk_mul_f32 v[132:133], v[208:209], v[192:193]
	v_pk_mul_f32 v[134:135], v[210:211], v[194:195]
	v_cvt_pk_bf16_f32 v132, v132, v133
	v_cvt_pk_bf16_f32 v133, v134, v135
	global_store_dwordx2 v173, v[132:133], s[8:9] offset:256
	v_fmac_f32_e32 v142, v208, v208
	v_fmac_f32_e32 v142, v209, v209
	v_fmac_f32_e32 v142, v210, v210
	v_fmac_f32_e32 v142, v211, v211
	global_load_dwordx4 v[208:211], v164, s[98:99] offset:512 nt
	s_waitcnt vmcnt(13)
	v_pk_fma_f32 v[212:213], v[128:129], v[96:97], v[212:213]
	v_pk_fma_f32 v[214:215], v[130:131], v[98:99], v[214:215]
	global_store_dwordx4 v165, v[212:215], s[66:67] offset:576
	v_pk_mul_f32 v[128:129], v[212:213], v[196:197]
	v_pk_mul_f32 v[130:131], v[214:215], v[198:199]
	v_cvt_pk_bf16_f32 v128, v128, v129
	v_cvt_pk_bf16_f32 v129, v130, v131
	global_store_dwordx2 v173, v[128:129], s[8:9] offset:288
	v_fmac_f32_e32 v142, v212, v212
	v_fmac_f32_e32 v142, v213, v213
	v_fmac_f32_e32 v142, v214, v214
	v_fmac_f32_e32 v142, v215, v215
	v_add_u32_e32 v165, 0x20000, v165
	v_lshrrev_b32_e32 v173, 1, v165
	global_load_dwordx4 v[212:215], v164, s[98:99] offset:576 nt
	v_add_u32_e32 v164, 0x20000, v164
	s_waitcnt vmcnt(15)
	v_pk_fma_f32 v[156:157], v[124:125], v[72:73], v[156:157]
	v_pk_fma_f32 v[158:159], v[126:127], v[74:75], v[158:159]
	global_store_dwordx4 v165, v[156:159], s[66:67]
	v_pk_mul_f32 v[124:125], v[156:157], v[182:183]
	v_pk_mul_f32 v[126:127], v[158:159], v[184:185]
	v_cvt_pk_bf16_f32 v124, v124, v125
	v_cvt_pk_bf16_f32 v125, v126, v127
	global_store_dwordx2 v173, v[124:125], s[8:9]
	v_mul_f32_e32 v126, v156, v156
	v_fmac_f32_e32 v126, v157, v157
	v_fmac_f32_e32 v126, v158, v158
	v_fmac_f32_e32 v126, v159, v159
	global_load_dwordx4 v[156:159], v164, s[98:99] nt
	s_waitcnt vmcnt(17)
; __device__ __forceinline__ unsigned cvt_pk_bf16(float lo, float hi) { unsigned r; asm volatile("v_cvt_pk_bf16_f32 %0, %1, %2" : "=v"(r) : "v"(lo), "v"(hi)); return r; }
;     __device__ __forceinline__ void operator()(const f32x4 (&acc)[2][2][4][2], const Unit& u, int wr, int wc, int fr, int fq) const {
;     ...
;             for (int m = 0; m < 4; ++m) { const int row = row0 + ai * HALF + m * 16; const size_t off = (size_t)row * 2048 + col0; float ss = 0.f;
; #pragma unroll
;                 for (int bj = 0; bj < 2; ++bj)
; #pragma unroll
;                     for (int n = 0; n < 2; ++n) { const f32x4 bs = __builtin_nontemporal_load((const f32x4*)(base + off + bj * HALF + n * 16)); const f32x4 x1 = bs + gv[bj][n] * acc[ai][bj][m][n];
;                         *(f32x4*)(out + off + bj * HALF + n * 16) = x1; ss += (x1.x * x1.x + x1.y * x1.y) + (x1.z * x1.z + x1.w * x1.w);
;                         const f32x4 hh = x1 * Gv[bj][n]; u32x2 w; w.x = cvt_pk_bf16(hh.x, hh.y); w.y = cvt_pk_bf16(hh.z, hh.w); *(u32x2*)(A2 + off + bj * HALF + n * 16) = w; }
	v_pk_fma_f32 v[160:161], v[120:121], v[84:85], v[160:161]
	v_pk_fma_f32 v[162:163], v[122:123], v[86:87], v[162:163]
	global_store_dwordx4 v165, v[160:163], s[66:67] offset:64
	v_pk_mul_f32 v[120:121], v[160:161], v[188:189]
	v_pk_mul_f32 v[122:123], v[162:163], v[190:191]
	v_cvt_pk_bf16_f32 v120, v120, v121
	v_cvt_pk_bf16_f32 v121, v122, v123
	global_store_dwordx2 v173, v[120:121], s[8:9] offset:32
	v_fmac_f32_e32 v126, v160, v160
	v_fmac_f32_e32 v126, v161, v161
	v_fmac_f32_e32 v126, v162, v162
	v_fmac_f32_e32 v126, v163, v163
	global_load_dwordx4 v[160:163], v164, s[98:99] offset:64 nt
	s_waitcnt vmcnt(19)
	v_pk_fma_f32 v[174:175], v[116:117], v[92:93], v[174:175]
	v_pk_fma_f32 v[176:177], v[118:119], v[94:95], v[176:177]
	global_store_dwordx4 v165, v[174:177], s[66:67] offset:512
	v_pk_mul_f32 v[116:117], v[174:175], v[192:193]
	v_pk_mul_f32 v[118:119], v[176:177], v[194:195]
	v_cvt_pk_bf16_f32 v116, v116, v117
	v_cvt_pk_bf16_f32 v117, v118, v119
	global_store_dwordx2 v173, v[116:117], s[8:9] offset:256
	v_fmac_f32_e32 v126, v174, v174
	v_fmac_f32_e32 v126, v175, v175
	v_fmac_f32_e32 v126, v176, v176
	v_fmac_f32_e32 v126, v177, v177
	global_load_dwordx4 v[174:177], v164, s[98:99] offset:512 nt
	s_waitcnt vmcnt(21)
	v_pk_fma_f32 v[178:179], v[112:113], v[96:97], v[178:179]
	v_pk_fma_f32 v[180:181], v[114:115], v[98:99], v[180:181]
	global_store_dwordx4 v165, v[178:181], s[66:67] offset:576
	v_pk_mul_f32 v[112:113], v[178:179], v[196:197]
	v_pk_mul_f32 v[114:115], v[180:181], v[198:199]
	v_cvt_pk_bf16_f32 v112, v112, v113
	v_cvt_pk_bf16_f32 v113, v114, v115
	global_store_dwordx2 v173, v[112:113], s[8:9] offset:288
	v_fmac_f32_e32 v126, v178, v178
	v_fmac_f32_e32 v126, v179, v179
	v_fmac_f32_e32 v126, v180, v180
	v_fmac_f32_e32 v126, v181, v181
	v_add_u32_e32 v165, 0x20000, v165
	v_lshrrev_b32_e32 v173, 1, v165
	global_load_dwordx4 v[178:181], v164, s[98:99] offset:576 nt
	v_add_u32_e32 v164, 0xa0000, v164
	s_waitcnt vmcnt(21)
	v_pk_fma_f32 v[200:201], v[108:109], v[72:73], v[200:201]
	v_pk_fma_f32 v[202:203], v[110:111], v[74:75], v[202:203]
	global_store_dwordx4 v165, v[200:203], s[66:67]
	v_pk_mul_f32 v[108:109], v[200:201], v[182:183]
	v_pk_mul_f32 v[110:111], v[202:203], v[184:185]
	v_cvt_pk_bf16_f32 v108, v108, v109
	v_cvt_pk_bf16_f32 v109, v110, v111
	global_store_dwordx2 v173, v[108:109], s[8:9]
	v_mul_f32_e32 v110, v200, v200
	v_fmac_f32_e32 v110, v201, v201
	v_fmac_f32_e32 v110, v202, v202
	v_fmac_f32_e32 v110, v203, v203
	global_load_dwordx4 v[200:203], v164, s[98:99] nt
	s_waitcnt vmcnt(21)
	v_pk_fma_f32 v[204:205], v[104:105], v[84:85], v[204:205]
	v_pk_fma_f32 v[206:207], v[106:107], v[86:87], v[206:207]
	global_store_dwordx4 v165, v[204:207], s[66:67] offset:64
	v_pk_mul_f32 v[104:105], v[204:205], v[188:189]
	v_pk_mul_f32 v[106:107], v[206:207], v[190:191]
	v_cvt_pk_bf16_f32 v104, v104, v105
	v_cvt_pk_bf16_f32 v105, v106, v107
	global_store_dwordx2 v173, v[104:105], s[8:9] offset:32
	v_fmac_f32_e32 v110, v204, v204
	v_fmac_f32_e32 v110, v205, v205
	v_fmac_f32_e32 v110, v206, v206
	v_fmac_f32_e32 v110, v207, v207
	global_load_dwordx4 v[204:207], v164, s[98:99] offset:64 nt
	s_waitcnt vmcnt(21)
	v_pk_fma_f32 v[208:209], v[100:101], v[92:93], v[208:209]
	v_pk_fma_f32 v[210:211], v[102:103], v[94:95], v[210:211]
	global_store_dwordx4 v165, v[208:211], s[66:67] offset:512
	v_pk_mul_f32 v[100:101], v[208:209], v[192:193]
	v_pk_mul_f32 v[102:103], v[210:211], v[194:195]
	v_cvt_pk_bf16_f32 v100, v100, v101
	v_cvt_pk_bf16_f32 v101, v102, v103
	global_store_dwordx2 v173, v[100:101], s[8:9] offset:256
	v_fmac_f32_e32 v110, v208, v208
	v_fmac_f32_e32 v110, v209, v209
	v_fmac_f32_e32 v110, v210, v210
	v_fmac_f32_e32 v110, v211, v211
	global_load_dwordx4 v[208:211], v164, s[98:99] offset:512 nt
	s_waitcnt vmcnt(21)
	v_pk_fma_f32 v[212:213], v[88:89], v[96:97], v[212:213]
	v_pk_fma_f32 v[214:215], v[90:91], v[98:99], v[214:215]
	global_store_dwordx4 v165, v[212:215], s[66:67] offset:576
	v_pk_mul_f32 v[88:89], v[212:213], v[196:197]
	v_pk_mul_f32 v[90:91], v[214:215], v[198:199]
	v_cvt_pk_bf16_f32 v88, v88, v89
	v_cvt_pk_bf16_f32 v89, v90, v91
	global_store_dwordx2 v173, v[88:89], s[8:9] offset:288
	v_fmac_f32_e32 v110, v212, v212
	v_fmac_f32_e32 v110, v213, v213
	v_fmac_f32_e32 v110, v214, v214
	v_fmac_f32_e32 v110, v215, v215
	v_add_u32_e32 v165, 0x20000, v165
	v_lshrrev_b32_e32 v173, 1, v165
	global_load_dwordx4 v[212:215], v164, s[98:99] offset:576 nt
	v_add_u32_e32 v164, 0x20000, v164
	s_waitcnt vmcnt(21)
	v_pk_fma_f32 v[156:157], v[80:81], v[72:73], v[156:157]
	v_pk_fma_f32 v[158:159], v[82:83], v[74:75], v[158:159]
	global_store_dwordx4 v165, v[156:159], s[66:67]
	v_pk_mul_f32 v[80:81], v[156:157], v[182:183]
	v_pk_mul_f32 v[82:83], v[158:159], v[184:185]
	v_cvt_pk_bf16_f32 v80, v80, v81
	v_cvt_pk_bf16_f32 v81, v82, v83
	global_store_dwordx2 v173, v[80:81], s[8:9]
	v_mul_f32_e32 v82, v156, v156
	v_fmac_f32_e32 v82, v157, v157
	v_fmac_f32_e32 v82, v158, v158
	v_fmac_f32_e32 v82, v159, v159
	global_load_dwordx4 v[156:159], v164, s[98:99] nt
	s_waitcnt vmcnt(21)
	v_pk_fma_f32 v[160:161], v[76:77], v[84:85], v[160:161]
	v_pk_fma_f32 v[162:163], v[78:79], v[86:87], v[162:163]
	global_store_dwordx4 v165, v[160:163], s[66:67] offset:64
	v_pk_mul_f32 v[76:77], v[160:161], v[188:189]
	v_pk_mul_f32 v[78:79], v[162:163], v[190:191]
	v_cvt_pk_bf16_f32 v76, v76, v77
	v_cvt_pk_bf16_f32 v77, v78, v79
	global_store_dwordx2 v173, v[76:77], s[8:9] offset:32
	v_fmac_f32_e32 v82, v160, v160
	v_fmac_f32_e32 v82, v161, v161
	v_fmac_f32_e32 v82, v162, v162
	v_fmac_f32_e32 v82, v163, v163
	global_load_dwordx4 v[160:163], v164, s[98:99] offset:64 nt
	s_waitcnt vmcnt(21)
; __device__ __forceinline__ unsigned cvt_pk_bf16(float lo, float hi) { unsigned r; asm volatile("v_cvt_pk_bf16_f32 %0, %1, %2" : "=v"(r) : "v"(lo), "v"(hi)); return r; }
;     __device__ __forceinline__ void operator()(const f32x4 (&acc)[2][2][4][2], const Unit& u, int wr, int wc, int fr, int fq) const {
;     ...
;             for (int m = 0; m < 4; ++m) { const int row = row0 + ai * HALF + m * 16; const size_t off = (size_t)row * 2048 + col0; float ss = 0.f;
; #pragma unroll
;                 for (int bj = 0; bj < 2; ++bj)
; #pragma unroll
;                     for (int n = 0; n < 2; ++n) { const f32x4 bs = __builtin_nontemporal_load((const f32x4*)(base + off + bj * HALF + n * 16)); const f32x4 x1 = bs + gv[bj][n] * acc[ai][bj][m][n];
;                         *(f32x4*)(out + off + bj * HALF + n * 16) = x1; ss += (x1.x * x1.x + x1.y * x1.y) + (x1.z * x1.z + x1.w * x1.w);
;                         const f32x4 hh = x1 * Gv[bj][n]; u32x2 w; w.x = cvt_pk_bf16(hh.x, hh.y); w.y = cvt_pk_bf16(hh.z, hh.w); *(u32x2*)(A2 + off + bj * HALF + n * 16) = w; }
	v_pk_fma_f32 v[174:175], v[68:69], v[92:93], v[174:175]
	v_pk_fma_f32 v[176:177], v[70:71], v[94:95], v[176:177]
	global_store_dwordx4 v165, v[174:177], s[66:67] offset:512
	v_pk_mul_f32 v[68:69], v[174:175], v[192:193]
	v_pk_mul_f32 v[70:71], v[176:177], v[194:195]
	v_cvt_pk_bf16_f32 v68, v68, v69
	v_cvt_pk_bf16_f32 v69, v70, v71
	global_store_dwordx2 v173, v[68:69], s[8:9] offset:256
	v_fmac_f32_e32 v82, v174, v174
	v_fmac_f32_e32 v82, v175, v175
	v_fmac_f32_e32 v82, v176, v176
	v_fmac_f32_e32 v82, v177, v177
	global_load_dwordx4 v[174:177], v164, s[98:99] offset:512 nt
	s_waitcnt vmcnt(21)
	v_pk_fma_f32 v[178:179], v[64:65], v[96:97], v[178:179]
	v_pk_fma_f32 v[180:181], v[66:67], v[98:99], v[180:181]
	global_store_dwordx4 v165, v[178:181], s[66:67] offset:576
	v_pk_mul_f32 v[64:65], v[178:179], v[196:197]
	v_pk_mul_f32 v[66:67], v[180:181], v[198:199]
	v_cvt_pk_bf16_f32 v64, v64, v65
	v_cvt_pk_bf16_f32 v65, v66, v67
	global_store_dwordx2 v173, v[64:65], s[8:9] offset:288
	v_fmac_f32_e32 v82, v178, v178
	v_fmac_f32_e32 v82, v179, v179
	v_fmac_f32_e32 v82, v180, v180
	v_fmac_f32_e32 v82, v181, v181
	v_add_u32_e32 v165, 0xa0000, v165
	v_lshrrev_b32_e32 v173, 1, v165
	global_load_dwordx4 v[178:181], v164, s[98:99] offset:576 nt
	v_add_u32_e32 v164, 0x20000, v164
	s_waitcnt vmcnt(21)
	v_pk_fma_f32 v[200:201], v[60:61], v[72:73], v[200:201]
	v_pk_fma_f32 v[202:203], v[62:63], v[74:75], v[202:203]
	global_store_dwordx4 v165, v[200:203], s[66:67]
	v_pk_mul_f32 v[60:61], v[200:201], v[182:183]
	v_pk_mul_f32 v[62:63], v[202:203], v[184:185]
	v_cvt_pk_bf16_f32 v60, v60, v61
	v_cvt_pk_bf16_f32 v61, v62, v63
	global_store_dwordx2 v173, v[60:61], s[8:9]
	v_mul_f32_e32 v62, v200, v200
	v_fmac_f32_e32 v62, v201, v201
	v_fmac_f32_e32 v62, v202, v202
	v_fmac_f32_e32 v62, v203, v203
	global_load_dwordx4 v[200:203], v164, s[98:99] nt
	s_waitcnt vmcnt(21)
	v_pk_fma_f32 v[204:205], v[56:57], v[84:85], v[204:205]
	v_pk_fma_f32 v[206:207], v[58:59], v[86:87], v[206:207]
	global_store_dwordx4 v165, v[204:207], s[66:67] offset:64
	v_pk_mul_f32 v[56:57], v[204:205], v[188:189]
	v_pk_mul_f32 v[58:59], v[206:207], v[190:191]
	v_cvt_pk_bf16_f32 v56, v56, v57
	v_cvt_pk_bf16_f32 v57, v58, v59
	global_store_dwordx2 v173, v[56:57], s[8:9] offset:32
	v_fmac_f32_e32 v62, v204, v204
	v_fmac_f32_e32 v62, v205, v205
	v_fmac_f32_e32 v62, v206, v206
	v_fmac_f32_e32 v62, v207, v207
	global_load_dwordx4 v[204:207], v164, s[98:99] offset:64 nt
	s_waitcnt vmcnt(21)
	v_pk_fma_f32 v[208:209], v[52:53], v[92:93], v[208:209]
	v_pk_fma_f32 v[210:211], v[54:55], v[94:95], v[210:211]
	global_store_dwordx4 v165, v[208:211], s[66:67] offset:512
	v_pk_mul_f32 v[52:53], v[208:209], v[192:193]
	v_pk_mul_f32 v[54:55], v[210:211], v[194:195]
	v_cvt_pk_bf16_f32 v52, v52, v53
	v_cvt_pk_bf16_f32 v53, v54, v55
	global_store_dwordx2 v173, v[52:53], s[8:9] offset:256
	v_fmac_f32_e32 v62, v208, v208
	v_fmac_f32_e32 v62, v209, v209
	v_fmac_f32_e32 v62, v210, v210
	v_fmac_f32_e32 v62, v211, v211
	global_load_dwordx4 v[208:211], v164, s[98:99] offset:512 nt
	s_waitcnt vmcnt(21)
	v_pk_fma_f32 v[212:213], v[48:49], v[96:97], v[212:213]
	v_pk_fma_f32 v[214:215], v[50:51], v[98:99], v[214:215]
	global_store_dwordx4 v165, v[212:215], s[66:67] offset:576
	v_pk_mul_f32 v[48:49], v[212:213], v[196:197]
	v_pk_mul_f32 v[50:51], v[214:215], v[198:199]
	v_cvt_pk_bf16_f32 v48, v48, v49
	v_cvt_pk_bf16_f32 v49, v50, v51
	global_store_dwordx2 v173, v[48:49], s[8:9] offset:288
	v_fmac_f32_e32 v62, v212, v212
	v_fmac_f32_e32 v62, v213, v213
	v_fmac_f32_e32 v62, v214, v214
	v_fmac_f32_e32 v62, v215, v215
	v_add_u32_e32 v165, 0x20000, v165
	v_lshrrev_b32_e32 v173, 1, v165
	global_load_dwordx4 v[212:215], v164, s[98:99] offset:576 nt
	v_add_u32_e32 v164, 0x20000, v164
	s_waitcnt vmcnt(21)
	v_pk_fma_f32 v[156:157], v[44:45], v[72:73], v[156:157]
	v_pk_fma_f32 v[158:159], v[46:47], v[74:75], v[158:159]
	global_store_dwordx4 v165, v[156:159], s[66:67]
	v_pk_mul_f32 v[44:45], v[156:157], v[182:183]
	v_pk_mul_f32 v[46:47], v[158:159], v[184:185]
	v_cvt_pk_bf16_f32 v44, v44, v45
	v_cvt_pk_bf16_f32 v45, v46, v47
	global_store_dwordx2 v173, v[44:45], s[8:9]
	v_mul_f32_e32 v46, v156, v156
	v_fmac_f32_e32 v46, v157, v157
	v_fmac_f32_e32 v46, v158, v158
	v_fmac_f32_e32 v46, v159, v159
	global_load_dwordx4 v[156:159], v164, s[98:99] nt
	s_waitcnt vmcnt(21)
	v_pk_fma_f32 v[160:161], v[40:41], v[84:85], v[160:161]
	v_pk_fma_f32 v[162:163], v[42:43], v[86:87], v[162:163]
	global_store_dwordx4 v165, v[160:163], s[66:67] offset:64
	v_pk_mul_f32 v[40:41], v[160:161], v[188:189]
	v_pk_mul_f32 v[42:43], v[162:163], v[190:191]
	v_cvt_pk_bf16_f32 v40, v40, v41
	v_cvt_pk_bf16_f32 v41, v42, v43
	global_store_dwordx2 v173, v[40:41], s[8:9] offset:32
	v_fmac_f32_e32 v46, v160, v160
	v_fmac_f32_e32 v46, v161, v161
	v_fmac_f32_e32 v46, v162, v162
	v_fmac_f32_e32 v46, v163, v163
	global_load_dwordx4 v[160:163], v164, s[98:99] offset:64 nt
	s_waitcnt vmcnt(21)
	v_pk_fma_f32 v[174:175], v[36:37], v[92:93], v[174:175]
	v_pk_fma_f32 v[176:177], v[38:39], v[94:95], v[176:177]
	global_store_dwordx4 v165, v[174:177], s[66:67] offset:512
	v_pk_mul_f32 v[36:37], v[174:175], v[192:193]
	v_pk_mul_f32 v[38:39], v[176:177], v[194:195]
	v_cvt_pk_bf16_f32 v36, v36, v37
	v_cvt_pk_bf16_f32 v37, v38, v39
	global_store_dwordx2 v173, v[36:37], s[8:9] offset:256
	v_fmac_f32_e32 v46, v174, v174
	v_fmac_f32_e32 v46, v175, v175
	v_fmac_f32_e32 v46, v176, v176
	v_fmac_f32_e32 v46, v177, v177
	global_load_dwordx4 v[174:177], v164, s[98:99] offset:512 nt
	s_waitcnt vmcnt(21)
; __device__ __forceinline__ unsigned cvt_pk_bf16(float lo, float hi) { unsigned r; asm volatile("v_cvt_pk_bf16_f32 %0, %1, %2" : "=v"(r) : "v"(lo), "v"(hi)); return r; }
;     __device__ __forceinline__ void operator()(const f32x4 (&acc)[2][2][4][2], const Unit& u, int wr, int wc, int fr, int fq) const {
;     ...
;             for (int m = 0; m < 4; ++m) { const int row = row0 + ai * HALF + m * 16; const size_t off = (size_t)row * 2048 + col0; float ss = 0.f;
; #pragma unroll
;                 for (int bj = 0; bj < 2; ++bj)
; #pragma unroll
;                     for (int n = 0; n < 2; ++n) { const f32x4 bs = __builtin_nontemporal_load((const f32x4*)(base + off + bj * HALF + n * 16)); const f32x4 x1 = bs + gv[bj][n] * acc[ai][bj][m][n];
;                         *(f32x4*)(out + off + bj * HALF + n * 16) = x1; ss += (x1.x * x1.x + x1.y * x1.y) + (x1.z * x1.z + x1.w * x1.w);
;                         const f32x4 hh = x1 * Gv[bj][n]; u32x2 w; w.x = cvt_pk_bf16(hh.x, hh.y); w.y = cvt_pk_bf16(hh.z, hh.w); *(u32x2*)(A2 + off + bj * HALF + n * 16) = w; }
;                 ss += __shfl_xor(ss, 16); ss += __shfl_xor(ss, 32);
;                 if (fq == 0) prow[row] = ss; }
; template <class Epi, class Sched, bool ALIGN_EPI = false, bool SP2 = false>
; __device__ __forceinline__ void gemm_phase(PG8_LAS unsigned char* lds, const Gemm g, const Sched& S, const Epi& E) {
;     ...
;         if constexpr (!Epi::AFTER_DRAIN) { E(acc, cur, wr, wc, fr, fq); S.done(cur); }
;         if (!has_next) break;
	v_pk_fma_f32 v[178:179], v[32:33], v[96:97], v[178:179]
	v_pk_fma_f32 v[180:181], v[34:35], v[98:99], v[180:181]
	global_store_dwordx4 v165, v[178:181], s[66:67] offset:576
	v_pk_mul_f32 v[32:33], v[178:179], v[196:197]
	v_pk_mul_f32 v[34:35], v[180:181], v[198:199]
	v_cvt_pk_bf16_f32 v32, v32, v33
	v_cvt_pk_bf16_f32 v33, v34, v35
	global_store_dwordx2 v173, v[32:33], s[8:9] offset:288
	v_fmac_f32_e32 v46, v178, v178
	v_fmac_f32_e32 v46, v179, v179
	v_fmac_f32_e32 v46, v180, v180
	v_fmac_f32_e32 v46, v181, v181
	v_add_u32_e32 v165, 0x20000, v165
	v_lshrrev_b32_e32 v173, 1, v165
	global_load_dwordx4 v[178:181], v164, s[98:99] offset:576 nt
	s_waitcnt vmcnt(21)
	v_pk_fma_f32 v[200:201], v[28:29], v[72:73], v[200:201]
	v_pk_fma_f32 v[202:203], v[30:31], v[74:75], v[202:203]
	global_store_dwordx4 v165, v[200:203], s[66:67]
	v_pk_mul_f32 v[28:29], v[200:201], v[182:183]
	v_pk_mul_f32 v[30:31], v[202:203], v[184:185]
	v_cvt_pk_bf16_f32 v28, v28, v29
	v_cvt_pk_bf16_f32 v29, v30, v31
	global_store_dwordx2 v173, v[28:29], s[8:9]
	v_mul_f32_e32 v30, v200, v200
	v_fmac_f32_e32 v30, v201, v201
	v_fmac_f32_e32 v30, v202, v202
	v_fmac_f32_e32 v30, v203, v203
	s_waitcnt vmcnt(20)
	v_pk_fma_f32 v[204:205], v[24:25], v[84:85], v[204:205]
	v_pk_fma_f32 v[206:207], v[26:27], v[86:87], v[206:207]
	global_store_dwordx4 v165, v[204:207], s[66:67] offset:64
	v_pk_mul_f32 v[24:25], v[204:205], v[188:189]
	v_pk_mul_f32 v[26:27], v[206:207], v[190:191]
	v_cvt_pk_bf16_f32 v24, v24, v25
	v_cvt_pk_bf16_f32 v25, v26, v27
	global_store_dwordx2 v173, v[24:25], s[8:9] offset:32
	v_fmac_f32_e32 v30, v204, v204
	v_fmac_f32_e32 v30, v205, v205
	v_fmac_f32_e32 v30, v206, v206
	v_fmac_f32_e32 v30, v207, v207
	s_waitcnt vmcnt(19)
	v_pk_fma_f32 v[208:209], v[20:21], v[92:93], v[208:209]
	v_pk_fma_f32 v[210:211], v[22:23], v[94:95], v[210:211]
	global_store_dwordx4 v165, v[208:211], s[66:67] offset:512
	v_pk_mul_f32 v[20:21], v[208:209], v[192:193]
	v_pk_mul_f32 v[22:23], v[210:211], v[194:195]
	v_cvt_pk_bf16_f32 v20, v20, v21
	v_cvt_pk_bf16_f32 v21, v22, v23
	global_store_dwordx2 v173, v[20:21], s[8:9] offset:256
	v_fmac_f32_e32 v30, v208, v208
	v_fmac_f32_e32 v30, v209, v209
	v_fmac_f32_e32 v30, v210, v210
	v_fmac_f32_e32 v30, v211, v211
	s_waitcnt vmcnt(18)
	v_pk_fma_f32 v[212:213], v[16:17], v[96:97], v[212:213]
	v_pk_fma_f32 v[214:215], v[18:19], v[98:99], v[214:215]
	global_store_dwordx4 v165, v[212:215], s[66:67] offset:576
	v_pk_mul_f32 v[16:17], v[212:213], v[196:197]
	v_pk_mul_f32 v[18:19], v[214:215], v[198:199]
	v_cvt_pk_bf16_f32 v16, v16, v17
	v_cvt_pk_bf16_f32 v17, v18, v19
	global_store_dwordx2 v173, v[16:17], s[8:9] offset:288
	v_fmac_f32_e32 v30, v212, v212
	v_fmac_f32_e32 v30, v213, v213
	v_fmac_f32_e32 v30, v214, v214
	v_fmac_f32_e32 v30, v215, v215
	v_add_u32_e32 v165, 0x20000, v165
	v_lshrrev_b32_e32 v173, 1, v165
	s_waitcnt vmcnt(17)
	v_pk_fma_f32 v[156:157], v[12:13], v[72:73], v[156:157]
	v_pk_fma_f32 v[158:159], v[14:15], v[74:75], v[158:159]
	global_store_dwordx4 v165, v[156:159], s[66:67]
	v_pk_mul_f32 v[12:13], v[156:157], v[182:183]
	v_pk_mul_f32 v[14:15], v[158:159], v[184:185]
	v_cvt_pk_bf16_f32 v12, v12, v13
	v_cvt_pk_bf16_f32 v13, v14, v15
	global_store_dwordx2 v173, v[12:13], s[8:9]
	v_mul_f32_e32 v14, v156, v156
	v_fmac_f32_e32 v14, v157, v157
	v_fmac_f32_e32 v14, v158, v158
	v_fmac_f32_e32 v14, v159, v159
	s_waitcnt vmcnt(16)
	v_pk_fma_f32 v[160:161], v[8:9], v[84:85], v[160:161]
	v_pk_fma_f32 v[162:163], v[10:11], v[86:87], v[162:163]
	global_store_dwordx4 v165, v[160:163], s[66:67] offset:64
	v_pk_mul_f32 v[8:9], v[160:161], v[188:189]
	v_pk_mul_f32 v[10:11], v[162:163], v[190:191]
	v_cvt_pk_bf16_f32 v8, v8, v9
	v_cvt_pk_bf16_f32 v9, v10, v11
	global_store_dwordx2 v173, v[8:9], s[8:9] offset:32
	v_fmac_f32_e32 v14, v160, v160
	v_fmac_f32_e32 v14, v161, v161
	v_fmac_f32_e32 v14, v162, v162
	v_fmac_f32_e32 v14, v163, v163
	s_waitcnt vmcnt(15)
	v_pk_fma_f32 v[174:175], v[4:5], v[92:93], v[174:175]
	v_pk_fma_f32 v[176:177], v[6:7], v[94:95], v[176:177]
	global_store_dwordx4 v165, v[174:177], s[66:67] offset:512
	v_pk_mul_f32 v[4:5], v[174:175], v[192:193]
	v_pk_mul_f32 v[6:7], v[176:177], v[194:195]
	v_cvt_pk_bf16_f32 v4, v4, v5
	v_cvt_pk_bf16_f32 v5, v6, v7
	global_store_dwordx2 v173, v[4:5], s[8:9] offset:256
	v_fmac_f32_e32 v14, v174, v174
	v_fmac_f32_e32 v14, v175, v175
	v_fmac_f32_e32 v14, v176, v176
	v_fmac_f32_e32 v14, v177, v177
	s_waitcnt vmcnt(14)
	v_pk_fma_f32 v[178:179], v[0:1], v[96:97], v[178:179]
	v_pk_fma_f32 v[180:181], v[2:3], v[98:99], v[180:181]
	global_store_dwordx4 v165, v[178:181], s[66:67] offset:576
	v_pk_mul_f32 v[0:1], v[178:179], v[196:197]
	v_pk_mul_f32 v[2:3], v[180:181], v[198:199]
	v_cvt_pk_bf16_f32 v0, v0, v1
	v_cvt_pk_bf16_f32 v1, v2, v3
	global_store_dwordx2 v173, v[0:1], s[8:9] offset:288
	v_fmac_f32_e32 v14, v178, v178
	v_fmac_f32_e32 v14, v179, v179
	v_fmac_f32_e32 v14, v180, v180
	v_fmac_f32_e32 v14, v181, v181
	ds_bpermute_b32 v143, v216, v142
	ds_bpermute_b32 v127, v216, v126
	ds_bpermute_b32 v111, v216, v110
	ds_bpermute_b32 v83, v216, v82
	ds_bpermute_b32 v63, v216, v62
	ds_bpermute_b32 v47, v216, v46
	ds_bpermute_b32 v31, v216, v30
	ds_bpermute_b32 v15, v216, v14
	s_waitcnt lgkmcnt(0)
	v_add_f32_e32 v142, v142, v143
	v_add_f32_e32 v126, v126, v127
	v_add_f32_e32 v110, v110, v111
	v_add_f32_e32 v82, v82, v83
	v_add_f32_e32 v62, v62, v63
	v_add_f32_e32 v46, v46, v47
	v_add_f32_e32 v30, v30, v31
	v_add_f32_e32 v14, v14, v15
	ds_bpermute_b32 v143, v217, v142
	ds_bpermute_b32 v127, v217, v126
	ds_bpermute_b32 v111, v217, v110
	ds_bpermute_b32 v83, v217, v82
	ds_bpermute_b32 v63, v217, v62
	ds_bpermute_b32 v47, v217, v46
	ds_bpermute_b32 v31, v217, v30
	ds_bpermute_b32 v15, v217, v14
	s_lshl_b32 s25, s34, 2
	s_or_b32 s25, s25, s47
	s_lshl_b32 s25, s25, 16
	v_lshl_add_u32 v164, s36, 8, v166
	v_lshl_add_u32 v164, v164, 2, s25
	s_waitcnt lgkmcnt(0)
	v_add_f32_e32 v142, v142, v143
	v_add_f32_e32 v126, v126, v127
	v_add_f32_e32 v110, v110, v111
	v_add_f32_e32 v82, v82, v83
	v_add_f32_e32 v62, v62, v63
	v_add_f32_e32 v46, v46, v47
	v_add_f32_e32 v30, v30, v31
	v_add_f32_e32 v14, v14, v15
	s_and_saveexec_b64 s[100:101], s[4:5]
	global_store_dword v164, v142, s[48:49]
	global_store_dword v164, v126, s[48:49] offset:64
	global_store_dword v164, v110, s[48:49] offset:128
	global_store_dword v164, v82, s[48:49] offset:192
	global_store_dword v164, v62, s[48:49] offset:512
	global_store_dword v164, v46, s[48:49] offset:576
	global_store_dword v164, v30, s[48:49] offset:640
	global_store_dword v164, v14, s[48:49] offset:704
	s_or_b64 exec, exec, s[100:101]
	s_andn2_b64 vcc, exec, s[6:7]
	s_mov_b64 s[6:7], -1
	s_mov_b32 s99, 1
	s_cbranch_vccnz .LBB0_886
	s_andn2_b64 vcc, exec, s[10:11]
	s_cbranch_vccnz .LBB0_885
	s_barrier
	s_branch .LBB0_885

;     __device__ __forceinline__ bool next(int i, Unit& u) const { if (!base.next(i >> 1, u)) return false; if (i & 1) { u.pm += 64; u.pn += 8; } return true; }
; #define PG8_STAGE(bufoff, gbase, voff) do { _Pragma("unroll") for (int _i = 0; _i < 2; ++_i) \
;         __builtin_amdgcn_global_load_lds((const unsigned*)((const char*)(gbase) + (voff)[_i]), (PG8_LAS unsigned*)(lds + (bufoff) + ldsw + _i * 8192), 16, 0, 0); } while (0)
; #define PG8_WAIT_V(n) asm volatile("s_waitcnt vmcnt(" #n ")" ::: "memory")
; #define PG8_BAR __builtin_amdgcn_s_barrier()
; template <class Epi, class Sched, bool ALIGN_EPI = false, bool SP2 = false>
; __device__ __forceinline__ void gemm_phase(PG8_LAS unsigned char* lds, const Gemm g, const Sched& S, const Epi& E) {
;     ...
;     for (int i = 0; i < 2; ++i) { int R, C; stage_rc(tid * 16 + i * 8192, R, C); const int Rb = Epi::PERM ? ((R & ~31) + perm32(R & 31)) : R;
;         voffA[i] = (unsigned)(R * K + C) * 2u; voffB[i] = (unsigned)(Rb * K + C) * 2u; }
;     const size_t kstep = (size_t)(BK * 2);
;     const size_t hstep = (size_t)HALF * K * 2;
;     const size_t tstep = 2 * hstep;
;     const unsigned ldsw = (unsigned)wid * 1024u;
;     const int aoff = lds_byte(wr * 64 + fr, fq * 8), boff = lds_byte(wc * 32 + fr, fq * 8);
;     ...
;     Unit cur, nxt; int ui = 0;
;     if (!S.next(0, cur)) return;
;     f32x4 acc[2][2][4][2];
; #pragma unroll
;     for (int a = 0; a < 2; ++a)
; #pragma unroll
;         for (int b = 0; b < 2; ++b)
; #pragma unroll
;             for (int m = 0; m < 4; ++m)
; #pragma unroll
;                 for (int n = 0; n < 2; ++n) acc[a][b][m][n] = (f32x4){0.f, 0.f, 0.f, 0.f};
;     bf16x8 At[4][2], B0[2][2], B1[2][2];
;     const char* cA = (const char*)g.A + (size_t)cur.pm * tstep; const char* cB = (const char*)g.Bt + (size_t)cur.pn * tstep;
;     S.a_ready(cur);
;     if constexpr (SP2) {
;         PG8_STAGE(PG8_SB(0, 0), cB, voffB); PG8_STAGE(PG8_SB(0, 1), cB + hstep, voffB); PG8_STAGE(PG8_SA(0, 0), cA, voffA); PG8_STAGE(PG8_SA(0, 1), cA + hstep, voffA);
;         if (wr == 1) PG8_BAR;
;         PG8_WAIT_V(2); PG8_BAR;
;         PG8_STAGE(PG8_SB(1, 0), cB + kstep, voffB); PG8_STAGE(PG8_SA(1, 0), cA + kstep, voffA); PG8_STAGE(PG8_SB(1, 1), cB + hstep + kstep, voffB);
;         PG8_WAIT_V(6); PG8_BAR;
.LBB0_984:
	s_mov_b32 s99, 0
	s_lshl_b32 s10, s10, 5
	s_and_b32 s15, s10, 0x60
	s_lshl_b32 s14, s5, 13
	s_lshl_b32 s16, s15, 7
	s_add_u32 s36, s68, 0x40000
	s_mov_b64 s[10:11], 0x80
	s_addc_u32 s37, s69, 0
	s_add_i32 m0, s23, 0x18000
	v_lshl_add_u64 v[6:7], v[6:7], 0, s[10:11]
	s_waitcnt vmcnt(2)
	s_barrier
	global_load_lds_dwordx4 v[6:7], off
	v_lshl_add_u64 v[4:5], v[4:5], 0, s[10:11]
	s_add_i32 m0, s23, 0x1a000
	s_add_i32 s38, s23, 0x8000
	s_add_i32 s39, s23, 0xa000
	global_load_lds_dwordx4 v[4:5], off
	v_lshl_add_u64 v[0:1], v[0:1], 0, s[10:11]
	s_mov_b32 m0, s38
	s_add_u32 s12, s26, 0x80080
	global_load_lds_dwordx4 v[0:1], off
	v_lshl_add_u64 v[0:1], v[2:3], 0, s[10:11]
	s_mov_b32 m0, s39
	s_addc_u32 s13, s27, 0
	global_load_lds_dwordx4 v[0:1], off
	s_add_i32 m0, s23, 0x1c000
	v_lshl_add_u64 v[0:1], s[12:13], 0, v[146:147]
	global_load_lds_dwordx4 v[0:1], off
	v_lshl_add_u64 v[0:1], s[12:13], 0, v[150:151]
	s_add_i32 m0, s23, 0x1e000
	v_lshlrev_b32_e32 v4, 2, v8
	global_load_lds_dwordx4 v[0:1], off
	v_lshrrev_b32_e32 v1, 1, v8
	v_and_b32_e32 v0, 15, v8
	v_and_b32_e32 v1, 24, v1
	v_lshl_or_b32 v162, s5, 6, v0
	v_lshlrev_b32_e32 v2, 1, v1
	v_lshl_or_b32 v0, v0, 6, v2
	v_lshlrev_b32_e32 v2, 2, v162
	v_and_b32_e32 v3, 32, v2
	v_and_b32_e32 v4, 32, v4
	v_bitop3_b32 v3, v0, s14, v3 bitop3:0xde
	v_bitop3_b32 v163, v0, s16, v4 bitop3:0xde
	v_lshlrev_b32_e32 v0, 15, v9
	v_and_b32_e32 v0, 0xffff0000, v0
	v_or_b32_e32 v171, s15, v1
	v_lshl_add_u32 v0, v10, 12, v0
	v_and_b32_e32 v1, 1, v9
	v_lshl_or_b32 v0, v1, 6, v0
	v_lshl_add_u32 v152, v11, 1, v0
	v_lshlrev_b32_e32 v0, 15, v12
	v_and_b32_e32 v0, 0xffff0000, v0
	s_waitcnt vmcnt(6)
	s_cmpk_lt_u32 s4, 0x100
	v_lshl_add_u32 v0, v13, 12, v0
	v_and_b32_e32 v1, 1, v12
	s_sext_i32_i8 s42, s2
	s_cselect_b64 s[12:13], -1, 0
	s_add_i32 s2, 0, 0x20400
	v_lshl_or_b32 v0, v1, 6, v0
	s_add_i32 s40, 0, 0x10000
	s_add_i32 s41, 0, 0x14000
	v_or_b32_e32 v164, 16, v162
	v_or_b32_e32 v165, 32, v162
	v_or_b32_e32 v166, 48, v162
	v_add_u32_e32 v167, 0x80, v162
	v_add_u32_e32 v168, 0x90, v162
	v_add_u32_e32 v169, 0xa0, v162
	v_add_u32_e32 v170, 0xb0, v162
	v_add_u32_e32 v172, s2, v2
	v_mov_b32_e32 v153, v147
	v_lshl_add_u32 v154, v14, 1, v0
	v_mov_b32_e32 v155, v147
	v_mov_b64_e32 v[156:157], 0x800
	v_mov_b64_e32 v[158:159], 0x7ff
	v_add_u32_e32 v173, s40, v163
	v_add_u32_e32 v174, s41, v163
	v_add_u32_e32 v175, 0, v3
	s_mov_b32 s2, s3
	s_barrier
	s_branch .LBB0_987

; #define PG8_STAGE(bufoff, gbase, voff) do { _Pragma("unroll") for (int _i = 0; _i < 2; ++_i) \
;         __builtin_amdgcn_global_load_lds((const unsigned*)((const char*)(gbase) + (voff)[_i]), (PG8_LAS unsigned*)(lds + (bufoff) + ldsw + _i * 8192), 16, 0, 0); } while (0)
; #define PG8_LDA(dst, b, h) do { _Pragma("unroll") for (int m = 0; m < 4; ++m) _Pragma("unroll") for (int k = 0; k < 2; ++k) dst[m][k] = *(const PG8_LAS bf16x8*)(lds + PG8_SA(b, h) + aoff + m * 2048 + k * 1024); } while (0)
; #define PG8_LDB(dst, b, h) do { _Pragma("unroll") for (int n = 0; n < 2; ++n) _Pragma("unroll") for (int k = 0; k < 2; ++k) dst[n][k] = *(const PG8_LAS bf16x8*)(lds + PG8_SB(b, h) + boff + n * 2048 + k * 1024); } while (0)
; #define PG8_WAIT_V(n) asm volatile("s_waitcnt vmcnt(" #n ")" ::: "memory")
; #define PG8_WAIT_L(n) asm volatile("s_waitcnt lgkmcnt(" #n ")" ::: "memory")
; #define PG8_BAR __builtin_amdgcn_s_barrier()
; #define PG8_SCHED __builtin_amdgcn_sched_barrier(0)
; template <class Epi, class Sched, bool ALIGN_EPI = false, bool SP2 = false>
; __device__ __forceinline__ void gemm_phase(PG8_LAS unsigned char* lds, const Gemm g, const Sched& S, const Epi& E) {
;     ...
;         const char* nA = has_next ? (const char*)g.A + (size_t)nxt.pm * tstep : cA; const char* nB = has_next ? (const char*)g.Bt + (size_t)nxt.pn * tstep : cB;
;         for (int t = 0; t < nt; t += 2) {
;             const bool last = (t == nt - 2);
;             const char* a1 = cA + (size_t)(t + 1) * kstep;
;             const char* a2 = last ? nA : cA + (size_t)(t + 2) * kstep; const char* b2 = last ? nB : cB + (size_t)(t + 2) * kstep;
;             const char* a3 = a2 + kstep; const char* b3 = b2 + kstep;
;             if (last && has_next) S.a_ready(nxt);
;             if constexpr (SP2) {
;             PG8_LDB(B0, 0, 0); PG8_LDB(B1, 0, 1); PG8_SCHED; PG8_LDA(At, 0, 0); PG8_STAGE(PG8_SA(1, 1), a1 + hstep, voffA);
;             PG8_WAIT_V(8); PG8_WAIT_L(0); PG8_BAR; PG8_MMA(0, 0, At, B0); PG8_MMA(0, 1, At, B1); PG8_BAR; PG8_SCHED;
;     ...
;         for (int a = 0; a < 2; ++a)
; #pragma unroll
;             for (int b = 0; b < 2; ++b)
; #pragma unroll
;                 for (int m = 0; m < 4; ++m)
; #pragma unroll
;                     for (int n = 0; n < 2; ++n) acc[a][b][m][n] = (f32x4){0.f, 0.f, 0.f, 0.f};
;         cur = nxt; cA = nA; cB = nB; ++ui;
.LBB0_993:
	s_ashr_i32 s15, s14, 31
	s_lshl_b64 s[18:19], s[14:15], 20
	s_add_u32 s18, s8, s18
	s_addc_u32 s19, s9, s19
	s_and_b64 s[20:21], s[4:5], exec
	s_cselect_b32 s15, s19, s25
	s_cselect_b32 s43, s18, s24
	s_ashr_i32 s17, s16, 31
	s_lshl_b64 s[20:21], s[16:17], 20
	v_readlane_b32 s28, v236, 52
	v_readlane_b32 s29, v236, 53
	s_add_u32 s20, s28, s20
	s_addc_u32 s21, s29, s21
	s_and_b64 s[28:29], s[4:5], exec
	s_cselect_b32 s17, s21, s27
	s_cselect_b32 s44, s20, s26
	s_add_u32 s24, s24, 0x80080
	s_addc_u32 s25, s25, 0
	s_add_u32 s45, s26, 0x100
	v_mov_b32_e32 v0, 0
	s_addc_u32 s46, s27, 0
	s_mov_b32 s47, -2
	v_mov_b32_e32 v1, v0
	v_mov_b32_e32 v2, v0
	v_mov_b32_e32 v3, v0
	v_mov_b32_e32 v4, v0
	v_mov_b32_e32 v5, v0
	v_mov_b32_e32 v6, v0
	v_mov_b32_e32 v7, v0
	v_mov_b32_e32 v16, v0
	v_mov_b32_e32 v17, v0
	v_mov_b32_e32 v18, v0
	v_mov_b32_e32 v19, v0
	v_mov_b32_e32 v20, v0
	v_mov_b32_e32 v21, v0
	v_mov_b32_e32 v22, v0
	v_mov_b32_e32 v23, v0
	v_mov_b32_e32 v32, v0
	v_mov_b32_e32 v33, v0
	v_mov_b32_e32 v34, v0
	v_mov_b32_e32 v35, v0
	v_mov_b32_e32 v36, v0
	v_mov_b32_e32 v37, v0
	v_mov_b32_e32 v38, v0
	v_mov_b32_e32 v39, v0
	v_mov_b32_e32 v48, v0
	v_mov_b32_e32 v49, v0
	v_mov_b32_e32 v50, v0
	v_mov_b32_e32 v51, v0
	v_mov_b32_e32 v52, v0
	v_mov_b32_e32 v53, v0
	v_mov_b32_e32 v54, v0
	v_mov_b32_e32 v55, v0
	v_mov_b32_e32 v8, v0
	v_mov_b32_e32 v9, v0
	v_mov_b32_e32 v10, v0
	v_mov_b32_e32 v11, v0
	v_mov_b32_e32 v12, v0
	v_mov_b32_e32 v13, v0
	v_mov_b32_e32 v14, v0
	v_mov_b32_e32 v15, v0
	v_mov_b32_e32 v24, v0
	v_mov_b32_e32 v25, v0
	v_mov_b32_e32 v26, v0
	v_mov_b32_e32 v27, v0
	v_mov_b32_e32 v28, v0
	v_mov_b32_e32 v29, v0
	v_mov_b32_e32 v30, v0
	v_mov_b32_e32 v31, v0
	v_mov_b32_e32 v40, v0
	v_mov_b32_e32 v41, v0
	v_mov_b32_e32 v42, v0
	v_mov_b32_e32 v43, v0
	v_mov_b32_e32 v44, v0
	v_mov_b32_e32 v45, v0
	v_mov_b32_e32 v46, v0
	v_mov_b32_e32 v47, v0
	v_mov_b32_e32 v56, v0
	v_mov_b32_e32 v57, v0
	v_mov_b32_e32 v58, v0
	v_mov_b32_e32 v59, v0
	v_mov_b32_e32 v60, v0
	v_mov_b32_e32 v61, v0
	v_mov_b32_e32 v62, v0
	v_mov_b32_e32 v63, v0
	v_mov_b32_e32 v64, v0
	v_mov_b32_e32 v65, v0
	v_mov_b32_e32 v66, v0
	v_mov_b32_e32 v67, v0
	v_mov_b32_e32 v68, v0
	v_mov_b32_e32 v69, v0
	v_mov_b32_e32 v70, v0
	v_mov_b32_e32 v71, v0
	v_mov_b32_e32 v80, v0
	v_mov_b32_e32 v81, v0
	v_mov_b32_e32 v82, v0
	v_mov_b32_e32 v83, v0
	v_mov_b32_e32 v84, v0
	v_mov_b32_e32 v85, v0
	v_mov_b32_e32 v86, v0
	v_mov_b32_e32 v87, v0
	v_mov_b32_e32 v96, v0
	v_mov_b32_e32 v97, v0
	v_mov_b32_e32 v98, v0
	v_mov_b32_e32 v99, v0
	v_mov_b32_e32 v100, v0
	v_mov_b32_e32 v101, v0
	v_mov_b32_e32 v102, v0
	v_mov_b32_e32 v103, v0
	v_mov_b32_e32 v112, v0
	v_mov_b32_e32 v113, v0
	v_mov_b32_e32 v114, v0
	v_mov_b32_e32 v115, v0
	v_mov_b32_e32 v116, v0
	v_mov_b32_e32 v117, v0
	v_mov_b32_e32 v118, v0
	v_mov_b32_e32 v119, v0
	v_mov_b32_e32 v72, v0
	v_mov_b32_e32 v73, v0
	v_mov_b32_e32 v74, v0
	v_mov_b32_e32 v75, v0
	v_mov_b32_e32 v76, v0
	v_mov_b32_e32 v77, v0
	v_mov_b32_e32 v78, v0
	v_mov_b32_e32 v79, v0
	v_mov_b32_e32 v88, v0
	v_mov_b32_e32 v89, v0
	v_mov_b32_e32 v90, v0
	v_mov_b32_e32 v91, v0
	v_mov_b32_e32 v92, v0
	v_mov_b32_e32 v93, v0
	v_mov_b32_e32 v94, v0
	v_mov_b32_e32 v95, v0
	v_mov_b32_e32 v104, v0
	v_mov_b32_e32 v105, v0
	v_mov_b32_e32 v106, v0
	v_mov_b32_e32 v107, v0
	v_mov_b32_e32 v108, v0
	v_mov_b32_e32 v109, v0
	v_mov_b32_e32 v110, v0
	v_mov_b32_e32 v111, v0
	v_mov_b32_e32 v120, v0
	v_mov_b32_e32 v121, v0
	v_mov_b32_e32 v122, v0
	v_mov_b32_e32 v123, v0
	v_mov_b32_e32 v124, v0
	v_mov_b32_e32 v125, v0
	v_mov_b32_e32 v126, v0
	v_mov_b32_e32 v127, v0
	s_cmp_eq_u32 s99, 0
	s_cbranch_scc1 .LBB0_994
	ds_read_b128 v[128:131], v173
	ds_read_b128 v[132:135], v173 offset:1024
	ds_read_b128 v[136:139], v173 offset:2048
	ds_read_b128 v[140:143], v173 offset:3072
	ds_read_b128 v[176:179], v174
	ds_read_b128 v[180:183], v174 offset:1024
	ds_read_b128 v[188:191], v174 offset:2048
	ds_read_b128 v[192:195], v174 offset:3072
	s_add_u32 s26, s24, 0xfff80080
	s_addc_u32 s27, s25, -1
	s_cmp_eq_u32 s47, 28
	s_cselect_b32 s29, s15, s27
	s_cselect_b32 s28, s43, s26
	s_cselect_b32 s27, s17, s46
	s_cselect_b32 s26, s44, s45
	v_lshl_add_u64 v[160:161], s[24:25], 0, v[152:153]
	s_add_i32 m0, s23, 0xc000
	ds_read_b128 v[196:199], v175
	ds_read_b128 v[200:203], v175 offset:1024
	ds_read_b128 v[204:207], v175 offset:2048
	ds_read_b128 v[208:211], v175 offset:3072
	ds_read_b128 v[212:215], v175 offset:4096
	ds_read_b128 v[216:219], v175 offset:5120
	ds_read_b128 v[220:223], v175 offset:6144
	ds_read_b128 v[224:227], v175 offset:7168
	global_load_lds_dwordx4 v[160:161], off
	v_lshl_add_u64 v[160:161], s[24:25], 0, v[154:155]
	s_add_i32 m0, s23, 0xe000
	s_nop 0
	global_load_lds_dwordx4 v[160:161], off
	s_waitcnt vmcnt(24)
	s_waitcnt lgkmcnt(0)
	s_barrier
; #define PG8_STAGE(bufoff, gbase, voff) do { _Pragma("unroll") for (int _i = 0; _i < 2; ++_i) \
;         __builtin_amdgcn_global_load_lds((const unsigned*)((const char*)(gbase) + (voff)[_i]), (PG8_LAS unsigned*)(lds + (bufoff) + ldsw + _i * 8192), 16, 0, 0); } while (0)
; #define PG8_LDA(dst, b, h) do { _Pragma("unroll") for (int m = 0; m < 4; ++m) _Pragma("unroll") for (int k = 0; k < 2; ++k) dst[m][k] = *(const PG8_LAS bf16x8*)(lds + PG8_SA(b, h) + aoff + m * 2048 + k * 1024); } while (0)
; #define PG8_LDB(dst, b, h) do { _Pragma("unroll") for (int n = 0; n < 2; ++n) _Pragma("unroll") for (int k = 0; k < 2; ++k) dst[n][k] = *(const PG8_LAS bf16x8*)(lds + PG8_SB(b, h) + boff + n * 2048 + k * 1024); } while (0)
; #define PG8_MMA(ai, bj, At, Bt) do { __builtin_amdgcn_s_setprio(1); _Pragma("unroll") for (int m = 0; m < 4; ++m) _Pragma("unroll") for (int n = 0; n < 2; ++n) _Pragma("unroll") for (int k = 0; k < 2; ++k) \
;         acc[ai][bj][m][n] = __builtin_amdgcn_mfma_f32_16x16x32_bf16(Bt[n][k], At[m][k], acc[ai][bj][m][n], 0, 0, 0); __builtin_amdgcn_s_setprio(0); } while (0)
; #define PG8_WAIT_V(n) asm volatile("s_waitcnt vmcnt(" #n ")" ::: "memory")
; #define PG8_WAIT_L(n) asm volatile("s_waitcnt lgkmcnt(" #n ")" ::: "memory")
; #define PG8_BAR __builtin_amdgcn_s_barrier()
; #define PG8_SCHED __builtin_amdgcn_sched_barrier(0)
; template <class Epi, class Sched, bool ALIGN_EPI = false, bool SP2 = false>
; __device__ __forceinline__ void gemm_phase(PG8_LAS unsigned char* lds, const Gemm g, const Sched& S, const Epi& E) {
;     ...
;             PG8_LDB(B0, 0, 0); PG8_LDB(B1, 0, 1); PG8_SCHED; PG8_LDA(At, 0, 0); PG8_STAGE(PG8_SA(1, 1), a1 + hstep, voffA);
;             PG8_WAIT_V(8); PG8_WAIT_L(0); PG8_BAR; PG8_MMA(0, 0, At, B0); PG8_MMA(0, 1, At, B1); PG8_BAR; PG8_SCHED;
;             PG8_LDA(At, 0, 1); PG8_STAGE(PG8_SB(0, 0), b2, voffB); PG8_STAGE(PG8_SB(0, 1), b2 + hstep, voffB); PG8_STAGE(PG8_SA(0, 0), a2, voffA);
;             PG8_WAIT_V(8); PG8_WAIT_L(0); PG8_BAR; PG8_MMA(1, 0, At, B0); PG8_MMA(1, 1, At, B1); PG8_BAR; PG8_SCHED;
	s_setprio 1
	s_waitcnt lgkmcnt(0)
	v_mfma_f32_16x16x32_bf16 v[124:127], v[128:131], v[196:199], v[124:127]
	v_mfma_f32_16x16x32_bf16 v[120:123], v[136:139], v[196:199], v[120:123]
	v_mfma_f32_16x16x32_bf16 v[108:111], v[128:131], v[204:207], v[108:111]
	v_mfma_f32_16x16x32_bf16 v[104:107], v[136:139], v[204:207], v[104:107]
	v_mfma_f32_16x16x32_bf16 v[92:95], v[128:131], v[212:215], v[92:95]
	v_mfma_f32_16x16x32_bf16 v[88:91], v[136:139], v[212:215], v[88:91]
	v_mfma_f32_16x16x32_bf16 v[76:79], v[128:131], v[220:223], v[76:79]
	v_mfma_f32_16x16x32_bf16 v[72:75], v[136:139], v[220:223], v[72:75]
	v_mfma_f32_16x16x32_bf16 v[124:127], v[132:135], v[200:203], v[124:127]
	v_mfma_f32_16x16x32_bf16 v[120:123], v[140:143], v[200:203], v[120:123]
	v_mfma_f32_16x16x32_bf16 v[108:111], v[132:135], v[208:211], v[108:111]
	v_mfma_f32_16x16x32_bf16 v[104:107], v[140:143], v[208:211], v[104:107]
	v_mfma_f32_16x16x32_bf16 v[92:95], v[132:135], v[216:219], v[92:95]
	v_mfma_f32_16x16x32_bf16 v[88:91], v[140:143], v[216:219], v[88:91]
	v_mfma_f32_16x16x32_bf16 v[76:79], v[132:135], v[224:227], v[76:79]
	v_mfma_f32_16x16x32_bf16 v[72:75], v[140:143], v[224:227], v[72:75]
	s_setprio 0
	s_setprio 1
	v_mfma_f32_16x16x32_bf16 v[116:119], v[176:179], v[196:199], v[116:119]
	v_mfma_f32_16x16x32_bf16 v[112:115], v[188:191], v[196:199], v[112:115]
	v_mfma_f32_16x16x32_bf16 v[100:103], v[176:179], v[204:207], v[100:103]
	v_mfma_f32_16x16x32_bf16 v[96:99], v[188:191], v[204:207], v[96:99]
	v_mfma_f32_16x16x32_bf16 v[84:87], v[176:179], v[212:215], v[84:87]
	v_mfma_f32_16x16x32_bf16 v[80:83], v[188:191], v[212:215], v[80:83]
	v_mfma_f32_16x16x32_bf16 v[68:71], v[176:179], v[220:223], v[68:71]
	v_mfma_f32_16x16x32_bf16 v[64:67], v[188:191], v[220:223], v[64:67]
	v_mfma_f32_16x16x32_bf16 v[116:119], v[180:183], v[200:203], v[116:119]
	v_mfma_f32_16x16x32_bf16 v[112:115], v[192:195], v[200:203], v[112:115]
	v_mfma_f32_16x16x32_bf16 v[100:103], v[180:183], v[208:211], v[100:103]
	v_mfma_f32_16x16x32_bf16 v[96:99], v[192:195], v[208:211], v[96:99]
	v_mfma_f32_16x16x32_bf16 v[84:87], v[180:183], v[216:219], v[84:87]
	v_mfma_f32_16x16x32_bf16 v[80:83], v[192:195], v[216:219], v[80:83]
	v_mfma_f32_16x16x32_bf16 v[68:71], v[180:183], v[224:227], v[68:71]
	v_mfma_f32_16x16x32_bf16 v[64:67], v[192:195], v[224:227], v[64:67]
	s_setprio 0
	s_barrier
	s_add_i32 s48, s40, s31
	v_lshl_add_u64 v[160:161], s[26:27], 0, v[146:147]
	s_mov_b32 m0, s48
	ds_read_b128 v[196:199], v175 offset:16384
	ds_read_b128 v[200:203], v175 offset:17408
	ds_read_b128 v[204:207], v175 offset:18432
	ds_read_b128 v[208:211], v175 offset:19456
	ds_read_b128 v[212:215], v175 offset:20480
	ds_read_b128 v[216:219], v175 offset:21504
	ds_read_b128 v[220:223], v175 offset:22528
	ds_read_b128 v[224:227], v175 offset:23552
	global_load_lds_dwordx4 v[160:161], off
	s_add_i32 m0, s48, 0x2000
	s_add_u32 s48, s26, 0x80000
	v_lshl_add_u64 v[184:185], s[26:27], 0, v[150:151]
	s_addc_u32 s49, s27, 0
	s_add_i32 s50, s41, s31
	global_load_lds_dwordx4 v[184:185], off
	v_lshl_add_u64 v[228:229], s[48:49], 0, v[146:147]
	s_mov_b32 m0, s50
	v_lshl_add_u64 v[230:231], s[28:29], 0, v[148:149]
	global_load_lds_dwordx4 v[228:229], off
	v_lshl_add_u64 v[228:229], s[48:49], 0, v[150:151]
	s_add_i32 m0, s50, 0x2000
	s_nop 0
	global_load_lds_dwordx4 v[228:229], off
	v_lshl_add_u64 v[228:229], s[28:29], 0, v[144:145]
	s_mov_b32 m0, s23
	s_nop 0
	global_load_lds_dwordx4 v[228:229], off
	s_mov_b32 m0, s33
	s_nop 0
	global_load_lds_dwordx4 v[230:231], off
	s_waitcnt vmcnt(24)
	s_waitcnt lgkmcnt(0)
	s_barrier
	s_setprio 1
	s_waitcnt lgkmcnt(0)
	v_mfma_f32_16x16x32_bf16 v[60:63], v[128:131], v[196:199], v[60:63]
	v_mfma_f32_16x16x32_bf16 v[56:59], v[136:139], v[196:199], v[56:59]
	v_mfma_f32_16x16x32_bf16 v[44:47], v[128:131], v[204:207], v[44:47]
	v_mfma_f32_16x16x32_bf16 v[40:43], v[136:139], v[204:207], v[40:43]
	v_mfma_f32_16x16x32_bf16 v[28:31], v[128:131], v[212:215], v[28:31]
	v_mfma_f32_16x16x32_bf16 v[24:27], v[136:139], v[212:215], v[24:27]
	v_mfma_f32_16x16x32_bf16 v[12:15], v[128:131], v[220:223], v[12:15]
	v_mfma_f32_16x16x32_bf16 v[8:11], v[136:139], v[220:223], v[8:11]
	v_mfma_f32_16x16x32_bf16 v[60:63], v[132:135], v[200:203], v[60:63]
	v_mfma_f32_16x16x32_bf16 v[56:59], v[140:143], v[200:203], v[56:59]
	v_mfma_f32_16x16x32_bf16 v[44:47], v[132:135], v[208:211], v[44:47]
	v_mfma_f32_16x16x32_bf16 v[40:43], v[140:143], v[208:211], v[40:43]
	v_mfma_f32_16x16x32_bf16 v[28:31], v[132:135], v[216:219], v[28:31]
	v_mfma_f32_16x16x32_bf16 v[24:27], v[140:143], v[216:219], v[24:27]
	v_mfma_f32_16x16x32_bf16 v[12:15], v[132:135], v[224:227], v[12:15]
	v_mfma_f32_16x16x32_bf16 v[8:11], v[140:143], v[224:227], v[8:11]
	s_setprio 0
	s_setprio 1
	v_mfma_f32_16x16x32_bf16 v[52:55], v[176:179], v[196:199], v[52:55]
	v_mfma_f32_16x16x32_bf16 v[48:51], v[188:191], v[196:199], v[48:51]
	v_mfma_f32_16x16x32_bf16 v[36:39], v[176:179], v[204:207], v[36:39]
	v_mfma_f32_16x16x32_bf16 v[32:35], v[188:191], v[204:207], v[32:35]
	v_mfma_f32_16x16x32_bf16 v[20:23], v[176:179], v[212:215], v[20:23]
	v_mfma_f32_16x16x32_bf16 v[16:19], v[188:191], v[212:215], v[16:19]
	v_mfma_f32_16x16x32_bf16 v[4:7], v[176:179], v[220:223], v[4:7]
	v_mfma_f32_16x16x32_bf16 v[0:3], v[188:191], v[220:223], v[0:3]
	v_mfma_f32_16x16x32_bf16 v[52:55], v[180:183], v[200:203], v[52:55]
	v_mfma_f32_16x16x32_bf16 v[48:51], v[192:195], v[200:203], v[48:51]
	v_mfma_f32_16x16x32_bf16 v[36:39], v[180:183], v[208:211], v[36:39]
	v_mfma_f32_16x16x32_bf16 v[32:35], v[192:195], v[208:211], v[32:35]
	v_mfma_f32_16x16x32_bf16 v[20:23], v[180:183], v[216:219], v[20:23]
	v_mfma_f32_16x16x32_bf16 v[16:19], v[192:195], v[216:219], v[16:19]
	v_mfma_f32_16x16x32_bf16 v[4:7], v[180:183], v[224:227], v[4:7]
	v_mfma_f32_16x16x32_bf16 v[0:3], v[192:195], v[224:227], v[0:3]
	s_setprio 0
	s_barrier
; #define PG8_STAGE(bufoff, gbase, voff) do { _Pragma("unroll") for (int _i = 0; _i < 2; ++_i) \
;         __builtin_amdgcn_global_load_lds((const unsigned*)((const char*)(gbase) + (voff)[_i]), (PG8_LAS unsigned*)(lds + (bufoff) + ldsw + _i * 8192), 16, 0, 0); } while (0)
; #define PG8_LDA(dst, b, h) do { _Pragma("unroll") for (int m = 0; m < 4; ++m) _Pragma("unroll") for (int k = 0; k < 2; ++k) dst[m][k] = *(const PG8_LAS bf16x8*)(lds + PG8_SA(b, h) + aoff + m * 2048 + k * 1024); } while (0)
; #define PG8_LDB(dst, b, h) do { _Pragma("unroll") for (int n = 0; n < 2; ++n) _Pragma("unroll") for (int k = 0; k < 2; ++k) dst[n][k] = *(const PG8_LAS bf16x8*)(lds + PG8_SB(b, h) + boff + n * 2048 + k * 1024); } while (0)
; #define PG8_MMA(ai, bj, At, Bt) do { __builtin_amdgcn_s_setprio(1); _Pragma("unroll") for (int m = 0; m < 4; ++m) _Pragma("unroll") for (int n = 0; n < 2; ++n) _Pragma("unroll") for (int k = 0; k < 2; ++k) \
;         acc[ai][bj][m][n] = __builtin_amdgcn_mfma_f32_16x16x32_bf16(Bt[n][k], At[m][k], acc[ai][bj][m][n], 0, 0, 0); __builtin_amdgcn_s_setprio(0); } while (0)
; #define PG8_WAIT_V(n) asm volatile("s_waitcnt vmcnt(" #n ")" ::: "memory")
; #define PG8_WAIT_L(n) asm volatile("s_waitcnt lgkmcnt(" #n ")" ::: "memory")
; #define PG8_BAR __builtin_amdgcn_s_barrier()
; #define PG8_SCHED __builtin_amdgcn_sched_barrier(0)
; template <class Epi, class Sched, bool ALIGN_EPI = false, bool SP2 = false>
; __device__ __forceinline__ void gemm_phase(PG8_LAS unsigned char* lds, const Gemm g, const Sched& S, const Epi& E) {
;     ...
;             PG8_LDB(B0, 1, 0); PG8_LDB(B1, 1, 1); PG8_SCHED; PG8_LDA(At, 1, 0); PG8_STAGE(PG8_SA(0, 1), a2 + hstep, voffA);
;             PG8_WAIT_V(8); PG8_WAIT_L(0); PG8_BAR; PG8_MMA(0, 0, At, B0); PG8_MMA(0, 1, At, B1); PG8_BAR; PG8_SCHED;
	s_add_i32 s48, 0, 0x18000
	s_add_i32 s49, 0, 0x1c000
	v_add_u32_e32 v140, s48, v163
	v_add_u32_e32 v187, s49, v163
	ds_read_b128 v[128:131], v140
	ds_read_b128 v[132:135], v140 offset:1024
	ds_read_b128 v[136:139], v140 offset:2048
	ds_read_b128 v[140:143], v140 offset:3072
	ds_read_b128 v[176:179], v187
	ds_read_b128 v[180:183], v187 offset:1024
	ds_read_b128 v[188:191], v187 offset:2048
	ds_read_b128 v[192:195], v187 offset:3072
	s_add_u32 s28, s28, 0x80000
	s_addc_u32 s29, s29, 0
	s_mov_b32 m0, s34
	v_lshl_add_u64 v[232:233], s[28:29], 0, v[144:145]
	ds_read_b128 v[196:199], v175 offset:32768
	ds_read_b128 v[200:203], v175 offset:33792
	ds_read_b128 v[204:207], v175 offset:34816
	ds_read_b128 v[208:211], v175 offset:35840
	ds_read_b128 v[212:215], v175 offset:36864
	ds_read_b128 v[216:219], v175 offset:37888
	ds_read_b128 v[220:223], v175 offset:38912
	ds_read_b128 v[224:227], v175 offset:39936
	global_load_lds_dwordx4 v[232:233], off
	v_lshl_add_u64 v[232:233], s[28:29], 0, v[148:149]
	s_mov_b32 m0, s35
	s_nop 0
	global_load_lds_dwordx4 v[232:233], off
	s_waitcnt vmcnt(8)
	s_waitcnt lgkmcnt(0)
	s_barrier
	s_setprio 1
	s_waitcnt lgkmcnt(0)
	v_mfma_f32_16x16x32_bf16 v[124:127], v[128:131], v[196:199], v[124:127]
	v_mfma_f32_16x16x32_bf16 v[120:123], v[136:139], v[196:199], v[120:123]
	v_mfma_f32_16x16x32_bf16 v[108:111], v[128:131], v[204:207], v[108:111]
	v_mfma_f32_16x16x32_bf16 v[104:107], v[136:139], v[204:207], v[104:107]
	v_mfma_f32_16x16x32_bf16 v[92:95], v[128:131], v[212:215], v[92:95]
	v_mfma_f32_16x16x32_bf16 v[88:91], v[136:139], v[212:215], v[88:91]
	v_mfma_f32_16x16x32_bf16 v[76:79], v[128:131], v[220:223], v[76:79]
	v_mfma_f32_16x16x32_bf16 v[72:75], v[136:139], v[220:223], v[72:75]
	v_mfma_f32_16x16x32_bf16 v[124:127], v[132:135], v[200:203], v[124:127]
	v_mfma_f32_16x16x32_bf16 v[120:123], v[140:143], v[200:203], v[120:123]
	v_mfma_f32_16x16x32_bf16 v[108:111], v[132:135], v[208:211], v[108:111]
	v_mfma_f32_16x16x32_bf16 v[104:107], v[140:143], v[208:211], v[104:107]
	v_mfma_f32_16x16x32_bf16 v[92:95], v[132:135], v[216:219], v[92:95]
	v_mfma_f32_16x16x32_bf16 v[88:91], v[140:143], v[216:219], v[88:91]
	v_mfma_f32_16x16x32_bf16 v[76:79], v[132:135], v[224:227], v[76:79]
	v_mfma_f32_16x16x32_bf16 v[72:75], v[140:143], v[224:227], v[72:75]
	s_setprio 0
	s_setprio 1
	v_mfma_f32_16x16x32_bf16 v[116:119], v[176:179], v[196:199], v[116:119]
	v_mfma_f32_16x16x32_bf16 v[112:115], v[188:191], v[196:199], v[112:115]
	v_mfma_f32_16x16x32_bf16 v[100:103], v[176:179], v[204:207], v[100:103]
	v_mfma_f32_16x16x32_bf16 v[96:99], v[188:191], v[204:207], v[96:99]
	v_mfma_f32_16x16x32_bf16 v[84:87], v[176:179], v[212:215], v[84:87]
	v_mfma_f32_16x16x32_bf16 v[80:83], v[188:191], v[212:215], v[80:83]
	v_mfma_f32_16x16x32_bf16 v[68:71], v[176:179], v[220:223], v[68:71]
	v_mfma_f32_16x16x32_bf16 v[64:67], v[188:191], v[220:223], v[64:67]
	v_mfma_f32_16x16x32_bf16 v[116:119], v[180:183], v[200:203], v[116:119]
	v_mfma_f32_16x16x32_bf16 v[112:115], v[192:195], v[200:203], v[112:115]
	v_mfma_f32_16x16x32_bf16 v[100:103], v[180:183], v[208:211], v[100:103]
	v_mfma_f32_16x16x32_bf16 v[96:99], v[192:195], v[208:211], v[96:99]
	v_mfma_f32_16x16x32_bf16 v[84:87], v[180:183], v[216:219], v[84:87]
	v_mfma_f32_16x16x32_bf16 v[80:83], v[192:195], v[216:219], v[80:83]
	v_mfma_f32_16x16x32_bf16 v[68:71], v[180:183], v[224:227], v[68:71]
	v_mfma_f32_16x16x32_bf16 v[64:67], v[192:195], v[224:227], v[64:67]
	s_setprio 0
	s_barrier
; #define PG8_STAGE(bufoff, gbase, voff) do { _Pragma("unroll") for (int _i = 0; _i < 2; ++_i) \
;         __builtin_amdgcn_global_load_lds((const unsigned*)((const char*)(gbase) + (voff)[_i]), (PG8_LAS unsigned*)(lds + (bufoff) + ldsw + _i * 8192), 16, 0, 0); } while (0)
; #define PG8_LDA(dst, b, h) do { _Pragma("unroll") for (int m = 0; m < 4; ++m) _Pragma("unroll") for (int k = 0; k < 2; ++k) dst[m][k] = *(const PG8_LAS bf16x8*)(lds + PG8_SA(b, h) + aoff + m * 2048 + k * 1024); } while (0)
; #define PG8_LDB(dst, b, h) do { _Pragma("unroll") for (int n = 0; n < 2; ++n) _Pragma("unroll") for (int k = 0; k < 2; ++k) dst[n][k] = *(const PG8_LAS bf16x8*)(lds + PG8_SB(b, h) + boff + n * 2048 + k * 1024); } while (0)
; template <class Epi, class Sched, bool ALIGN_EPI = false, bool SP2 = false>
; __device__ __forceinline__ void gemm_phase(PG8_LAS unsigned char* lds, const Gemm g, const Sched& S, const Epi& E) {
;     ...
;         for (int t = 0; t < nt; t += 2) {
;             const bool last = (t == nt - 2);
;             const char* a1 = cA + (size_t)(t + 1) * kstep;
;             const char* a2 = last ? nA : cA + (size_t)(t + 2) * kstep; const char* b2 = last ? nB : cB + (size_t)(t + 2) * kstep;
;             const char* a3 = a2 + kstep; const char* b3 = b2 + kstep;
;             if (last && has_next) S.a_ready(nxt);
;             if constexpr (SP2) {
;             PG8_LDB(B0, 0, 0); PG8_LDB(B1, 0, 1); PG8_SCHED; PG8_LDA(At, 0, 0); PG8_STAGE(PG8_SA(1, 1), a1 + hstep, voffA);
;             PG8_WAIT_V(8); PG8_WAIT_L(0); PG8_BAR; PG8_MMA(0, 0, At, B0); PG8_MMA(0, 1, At, B1); PG8_BAR; PG8_SCHED;
;             PG8_LDA(At, 0, 1); PG8_STAGE(PG8_SB(0, 0), b2, voffB); PG8_STAGE(PG8_SB(0, 1), b2 + hstep, voffB); PG8_STAGE(PG8_SA(0, 0), a2, voffA);
;             PG8_WAIT_V(8); PG8_WAIT_L(0); PG8_BAR; PG8_MMA(1, 0, At, B0); PG8_MMA(1, 1, At, B1); PG8_BAR; PG8_SCHED;
;             PG8_LDB(B0, 1, 0); PG8_LDB(B1, 1, 1); PG8_SCHED; PG8_LDA(At, 1, 0); PG8_STAGE(PG8_SA(0, 1), a2 + hstep, voffA);
;             PG8_WAIT_V(8); PG8_WAIT_L(0); PG8_BAR; PG8_MMA(0, 0, At, B0); PG8_MMA(0, 1, At, B1); PG8_BAR; PG8_SCHED;
;             PG8_LDA(At, 1, 1); PG8_STAGE(PG8_SB(1, 0), b3, voffB); PG8_STAGE(PG8_SB(1, 1), b3 + hstep, voffB); PG8_STAGE(PG8_SA(1, 0), a3, voffA);
;             PG8_WAIT_V(8); PG8_WAIT_L(0); PG8_BAR; PG8_MMA(1, 0, At, B0); PG8_MMA(1, 1, At, B1); PG8_BAR; PG8_SCHED;
	s_add_i32 s28, s48, s31
	v_lshl_add_u64 v[160:161], v[160:161], 0, s[10:11]
	s_mov_b32 m0, s28
	ds_read_b128 v[196:199], v175 offset:49152
	ds_read_b128 v[200:203], v175 offset:50176
	ds_read_b128 v[204:207], v175 offset:51200
	ds_read_b128 v[208:211], v175 offset:52224
	ds_read_b128 v[212:215], v175 offset:53248
	ds_read_b128 v[216:219], v175 offset:54272
	ds_read_b128 v[220:223], v175 offset:55296
	ds_read_b128 v[224:227], v175 offset:56320
	global_load_lds_dwordx4 v[160:161], off
	s_add_i32 m0, s28, 0x2000
	s_add_u32 s26, s26, 0x80080
	v_lshl_add_u64 v[160:161], v[184:185], 0, s[10:11]
	s_addc_u32 s27, s27, 0
	s_add_i32 s28, s49, s31
	global_load_lds_dwordx4 v[160:161], off
	v_lshl_add_u64 v[160:161], s[26:27], 0, v[146:147]
	s_mov_b32 m0, s28
	s_nop 0
	global_load_lds_dwordx4 v[160:161], off
	v_lshl_add_u64 v[160:161], s[26:27], 0, v[150:151]
	s_add_i32 m0, s28, 0x2000
	s_nop 0
	global_load_lds_dwordx4 v[160:161], off
	v_lshl_add_u64 v[160:161], v[228:229], 0, s[10:11]
	s_mov_b32 m0, s38
	s_nop 0
	global_load_lds_dwordx4 v[160:161], off
	v_lshl_add_u64 v[160:161], v[230:231], 0, s[10:11]
	s_mov_b32 m0, s39
	s_nop 0
	global_load_lds_dwordx4 v[160:161], off
	s_waitcnt vmcnt(8)
	s_waitcnt lgkmcnt(0)
	s_barrier
	s_setprio 1
	s_waitcnt lgkmcnt(0)
	v_mfma_f32_16x16x32_bf16 v[60:63], v[128:131], v[196:199], v[60:63]
	v_mfma_f32_16x16x32_bf16 v[56:59], v[136:139], v[196:199], v[56:59]
	v_mfma_f32_16x16x32_bf16 v[44:47], v[128:131], v[204:207], v[44:47]
	v_mfma_f32_16x16x32_bf16 v[40:43], v[136:139], v[204:207], v[40:43]
	v_mfma_f32_16x16x32_bf16 v[28:31], v[128:131], v[212:215], v[28:31]
	v_mfma_f32_16x16x32_bf16 v[24:27], v[136:139], v[212:215], v[24:27]
	v_mfma_f32_16x16x32_bf16 v[12:15], v[128:131], v[220:223], v[12:15]
	v_mfma_f32_16x16x32_bf16 v[8:11], v[136:139], v[220:223], v[8:11]
	v_mfma_f32_16x16x32_bf16 v[60:63], v[132:135], v[200:203], v[60:63]
	v_mfma_f32_16x16x32_bf16 v[56:59], v[140:143], v[200:203], v[56:59]
	v_mfma_f32_16x16x32_bf16 v[44:47], v[132:135], v[208:211], v[44:47]
	v_mfma_f32_16x16x32_bf16 v[40:43], v[140:143], v[208:211], v[40:43]
	v_mfma_f32_16x16x32_bf16 v[28:31], v[132:135], v[216:219], v[28:31]
	v_mfma_f32_16x16x32_bf16 v[24:27], v[140:143], v[216:219], v[24:27]
	v_mfma_f32_16x16x32_bf16 v[12:15], v[132:135], v[224:227], v[12:15]
	v_mfma_f32_16x16x32_bf16 v[8:11], v[140:143], v[224:227], v[8:11]
	s_setprio 0
	s_setprio 1
	v_mfma_f32_16x16x32_bf16 v[52:55], v[176:179], v[196:199], v[52:55]
	v_mfma_f32_16x16x32_bf16 v[48:51], v[188:191], v[196:199], v[48:51]
	v_mfma_f32_16x16x32_bf16 v[36:39], v[176:179], v[204:207], v[36:39]
	v_mfma_f32_16x16x32_bf16 v[32:35], v[188:191], v[204:207], v[32:35]
	v_mfma_f32_16x16x32_bf16 v[20:23], v[176:179], v[212:215], v[20:23]
	v_mfma_f32_16x16x32_bf16 v[16:19], v[188:191], v[212:215], v[16:19]
	v_mfma_f32_16x16x32_bf16 v[4:7], v[176:179], v[220:223], v[4:7]
	v_mfma_f32_16x16x32_bf16 v[0:3], v[188:191], v[220:223], v[0:3]
	v_mfma_f32_16x16x32_bf16 v[52:55], v[180:183], v[200:203], v[52:55]
	v_mfma_f32_16x16x32_bf16 v[48:51], v[192:195], v[200:203], v[48:51]
	v_mfma_f32_16x16x32_bf16 v[36:39], v[180:183], v[208:211], v[36:39]
	v_mfma_f32_16x16x32_bf16 v[32:35], v[192:195], v[208:211], v[32:35]
	v_mfma_f32_16x16x32_bf16 v[20:23], v[180:183], v[216:219], v[20:23]
	v_mfma_f32_16x16x32_bf16 v[16:19], v[192:195], v[216:219], v[16:19]
	v_mfma_f32_16x16x32_bf16 v[4:7], v[180:183], v[224:227], v[4:7]
	v_mfma_f32_16x16x32_bf16 v[0:3], v[192:195], v[224:227], v[0:3]
	s_setprio 0
	s_barrier
	s_add_i32 s47, s47, 2
	s_add_u32 s24, s24, 0x100
	s_addc_u32 s25, s25, 0
	s_add_u32 s45, s45, 0x100
	s_addc_u32 s46, s46, 0
	s_cmp_gt_u32 s47, 29

; __device__ __forceinline__ unsigned cvt_pk_bf16(float lo, float hi) { unsigned r; asm volatile("v_cvt_pk_bf16_f32 %0, %1, %2" : "=v"(r) : "v"(lo), "v"(hi)); return r; }
;     __device__ __forceinline__ void operator()(const f32x4 (&acc)[2][2][4][2], const Unit& u, int wr, int wc, int fr, int fq) const {
;     ...
;         f32x4 cbv[2][2];
; #pragma unroll
;         for (int bj = 0; bj < 2; ++bj)
; #pragma unroll
;             for (int n = 0; n < 2; ++n) cbv[bj][n] = *(const f32x4*)(cb + (size_t)b * 8192 + col0 + bj * HALF + 4 * n);
; #pragma unroll
;         for (int ai = 0; ai < 2; ++ai)
; #pragma unroll
;             for (int m = 0; m < 4; ++m) { const int rl = wr * 64 + fr + ai * HALF + m * 16; bf16_t* rowp = O + (size_t)(u.pm * BM + rl) * ldc + col0;
;                 const float rs = rstd[((u.pm >> 2) & 1) * 256 + rl];
; #pragma unroll
;                 for (int bj = 0; bj < 2; ++bj) { float v[8];
; #pragma unroll
;                     for (int e = 0; e < 8; ++e) { const float x = fmaxf(acc[ai][bj][m][e >> 2][e & 3] * rs + cbv[bj][e >> 2][e & 3], 0.f); v[e] = x * x; }
;                     u32x4 w; w.x = cvt_pk_bf16(v[0], v[1]); w.y = cvt_pk_bf16(v[2], v[3]); w.z = cvt_pk_bf16(v[4], v[5]); w.w = cvt_pk_bf16(v[6], v[7]);
;                     *(u32x4*)(rowp + bj * HALF) = w; } }
.LBB0_997:
	s_ashr_i32 s24, s22, 4
	s_ashr_i32 s25, s24, 31
	s_lshl_b64 s[24:25], s[24:25], 15
	v_lshl_or_b32 v160, s42, 8, v171
	s_add_u32 s24, s36, s24
	s_addc_u32 s25, s37, s25
	v_ashrrev_i32_e32 v161, 31, v160
	v_lshl_add_u64 v[128:129], v[160:161], 2, s[24:25]
	global_load_dwordx4 v[140:143], v[128:129], off
	global_load_dwordx4 v[136:139], v[128:129], off offset:16
	global_load_dwordx4 v[132:135], v[128:129], off offset:512
	s_nop 0
	global_load_dwordx4 v[128:131], v[128:129], off offset:528
	s_lshl_b32 s15, s22, 8
	s_and_b32 s17, s15, 0x400
	v_add_u32_e32 v176, s17, v172
	ds_read_b32 v177, v176
	v_add_u32_e32 v178, s15, v162
	v_ashrrev_i32_e32 v179, 31, v178
	v_lshlrev_b64 v[178:179], 14, v[178:179]
	v_lshlrev_b64 v[160:161], 1, v[160:161]
	v_lshl_add_u64 v[178:179], s[72:73], 0, v[178:179]
	v_lshl_add_u64 v[178:179], v[178:179], 0, v[160:161]
	v_add_u32_e32 v180, s15, v164
	v_ashrrev_i32_e32 v181, 31, v180
	s_andn2_b64 vcc, exec, s[4:5]
	s_mov_b64 s[4:5], -1
	s_waitcnt vmcnt(0) lgkmcnt(0)
	v_fma_f32 v124, v124, v177, v140
	v_fma_f32 v125, v125, v177, v141
	v_fma_f32 v126, v126, v177, v142
	v_fma_f32 v127, v127, v177, v143
	v_fma_f32 v120, v120, v177, v136
	v_fma_f32 v121, v121, v177, v137
	v_fma_f32 v122, v122, v177, v138
	v_fma_f32 v123, v123, v177, v139
	v_fma_f32 v118, v118, v177, v134
	v_fma_f32 v112, v112, v177, v128
	v_fma_f32 v113, v113, v177, v129
	v_fma_f32 v114, v114, v177, v130
	v_fma_f32 v115, v115, v177, v131
	v_fma_f32 v116, v116, v177, v132
	v_fma_f32 v117, v117, v177, v133
	v_fma_f32 v119, v119, v177, v135
	v_max_f32_e32 v124, 0, v124
	v_max_f32_e32 v125, 0, v125
	v_max_f32_e32 v126, 0, v126
	v_max_f32_e32 v127, 0, v127
	v_max_f32_e32 v120, 0, v120
	v_max_f32_e32 v121, 0, v121
	v_max_f32_e32 v122, 0, v122
	v_max_f32_e32 v123, 0, v123
	v_max_f32_e32 v118, 0, v118
	v_max_f32_e32 v112, 0, v112
	v_max_f32_e32 v113, 0, v113
	v_max_f32_e32 v114, 0, v114
	v_max_f32_e32 v115, 0, v115
	v_max_f32_e32 v116, 0, v116
	v_max_f32_e32 v117, 0, v117
	v_max_f32_e32 v119, 0, v119
	v_mul_f32_e32 v124, v124, v124
	v_mul_f32_e32 v125, v125, v125
	v_mul_f32_e32 v126, v126, v126
	v_mul_f32_e32 v127, v127, v127
	v_mul_f32_e32 v120, v120, v120
	v_mul_f32_e32 v121, v121, v121
	v_mul_f32_e32 v122, v122, v122
	v_mul_f32_e32 v123, v123, v123
	v_mul_f32_e32 v118, v118, v118
	v_mul_f32_e32 v177, v112, v112
	v_mul_f32_e32 v182, v113, v113
	v_mul_f32_e32 v183, v114, v114
	v_mul_f32_e32 v184, v115, v115
	v_cvt_pk_bf16_f32 v112, v124, v125
	v_cvt_pk_bf16_f32 v113, v126, v127
	v_cvt_pk_bf16_f32 v114, v120, v121
	v_cvt_pk_bf16_f32 v115, v122, v123
	v_mul_f32_e32 v116, v116, v116
	v_mul_f32_e32 v117, v117, v117
	v_mul_f32_e32 v119, v119, v119
	global_store_dwordx4 v[178:179], v[112:115], off
	s_nop 1
	v_cvt_pk_bf16_f32 v112, v116, v117
	v_cvt_pk_bf16_f32 v113, v118, v119
	v_cvt_pk_bf16_f32 v114, v177, v182
	v_cvt_pk_bf16_f32 v115, v183, v184
	ds_read_b32 v118, v176 offset:64
	global_store_dwordx4 v[178:179], v[112:115], off offset:256
	v_lshlrev_b64 v[116:117], 14, v[180:181]
	v_lshl_add_u64 v[116:117], s[72:73], 0, v[116:117]
	v_lshl_add_u64 v[116:117], v[116:117], 0, v[160:161]
	s_waitcnt lgkmcnt(0)
	v_fma_f32 v104, v104, v118, v136
	v_max_f32_e32 v104, 0, v104
	v_mul_f32_e32 v112, v104, v104
	v_fma_f32 v104, v105, v118, v137
	v_max_f32_e32 v104, 0, v104
	v_mul_f32_e32 v113, v104, v104
	v_fma_f32 v104, v106, v118, v138
	v_max_f32_e32 v104, 0, v104
	v_fma_f32 v108, v108, v118, v140
	v_fma_f32 v109, v109, v118, v141
	v_mul_f32_e32 v114, v104, v104
	v_fma_f32 v104, v107, v118, v139
	v_fma_f32 v110, v110, v118, v142
	v_fma_f32 v111, v111, v118, v143
	v_max_f32_e32 v108, 0, v108
	v_max_f32_e32 v109, 0, v109
	v_max_f32_e32 v104, 0, v104
	v_fma_f32 v96, v96, v118, v128
	v_max_f32_e32 v110, 0, v110
	v_max_f32_e32 v111, 0, v111
	v_mul_f32_e32 v108, v108, v108
	v_mul_f32_e32 v109, v109, v109
	v_mul_f32_e32 v107, v104, v104
	v_cvt_pk_bf16_f32 v104, v108, v109
	v_max_f32_e32 v96, 0, v96
	v_mul_f32_e32 v110, v110, v110
	v_mul_f32_e32 v111, v111, v111
	v_cvt_pk_bf16_f32 v105, v110, v111
	v_cvt_pk_bf16_f32 v106, v112, v113
	v_cvt_pk_bf16_f32 v107, v114, v107
	global_store_dwordx4 v[116:117], v[104:107], off
	v_fma_f32 v100, v100, v118, v132
	v_fma_f32 v101, v101, v118, v133
	v_mul_f32_e32 v104, v96, v96
	v_fma_f32 v96, v97, v118, v129
	v_max_f32_e32 v96, 0, v96
	v_mul_f32_e32 v105, v96, v96
	v_fma_f32 v96, v98, v118, v130
	v_max_f32_e32 v96, 0, v96
	v_fma_f32 v102, v102, v118, v134
	v_fma_f32 v103, v103, v118, v135
	v_mul_f32_e32 v106, v96, v96
	v_fma_f32 v96, v99, v118, v131
	v_max_f32_e32 v100, 0, v100
	v_max_f32_e32 v101, 0, v101
	v_max_f32_e32 v102, 0, v102
	v_max_f32_e32 v103, 0, v103
	v_max_f32_e32 v96, 0, v96
	v_mul_f32_e32 v100, v100, v100
	v_mul_f32_e32 v101, v101, v101
	v_mul_f32_e32 v102, v102, v102
	v_mul_f32_e32 v103, v103, v103
	v_mul_f32_e32 v99, v96, v96
	v_cvt_pk_bf16_f32 v96, v100, v101
	v_cvt_pk_bf16_f32 v97, v102, v103
	v_cvt_pk_bf16_f32 v98, v104, v105
	v_cvt_pk_bf16_f32 v99, v106, v99
	global_store_dwordx4 v[116:117], v[96:99], off offset:256
	ds_read_b32 v98, v176 offset:128
	s_waitcnt lgkmcnt(0)
; __device__ __forceinline__ unsigned cvt_pk_bf16(float lo, float hi) { unsigned r; asm volatile("v_cvt_pk_bf16_f32 %0, %1, %2" : "=v"(r) : "v"(lo), "v"(hi)); return r; }
;     __device__ __forceinline__ void operator()(const f32x4 (&acc)[2][2][4][2], const Unit& u, int wr, int wc, int fr, int fq) const {
;     ...
; #pragma unroll
;         for (int ai = 0; ai < 2; ++ai)
; #pragma unroll
;             for (int m = 0; m < 4; ++m) { const int rl = wr * 64 + fr + ai * HALF + m * 16; bf16_t* rowp = O + (size_t)(u.pm * BM + rl) * ldc + col0;
;                 const float rs = rstd[((u.pm >> 2) & 1) * 256 + rl];
; #pragma unroll
;                 for (int bj = 0; bj < 2; ++bj) { float v[8];
; #pragma unroll
;                     for (int e = 0; e < 8; ++e) { const float x = fmaxf(acc[ai][bj][m][e >> 2][e & 3] * rs + cbv[bj][e >> 2][e & 3], 0.f); v[e] = x * x; }
;                     u32x4 w; w.x = cvt_pk_bf16(v[0], v[1]); w.y = cvt_pk_bf16(v[2], v[3]); w.z = cvt_pk_bf16(v[4], v[5]); w.w = cvt_pk_bf16(v[6], v[7]);
;                     *(u32x4*)(rowp + bj * HALF) = w; } }
	v_fma_f32 v88, v88, v98, v136
	v_max_f32_e32 v88, 0, v88
	v_mul_f32_e32 v99, v88, v88
	v_fma_f32 v88, v89, v98, v137
	v_max_f32_e32 v88, 0, v88
	v_add_u32_e32 v96, s15, v165
	v_mul_f32_e32 v100, v88, v88
	v_fma_f32 v88, v90, v98, v138
	v_ashrrev_i32_e32 v97, 31, v96
	v_max_f32_e32 v88, 0, v88
	v_lshlrev_b64 v[96:97], 14, v[96:97]
	v_fma_f32 v92, v92, v98, v140
	v_fma_f32 v93, v93, v98, v141
	v_mul_f32_e32 v101, v88, v88
	v_fma_f32 v88, v91, v98, v139
	v_lshl_add_u64 v[96:97], s[72:73], 0, v[96:97]
	v_max_f32_e32 v92, 0, v92
	v_max_f32_e32 v93, 0, v93
	v_fma_f32 v94, v94, v98, v142
	v_fma_f32 v95, v95, v98, v143
	v_max_f32_e32 v88, 0, v88
	v_fma_f32 v80, v80, v98, v128
	v_lshl_add_u64 v[96:97], v[96:97], 0, v[160:161]
	v_mul_f32_e32 v92, v92, v92
	v_mul_f32_e32 v93, v93, v93
	v_max_f32_e32 v94, 0, v94
	v_max_f32_e32 v95, 0, v95
	v_mul_f32_e32 v91, v88, v88
	v_cvt_pk_bf16_f32 v88, v92, v93
	v_max_f32_e32 v80, 0, v80
	v_mul_f32_e32 v94, v94, v94
	v_mul_f32_e32 v95, v95, v95
	v_cvt_pk_bf16_f32 v89, v94, v95
	v_cvt_pk_bf16_f32 v90, v99, v100
	v_cvt_pk_bf16_f32 v91, v101, v91
	global_store_dwordx4 v[96:97], v[88:91], off
	v_fma_f32 v84, v84, v98, v132
	v_fma_f32 v85, v85, v98, v133
	v_mul_f32_e32 v88, v80, v80
	v_fma_f32 v80, v81, v98, v129
	v_max_f32_e32 v80, 0, v80
	v_mul_f32_e32 v89, v80, v80
	v_fma_f32 v80, v82, v98, v130
	v_max_f32_e32 v80, 0, v80
	v_fma_f32 v86, v86, v98, v134
	v_fma_f32 v87, v87, v98, v135
	v_mul_f32_e32 v90, v80, v80
	v_fma_f32 v80, v83, v98, v131
	v_max_f32_e32 v84, 0, v84
	v_max_f32_e32 v85, 0, v85
	v_max_f32_e32 v86, 0, v86
	v_max_f32_e32 v87, 0, v87
	v_max_f32_e32 v80, 0, v80
	v_mul_f32_e32 v84, v84, v84
	v_mul_f32_e32 v85, v85, v85
	v_mul_f32_e32 v86, v86, v86
	v_mul_f32_e32 v87, v87, v87
	v_mul_f32_e32 v83, v80, v80
	v_cvt_pk_bf16_f32 v80, v84, v85
	v_cvt_pk_bf16_f32 v81, v86, v87
	v_cvt_pk_bf16_f32 v82, v88, v89
	v_cvt_pk_bf16_f32 v83, v90, v83
	global_store_dwordx4 v[96:97], v[80:83], off offset:256
	ds_read_b32 v82, v176 offset:192
	s_waitcnt lgkmcnt(0)
	v_fma_f32 v72, v72, v82, v136
	v_max_f32_e32 v72, 0, v72
	v_mul_f32_e32 v83, v72, v72
	v_fma_f32 v72, v73, v82, v137
	v_max_f32_e32 v72, 0, v72
	v_add_u32_e32 v80, s15, v166
	v_mul_f32_e32 v84, v72, v72
	v_fma_f32 v72, v74, v82, v138
	v_ashrrev_i32_e32 v81, 31, v80
	v_max_f32_e32 v72, 0, v72
	v_lshlrev_b64 v[80:81], 14, v[80:81]
	v_fma_f32 v76, v76, v82, v140
	v_fma_f32 v77, v77, v82, v141
	v_mul_f32_e32 v85, v72, v72
	v_fma_f32 v72, v75, v82, v139
	v_lshl_add_u64 v[80:81], s[72:73], 0, v[80:81]
	v_max_f32_e32 v76, 0, v76
	v_max_f32_e32 v77, 0, v77
	v_fma_f32 v78, v78, v82, v142
	v_fma_f32 v79, v79, v82, v143
	v_max_f32_e32 v72, 0, v72
	v_fma_f32 v64, v64, v82, v128
	v_lshl_add_u64 v[80:81], v[80:81], 0, v[160:161]
	v_mul_f32_e32 v76, v76, v76
	v_mul_f32_e32 v77, v77, v77
	v_max_f32_e32 v78, 0, v78
	v_max_f32_e32 v79, 0, v79
	v_mul_f32_e32 v75, v72, v72
	v_cvt_pk_bf16_f32 v72, v76, v77
	v_max_f32_e32 v64, 0, v64
	v_mul_f32_e32 v78, v78, v78
	v_mul_f32_e32 v79, v79, v79
	v_cvt_pk_bf16_f32 v73, v78, v79
	v_cvt_pk_bf16_f32 v74, v83, v84
	v_cvt_pk_bf16_f32 v75, v85, v75
	global_store_dwordx4 v[80:81], v[72:75], off
	v_fma_f32 v68, v68, v82, v132
	v_fma_f32 v69, v69, v82, v133
	v_mul_f32_e32 v72, v64, v64
	v_fma_f32 v64, v65, v82, v129
	v_max_f32_e32 v64, 0, v64
	v_mul_f32_e32 v73, v64, v64
	v_fma_f32 v64, v66, v82, v130
	v_max_f32_e32 v64, 0, v64
	v_fma_f32 v70, v70, v82, v134
	v_fma_f32 v71, v71, v82, v135
	v_mul_f32_e32 v74, v64, v64
	v_fma_f32 v64, v67, v82, v131
	v_max_f32_e32 v68, 0, v68
	v_max_f32_e32 v69, 0, v69
	v_max_f32_e32 v70, 0, v70
	v_max_f32_e32 v71, 0, v71
	v_max_f32_e32 v64, 0, v64
	v_mul_f32_e32 v68, v68, v68
	v_mul_f32_e32 v69, v69, v69
	v_mul_f32_e32 v70, v70, v70
	v_mul_f32_e32 v71, v71, v71
	v_mul_f32_e32 v67, v64, v64
	v_cvt_pk_bf16_f32 v64, v68, v69
	v_cvt_pk_bf16_f32 v65, v70, v71
	v_cvt_pk_bf16_f32 v66, v72, v73
	v_cvt_pk_bf16_f32 v67, v74, v67
	global_store_dwordx4 v[80:81], v[64:67], off offset:256
	ds_read_b32 v66, v176 offset:512
	s_waitcnt lgkmcnt(0)
	v_fma_f32 v56, v56, v66, v136
	v_max_f32_e32 v56, 0, v56
	v_mul_f32_e32 v67, v56, v56
	v_fma_f32 v56, v57, v66, v137
	v_max_f32_e32 v56, 0, v56
	v_add_u32_e32 v64, s15, v167
	v_mul_f32_e32 v68, v56, v56
	v_fma_f32 v56, v58, v66, v138
	v_ashrrev_i32_e32 v65, 31, v64
	v_max_f32_e32 v56, 0, v56
	v_lshlrev_b64 v[64:65], 14, v[64:65]
	v_fma_f32 v60, v60, v66, v140
	v_fma_f32 v61, v61, v66, v141
	v_mul_f32_e32 v69, v56, v56
	v_fma_f32 v56, v59, v66, v139
	v_lshl_add_u64 v[64:65], s[72:73], 0, v[64:65]
	v_max_f32_e32 v60, 0, v60
	v_max_f32_e32 v61, 0, v61
	v_fma_f32 v62, v62, v66, v142
	v_fma_f32 v63, v63, v66, v143
	v_max_f32_e32 v56, 0, v56
	v_fma_f32 v48, v48, v66, v128
	v_lshl_add_u64 v[64:65], v[64:65], 0, v[160:161]
	v_mul_f32_e32 v60, v60, v60
	v_mul_f32_e32 v61, v61, v61
	v_max_f32_e32 v62, 0, v62
	v_max_f32_e32 v63, 0, v63
	v_mul_f32_e32 v59, v56, v56
	v_cvt_pk_bf16_f32 v56, v60, v61
	v_max_f32_e32 v48, 0, v48
	v_mul_f32_e32 v62, v62, v62
	v_mul_f32_e32 v63, v63, v63
	v_cvt_pk_bf16_f32 v57, v62, v63
	v_cvt_pk_bf16_f32 v58, v67, v68
	v_cvt_pk_bf16_f32 v59, v69, v59
	global_store_dwordx4 v[64:65], v[56:59], off
	v_fma_f32 v52, v52, v66, v132
	v_fma_f32 v53, v53, v66, v133
	v_mul_f32_e32 v56, v48, v48
	v_fma_f32 v48, v49, v66, v129
	v_max_f32_e32 v48, 0, v48
	v_mul_f32_e32 v57, v48, v48
	v_fma_f32 v48, v50, v66, v130
	v_max_f32_e32 v48, 0, v48
	v_fma_f32 v54, v54, v66, v134
	v_fma_f32 v55, v55, v66, v135
	v_mul_f32_e32 v58, v48, v48
	v_fma_f32 v48, v51, v66, v131
	v_max_f32_e32 v52, 0, v52
	v_max_f32_e32 v53, 0, v53
	v_max_f32_e32 v54, 0, v54
	v_max_f32_e32 v55, 0, v55
	v_max_f32_e32 v48, 0, v48
	v_mul_f32_e32 v52, v52, v52
	v_mul_f32_e32 v53, v53, v53
	v_mul_f32_e32 v54, v54, v54
	v_mul_f32_e32 v55, v55, v55
	v_mul_f32_e32 v51, v48, v48
	v_cvt_pk_bf16_f32 v48, v52, v53
	v_cvt_pk_bf16_f32 v49, v54, v55
	v_cvt_pk_bf16_f32 v50, v56, v57
	v_cvt_pk_bf16_f32 v51, v58, v51
	global_store_dwordx4 v[64:65], v[48:51], off offset:256
	ds_read_b32 v50, v176 offset:576
	s_waitcnt lgkmcnt(0)
; __device__ __forceinline__ unsigned cvt_pk_bf16(float lo, float hi) { unsigned r; asm volatile("v_cvt_pk_bf16_f32 %0, %1, %2" : "=v"(r) : "v"(lo), "v"(hi)); return r; }
;     __device__ __forceinline__ void operator()(const f32x4 (&acc)[2][2][4][2], const Unit& u, int wr, int wc, int fr, int fq) const {
;     ...
; #pragma unroll
;         for (int ai = 0; ai < 2; ++ai)
; #pragma unroll
;             for (int m = 0; m < 4; ++m) { const int rl = wr * 64 + fr + ai * HALF + m * 16; bf16_t* rowp = O + (size_t)(u.pm * BM + rl) * ldc + col0;
;                 const float rs = rstd[((u.pm >> 2) & 1) * 256 + rl];
; #pragma unroll
;                 for (int bj = 0; bj < 2; ++bj) { float v[8];
; #pragma unroll
;                     for (int e = 0; e < 8; ++e) { const float x = fmaxf(acc[ai][bj][m][e >> 2][e & 3] * rs + cbv[bj][e >> 2][e & 3], 0.f); v[e] = x * x; }
;                     u32x4 w; w.x = cvt_pk_bf16(v[0], v[1]); w.y = cvt_pk_bf16(v[2], v[3]); w.z = cvt_pk_bf16(v[4], v[5]); w.w = cvt_pk_bf16(v[6], v[7]);
;                     *(u32x4*)(rowp + bj * HALF) = w; } }
; template <class Epi, class Sched, bool ALIGN_EPI = false, bool SP2 = false>
; __device__ __forceinline__ void gemm_phase(PG8_LAS unsigned char* lds, const Gemm g, const Sched& S, const Epi& E) {
;     ...
;         if constexpr (!Epi::AFTER_DRAIN) { E(acc, cur, wr, wc, fr, fq); S.done(cur); }
;         if (!has_next) break;
	v_fma_f32 v40, v40, v50, v136
	v_max_f32_e32 v40, 0, v40
	v_mul_f32_e32 v51, v40, v40
	v_fma_f32 v40, v41, v50, v137
	v_max_f32_e32 v40, 0, v40
	v_add_u32_e32 v48, s15, v168
	v_mul_f32_e32 v52, v40, v40
	v_fma_f32 v40, v42, v50, v138
	v_ashrrev_i32_e32 v49, 31, v48
	v_max_f32_e32 v40, 0, v40
	v_lshlrev_b64 v[48:49], 14, v[48:49]
	v_fma_f32 v44, v44, v50, v140
	v_fma_f32 v45, v45, v50, v141
	v_mul_f32_e32 v53, v40, v40
	v_fma_f32 v40, v43, v50, v139
	v_lshl_add_u64 v[48:49], s[72:73], 0, v[48:49]
	v_max_f32_e32 v44, 0, v44
	v_max_f32_e32 v45, 0, v45
	v_fma_f32 v46, v46, v50, v142
	v_fma_f32 v47, v47, v50, v143
	v_max_f32_e32 v40, 0, v40
	v_fma_f32 v32, v32, v50, v128
	v_lshl_add_u64 v[48:49], v[48:49], 0, v[160:161]
	v_mul_f32_e32 v44, v44, v44
	v_mul_f32_e32 v45, v45, v45
	v_max_f32_e32 v46, 0, v46
	v_max_f32_e32 v47, 0, v47
	v_mul_f32_e32 v43, v40, v40
	v_cvt_pk_bf16_f32 v40, v44, v45
	v_max_f32_e32 v32, 0, v32
	v_mul_f32_e32 v46, v46, v46
	v_mul_f32_e32 v47, v47, v47
	v_cvt_pk_bf16_f32 v41, v46, v47
	v_cvt_pk_bf16_f32 v42, v51, v52
	v_cvt_pk_bf16_f32 v43, v53, v43
	global_store_dwordx4 v[48:49], v[40:43], off
	v_fma_f32 v36, v36, v50, v132
	v_fma_f32 v37, v37, v50, v133
	v_mul_f32_e32 v40, v32, v32
	v_fma_f32 v32, v33, v50, v129
	v_max_f32_e32 v32, 0, v32
	v_mul_f32_e32 v41, v32, v32
	v_fma_f32 v32, v34, v50, v130
	v_max_f32_e32 v32, 0, v32
	v_fma_f32 v38, v38, v50, v134
	v_fma_f32 v39, v39, v50, v135
	v_mul_f32_e32 v42, v32, v32
	v_fma_f32 v32, v35, v50, v131
	v_max_f32_e32 v36, 0, v36
	v_max_f32_e32 v37, 0, v37
	v_max_f32_e32 v38, 0, v38
	v_max_f32_e32 v39, 0, v39
	v_max_f32_e32 v32, 0, v32
	v_mul_f32_e32 v36, v36, v36
	v_mul_f32_e32 v37, v37, v37
	v_mul_f32_e32 v38, v38, v38
	v_mul_f32_e32 v39, v39, v39
	v_mul_f32_e32 v35, v32, v32
	v_cvt_pk_bf16_f32 v32, v36, v37
	v_cvt_pk_bf16_f32 v33, v38, v39
	v_cvt_pk_bf16_f32 v34, v40, v41
	v_cvt_pk_bf16_f32 v35, v42, v35
	global_store_dwordx4 v[48:49], v[32:35], off offset:256
	ds_read_b32 v34, v176 offset:640
	s_waitcnt lgkmcnt(0)
	v_fma_f32 v24, v24, v34, v136
	v_max_f32_e32 v24, 0, v24
	v_mul_f32_e32 v35, v24, v24
	v_fma_f32 v24, v25, v34, v137
	v_max_f32_e32 v24, 0, v24
	v_add_u32_e32 v32, s15, v169
	v_mul_f32_e32 v36, v24, v24
	v_fma_f32 v24, v26, v34, v138
	v_ashrrev_i32_e32 v33, 31, v32
	v_max_f32_e32 v24, 0, v24
	v_lshlrev_b64 v[32:33], 14, v[32:33]
	v_fma_f32 v28, v28, v34, v140
	v_fma_f32 v29, v29, v34, v141
	v_mul_f32_e32 v37, v24, v24
	v_fma_f32 v24, v27, v34, v139
	v_lshl_add_u64 v[32:33], s[72:73], 0, v[32:33]
	v_max_f32_e32 v28, 0, v28
	v_max_f32_e32 v29, 0, v29
	v_fma_f32 v30, v30, v34, v142
	v_fma_f32 v31, v31, v34, v143
	v_max_f32_e32 v24, 0, v24
	v_fma_f32 v16, v16, v34, v128
	v_lshl_add_u64 v[32:33], v[32:33], 0, v[160:161]
	v_mul_f32_e32 v28, v28, v28
	v_mul_f32_e32 v29, v29, v29
	v_max_f32_e32 v30, 0, v30
	v_max_f32_e32 v31, 0, v31
	v_mul_f32_e32 v27, v24, v24
	v_cvt_pk_bf16_f32 v24, v28, v29
	v_max_f32_e32 v16, 0, v16
	v_mul_f32_e32 v30, v30, v30
	v_mul_f32_e32 v31, v31, v31
	v_cvt_pk_bf16_f32 v25, v30, v31
	v_cvt_pk_bf16_f32 v26, v35, v36
	v_cvt_pk_bf16_f32 v27, v37, v27
	global_store_dwordx4 v[32:33], v[24:27], off
	v_fma_f32 v20, v20, v34, v132
	v_fma_f32 v21, v21, v34, v133
	v_mul_f32_e32 v24, v16, v16
	v_fma_f32 v16, v17, v34, v129
	v_max_f32_e32 v16, 0, v16
	v_mul_f32_e32 v25, v16, v16
	v_fma_f32 v16, v18, v34, v130
	v_max_f32_e32 v16, 0, v16
	v_fma_f32 v22, v22, v34, v134
	v_fma_f32 v23, v23, v34, v135
	v_mul_f32_e32 v26, v16, v16
	v_fma_f32 v16, v19, v34, v131
	v_max_f32_e32 v20, 0, v20
	v_max_f32_e32 v21, 0, v21
	v_max_f32_e32 v22, 0, v22
	v_max_f32_e32 v23, 0, v23
	v_max_f32_e32 v16, 0, v16
	v_mul_f32_e32 v20, v20, v20
	v_mul_f32_e32 v21, v21, v21
	v_mul_f32_e32 v22, v22, v22
	v_mul_f32_e32 v23, v23, v23
	v_mul_f32_e32 v19, v16, v16
	v_cvt_pk_bf16_f32 v16, v20, v21
	v_cvt_pk_bf16_f32 v17, v22, v23
	v_cvt_pk_bf16_f32 v18, v24, v25
	v_cvt_pk_bf16_f32 v19, v26, v19
	global_store_dwordx4 v[32:33], v[16:19], off offset:256
	ds_read_b32 v18, v176 offset:704
	s_waitcnt lgkmcnt(0)
	v_fma_f32 v8, v8, v18, v136
	v_max_f32_e32 v8, 0, v8
	v_mul_f32_e32 v19, v8, v8
	v_fma_f32 v8, v9, v18, v137
	v_add_u32_e32 v16, s15, v170
	v_max_f32_e32 v8, 0, v8
	v_ashrrev_i32_e32 v17, 31, v16
	v_mul_f32_e32 v20, v8, v8
	v_fma_f32 v8, v10, v18, v138
	v_lshlrev_b64 v[16:17], 14, v[16:17]
	v_fma_f32 v12, v12, v18, v140
	v_fma_f32 v13, v13, v18, v141
	v_max_f32_e32 v8, 0, v8
	v_fmac_f32_e32 v139, v11, v18
	v_lshl_add_u64 v[16:17], s[72:73], 0, v[16:17]
	v_max_f32_e32 v12, 0, v12
	v_max_f32_e32 v13, 0, v13
	v_fma_f32 v14, v14, v18, v142
	v_fmac_f32_e32 v143, v15, v18
	v_mul_f32_e32 v21, v8, v8
	v_max_f32_e32 v8, 0, v139
	v_fma_f32 v0, v0, v18, v128
	v_lshl_add_u64 v[16:17], v[16:17], 0, v[160:161]
	v_mul_f32_e32 v12, v12, v12
	v_mul_f32_e32 v13, v13, v13
	v_max_f32_e32 v14, 0, v14
	v_max_f32_e32 v15, 0, v143
	v_mul_f32_e32 v11, v8, v8
	v_cvt_pk_bf16_f32 v8, v12, v13
	v_max_f32_e32 v0, 0, v0
	v_mul_f32_e32 v14, v14, v14
	v_mul_f32_e32 v15, v15, v15
	v_cvt_pk_bf16_f32 v9, v14, v15
	v_cvt_pk_bf16_f32 v10, v19, v20
	v_cvt_pk_bf16_f32 v11, v21, v11
	global_store_dwordx4 v[16:17], v[8:11], off
	v_fmac_f32_e32 v131, v3, v18
	v_fma_f32 v4, v4, v18, v132
	v_mul_f32_e32 v8, v0, v0
	v_fma_f32 v0, v1, v18, v129
	v_max_f32_e32 v0, 0, v0
	v_mul_f32_e32 v9, v0, v0
	v_fma_f32 v0, v2, v18, v130
	v_max_f32_e32 v0, 0, v0
	v_fma_f32 v5, v5, v18, v133
	v_fma_f32 v6, v6, v18, v134
	v_fmac_f32_e32 v135, v7, v18
	v_mul_f32_e32 v10, v0, v0
	v_max_f32_e32 v0, 0, v131
	v_max_f32_e32 v4, 0, v4
	v_max_f32_e32 v5, 0, v5
	v_max_f32_e32 v6, 0, v6
	v_max_f32_e32 v7, 0, v135
	v_mul_f32_e32 v3, v0, v0
	v_mul_f32_e32 v4, v4, v4
	v_mul_f32_e32 v5, v5, v5
	v_mul_f32_e32 v6, v6, v6
	v_mul_f32_e32 v7, v7, v7
	v_cvt_pk_bf16_f32 v0, v4, v5
	v_cvt_pk_bf16_f32 v1, v6, v7
	v_cvt_pk_bf16_f32 v2, v8, v9
	v_cvt_pk_bf16_f32 v3, v10, v3
	global_store_dwordx4 v[16:17], v[0:3], off offset:256
	s_mov_b32 s99, 1
	s_cbranch_vccnz .LBB0_986
	s_andn2_b64 vcc, exec, s[6:7]
	s_cbranch_vccnz .LBB0_985
	s_barrier
	s_branch .LBB0_985

;     __device__ __forceinline__ bool next(int i, Unit& u) const { if (!base.next(i >> 1, u)) return false; if (i & 1) { u.pm += 64; u.pn += 8; } return true; }
; #define PG8_STAGE(bufoff, gbase, voff) do { _Pragma("unroll") for (int _i = 0; _i < 2; ++_i) \
;         __builtin_amdgcn_global_load_lds((const unsigned*)((const char*)(gbase) + (voff)[_i]), (PG8_LAS unsigned*)(lds + (bufoff) + ldsw + _i * 8192), 16, 0, 0); } while (0)
; #define PG8_WAIT_V(n) asm volatile("s_waitcnt vmcnt(" #n ")" ::: "memory")
; #define PG8_BAR __builtin_amdgcn_s_barrier()
; template <class Epi, class Sched, bool ALIGN_EPI = false, bool SP2 = false>
; __device__ __forceinline__ void gemm_phase(PG8_LAS unsigned char* lds, const Gemm g, const Sched& S, const Epi& E) {
;     ...
;     for (int i = 0; i < 2; ++i) { int R, C; stage_rc(tid * 16 + i * 8192, R, C); const int Rb = Epi::PERM ? ((R & ~31) + perm32(R & 31)) : R;
;         voffA[i] = (unsigned)(R * K + C) * 2u; voffB[i] = (unsigned)(Rb * K + C) * 2u; }
;     const size_t kstep = (size_t)(BK * 2);
;     const size_t hstep = (size_t)HALF * K * 2;
;     const size_t tstep = 2 * hstep;
;     const unsigned ldsw = (unsigned)wid * 1024u;
;     const int aoff = lds_byte(wr * 64 + fr, fq * 8), boff = lds_byte(wc * 32 + fr, fq * 8);
;     ...
;     Unit cur, nxt; int ui = 0;
;     if (!S.next(0, cur)) return;
;     f32x4 acc[2][2][4][2];
; #pragma unroll
;     for (int a = 0; a < 2; ++a)
; #pragma unroll
;         for (int b = 0; b < 2; ++b)
; #pragma unroll
;             for (int m = 0; m < 4; ++m)
; #pragma unroll
;                 for (int n = 0; n < 2; ++n) acc[a][b][m][n] = (f32x4){0.f, 0.f, 0.f, 0.f};
;     bf16x8 At[4][2], B0[2][2], B1[2][2];
;     const char* cA = (const char*)g.A + (size_t)cur.pm * tstep; const char* cB = (const char*)g.Bt + (size_t)cur.pn * tstep;
;     S.a_ready(cur);
;     if constexpr (SP2) {
;         PG8_STAGE(PG8_SB(0, 0), cB, voffB); PG8_STAGE(PG8_SB(0, 1), cB + hstep, voffB); PG8_STAGE(PG8_SA(0, 0), cA, voffA); PG8_STAGE(PG8_SA(0, 1), cA + hstep, voffA);
;         if (wr == 1) PG8_BAR;
;         PG8_WAIT_V(2); PG8_BAR;
;         PG8_STAGE(PG8_SB(1, 0), cB + kstep, voffB); PG8_STAGE(PG8_SA(1, 0), cA + kstep, voffA); PG8_STAGE(PG8_SB(1, 1), cB + hstep + kstep, voffB);
;         PG8_WAIT_V(6); PG8_BAR;
.LBB0_1061:
	s_mov_b32 s99, 0
	s_add_u32 s40, s68, 0xa000
	s_addc_u32 s41, s69, 0
	s_lshl_b32 s4, s4, 5
	s_and_b32 s10, s4, 0x60
	s_mov_b64 s[4:5], 0x80
	s_add_i32 m0, s35, 0x18000
	v_lshl_add_u64 v[6:7], v[6:7], 0, s[4:5]
	s_lshl_b32 s7, s1, 13
	s_lshl_b32 s11, s10, 7
	s_waitcnt vmcnt(2)
	s_barrier
	global_load_lds_dwordx4 v[6:7], off
	v_lshl_add_u64 v[4:5], v[4:5], 0, s[4:5]
	s_add_i32 m0, s35, 0x1a000
	s_add_i32 s42, s35, 0x8000
	s_add_i32 s43, s35, 0xa000
	global_load_lds_dwordx4 v[4:5], off
	v_lshl_add_u64 v[0:1], v[0:1], 0, s[4:5]
	s_mov_b32 m0, s42
	s_add_u32 s8, s28, 0x200080
	global_load_lds_dwordx4 v[0:1], off
	v_lshl_add_u64 v[0:1], v[2:3], 0, s[4:5]
	s_mov_b32 m0, s43
	s_addc_u32 s9, s29, 0
	global_load_lds_dwordx4 v[0:1], off
	s_add_i32 m0, s35, 0x1c000
	v_lshl_add_u64 v[0:1], s[8:9], 0, v[144:145]
	global_load_lds_dwordx4 v[0:1], off
	v_lshl_add_u64 v[0:1], s[8:9], 0, v[146:147]
	s_add_i32 m0, s35, 0x1e000
	s_cmpk_lt_u32 s6, 0x100
	global_load_lds_dwordx4 v[0:1], off
	v_bfe_u32 v1, v186, 4, 2
	v_and_b32_e32 v0, 15, v186
	v_lshlrev_b32_e32 v2, 4, v1
	v_lshl_or_b32 v162, s1, 6, v0
	v_lshl_or_b32 v0, v0, 6, v2
	v_lshlrev_b32_e32 v2, 2, v186
	v_and_b32_e32 v2, 32, v2
	v_bitop3_b32 v3, v0, s7, v2 bitop3:0xde
	v_bitop3_b32 v163, v0, s11, v2 bitop3:0xde
	v_lshlrev_b32_e32 v0, 17, v8
	v_and_b32_e32 v0, 0xfffc0000, v0
	v_lshl_or_b32 v164, v1, 2, s10
	v_lshl_add_u32 v0, v9, 14, v0
	v_and_b32_e32 v1, 1, v8
	v_lshl_or_b32 v0, v1, 6, v0
	v_lshl_add_u32 v148, v10, 1, v0
	v_lshlrev_b32_e32 v0, 17, v11
	v_and_b32_e32 v0, 0xfffc0000, v0
	s_waitcnt vmcnt(6)
	v_lshl_add_u32 v0, v12, 14, v0
	v_and_b32_e32 v1, 1, v11
	s_cselect_b64 s[6:7], -1, 0
	v_lshl_or_b32 v0, v1, 6, v0
	s_add_i32 s45, 0, 0x10000
	s_add_i32 s46, 0, 0x14000
	s_sext_i32_i8 s25, s0
	s_ashr_i32 s44, s70, 31
	v_mov_b32_e32 v149, v145
	v_lshl_add_u32 v150, v13, 1, v0
	v_mov_b32_e32 v151, v145
	v_mov_b64_e32 v[152:153], 0x200
	v_mov_b64_e32 v[154:155], 0x1ff
	v_add_u32_e32 v165, s45, v163
	v_add_u32_e32 v166, s46, v163
	v_add_u32_e32 v167, 0, v3
	s_mov_b64 s[8:9], 0x100000
	s_mov_b32 s47, 0x100000
	s_mov_b64 s[10:11], 0x120000
	s_mov_b32 s48, 0x120000
	s_mov_b64 s[12:13], 0x140000
	s_mov_b32 s49, 0x140000
	s_mov_b64 s[14:15], 0x160000
	s_mov_b32 s50, 0x160000
	s_barrier
	s_branch .LBB0_1064

; #define PG8_STAGE(bufoff, gbase, voff) do { _Pragma("unroll") for (int _i = 0; _i < 2; ++_i) \
;         __builtin_amdgcn_global_load_lds((const unsigned*)((const char*)(gbase) + (voff)[_i]), (PG8_LAS unsigned*)(lds + (bufoff) + ldsw + _i * 8192), 16, 0, 0); } while (0)
; #define PG8_LDA(dst, b, h) do { _Pragma("unroll") for (int m = 0; m < 4; ++m) _Pragma("unroll") for (int k = 0; k < 2; ++k) dst[m][k] = *(const PG8_LAS bf16x8*)(lds + PG8_SA(b, h) + aoff + m * 2048 + k * 1024); } while (0)
; #define PG8_LDB(dst, b, h) do { _Pragma("unroll") for (int n = 0; n < 2; ++n) _Pragma("unroll") for (int k = 0; k < 2; ++k) dst[n][k] = *(const PG8_LAS bf16x8*)(lds + PG8_SB(b, h) + boff + n * 2048 + k * 1024); } while (0)
; #define PG8_WAIT_V(n) asm volatile("s_waitcnt vmcnt(" #n ")" ::: "memory")
; #define PG8_WAIT_L(n) asm volatile("s_waitcnt lgkmcnt(" #n ")" ::: "memory")
; #define PG8_BAR __builtin_amdgcn_s_barrier()
; #define PG8_SCHED __builtin_amdgcn_sched_barrier(0)
; template <class Epi, class Sched, bool ALIGN_EPI = false, bool SP2 = false>
; __device__ __forceinline__ void gemm_phase(PG8_LAS unsigned char* lds, const Gemm g, const Sched& S, const Epi& E) {
;     ...
;         const char* nA = has_next ? (const char*)g.A + (size_t)nxt.pm * tstep : cA; const char* nB = has_next ? (const char*)g.Bt + (size_t)nxt.pn * tstep : cB;
;         for (int t = 0; t < nt; t += 2) {
;             const bool last = (t == nt - 2);
;             const char* a1 = cA + (size_t)(t + 1) * kstep;
;             const char* a2 = last ? nA : cA + (size_t)(t + 2) * kstep; const char* b2 = last ? nB : cB + (size_t)(t + 2) * kstep;
;             const char* a3 = a2 + kstep; const char* b3 = b2 + kstep;
;             if (last && has_next) S.a_ready(nxt);
;             if constexpr (SP2) {
;             PG8_LDB(B0, 0, 0); PG8_LDB(B1, 0, 1); PG8_SCHED; PG8_LDA(At, 0, 0); PG8_STAGE(PG8_SA(1, 1), a1 + hstep, voffA);
;             PG8_WAIT_V(8); PG8_WAIT_L(0); PG8_BAR; PG8_MMA(0, 0, At, B0); PG8_MMA(0, 1, At, B1); PG8_BAR; PG8_SCHED;
;     ...
;         for (int a = 0; a < 2; ++a)
; #pragma unroll
;             for (int b = 0; b < 2; ++b)
; #pragma unroll
;                 for (int m = 0; m < 4; ++m)
; #pragma unroll
;                     for (int n = 0; n < 2; ++n) acc[a][b][m][n] = (f32x4){0.f, 0.f, 0.f, 0.f};
;         cur = nxt; cA = nA; cB = nB; ++ui;
.LBB0_1070:
	s_ashr_i32 s19, s18, 31
	s_lshl_b64 s[20:21], s[18:19], 22
	s_add_u32 s20, s72, s20
	s_addc_u32 s21, s73, s21
	s_and_b64 s[22:23], s[0:1], exec
	s_cselect_b32 s19, s21, s27
	s_cselect_b32 s51, s20, s26
	s_ashr_i32 s17, s16, 31
	s_lshl_b64 s[22:23], s[16:17], 22
	v_readlane_b32 s30, v236, 54
	v_readlane_b32 s31, v236, 55
	s_add_u32 s22, s30, s22
	s_addc_u32 s23, s31, s23
	s_and_b64 s[30:31], s[0:1], exec
	s_cselect_b32 s17, s23, s29
	s_cselect_b32 s52, s22, s28
	s_add_u32 s26, s26, 0x200080
	s_addc_u32 s27, s27, 0
	s_add_u32 s53, s28, 0x100
	v_mov_b32_e32 v0, 0
	s_addc_u32 s54, s29, 0
	s_mov_b32 s55, -2
	v_mov_b32_e32 v1, v0
	v_mov_b32_e32 v2, v0
	v_mov_b32_e32 v3, v0
	v_mov_b32_e32 v4, v0
	v_mov_b32_e32 v5, v0
	v_mov_b32_e32 v6, v0
	v_mov_b32_e32 v7, v0
	v_mov_b32_e32 v16, v0
	v_mov_b32_e32 v17, v0
	v_mov_b32_e32 v18, v0
	v_mov_b32_e32 v19, v0
	v_mov_b32_e32 v20, v0
	v_mov_b32_e32 v21, v0
	v_mov_b32_e32 v22, v0
	v_mov_b32_e32 v23, v0
	v_mov_b32_e32 v32, v0
	v_mov_b32_e32 v33, v0
	v_mov_b32_e32 v34, v0
	v_mov_b32_e32 v35, v0
	v_mov_b32_e32 v36, v0
	v_mov_b32_e32 v37, v0
	v_mov_b32_e32 v38, v0
	v_mov_b32_e32 v39, v0
	v_mov_b32_e32 v48, v0
	v_mov_b32_e32 v49, v0
	v_mov_b32_e32 v50, v0
	v_mov_b32_e32 v51, v0
	v_mov_b32_e32 v52, v0
	v_mov_b32_e32 v53, v0
	v_mov_b32_e32 v54, v0
	v_mov_b32_e32 v55, v0
	v_mov_b32_e32 v8, v0
	v_mov_b32_e32 v9, v0
	v_mov_b32_e32 v10, v0
	v_mov_b32_e32 v11, v0
	v_mov_b32_e32 v12, v0
	v_mov_b32_e32 v13, v0
	v_mov_b32_e32 v14, v0
	v_mov_b32_e32 v15, v0
	v_mov_b32_e32 v24, v0
	v_mov_b32_e32 v25, v0
	v_mov_b32_e32 v26, v0
	v_mov_b32_e32 v27, v0
	v_mov_b32_e32 v28, v0
	v_mov_b32_e32 v29, v0
	v_mov_b32_e32 v30, v0
	v_mov_b32_e32 v31, v0
	v_mov_b32_e32 v40, v0
	v_mov_b32_e32 v41, v0
	v_mov_b32_e32 v42, v0
	v_mov_b32_e32 v43, v0
	v_mov_b32_e32 v44, v0
	v_mov_b32_e32 v45, v0
	v_mov_b32_e32 v46, v0
	v_mov_b32_e32 v47, v0
	v_mov_b32_e32 v56, v0
	v_mov_b32_e32 v57, v0
	v_mov_b32_e32 v58, v0
	v_mov_b32_e32 v59, v0
	v_mov_b32_e32 v60, v0
	v_mov_b32_e32 v61, v0
	v_mov_b32_e32 v62, v0
	v_mov_b32_e32 v63, v0
	v_mov_b32_e32 v68, v0
	v_mov_b32_e32 v69, v0
	v_mov_b32_e32 v70, v0
	v_mov_b32_e32 v71, v0
	v_mov_b32_e32 v72, v0
	v_mov_b32_e32 v73, v0
	v_mov_b32_e32 v74, v0
	v_mov_b32_e32 v75, v0
	v_mov_b32_e32 v84, v0
	v_mov_b32_e32 v85, v0
	v_mov_b32_e32 v86, v0
	v_mov_b32_e32 v87, v0
	v_mov_b32_e32 v88, v0
	v_mov_b32_e32 v89, v0
	v_mov_b32_e32 v90, v0
	v_mov_b32_e32 v91, v0
	v_mov_b32_e32 v100, v0
	v_mov_b32_e32 v101, v0
	v_mov_b32_e32 v102, v0
	v_mov_b32_e32 v103, v0
	v_mov_b32_e32 v104, v0
	v_mov_b32_e32 v105, v0
	v_mov_b32_e32 v106, v0
	v_mov_b32_e32 v107, v0
	v_mov_b32_e32 v124, v0
	v_mov_b32_e32 v125, v0
	v_mov_b32_e32 v126, v0
	v_mov_b32_e32 v127, v0
	v_mov_b32_e32 v132, v0
	v_mov_b32_e32 v133, v0
	v_mov_b32_e32 v134, v0
	v_mov_b32_e32 v135, v0
	v_mov_b32_e32 v76, v0
	v_mov_b32_e32 v77, v0
	v_mov_b32_e32 v78, v0
	v_mov_b32_e32 v79, v0
	v_mov_b32_e32 v80, v0
	v_mov_b32_e32 v81, v0
	v_mov_b32_e32 v82, v0
	v_mov_b32_e32 v83, v0
	v_mov_b32_e32 v92, v0
	v_mov_b32_e32 v93, v0
	v_mov_b32_e32 v94, v0
	v_mov_b32_e32 v95, v0
	v_mov_b32_e32 v96, v0
	v_mov_b32_e32 v97, v0
	v_mov_b32_e32 v98, v0
	v_mov_b32_e32 v99, v0
	v_mov_b32_e32 v112, v0
	v_mov_b32_e32 v113, v0
	v_mov_b32_e32 v114, v0
	v_mov_b32_e32 v115, v0
	v_mov_b32_e32 v120, v0
	v_mov_b32_e32 v121, v0
	v_mov_b32_e32 v122, v0
	v_mov_b32_e32 v123, v0
	v_mov_b32_e32 v136, v0
	v_mov_b32_e32 v137, v0
	v_mov_b32_e32 v138, v0
	v_mov_b32_e32 v139, v0
	v_mov_b32_e32 v140, v0
	v_mov_b32_e32 v141, v0
	v_mov_b32_e32 v142, v0
	v_mov_b32_e32 v143, v0
	s_cmp_eq_u32 s99, 0
	s_cbranch_scc1 .LBB0_1071
	ds_read_b128 v[64:67], v165
	ds_read_b128 v[108:111], v165 offset:1024
	ds_read_b128 v[116:119], v165 offset:2048
	ds_read_b128 v[128:131], v165 offset:3072
	ds_read_b128 v[156:159], v166
	ds_read_b128 v[168:171], v166 offset:1024
	ds_read_b128 v[172:175], v166 offset:2048
	ds_read_b128 v[176:179], v166 offset:3072
	s_add_u32 s28, s26, 0xffe00080
	s_addc_u32 s29, s27, -1
	s_cmpk_eq_i32 s55, 0x7c
	s_cselect_b32 s31, s19, s29
	s_cselect_b32 s30, s51, s28
	s_cselect_b32 s29, s17, s54
	s_cselect_b32 s28, s52, s53
	v_lshl_add_u64 v[160:161], s[26:27], 0, v[148:149]
	s_add_i32 m0, s35, 0xc000
	ds_read_b128 v[180:183], v167
	ds_read_b128 v[184:187], v167 offset:1024
	ds_read_b128 v[188:191], v167 offset:2048
	ds_read_b128 v[192:195], v167 offset:3072
	ds_read_b128 v[196:199], v167 offset:4096
	ds_read_b128 v[200:203], v167 offset:5120
	ds_read_b128 v[204:207], v167 offset:6144
	ds_read_b128 v[208:211], v167 offset:7168
	global_load_lds_dwordx4 v[160:161], off
	v_lshl_add_u64 v[160:161], s[26:27], 0, v[150:151]
	s_add_i32 m0, s35, 0xe000
	s_nop 0
	global_load_lds_dwordx4 v[160:161], off
	s_waitcnt vmcnt(24)
	s_waitcnt lgkmcnt(0)
	s_barrier
; #define PG8_STAGE(bufoff, gbase, voff) do { _Pragma("unroll") for (int _i = 0; _i < 2; ++_i) \
;         __builtin_amdgcn_global_load_lds((const unsigned*)((const char*)(gbase) + (voff)[_i]), (PG8_LAS unsigned*)(lds + (bufoff) + ldsw + _i * 8192), 16, 0, 0); } while (0)
; #define PG8_LDA(dst, b, h) do { _Pragma("unroll") for (int m = 0; m < 4; ++m) _Pragma("unroll") for (int k = 0; k < 2; ++k) dst[m][k] = *(const PG8_LAS bf16x8*)(lds + PG8_SA(b, h) + aoff + m * 2048 + k * 1024); } while (0)
; #define PG8_LDB(dst, b, h) do { _Pragma("unroll") for (int n = 0; n < 2; ++n) _Pragma("unroll") for (int k = 0; k < 2; ++k) dst[n][k] = *(const PG8_LAS bf16x8*)(lds + PG8_SB(b, h) + boff + n * 2048 + k * 1024); } while (0)
; #define PG8_MMA(ai, bj, At, Bt) do { __builtin_amdgcn_s_setprio(1); _Pragma("unroll") for (int m = 0; m < 4; ++m) _Pragma("unroll") for (int n = 0; n < 2; ++n) _Pragma("unroll") for (int k = 0; k < 2; ++k) \
;         acc[ai][bj][m][n] = __builtin_amdgcn_mfma_f32_16x16x32_bf16(Bt[n][k], At[m][k], acc[ai][bj][m][n], 0, 0, 0); __builtin_amdgcn_s_setprio(0); } while (0)
; #define PG8_WAIT_V(n) asm volatile("s_waitcnt vmcnt(" #n ")" ::: "memory")
; #define PG8_WAIT_L(n) asm volatile("s_waitcnt lgkmcnt(" #n ")" ::: "memory")
; #define PG8_BAR __builtin_amdgcn_s_barrier()
; #define PG8_SCHED __builtin_amdgcn_sched_barrier(0)
; template <class Epi, class Sched, bool ALIGN_EPI = false, bool SP2 = false>
; __device__ __forceinline__ void gemm_phase(PG8_LAS unsigned char* lds, const Gemm g, const Sched& S, const Epi& E) {
;     ...
;             PG8_LDB(B0, 0, 0); PG8_LDB(B1, 0, 1); PG8_SCHED; PG8_LDA(At, 0, 0); PG8_STAGE(PG8_SA(1, 1), a1 + hstep, voffA);
;             PG8_WAIT_V(8); PG8_WAIT_L(0); PG8_BAR; PG8_MMA(0, 0, At, B0); PG8_MMA(0, 1, At, B1); PG8_BAR; PG8_SCHED;
;             PG8_LDA(At, 0, 1); PG8_STAGE(PG8_SB(0, 0), b2, voffB); PG8_STAGE(PG8_SB(0, 1), b2 + hstep, voffB); PG8_STAGE(PG8_SA(0, 0), a2, voffA);
;             PG8_WAIT_V(8); PG8_WAIT_L(0); PG8_BAR; PG8_MMA(1, 0, At, B0); PG8_MMA(1, 1, At, B1); PG8_BAR; PG8_SCHED;
	s_setprio 1
	s_waitcnt lgkmcnt(0)
	v_mfma_f32_16x16x32_bf16 v[140:143], v[64:67], v[180:183], v[140:143]
	v_mfma_f32_16x16x32_bf16 v[136:139], v[116:119], v[180:183], v[136:139]
	v_mfma_f32_16x16x32_bf16 v[120:123], v[64:67], v[188:191], v[120:123]
	v_mfma_f32_16x16x32_bf16 v[112:115], v[116:119], v[188:191], v[112:115]
	v_mfma_f32_16x16x32_bf16 v[96:99], v[64:67], v[196:199], v[96:99]
	v_mfma_f32_16x16x32_bf16 v[92:95], v[116:119], v[196:199], v[92:95]
	v_mfma_f32_16x16x32_bf16 v[80:83], v[64:67], v[204:207], v[80:83]
	v_mfma_f32_16x16x32_bf16 v[76:79], v[116:119], v[204:207], v[76:79]
	v_mfma_f32_16x16x32_bf16 v[140:143], v[108:111], v[184:187], v[140:143]
	v_mfma_f32_16x16x32_bf16 v[136:139], v[128:131], v[184:187], v[136:139]
	v_mfma_f32_16x16x32_bf16 v[120:123], v[108:111], v[192:195], v[120:123]
	v_mfma_f32_16x16x32_bf16 v[112:115], v[128:131], v[192:195], v[112:115]
	v_mfma_f32_16x16x32_bf16 v[96:99], v[108:111], v[200:203], v[96:99]
	v_mfma_f32_16x16x32_bf16 v[92:95], v[128:131], v[200:203], v[92:95]
	v_mfma_f32_16x16x32_bf16 v[80:83], v[108:111], v[208:211], v[80:83]
	v_mfma_f32_16x16x32_bf16 v[76:79], v[128:131], v[208:211], v[76:79]
	s_setprio 0
	s_setprio 1
	v_mfma_f32_16x16x32_bf16 v[132:135], v[156:159], v[180:183], v[132:135]
	v_mfma_f32_16x16x32_bf16 v[124:127], v[172:175], v[180:183], v[124:127]
	v_mfma_f32_16x16x32_bf16 v[104:107], v[156:159], v[188:191], v[104:107]
	v_mfma_f32_16x16x32_bf16 v[100:103], v[172:175], v[188:191], v[100:103]
	v_mfma_f32_16x16x32_bf16 v[88:91], v[156:159], v[196:199], v[88:91]
	v_mfma_f32_16x16x32_bf16 v[84:87], v[172:175], v[196:199], v[84:87]
	v_mfma_f32_16x16x32_bf16 v[72:75], v[156:159], v[204:207], v[72:75]
	v_mfma_f32_16x16x32_bf16 v[68:71], v[172:175], v[204:207], v[68:71]
	v_mfma_f32_16x16x32_bf16 v[132:135], v[168:171], v[184:187], v[132:135]
	v_mfma_f32_16x16x32_bf16 v[124:127], v[176:179], v[184:187], v[124:127]
	v_mfma_f32_16x16x32_bf16 v[104:107], v[168:171], v[192:195], v[104:107]
	v_mfma_f32_16x16x32_bf16 v[100:103], v[176:179], v[192:195], v[100:103]
	v_mfma_f32_16x16x32_bf16 v[88:91], v[168:171], v[200:203], v[88:91]
	v_mfma_f32_16x16x32_bf16 v[84:87], v[176:179], v[200:203], v[84:87]
	v_mfma_f32_16x16x32_bf16 v[72:75], v[168:171], v[208:211], v[72:75]
	v_mfma_f32_16x16x32_bf16 v[68:71], v[176:179], v[208:211], v[68:71]
	s_setprio 0
	s_barrier
	s_add_i32 s56, s45, s34
	v_lshl_add_u64 v[160:161], s[28:29], 0, v[144:145]
	s_mov_b32 m0, s56
	ds_read_b128 v[180:183], v167 offset:16384
	ds_read_b128 v[184:187], v167 offset:17408
	ds_read_b128 v[188:191], v167 offset:18432
	ds_read_b128 v[192:195], v167 offset:19456
	ds_read_b128 v[196:199], v167 offset:20480
	ds_read_b128 v[200:203], v167 offset:21504
	ds_read_b128 v[204:207], v167 offset:22528
	ds_read_b128 v[208:211], v167 offset:23552
	global_load_lds_dwordx4 v[160:161], off
	s_add_i32 m0, s56, 0x2000
	s_add_u32 s56, s28, 0x200000
	v_lshl_add_u64 v[212:213], s[28:29], 0, v[146:147]
	s_addc_u32 s57, s29, 0
	s_add_i32 s58, s46, s34
	global_load_lds_dwordx4 v[212:213], off
	v_lshl_add_u64 v[214:215], s[56:57], 0, v[144:145]
	s_mov_b32 m0, s58
	v_lshl_add_u64 v[216:217], s[30:31], 0, v[146:147]
	global_load_lds_dwordx4 v[214:215], off
	v_lshl_add_u64 v[214:215], s[56:57], 0, v[146:147]
	s_add_i32 m0, s58, 0x2000
	s_nop 0
	global_load_lds_dwordx4 v[214:215], off
	v_lshl_add_u64 v[214:215], s[30:31], 0, v[144:145]
	s_mov_b32 m0, s35
	s_nop 0
	global_load_lds_dwordx4 v[214:215], off
	s_mov_b32 m0, s36
	s_nop 0
	global_load_lds_dwordx4 v[216:217], off
	s_waitcnt vmcnt(24)
	s_waitcnt lgkmcnt(0)
	s_barrier
	s_setprio 1
	s_waitcnt lgkmcnt(0)
	v_mfma_f32_16x16x32_bf16 v[60:63], v[64:67], v[180:183], v[60:63]
	v_mfma_f32_16x16x32_bf16 v[56:59], v[116:119], v[180:183], v[56:59]
	v_mfma_f32_16x16x32_bf16 v[44:47], v[64:67], v[188:191], v[44:47]
	v_mfma_f32_16x16x32_bf16 v[40:43], v[116:119], v[188:191], v[40:43]
	v_mfma_f32_16x16x32_bf16 v[28:31], v[64:67], v[196:199], v[28:31]
	v_mfma_f32_16x16x32_bf16 v[24:27], v[116:119], v[196:199], v[24:27]
	v_mfma_f32_16x16x32_bf16 v[12:15], v[64:67], v[204:207], v[12:15]
	v_mfma_f32_16x16x32_bf16 v[8:11], v[116:119], v[204:207], v[8:11]
	v_mfma_f32_16x16x32_bf16 v[60:63], v[108:111], v[184:187], v[60:63]
	v_mfma_f32_16x16x32_bf16 v[56:59], v[128:131], v[184:187], v[56:59]
	v_mfma_f32_16x16x32_bf16 v[44:47], v[108:111], v[192:195], v[44:47]
	v_mfma_f32_16x16x32_bf16 v[40:43], v[128:131], v[192:195], v[40:43]
	v_mfma_f32_16x16x32_bf16 v[28:31], v[108:111], v[200:203], v[28:31]
	v_mfma_f32_16x16x32_bf16 v[24:27], v[128:131], v[200:203], v[24:27]
	v_mfma_f32_16x16x32_bf16 v[12:15], v[108:111], v[208:211], v[12:15]
	v_mfma_f32_16x16x32_bf16 v[8:11], v[128:131], v[208:211], v[8:11]
	s_setprio 0
	s_setprio 1
	v_mfma_f32_16x16x32_bf16 v[52:55], v[156:159], v[180:183], v[52:55]
	v_mfma_f32_16x16x32_bf16 v[48:51], v[172:175], v[180:183], v[48:51]
	v_mfma_f32_16x16x32_bf16 v[36:39], v[156:159], v[188:191], v[36:39]
	v_mfma_f32_16x16x32_bf16 v[32:35], v[172:175], v[188:191], v[32:35]
	v_mfma_f32_16x16x32_bf16 v[20:23], v[156:159], v[196:199], v[20:23]
	v_mfma_f32_16x16x32_bf16 v[16:19], v[172:175], v[196:199], v[16:19]
	v_mfma_f32_16x16x32_bf16 v[4:7], v[156:159], v[204:207], v[4:7]
	v_mfma_f32_16x16x32_bf16 v[0:3], v[172:175], v[204:207], v[0:3]
	v_mfma_f32_16x16x32_bf16 v[52:55], v[168:171], v[184:187], v[52:55]
	v_mfma_f32_16x16x32_bf16 v[48:51], v[176:179], v[184:187], v[48:51]
	v_mfma_f32_16x16x32_bf16 v[36:39], v[168:171], v[192:195], v[36:39]
	v_mfma_f32_16x16x32_bf16 v[32:35], v[176:179], v[192:195], v[32:35]
	v_mfma_f32_16x16x32_bf16 v[20:23], v[168:171], v[200:203], v[20:23]
	v_mfma_f32_16x16x32_bf16 v[16:19], v[176:179], v[200:203], v[16:19]
	v_mfma_f32_16x16x32_bf16 v[4:7], v[168:171], v[208:211], v[4:7]
	v_mfma_f32_16x16x32_bf16 v[0:3], v[176:179], v[208:211], v[0:3]
	s_setprio 0
	s_barrier
; #define PG8_STAGE(bufoff, gbase, voff) do { _Pragma("unroll") for (int _i = 0; _i < 2; ++_i) \
;         __builtin_amdgcn_global_load_lds((const unsigned*)((const char*)(gbase) + (voff)[_i]), (PG8_LAS unsigned*)(lds + (bufoff) + ldsw + _i * 8192), 16, 0, 0); } while (0)
; #define PG8_LDA(dst, b, h) do { _Pragma("unroll") for (int m = 0; m < 4; ++m) _Pragma("unroll") for (int k = 0; k < 2; ++k) dst[m][k] = *(const PG8_LAS bf16x8*)(lds + PG8_SA(b, h) + aoff + m * 2048 + k * 1024); } while (0)
; #define PG8_LDB(dst, b, h) do { _Pragma("unroll") for (int n = 0; n < 2; ++n) _Pragma("unroll") for (int k = 0; k < 2; ++k) dst[n][k] = *(const PG8_LAS bf16x8*)(lds + PG8_SB(b, h) + boff + n * 2048 + k * 1024); } while (0)
; #define PG8_MMA(ai, bj, At, Bt) do { __builtin_amdgcn_s_setprio(1); _Pragma("unroll") for (int m = 0; m < 4; ++m) _Pragma("unroll") for (int n = 0; n < 2; ++n) _Pragma("unroll") for (int k = 0; k < 2; ++k) \
;         acc[ai][bj][m][n] = __builtin_amdgcn_mfma_f32_16x16x32_bf16(Bt[n][k], At[m][k], acc[ai][bj][m][n], 0, 0, 0); __builtin_amdgcn_s_setprio(0); } while (0)
; #define PG8_WAIT_V(n) asm volatile("s_waitcnt vmcnt(" #n ")" ::: "memory")
; #define PG8_WAIT_L(n) asm volatile("s_waitcnt lgkmcnt(" #n ")" ::: "memory")
; #define PG8_BAR __builtin_amdgcn_s_barrier()
; #define PG8_SCHED __builtin_amdgcn_sched_barrier(0)
; template <class Epi, class Sched, bool ALIGN_EPI = false, bool SP2 = false>
; __device__ __forceinline__ void gemm_phase(PG8_LAS unsigned char* lds, const Gemm g, const Sched& S, const Epi& E) {
;     ...
;             PG8_LDB(B0, 1, 0); PG8_LDB(B1, 1, 1); PG8_SCHED; PG8_LDA(At, 1, 0); PG8_STAGE(PG8_SA(0, 1), a2 + hstep, voffA);
;             PG8_WAIT_V(8); PG8_WAIT_L(0); PG8_BAR; PG8_MMA(0, 0, At, B0); PG8_MMA(0, 1, At, B1); PG8_BAR; PG8_SCHED;
	s_add_i32 s56, 0, 0x18000
	s_add_i32 s57, 0, 0x1c000
	v_add_u32_e32 v128, s56, v163
	v_add_u32_e32 v176, s57, v163
	ds_read_b128 v[64:67], v128
	ds_read_b128 v[108:111], v128 offset:1024
	ds_read_b128 v[116:119], v128 offset:2048
	ds_read_b128 v[128:131], v128 offset:3072
	ds_read_b128 v[156:159], v176
	ds_read_b128 v[168:171], v176 offset:1024
	ds_read_b128 v[172:175], v176 offset:2048
	ds_read_b128 v[176:179], v176 offset:3072
	s_add_u32 s30, s30, 0x200000
	s_addc_u32 s31, s31, 0
	s_mov_b32 m0, s37
	v_lshl_add_u64 v[218:219], s[30:31], 0, v[144:145]
	ds_read_b128 v[180:183], v167 offset:32768
	ds_read_b128 v[184:187], v167 offset:33792
	ds_read_b128 v[188:191], v167 offset:34816
	ds_read_b128 v[192:195], v167 offset:35840
	ds_read_b128 v[196:199], v167 offset:36864
	ds_read_b128 v[200:203], v167 offset:37888
	ds_read_b128 v[204:207], v167 offset:38912
	ds_read_b128 v[208:211], v167 offset:39936
	global_load_lds_dwordx4 v[218:219], off
	v_lshl_add_u64 v[218:219], s[30:31], 0, v[146:147]
	s_mov_b32 m0, s38
	s_nop 0
	global_load_lds_dwordx4 v[218:219], off
	s_waitcnt vmcnt(8)
	s_waitcnt lgkmcnt(0)
	s_barrier
	s_setprio 1
	s_waitcnt lgkmcnt(0)
	v_mfma_f32_16x16x32_bf16 v[140:143], v[64:67], v[180:183], v[140:143]
	v_mfma_f32_16x16x32_bf16 v[136:139], v[116:119], v[180:183], v[136:139]
	v_mfma_f32_16x16x32_bf16 v[120:123], v[64:67], v[188:191], v[120:123]
	v_mfma_f32_16x16x32_bf16 v[112:115], v[116:119], v[188:191], v[112:115]
	v_mfma_f32_16x16x32_bf16 v[96:99], v[64:67], v[196:199], v[96:99]
	v_mfma_f32_16x16x32_bf16 v[92:95], v[116:119], v[196:199], v[92:95]
	v_mfma_f32_16x16x32_bf16 v[80:83], v[64:67], v[204:207], v[80:83]
	v_mfma_f32_16x16x32_bf16 v[76:79], v[116:119], v[204:207], v[76:79]
	v_mfma_f32_16x16x32_bf16 v[140:143], v[108:111], v[184:187], v[140:143]
	v_mfma_f32_16x16x32_bf16 v[136:139], v[128:131], v[184:187], v[136:139]
	v_mfma_f32_16x16x32_bf16 v[120:123], v[108:111], v[192:195], v[120:123]
	v_mfma_f32_16x16x32_bf16 v[112:115], v[128:131], v[192:195], v[112:115]
	v_mfma_f32_16x16x32_bf16 v[96:99], v[108:111], v[200:203], v[96:99]
	v_mfma_f32_16x16x32_bf16 v[92:95], v[128:131], v[200:203], v[92:95]
	v_mfma_f32_16x16x32_bf16 v[80:83], v[108:111], v[208:211], v[80:83]
	v_mfma_f32_16x16x32_bf16 v[76:79], v[128:131], v[208:211], v[76:79]
	s_setprio 0
	s_setprio 1
	v_mfma_f32_16x16x32_bf16 v[132:135], v[156:159], v[180:183], v[132:135]
	v_mfma_f32_16x16x32_bf16 v[124:127], v[172:175], v[180:183], v[124:127]
	v_mfma_f32_16x16x32_bf16 v[104:107], v[156:159], v[188:191], v[104:107]
	v_mfma_f32_16x16x32_bf16 v[100:103], v[172:175], v[188:191], v[100:103]
	v_mfma_f32_16x16x32_bf16 v[88:91], v[156:159], v[196:199], v[88:91]
	v_mfma_f32_16x16x32_bf16 v[84:87], v[172:175], v[196:199], v[84:87]
	v_mfma_f32_16x16x32_bf16 v[72:75], v[156:159], v[204:207], v[72:75]
	v_mfma_f32_16x16x32_bf16 v[68:71], v[172:175], v[204:207], v[68:71]
	v_mfma_f32_16x16x32_bf16 v[132:135], v[168:171], v[184:187], v[132:135]
	v_mfma_f32_16x16x32_bf16 v[124:127], v[176:179], v[184:187], v[124:127]
	v_mfma_f32_16x16x32_bf16 v[104:107], v[168:171], v[192:195], v[104:107]
	v_mfma_f32_16x16x32_bf16 v[100:103], v[176:179], v[192:195], v[100:103]
	v_mfma_f32_16x16x32_bf16 v[88:91], v[168:171], v[200:203], v[88:91]
	v_mfma_f32_16x16x32_bf16 v[84:87], v[176:179], v[200:203], v[84:87]
	v_mfma_f32_16x16x32_bf16 v[72:75], v[168:171], v[208:211], v[72:75]
	v_mfma_f32_16x16x32_bf16 v[68:71], v[176:179], v[208:211], v[68:71]
	s_setprio 0
	s_barrier
; #define PG8_STAGE(bufoff, gbase, voff) do { _Pragma("unroll") for (int _i = 0; _i < 2; ++_i) \
;         __builtin_amdgcn_global_load_lds((const unsigned*)((const char*)(gbase) + (voff)[_i]), (PG8_LAS unsigned*)(lds + (bufoff) + ldsw + _i * 8192), 16, 0, 0); } while (0)
; #define PG8_LDA(dst, b, h) do { _Pragma("unroll") for (int m = 0; m < 4; ++m) _Pragma("unroll") for (int k = 0; k < 2; ++k) dst[m][k] = *(const PG8_LAS bf16x8*)(lds + PG8_SA(b, h) + aoff + m * 2048 + k * 1024); } while (0)
; #define PG8_LDB(dst, b, h) do { _Pragma("unroll") for (int n = 0; n < 2; ++n) _Pragma("unroll") for (int k = 0; k < 2; ++k) dst[n][k] = *(const PG8_LAS bf16x8*)(lds + PG8_SB(b, h) + boff + n * 2048 + k * 1024); } while (0)
; template <class Epi, class Sched, bool ALIGN_EPI = false, bool SP2 = false>
; __device__ __forceinline__ void gemm_phase(PG8_LAS unsigned char* lds, const Gemm g, const Sched& S, const Epi& E) {
;     ...
;         for (int t = 0; t < nt; t += 2) {
;             const bool last = (t == nt - 2);
;             const char* a1 = cA + (size_t)(t + 1) * kstep;
;             const char* a2 = last ? nA : cA + (size_t)(t + 2) * kstep; const char* b2 = last ? nB : cB + (size_t)(t + 2) * kstep;
;             const char* a3 = a2 + kstep; const char* b3 = b2 + kstep;
;             if (last && has_next) S.a_ready(nxt);
;             if constexpr (SP2) {
;             PG8_LDB(B0, 0, 0); PG8_LDB(B1, 0, 1); PG8_SCHED; PG8_LDA(At, 0, 0); PG8_STAGE(PG8_SA(1, 1), a1 + hstep, voffA);
;             PG8_WAIT_V(8); PG8_WAIT_L(0); PG8_BAR; PG8_MMA(0, 0, At, B0); PG8_MMA(0, 1, At, B1); PG8_BAR; PG8_SCHED;
;             PG8_LDA(At, 0, 1); PG8_STAGE(PG8_SB(0, 0), b2, voffB); PG8_STAGE(PG8_SB(0, 1), b2 + hstep, voffB); PG8_STAGE(PG8_SA(0, 0), a2, voffA);
;             PG8_WAIT_V(8); PG8_WAIT_L(0); PG8_BAR; PG8_MMA(1, 0, At, B0); PG8_MMA(1, 1, At, B1); PG8_BAR; PG8_SCHED;
;             PG8_LDB(B0, 1, 0); PG8_LDB(B1, 1, 1); PG8_SCHED; PG8_LDA(At, 1, 0); PG8_STAGE(PG8_SA(0, 1), a2 + hstep, voffA);
;             PG8_WAIT_V(8); PG8_WAIT_L(0); PG8_BAR; PG8_MMA(0, 0, At, B0); PG8_MMA(0, 1, At, B1); PG8_BAR; PG8_SCHED;
;             PG8_LDA(At, 1, 1); PG8_STAGE(PG8_SB(1, 0), b3, voffB); PG8_STAGE(PG8_SB(1, 1), b3 + hstep, voffB); PG8_STAGE(PG8_SA(1, 0), a3, voffA);
;             PG8_WAIT_V(8); PG8_WAIT_L(0); PG8_BAR; PG8_MMA(1, 0, At, B0); PG8_MMA(1, 1, At, B1); PG8_BAR; PG8_SCHED;
	s_add_i32 s30, s56, s34
	v_lshl_add_u64 v[160:161], v[160:161], 0, s[4:5]
	s_mov_b32 m0, s30
	ds_read_b128 v[180:183], v167 offset:49152
	ds_read_b128 v[184:187], v167 offset:50176
	ds_read_b128 v[188:191], v167 offset:51200
	ds_read_b128 v[192:195], v167 offset:52224
	ds_read_b128 v[196:199], v167 offset:53248
	ds_read_b128 v[200:203], v167 offset:54272
	ds_read_b128 v[204:207], v167 offset:55296
	ds_read_b128 v[208:211], v167 offset:56320
	global_load_lds_dwordx4 v[160:161], off
	s_add_i32 m0, s30, 0x2000
	s_add_u32 s28, s28, 0x200080
	v_lshl_add_u64 v[160:161], v[212:213], 0, s[4:5]
	s_addc_u32 s29, s29, 0
	s_add_i32 s30, s57, s34
	global_load_lds_dwordx4 v[160:161], off
	v_lshl_add_u64 v[160:161], s[28:29], 0, v[144:145]
	s_mov_b32 m0, s30
	s_nop 0
	global_load_lds_dwordx4 v[160:161], off
	v_lshl_add_u64 v[160:161], s[28:29], 0, v[146:147]
	s_add_i32 m0, s30, 0x2000
	s_nop 0
	global_load_lds_dwordx4 v[160:161], off
	v_lshl_add_u64 v[160:161], v[214:215], 0, s[4:5]
	s_mov_b32 m0, s42
	s_nop 0
	global_load_lds_dwordx4 v[160:161], off
	v_lshl_add_u64 v[160:161], v[216:217], 0, s[4:5]
	s_mov_b32 m0, s43
	s_nop 0
	global_load_lds_dwordx4 v[160:161], off
	s_waitcnt vmcnt(8)
	s_waitcnt lgkmcnt(0)
	s_barrier
	s_setprio 1
	s_waitcnt lgkmcnt(0)
	v_mfma_f32_16x16x32_bf16 v[60:63], v[64:67], v[180:183], v[60:63]
	v_mfma_f32_16x16x32_bf16 v[56:59], v[116:119], v[180:183], v[56:59]
	v_mfma_f32_16x16x32_bf16 v[44:47], v[64:67], v[188:191], v[44:47]
	v_mfma_f32_16x16x32_bf16 v[40:43], v[116:119], v[188:191], v[40:43]
	v_mfma_f32_16x16x32_bf16 v[28:31], v[64:67], v[196:199], v[28:31]
	v_mfma_f32_16x16x32_bf16 v[24:27], v[116:119], v[196:199], v[24:27]
	v_mfma_f32_16x16x32_bf16 v[12:15], v[64:67], v[204:207], v[12:15]
	v_mfma_f32_16x16x32_bf16 v[8:11], v[116:119], v[204:207], v[8:11]
	v_mfma_f32_16x16x32_bf16 v[60:63], v[108:111], v[184:187], v[60:63]
	v_mfma_f32_16x16x32_bf16 v[56:59], v[128:131], v[184:187], v[56:59]
	v_mfma_f32_16x16x32_bf16 v[44:47], v[108:111], v[192:195], v[44:47]
	v_mfma_f32_16x16x32_bf16 v[40:43], v[128:131], v[192:195], v[40:43]
	v_mfma_f32_16x16x32_bf16 v[28:31], v[108:111], v[200:203], v[28:31]
	v_mfma_f32_16x16x32_bf16 v[24:27], v[128:131], v[200:203], v[24:27]
	v_mfma_f32_16x16x32_bf16 v[12:15], v[108:111], v[208:211], v[12:15]
	v_mfma_f32_16x16x32_bf16 v[8:11], v[128:131], v[208:211], v[8:11]
	s_setprio 0
	s_setprio 1
	v_mfma_f32_16x16x32_bf16 v[52:55], v[156:159], v[180:183], v[52:55]
	v_mfma_f32_16x16x32_bf16 v[48:51], v[172:175], v[180:183], v[48:51]
	v_mfma_f32_16x16x32_bf16 v[36:39], v[156:159], v[188:191], v[36:39]
	v_mfma_f32_16x16x32_bf16 v[32:35], v[172:175], v[188:191], v[32:35]
	v_mfma_f32_16x16x32_bf16 v[20:23], v[156:159], v[196:199], v[20:23]
	v_mfma_f32_16x16x32_bf16 v[16:19], v[172:175], v[196:199], v[16:19]
	v_mfma_f32_16x16x32_bf16 v[4:7], v[156:159], v[204:207], v[4:7]
	v_mfma_f32_16x16x32_bf16 v[0:3], v[172:175], v[204:207], v[0:3]
	v_mfma_f32_16x16x32_bf16 v[52:55], v[168:171], v[184:187], v[52:55]
	v_mfma_f32_16x16x32_bf16 v[48:51], v[176:179], v[184:187], v[48:51]
	v_mfma_f32_16x16x32_bf16 v[36:39], v[168:171], v[192:195], v[36:39]
	v_mfma_f32_16x16x32_bf16 v[32:35], v[176:179], v[192:195], v[32:35]
	v_mfma_f32_16x16x32_bf16 v[20:23], v[168:171], v[200:203], v[20:23]
	v_mfma_f32_16x16x32_bf16 v[16:19], v[176:179], v[200:203], v[16:19]
	v_mfma_f32_16x16x32_bf16 v[4:7], v[168:171], v[208:211], v[4:7]
	v_mfma_f32_16x16x32_bf16 v[0:3], v[176:179], v[208:211], v[0:3]
	s_setprio 0
	s_barrier
	s_add_i32 s55, s55, 2
	s_add_u32 s26, s26, 0x100
	s_addc_u32 s27, s27, 0
	s_add_u32 s53, s53, 0x100
	s_addc_u32 s54, s54, 0
	s_cmpk_gt_u32 s55, 0x7d

;     __device__ __forceinline__ void operator()(const f32x4 (&acc)[2][2][4][2], const Unit& u, int wr, int wc, int fr, int fq) const {
;         const int row0 = u.pm * BM + wr * 64 + fr, col0 = u.pn * BM + wc * 32 + 4 * fq, b = (u.pm * BM) >> 12;
;         f32x4 gv[2][2];
; #pragma unroll
;         for (int bj = 0; bj < 2; ++bj)
; #pragma unroll
;             for (int n = 0; n < 2; ++n) gv[bj][n] = *(const f32x4*)(gate + (size_t)b * 12288 + col0 + bj * HALF + n * 16);
; #pragma unroll
;         for (int ai = 0; ai < 2; ++ai)
; #pragma unroll
;             for (int m = 0; m < 4; ++m) { const size_t off = (size_t)(row0 + ai * HALF + m * 16) * 2048 + col0;
; #pragma unroll
;                 for (int bj = 0; bj < 2; ++bj)
; #pragma unroll
;                     for (int n = 0; n < 2; ++n) { const f32x4 bs = __builtin_nontemporal_load((const f32x4*)(base + off + bj * HALF + n * 16));
;                         *(f32x4*)(out + off + bj * HALF + n * 16) = bs + gv[bj][n] * acc[ai][bj][m][n]; } }
.LBB0_1074:
	s_ashr_i32 s17, s24, 4
	v_lshl_add_u32 v160, s24, 8, v162
	v_lshl_or_b32 v64, s25, 8, v164
	s_mul_hi_i32 s19, s17, 0xc000
	s_mul_i32 s17, s17, 0xc000
	v_ashrrev_i32_e32 v161, 31, v160
	s_add_u32 s26, s40, s17
	v_ashrrev_i32_e32 v65, 31, v64
	v_lshlrev_b64 v[156:157], 13, v[160:161]
	s_addc_u32 s27, s41, s19
	v_lshlrev_b64 v[158:159], 2, v[64:65]
	v_lshl_add_u64 v[156:157], s[66:67], 0, v[156:157]
	v_lshl_add_u64 v[64:65], s[26:27], 0, v[158:159]
	v_lshl_add_u64 v[156:157], v[156:157], 0, v[158:159]
	global_load_dwordx4 v[128:131], v[64:65], off
	global_load_dwordx4 v[116:119], v[64:65], off offset:64
	global_load_dwordx4 v[108:111], v[64:65], off offset:512
	s_nop 0
	global_load_dwordx4 v[64:67], v[64:65], off offset:576
	s_mov_b64 s[24:25], -1
	s_mov_b64 s[98:99], 0x20000
	s_mov_b64 s[100:101], 0xa0000
	v_mov_b64_e32 v[158:159], v[156:157]
	global_load_dwordx4 v[168:171], v[158:159], off nt
	global_load_dwordx4 v[172:175], v[158:159], off offset:64 nt
	global_load_dwordx4 v[176:179], v[158:159], off offset:512 nt
	global_load_dwordx4 v[180:183], v[158:159], off offset:576 nt
	v_lshl_add_u64 v[158:159], v[158:159], 0, s[98:99]
	global_load_dwordx4 v[184:187], v[158:159], off nt
	global_load_dwordx4 v[188:191], v[158:159], off offset:64 nt
	global_load_dwordx4 v[192:195], v[158:159], off offset:512 nt
	global_load_dwordx4 v[196:199], v[158:159], off offset:576 nt
	v_lshl_add_u64 v[158:159], v[158:159], 0, s[98:99]
	global_load_dwordx4 v[200:203], v[158:159], off nt
	global_load_dwordx4 v[204:207], v[158:159], off offset:64 nt
	global_load_dwordx4 v[208:211], v[158:159], off offset:512 nt
	s_waitcnt vmcnt(10)
	v_pk_fma_f32 v[142:143], v[142:143], v[130:131], v[170:171]
	v_pk_fma_f32 v[140:141], v[140:141], v[128:129], v[168:169]
	global_store_dwordx4 v[156:157], v[140:143], off
	global_load_dwordx4 v[168:171], v[158:159], off offset:576 nt
	v_lshl_add_u64 v[158:159], v[158:159], 0, s[98:99]
	s_waitcnt vmcnt(11)
	v_pk_fma_f32 v[138:139], v[138:139], v[118:119], v[174:175]
	v_pk_fma_f32 v[136:137], v[136:137], v[116:117], v[172:173]
	global_store_dwordx4 v[156:157], v[136:139], off offset:64
	global_load_dwordx4 v[172:175], v[158:159], off nt
	s_waitcnt vmcnt(12)
	v_pk_fma_f32 v[134:135], v[134:135], v[110:111], v[178:179]
	v_pk_fma_f32 v[132:133], v[132:133], v[108:109], v[176:177]
	global_store_dwordx4 v[156:157], v[132:135], off offset:512
	global_load_dwordx4 v[176:179], v[158:159], off offset:64 nt
	s_waitcnt vmcnt(13)
	v_pk_fma_f32 v[126:127], v[126:127], v[66:67], v[182:183]
	v_pk_fma_f32 v[124:125], v[124:125], v[64:65], v[180:181]
	global_store_dwordx4 v[156:157], v[124:127], off offset:576
	v_lshl_add_u64 v[156:157], v[156:157], 0, s[98:99]
	global_load_dwordx4 v[180:183], v[158:159], off offset:512 nt
	s_waitcnt vmcnt(14)
	v_pk_fma_f32 v[122:123], v[122:123], v[130:131], v[186:187]
	v_pk_fma_f32 v[120:121], v[120:121], v[128:129], v[184:185]
	global_store_dwordx4 v[156:157], v[120:123], off
	global_load_dwordx4 v[184:187], v[158:159], off offset:576 nt
	v_lshl_add_u64 v[158:159], v[158:159], 0, s[100:101]
	s_waitcnt vmcnt(15)
	v_pk_fma_f32 v[114:115], v[114:115], v[118:119], v[190:191]
	v_pk_fma_f32 v[112:113], v[112:113], v[116:117], v[188:189]
	global_store_dwordx4 v[156:157], v[112:115], off offset:64
	global_load_dwordx4 v[188:191], v[158:159], off nt
	s_waitcnt vmcnt(16)
	v_pk_fma_f32 v[106:107], v[106:107], v[110:111], v[194:195]
	v_pk_fma_f32 v[104:105], v[104:105], v[108:109], v[192:193]
	global_store_dwordx4 v[156:157], v[104:107], off offset:512
	global_load_dwordx4 v[192:195], v[158:159], off offset:64 nt
	s_waitcnt vmcnt(17)
	v_pk_fma_f32 v[102:103], v[102:103], v[66:67], v[198:199]
	v_pk_fma_f32 v[100:101], v[100:101], v[64:65], v[196:197]
	global_store_dwordx4 v[156:157], v[100:103], off offset:576
	v_lshl_add_u64 v[156:157], v[156:157], 0, s[98:99]
	global_load_dwordx4 v[196:199], v[158:159], off offset:512 nt
	s_waitcnt vmcnt(18)
	v_pk_fma_f32 v[98:99], v[98:99], v[130:131], v[202:203]
	v_pk_fma_f32 v[96:97], v[96:97], v[128:129], v[200:201]
	global_store_dwordx4 v[156:157], v[96:99], off
	global_load_dwordx4 v[200:203], v[158:159], off offset:576 nt
	v_lshl_add_u64 v[158:159], v[158:159], 0, s[98:99]
	s_waitcnt vmcnt(19)
	v_pk_fma_f32 v[94:95], v[94:95], v[118:119], v[206:207]
	v_pk_fma_f32 v[92:93], v[92:93], v[116:117], v[204:205]
	global_store_dwordx4 v[156:157], v[92:95], off offset:64
	global_load_dwordx4 v[204:207], v[158:159], off nt
	s_waitcnt vmcnt(20)
	v_pk_fma_f32 v[90:91], v[90:91], v[110:111], v[210:211]
	v_pk_fma_f32 v[88:89], v[88:89], v[108:109], v[208:209]
	global_store_dwordx4 v[156:157], v[88:91], off offset:512
	global_load_dwordx4 v[208:211], v[158:159], off offset:64 nt
	s_waitcnt vmcnt(20)
	v_pk_fma_f32 v[86:87], v[86:87], v[66:67], v[170:171]
	v_pk_fma_f32 v[84:85], v[84:85], v[64:65], v[168:169]
	global_store_dwordx4 v[156:157], v[84:87], off offset:576
	v_lshl_add_u64 v[156:157], v[156:157], 0, s[98:99]
	global_load_dwordx4 v[168:171], v[158:159], off offset:512 nt
	s_waitcnt vmcnt(20)
;     __device__ __forceinline__ void operator()(const f32x4 (&acc)[2][2][4][2], const Unit& u, int wr, int wc, int fr, int fq) const {
;     ...
;         for (int ai = 0; ai < 2; ++ai)
; #pragma unroll
;             for (int m = 0; m < 4; ++m) { const size_t off = (size_t)(row0 + ai * HALF + m * 16) * 2048 + col0;
; #pragma unroll
;                 for (int bj = 0; bj < 2; ++bj)
; #pragma unroll
;                     for (int n = 0; n < 2; ++n) { const f32x4 bs = __builtin_nontemporal_load((const f32x4*)(base + off + bj * HALF + n * 16));
;                         *(f32x4*)(out + off + bj * HALF + n * 16) = bs + gv[bj][n] * acc[ai][bj][m][n]; } }
; template <class Epi, class Sched, bool ALIGN_EPI = false, bool SP2 = false>
; __device__ __forceinline__ void gemm_phase(PG8_LAS unsigned char* lds, const Gemm g, const Sched& S, const Epi& E) {
;     ...
;         if constexpr (!Epi::AFTER_DRAIN) { E(acc, cur, wr, wc, fr, fq); S.done(cur); }
;         if (!has_next) break;
	v_pk_fma_f32 v[82:83], v[82:83], v[130:131], v[174:175]
	v_pk_fma_f32 v[80:81], v[80:81], v[128:129], v[172:173]
	global_store_dwordx4 v[156:157], v[80:83], off
	global_load_dwordx4 v[172:175], v[158:159], off offset:576 nt
	v_lshl_add_u64 v[158:159], v[158:159], 0, s[98:99]
	s_waitcnt vmcnt(20)
	v_pk_fma_f32 v[78:79], v[78:79], v[118:119], v[178:179]
	v_pk_fma_f32 v[76:77], v[76:77], v[116:117], v[176:177]
	global_store_dwordx4 v[156:157], v[76:79], off offset:64
	global_load_dwordx4 v[176:179], v[158:159], off nt
	s_waitcnt vmcnt(20)
	v_pk_fma_f32 v[74:75], v[74:75], v[110:111], v[182:183]
	v_pk_fma_f32 v[72:73], v[72:73], v[108:109], v[180:181]
	global_store_dwordx4 v[156:157], v[72:75], off offset:512
	global_load_dwordx4 v[180:183], v[158:159], off offset:64 nt
	s_waitcnt vmcnt(20)
	v_pk_fma_f32 v[70:71], v[70:71], v[66:67], v[186:187]
	v_pk_fma_f32 v[68:69], v[68:69], v[64:65], v[184:185]
	global_store_dwordx4 v[156:157], v[68:71], off offset:576
	v_lshl_add_u64 v[156:157], v[156:157], 0, s[100:101]
	global_load_dwordx4 v[184:187], v[158:159], off offset:512 nt
	s_waitcnt vmcnt(20)
	v_pk_fma_f32 v[62:63], v[62:63], v[130:131], v[190:191]
	v_pk_fma_f32 v[60:61], v[60:61], v[128:129], v[188:189]
	global_store_dwordx4 v[156:157], v[60:63], off
	global_load_dwordx4 v[188:191], v[158:159], off offset:576 nt
	v_lshl_add_u64 v[158:159], v[158:159], 0, s[98:99]
	s_waitcnt vmcnt(20)
	v_pk_fma_f32 v[58:59], v[58:59], v[118:119], v[194:195]
	v_pk_fma_f32 v[56:57], v[56:57], v[116:117], v[192:193]
	global_store_dwordx4 v[156:157], v[56:59], off offset:64
	global_load_dwordx4 v[192:195], v[158:159], off nt
	s_waitcnt vmcnt(20)
	v_pk_fma_f32 v[54:55], v[54:55], v[110:111], v[198:199]
	v_pk_fma_f32 v[52:53], v[52:53], v[108:109], v[196:197]
	global_store_dwordx4 v[156:157], v[52:55], off offset:512
	global_load_dwordx4 v[196:199], v[158:159], off offset:64 nt
	s_waitcnt vmcnt(20)
	v_pk_fma_f32 v[50:51], v[50:51], v[66:67], v[202:203]
	v_pk_fma_f32 v[48:49], v[48:49], v[64:65], v[200:201]
	global_store_dwordx4 v[156:157], v[48:51], off offset:576
	v_lshl_add_u64 v[156:157], v[156:157], 0, s[98:99]
	global_load_dwordx4 v[200:203], v[158:159], off offset:512 nt
	s_waitcnt vmcnt(20)
	v_pk_fma_f32 v[46:47], v[46:47], v[130:131], v[206:207]
	v_pk_fma_f32 v[44:45], v[44:45], v[128:129], v[204:205]
	global_store_dwordx4 v[156:157], v[44:47], off
	global_load_dwordx4 v[204:207], v[158:159], off offset:576 nt
	s_waitcnt vmcnt(20)
	v_pk_fma_f32 v[42:43], v[42:43], v[118:119], v[210:211]
	v_pk_fma_f32 v[40:41], v[40:41], v[116:117], v[208:209]
	global_store_dwordx4 v[156:157], v[40:43], off offset:64
	s_waitcnt vmcnt(19)
	v_pk_fma_f32 v[38:39], v[38:39], v[110:111], v[170:171]
	v_pk_fma_f32 v[36:37], v[36:37], v[108:109], v[168:169]
	global_store_dwordx4 v[156:157], v[36:39], off offset:512
	s_waitcnt vmcnt(18)
	v_pk_fma_f32 v[34:35], v[34:35], v[66:67], v[174:175]
	v_pk_fma_f32 v[32:33], v[32:33], v[64:65], v[172:173]
	global_store_dwordx4 v[156:157], v[32:35], off offset:576
	v_lshl_add_u64 v[156:157], v[156:157], 0, s[98:99]
	s_waitcnt vmcnt(17)
	v_pk_fma_f32 v[30:31], v[30:31], v[130:131], v[178:179]
	v_pk_fma_f32 v[28:29], v[28:29], v[128:129], v[176:177]
	global_store_dwordx4 v[156:157], v[28:31], off
	s_waitcnt vmcnt(16)
	v_pk_fma_f32 v[26:27], v[26:27], v[118:119], v[182:183]
	v_pk_fma_f32 v[24:25], v[24:25], v[116:117], v[180:181]
	global_store_dwordx4 v[156:157], v[24:27], off offset:64
	s_waitcnt vmcnt(15)
	v_pk_fma_f32 v[22:23], v[22:23], v[110:111], v[186:187]
	v_pk_fma_f32 v[20:21], v[20:21], v[108:109], v[184:185]
	global_store_dwordx4 v[156:157], v[20:23], off offset:512
	s_waitcnt vmcnt(14)
	v_pk_fma_f32 v[18:19], v[18:19], v[66:67], v[190:191]
	v_pk_fma_f32 v[16:17], v[16:17], v[64:65], v[188:189]
	global_store_dwordx4 v[156:157], v[16:19], off offset:576
	v_lshl_add_u64 v[156:157], v[156:157], 0, s[98:99]
	s_waitcnt vmcnt(13)
	v_pk_fma_f32 v[14:15], v[14:15], v[130:131], v[194:195]
	v_pk_fma_f32 v[12:13], v[12:13], v[128:129], v[192:193]
	global_store_dwordx4 v[156:157], v[12:15], off
	s_waitcnt vmcnt(12)
	v_pk_fma_f32 v[10:11], v[10:11], v[118:119], v[198:199]
	v_pk_fma_f32 v[8:9], v[8:9], v[116:117], v[196:197]
	global_store_dwordx4 v[156:157], v[8:11], off offset:64
	s_waitcnt vmcnt(11)
	v_pk_fma_f32 v[6:7], v[6:7], v[110:111], v[202:203]
	v_pk_fma_f32 v[4:5], v[4:5], v[108:109], v[200:201]
	global_store_dwordx4 v[156:157], v[4:7], off offset:512
	s_waitcnt vmcnt(10)
	v_pk_fma_f32 v[2:3], v[2:3], v[66:67], v[206:207]
	v_pk_fma_f32 v[0:1], v[0:1], v[64:65], v[204:205]
	global_store_dwordx4 v[156:157], v[0:3], off offset:576
	s_andn2_b64 vcc, exec, s[0:1]
	s_mov_b32 s99, 1
	s_cbranch_vccnz .LBB0_1063
	s_andn2_b64 vcc, exec, s[2:3]
	s_cbranch_vccnz .LBB0_1062
	s_barrier
	s_branch .LBB0_1062
